# speedup vs baseline: 1.0215x; 1.0039x over previous
; #define STAGE(P, RS, SOFF, OFF, kt) do { const int _so = (SOFF) + (kt) * (BK * 2); \
;     _Pragma("unroll") for (int _i = 0; _i < 2; ++_i) { \
;       __builtin_amdgcn_raw_ptr_buffer_load_lds(RS, (__attribute__((address_space(3))) void*)((P) + wave * 1024 + _i * 8192), 16, OFF[_i], _so, 0, 0); } } while (0)
; #define LDA(dst, b, h) _Pragma("unroll") for (int m = 0; m < 4; ++m) _Pragma("unroll") for (int k = 0; k < 2; ++k) \
;     dst[m][k] = *reinterpret_cast<const bf16x8*>(SA(b, h) + lds_byte(wr * 64 + m * 16 + fr, k * 32 + fq * 8))
; #define LDB(dst, b, h) _Pragma("unroll") for (int n = 0; n < 2; ++n) _Pragma("unroll") for (int k = 0; k < 2; ++k) \
;     dst[n][k] = *reinterpret_cast<const bf16x8*>(SB(b, h) + lds_byte(wc * 32 + n * 16 + fr, k * 32 + fq * 8))
; #define WAIT_V(n) asm volatile("s_waitcnt vmcnt(" #n ")" ::: "memory")
; #define WAIT_L(n) asm volatile("s_waitcnt lgkmcnt(" #n ")" ::: "memory")
; #define BAR __builtin_amdgcn_s_barrier()
; #define SCHED __builtin_amdgcn_sched_barrier(0)
;     ...
;     const int tid = opaque_tid(wave);
;     const int wid = tid >> 6, lane = tid & 63, wr = wid >> 2, wc = wid & 3, fr = lane & 15, fq = lane >> 4;
;     int offA[2], offB[2];
;     _Pragma("unroll") for (int i = 0; i < 2; ++i) {
;       int r, c; stage_rc(tid * 16 + i * 8192, r, c);
;       offA[i] = (r * lda + c) * 2; offB[i] = (r * ldb + c) * 2;
;     }
;     const int brow = pm * BM;
;     f32x4 acc[2][2][4][2];
;     _Pragma("unroll") for (int a = 0; a < 2; ++a) _Pragma("unroll") for (int b = 0; b < 2; ++b) _Pragma("unroll") for (int m = 0; m < 4; ++m) _Pragma("unroll") for (int n = 0; n < 2; ++n)
;       acc[a][b][m][n] = f32x4{0.f, 0.f, 0.f, 0.f};
;     bf16x8 At[4][2], B0[2][2], B1[2][2];
;     if (wr == 1) BAR;
;     if (first_tile) { WAIT_V(0); }
;     else if constexpr (mode == MODE_RESID_LN) { WAIT_V(0); }
;     else if constexpr (mode == MODE_SWIGLU) { WAIT_V(6); }
;     else if constexpr (mode == MODE_V) { WAIT_V(24); }
;     else { WAIT_V(12); }
;     first_tile = false;
;     BAR;
;     BAR;
;     for (int t = 0; t < nt - 2; t += 2) {
;       LDB(B0, 0, 0); SCHED; LDA(At, 0, 0); STAGE(SA(1, 1), rsA, sA1, offA, t + 1);
;       WAIT_L(8); BAR; WAIT_L(0); MMA(0, 0, At, B0); BAR; SCHED;
.LBB0_94:
	v_bfe_i32 v4, v130, 27, 1
	v_lshlrev_b32_e32 v2, 4, v130
	v_lshrrev_b32_e32 v4, 22, v4
	v_add_u32_e32 v4, v2, v4
	v_and_b32_e32 v4, 0xfffffc00, v4
	v_sub_u32_e32 v4, v2, v4
	v_lshrrev_b32_e32 v5, 4, v4
	v_bitop3_b32 v4, v5, v4, 32 bitop3:0x6c
	v_ashrrev_i32_e32 v3, 31, v130
	v_ashrrev_i32_e32 v6, 31, v4
	v_lshrrev_b32_e32 v3, 26, v3
	v_lshrrev_b32_e32 v6, 26, v6
	v_add_u32_e32 v3, v130, v3
	v_add_u32_e32 v6, v4, v6
	v_ashrrev_i32_e32 v3, 6, v3
	v_lshrrev_b32_e32 v7, 6, v6
	v_and_b32_e32 v6, 0xc0, v6
	v_lshlrev_b32_e32 v5, 3, v3
	v_lshlrev_b32_e32 v3, 5, v3
	v_sub_u32_e32 v4, v4, v6
	v_and_b32_e32 v5, 0xffff0, v5
	v_and_b32_e32 v3, 32, v3
	v_ashrrev_i16_sdwa v4, v128, sext(v4) dst_sel:DWORD dst_unused:UNUSED_PAD src0_sel:DWORD src1_sel:BYTE_0
	v_add_u32_sdwa v3, v3, sext(v4) dst_sel:DWORD dst_unused:UNUSED_PAD src0_sel:DWORD src1_sel:WORD_0
	v_add_lshl_u32 v4, v7, v5, 12
	v_add_u32_e32 v2, 0x2000, v2
	v_lshl_add_u32 v143, v3, 1, v4
	v_ashrrev_i32_e32 v3, 31, v2
	v_lshrrev_b32_e32 v3, 22, v3
	v_add_u32_e32 v3, v2, v3
	v_ashrrev_i32_e32 v3, 10, v3
	v_mul_i32_i24_e32 v4, 0x400, v3
	v_sub_u32_e32 v2, v2, v4
	v_lshrrev_b32_e32 v4, 4, v2
	v_bitop3_b32 v2, v4, v2, 32 bitop3:0x6c
	v_ashrrev_i32_e32 v5, 31, v2
	v_lshrrev_b32_e32 v5, 26, v5
	v_add_u32_e32 v5, v2, v5
	v_lshrrev_b32_e32 v6, 6, v5
	v_and_b32_e32 v5, 0xc0, v5
	v_lshlrev_b32_e32 v4, 3, v3
	v_lshlrev_b32_e32 v3, 5, v3
	v_sub_u32_e32 v2, v2, v5
	v_and_b32_e32 v4, 0xffff0, v4
	v_and_b32_e32 v3, 32, v3
	v_ashrrev_i16_sdwa v2, v128, sext(v2) dst_sel:DWORD dst_unused:UNUSED_PAD src0_sel:DWORD src1_sel:BYTE_0
	v_add_u32_sdwa v2, v3, sext(v2) dst_sel:DWORD dst_unused:UNUSED_PAD src0_sel:DWORD src1_sel:WORD_0
	v_add_lshl_u32 v3, v6, v4, 12
	v_lshl_add_u32 v144, v2, 1, v3
	v_and_b32_e32 v3, 15, v0
	v_lshlrev_b32_e32 v5, 2, v0
	v_and_b32_e32 v2, 48, v0
	v_lshlrev_b32_e32 v3, 6, v3
	v_and_b32_e32 v5, 32, v5
	v_lshlrev_b32_e32 v0, 6, v0
	v_or_b32_e32 v4, v3, v2
	v_bitop3_b32 v3, v3, v5, v2 bitop3:0x36
	v_lshlrev_b32_e32 v6, 6, v130
	v_lshlrev_b32_e32 v1, 13, v1
	v_and_or_b32 v0, v0, s34, v2
	v_and_or_b32 v3, v6, s33, v3
	v_bitop3_b32 v0, v1, v0, v5 bitop3:0xf6
	v_or_b32_e32 v6, 0x400, v3
	v_or_b32_e32 v7, 0x800, v3
	v_or_b32_e32 v8, 0xc00, v3
	v_or_b32_e32 v134, 0x800, v0
	v_or_b32_e32 v133, 0x1000, v0
	v_or_b32_e32 v132, 0x1800, v0
	v_mov_b32_e32 v0, 0
	v_bitop3_b32 v131, v4, v1, v5 bitop3:0xde
	s_mov_b32 s14, -2
	s_mov_b32 s15, 0
	v_or_b32_e32 v149, 0x10000, v3
	v_or_b32_e32 v150, 0x10000, v6
	v_or_b32_e32 v151, 0x10000, v7
	v_or_b32_e32 v152, 0x10000, v8
	v_or_b32_e32 v145, 0x14000, v3
	v_or_b32_e32 v146, 0x14000, v6
	v_or_b32_e32 v147, 0x14000, v7
	v_or_b32_e32 v148, 0x14000, v8
	v_or_b32_e32 v139, 0x18000, v3
	v_or_b32_e32 v140, 0x18000, v6
	v_or_b32_e32 v141, 0x18000, v7
	v_or_b32_e32 v142, 0x18000, v8
	v_or_b32_e32 v135, 0x1c000, v3
	v_or_b32_e32 v136, 0x1c000, v6
	v_or_b32_e32 v137, 0x1c000, v7
	v_or_b32_e32 v138, 0x1c000, v8
	s_barrier
	s_barrier
	ds_read_b128 v[154:157], v149
	ds_read_b128 v[158:161], v150
	ds_read_b128 v[162:165], v151
	ds_read_b128 v[166:169], v152
	s_add_i32 s43, s37, s15
	s_add_i32 s10, s43, 0x80
	s_mov_b32 m0, s30
	ds_read_b128 v[170:173], v131
	ds_read_b128 v[174:177], v131 offset:1024
	ds_read_b128 v[178:181], v134
	ds_read_b128 v[182:185], v134 offset:1024
	ds_read_b128 v[186:189], v133
	ds_read_b128 v[190:193], v133 offset:1024
	ds_read_b128 v[194:197], v132
	ds_read_b128 v[198:201], v132 offset:1024
	buffer_load_dwordx4 v143, s[4:7], s10 offen lds
	s_mov_b32 m0, s31
	s_nop 0
	buffer_load_dwordx4 v144, s[4:7], s10 offen lds
	s_waitcnt lgkmcnt(8)
	s_barrier
	s_waitcnt lgkmcnt(0)
	v_mfma_f32_16x16x32_bf16 v[124:127], v[154:157], v[170:173], 0
	v_mfma_f32_16x16x32_bf16 v[124:127], v[158:161], v[174:177], v[124:127]
	v_mfma_f32_16x16x32_bf16 v[120:123], v[166:169], v[174:177], 0
	v_mfma_f32_16x16x32_bf16 v[120:123], v[162:165], v[170:173], v[120:123]
	v_mfma_f32_16x16x32_bf16 v[112:115], v[162:165], v[178:181], 0
	v_mfma_f32_16x16x32_bf16 v[112:115], v[166:169], v[182:185], v[112:115]
	v_mfma_f32_16x16x32_bf16 v[116:119], v[158:161], v[182:185], 0
	v_mfma_f32_16x16x32_bf16 v[116:119], v[154:157], v[178:181], v[116:119]
	v_mfma_f32_16x16x32_bf16 v[108:111], v[154:157], v[186:189], 0
	v_mfma_f32_16x16x32_bf16 v[108:111], v[158:161], v[190:193], v[108:111]
	v_mfma_f32_16x16x32_bf16 v[104:107], v[166:169], v[190:193], 0
	v_mfma_f32_16x16x32_bf16 v[104:107], v[162:165], v[186:189], v[104:107]
	v_mfma_f32_16x16x32_bf16 v[96:99], v[162:165], v[194:197], 0
	v_mfma_f32_16x16x32_bf16 v[96:99], v[166:169], v[198:201], v[96:99]
	v_mfma_f32_16x16x32_bf16 v[100:103], v[158:161], v[198:201], 0
	v_mfma_f32_16x16x32_bf16 v[100:103], v[154:157], v[194:197], v[100:103]
	s_barrier
	s_add_i32 s44, s39, s15
	s_add_i32 s45, s44, 0x100
	s_mov_b32 s10, s6
	s_mov_b32 s11, s7
	s_mov_b32 m0, s1
	ds_read_b128 v[202:205], v145
	ds_read_b128 v[206:209], v146
	ds_read_b128 v[210:213], v147
	ds_read_b128 v[214:217], v148
	buffer_load_dwordx4 v143, s[8:11], s45 offen lds
	s_mov_b32 m0, s3
	s_nop 0
	buffer_load_dwordx4 v144, s[8:11], s45 offen lds
	s_barrier
; #define STAGE(P, RS, SOFF, OFF, kt) do { const int _so = (SOFF) + (kt) * (BK * 2); \
;     _Pragma("unroll") for (int _i = 0; _i < 2; ++_i) { \
;       __builtin_amdgcn_raw_ptr_buffer_load_lds(RS, (__attribute__((address_space(3))) void*)((P) + wave * 1024 + _i * 8192), 16, OFF[_i], _so, 0, 0); } } while (0)
; #define LDA(dst, b, h) _Pragma("unroll") for (int m = 0; m < 4; ++m) _Pragma("unroll") for (int k = 0; k < 2; ++k) \
;     dst[m][k] = *reinterpret_cast<const bf16x8*>(SA(b, h) + lds_byte(wr * 64 + m * 16 + fr, k * 32 + fq * 8))
; #define LDB(dst, b, h) _Pragma("unroll") for (int n = 0; n < 2; ++n) _Pragma("unroll") for (int k = 0; k < 2; ++k) \
;     dst[n][k] = *reinterpret_cast<const bf16x8*>(SB(b, h) + lds_byte(wc * 32 + n * 16 + fr, k * 32 + fq * 8))
; #define WAIT_V(n) asm volatile("s_waitcnt vmcnt(" #n ")" ::: "memory")
; #define WAIT_L(n) asm volatile("s_waitcnt lgkmcnt(" #n ")" ::: "memory")
; #define BAR __builtin_amdgcn_s_barrier()
; #define SCHED __builtin_amdgcn_sched_barrier(0)
;     ...
;       BAR; WAIT_L(0); MMA(0, 1, At, B1); BAR;
;       LDA(At, 0, 1); STAGE(SA(0, 0), rsA, sA0, offA, t + 2);
;       BAR; WAIT_L(0); MMA(1, 0, At, B0); BAR; SCHED;
;       STAGE(SB(0, 1), rsB, sB1, offB, t + 2);
;       WAIT_V(6); BAR; MMA(1, 1, At, B1); BAR;
;       LDB(B0, 1, 0); SCHED; LDA(At, 1, 0); STAGE(SA(0, 1), rsA, sA1, offA, t + 2);
;       WAIT_L(8); BAR; WAIT_L(0); MMA(0, 0, At, B0); BAR; SCHED;
	s_waitcnt lgkmcnt(0)
	v_mfma_f32_16x16x32_bf16 v[92:95], v[202:205], v[170:173], 0
	v_mfma_f32_16x16x32_bf16 v[92:95], v[206:209], v[174:177], v[92:95]
	v_mfma_f32_16x16x32_bf16 v[88:91], v[214:217], v[174:177], 0
	v_mfma_f32_16x16x32_bf16 v[88:91], v[210:213], v[170:173], v[88:91]
	v_mfma_f32_16x16x32_bf16 v[80:83], v[210:213], v[178:181], 0
	v_mfma_f32_16x16x32_bf16 v[80:83], v[214:217], v[182:185], v[80:83]
	v_mfma_f32_16x16x32_bf16 v[84:87], v[206:209], v[182:185], 0
	v_mfma_f32_16x16x32_bf16 v[84:87], v[202:205], v[178:181], v[84:87]
	v_mfma_f32_16x16x32_bf16 v[76:79], v[202:205], v[186:189], 0
	v_mfma_f32_16x16x32_bf16 v[76:79], v[206:209], v[190:193], v[76:79]
	v_mfma_f32_16x16x32_bf16 v[72:75], v[214:217], v[190:193], 0
	v_mfma_f32_16x16x32_bf16 v[72:75], v[210:213], v[186:189], v[72:75]
	v_mfma_f32_16x16x32_bf16 v[64:67], v[210:213], v[194:197], 0
	v_mfma_f32_16x16x32_bf16 v[64:67], v[214:217], v[198:201], v[64:67]
	v_mfma_f32_16x16x32_bf16 v[68:71], v[206:209], v[198:201], 0
	v_mfma_f32_16x16x32_bf16 v[68:71], v[202:205], v[194:197], v[68:71]
	s_barrier
	s_add_i32 s45, s38, s15
	s_add_i32 s46, s45, 0x100
	s_mov_b32 m0, s0
	ds_read_b128 v[170:173], v131 offset:16384
	ds_read_b128 v[174:177], v131 offset:17408
	ds_read_b128 v[178:181], v134 offset:16384
	ds_read_b128 v[182:185], v134 offset:17408
	ds_read_b128 v[186:189], v133 offset:16384
	ds_read_b128 v[190:193], v133 offset:17408
	ds_read_b128 v[194:197], v132 offset:16384
	ds_read_b128 v[198:201], v132 offset:17408
	buffer_load_dwordx4 v143, s[4:7], s46 offen lds
	s_mov_b32 m0, s18
	s_nop 0
	buffer_load_dwordx4 v144, s[4:7], s46 offen lds
	s_barrier
	s_waitcnt lgkmcnt(0)
	v_mfma_f32_16x16x32_bf16 v[60:63], v[154:157], v[170:173], 0
	v_mfma_f32_16x16x32_bf16 v[60:63], v[158:161], v[174:177], v[60:63]
	v_mfma_f32_16x16x32_bf16 v[56:59], v[166:169], v[174:177], 0
	v_mfma_f32_16x16x32_bf16 v[56:59], v[162:165], v[170:173], v[56:59]
	v_mfma_f32_16x16x32_bf16 v[48:51], v[162:165], v[178:181], 0
	v_mfma_f32_16x16x32_bf16 v[48:51], v[166:169], v[182:185], v[48:51]
	v_mfma_f32_16x16x32_bf16 v[52:55], v[158:161], v[182:185], 0
	v_mfma_f32_16x16x32_bf16 v[52:55], v[154:157], v[178:181], v[52:55]
	v_mfma_f32_16x16x32_bf16 v[44:47], v[154:157], v[186:189], 0
	v_mfma_f32_16x16x32_bf16 v[44:47], v[158:161], v[190:193], v[44:47]
	v_mfma_f32_16x16x32_bf16 v[40:43], v[166:169], v[190:193], 0
	v_mfma_f32_16x16x32_bf16 v[40:43], v[162:165], v[186:189], v[40:43]
	v_mfma_f32_16x16x32_bf16 v[32:35], v[162:165], v[194:197], 0
	v_mfma_f32_16x16x32_bf16 v[32:35], v[166:169], v[198:201], v[32:35]
	v_mfma_f32_16x16x32_bf16 v[36:39], v[158:161], v[198:201], 0
	v_mfma_f32_16x16x32_bf16 v[36:39], v[154:157], v[194:197], v[36:39]
	s_barrier
	s_add_i32 s46, s40, s15
	s_add_i32 s47, s46, 0x100
	s_mov_b32 m0, s19
	s_nop 0
	buffer_load_dwordx4 v143, s[8:11], s47 offen lds
	s_mov_b32 m0, s20
	s_nop 0
	buffer_load_dwordx4 v144, s[8:11], s47 offen lds
	s_waitcnt vmcnt(6)
	s_barrier
	v_mfma_f32_16x16x32_bf16 v[28:31], v[202:205], v[170:173], 0
	v_mfma_f32_16x16x32_bf16 v[28:31], v[206:209], v[174:177], v[28:31]
	v_mfma_f32_16x16x32_bf16 v[24:27], v[214:217], v[174:177], 0
	v_mfma_f32_16x16x32_bf16 v[24:27], v[210:213], v[170:173], v[24:27]
	v_mfma_f32_16x16x32_bf16 v[16:19], v[210:213], v[178:181], 0
	v_mfma_f32_16x16x32_bf16 v[16:19], v[214:217], v[182:185], v[16:19]
	v_mfma_f32_16x16x32_bf16 v[20:23], v[206:209], v[182:185], 0
	v_mfma_f32_16x16x32_bf16 v[20:23], v[202:205], v[178:181], v[20:23]
	v_mfma_f32_16x16x32_bf16 v[12:15], v[202:205], v[186:189], 0
	v_mfma_f32_16x16x32_bf16 v[12:15], v[206:209], v[190:193], v[12:15]
	v_mfma_f32_16x16x32_bf16 v[8:11], v[214:217], v[190:193], 0
	v_mfma_f32_16x16x32_bf16 v[8:11], v[210:213], v[186:189], v[8:11]
	v_mfma_f32_16x16x32_bf16 v[0:3], v[210:213], v[194:197], 0
	v_mfma_f32_16x16x32_bf16 v[0:3], v[214:217], v[198:201], v[0:3]
	v_mfma_f32_16x16x32_bf16 v[4:7], v[206:209], v[198:201], 0
	v_mfma_f32_16x16x32_bf16 v[4:7], v[202:205], v[194:197], v[4:7]
	s_barrier
	ds_read_b128 v[154:157], v139
	ds_read_b128 v[158:161], v140
	ds_read_b128 v[162:165], v141
	ds_read_b128 v[166:169], v142
	s_addk_i32 s43, 0x100
	s_mov_b32 m0, s21
	ds_read_b128 v[170:173], v131 offset:32768
	ds_read_b128 v[174:177], v131 offset:33792
	ds_read_b128 v[178:181], v134 offset:32768
	ds_read_b128 v[182:185], v134 offset:33792
	ds_read_b128 v[186:189], v133 offset:32768
	ds_read_b128 v[190:193], v133 offset:33792
	ds_read_b128 v[194:197], v132 offset:32768
	ds_read_b128 v[198:201], v132 offset:33792
	buffer_load_dwordx4 v143, s[4:7], s43 offen lds
	s_mov_b32 m0, s22
	s_nop 0
	buffer_load_dwordx4 v144, s[4:7], s43 offen lds
	s_waitcnt lgkmcnt(8)
	s_barrier
; #define STAGE(P, RS, SOFF, OFF, kt) do { const int _so = (SOFF) + (kt) * (BK * 2); \
;     _Pragma("unroll") for (int _i = 0; _i < 2; ++_i) { \
;       __builtin_amdgcn_raw_ptr_buffer_load_lds(RS, (__attribute__((address_space(3))) void*)((P) + wave * 1024 + _i * 8192), 16, OFF[_i], _so, 0, 0); } } while (0)
; #define LDA(dst, b, h) _Pragma("unroll") for (int m = 0; m < 4; ++m) _Pragma("unroll") for (int k = 0; k < 2; ++k) \
;     dst[m][k] = *reinterpret_cast<const bf16x8*>(SA(b, h) + lds_byte(wr * 64 + m * 16 + fr, k * 32 + fq * 8))
; #define LDB(dst, b, h) _Pragma("unroll") for (int n = 0; n < 2; ++n) _Pragma("unroll") for (int k = 0; k < 2; ++k) \
;     dst[n][k] = *reinterpret_cast<const bf16x8*>(SB(b, h) + lds_byte(wc * 32 + n * 16 + fr, k * 32 + fq * 8))
; #define WAIT_L(n) asm volatile("s_waitcnt lgkmcnt(" #n ")" ::: "memory")
; #define BAR __builtin_amdgcn_s_barrier()
; #define SCHED __builtin_amdgcn_sched_barrier(0)
;     ...
;       WAIT_L(8); BAR; WAIT_L(0); MMA(0, 0, At, B0); BAR; SCHED;
;       LDB(B1, 1, 1); STAGE(SB(1, 0), rsB, sB0, offB, t + 3);
;       BAR; WAIT_L(0); MMA(0, 1, At, B1); BAR;
;       LDA(At, 1, 1); STAGE(SA(1, 0), rsA, sA0, offA, t + 3);
;       BAR; WAIT_L(0); MMA(1, 0, At, B0); BAR; SCHED;
;       STAGE(SB(1, 1), rsB, sB1, offB, t + 3);
	s_waitcnt lgkmcnt(0)
	v_mfma_f32_16x16x32_bf16 v[124:127], v[154:157], v[170:173], v[124:127]
	v_mfma_f32_16x16x32_bf16 v[124:127], v[158:161], v[174:177], v[124:127]
	v_mfma_f32_16x16x32_bf16 v[120:123], v[166:169], v[174:177], v[120:123]
	v_mfma_f32_16x16x32_bf16 v[120:123], v[162:165], v[170:173], v[120:123]
	v_mfma_f32_16x16x32_bf16 v[112:115], v[162:165], v[178:181], v[112:115]
	v_mfma_f32_16x16x32_bf16 v[112:115], v[166:169], v[182:185], v[112:115]
	v_mfma_f32_16x16x32_bf16 v[116:119], v[158:161], v[182:185], v[116:119]
	v_mfma_f32_16x16x32_bf16 v[116:119], v[154:157], v[178:181], v[116:119]
	v_mfma_f32_16x16x32_bf16 v[108:111], v[154:157], v[186:189], v[108:111]
	v_mfma_f32_16x16x32_bf16 v[108:111], v[158:161], v[190:193], v[108:111]
	v_mfma_f32_16x16x32_bf16 v[104:107], v[166:169], v[190:193], v[104:107]
	v_mfma_f32_16x16x32_bf16 v[104:107], v[162:165], v[186:189], v[104:107]
	v_mfma_f32_16x16x32_bf16 v[96:99], v[162:165], v[194:197], v[96:99]
	v_mfma_f32_16x16x32_bf16 v[96:99], v[166:169], v[198:201], v[96:99]
	v_mfma_f32_16x16x32_bf16 v[100:103], v[158:161], v[198:201], v[100:103]
	v_mfma_f32_16x16x32_bf16 v[100:103], v[154:157], v[194:197], v[100:103]
	s_barrier
	s_addk_i32 s44, 0x180
	s_mov_b32 m0, s23
	ds_read_b128 v[202:205], v135
	ds_read_b128 v[206:209], v136
	ds_read_b128 v[210:213], v137
	ds_read_b128 v[214:217], v138
	buffer_load_dwordx4 v143, s[8:11], s44 offen lds
	s_mov_b32 m0, s24
	s_nop 0
	buffer_load_dwordx4 v144, s[8:11], s44 offen lds
	s_barrier
	s_waitcnt lgkmcnt(0)
	v_mfma_f32_16x16x32_bf16 v[92:95], v[202:205], v[170:173], v[92:95]
	v_mfma_f32_16x16x32_bf16 v[92:95], v[206:209], v[174:177], v[92:95]
	v_mfma_f32_16x16x32_bf16 v[88:91], v[214:217], v[174:177], v[88:91]
	v_mfma_f32_16x16x32_bf16 v[88:91], v[210:213], v[170:173], v[88:91]
	v_mfma_f32_16x16x32_bf16 v[80:83], v[210:213], v[178:181], v[80:83]
	v_mfma_f32_16x16x32_bf16 v[80:83], v[214:217], v[182:185], v[80:83]
	v_mfma_f32_16x16x32_bf16 v[84:87], v[206:209], v[182:185], v[84:87]
	v_mfma_f32_16x16x32_bf16 v[84:87], v[202:205], v[178:181], v[84:87]
	v_mfma_f32_16x16x32_bf16 v[76:79], v[202:205], v[186:189], v[76:79]
	v_mfma_f32_16x16x32_bf16 v[76:79], v[206:209], v[190:193], v[76:79]
	v_mfma_f32_16x16x32_bf16 v[72:75], v[214:217], v[190:193], v[72:75]
	v_mfma_f32_16x16x32_bf16 v[72:75], v[210:213], v[186:189], v[72:75]
	v_mfma_f32_16x16x32_bf16 v[64:67], v[210:213], v[194:197], v[64:67]
	v_mfma_f32_16x16x32_bf16 v[64:67], v[214:217], v[198:201], v[64:67]
	v_mfma_f32_16x16x32_bf16 v[68:71], v[206:209], v[198:201], v[68:71]
	v_mfma_f32_16x16x32_bf16 v[68:71], v[202:205], v[194:197], v[68:71]
	s_barrier
	s_addk_i32 s45, 0x180
	s_mov_b32 m0, s25
	ds_read_b128 v[170:173], v131 offset:49152
	ds_read_b128 v[174:177], v131 offset:50176
	ds_read_b128 v[178:181], v134 offset:49152
	ds_read_b128 v[182:185], v134 offset:50176
	ds_read_b128 v[186:189], v133 offset:49152
	ds_read_b128 v[190:193], v133 offset:50176
	ds_read_b128 v[194:197], v132 offset:49152
	ds_read_b128 v[198:201], v132 offset:50176
	buffer_load_dwordx4 v143, s[4:7], s45 offen lds
	s_mov_b32 m0, s26
	s_nop 0
	buffer_load_dwordx4 v144, s[4:7], s45 offen lds
	s_barrier
	s_waitcnt lgkmcnt(0)
	v_mfma_f32_16x16x32_bf16 v[60:63], v[154:157], v[170:173], v[60:63]
	v_mfma_f32_16x16x32_bf16 v[60:63], v[158:161], v[174:177], v[60:63]
	v_mfma_f32_16x16x32_bf16 v[56:59], v[166:169], v[174:177], v[56:59]
	v_mfma_f32_16x16x32_bf16 v[56:59], v[162:165], v[170:173], v[56:59]
	v_mfma_f32_16x16x32_bf16 v[48:51], v[162:165], v[178:181], v[48:51]
	v_mfma_f32_16x16x32_bf16 v[48:51], v[166:169], v[182:185], v[48:51]
	v_mfma_f32_16x16x32_bf16 v[52:55], v[158:161], v[182:185], v[52:55]
	v_mfma_f32_16x16x32_bf16 v[52:55], v[154:157], v[178:181], v[52:55]
	v_mfma_f32_16x16x32_bf16 v[44:47], v[154:157], v[186:189], v[44:47]
	v_mfma_f32_16x16x32_bf16 v[44:47], v[158:161], v[190:193], v[44:47]
	v_mfma_f32_16x16x32_bf16 v[40:43], v[166:169], v[190:193], v[40:43]
	v_mfma_f32_16x16x32_bf16 v[40:43], v[162:165], v[186:189], v[40:43]
	v_mfma_f32_16x16x32_bf16 v[32:35], v[162:165], v[194:197], v[32:35]
	v_mfma_f32_16x16x32_bf16 v[32:35], v[166:169], v[198:201], v[32:35]
	v_mfma_f32_16x16x32_bf16 v[36:39], v[158:161], v[198:201], v[36:39]
	v_mfma_f32_16x16x32_bf16 v[36:39], v[154:157], v[194:197], v[36:39]
	s_barrier
	s_addk_i32 s46, 0x180
	s_mov_b32 m0, s27
	s_nop 0
	buffer_load_dwordx4 v143, s[8:11], s46 offen lds
	s_mov_b32 m0, s28
	s_nop 0
	buffer_load_dwordx4 v144, s[8:11], s46 offen lds
	s_add_i32 s14, s14, 2
	s_addk_i32 s15, 0x100
	s_cmp_gt_u32 s14, 27
	s_cbranch_scc0 .LBB0_95
	s_branch .Lmy_post_95

; #define STAGE(P, RS, SOFF, OFF, kt) do { const int _so = (SOFF) + (kt) * (BK * 2); \
;     _Pragma("unroll") for (int _i = 0; _i < 2; ++_i) { \
;       __builtin_amdgcn_raw_ptr_buffer_load_lds(RS, (__attribute__((address_space(3))) void*)((P) + wave * 1024 + _i * 8192), 16, OFF[_i], _so, 0, 0); } } while (0)
; #define LDA(dst, b, h) _Pragma("unroll") for (int m = 0; m < 4; ++m) _Pragma("unroll") for (int k = 0; k < 2; ++k) \
;     dst[m][k] = *reinterpret_cast<const bf16x8*>(SA(b, h) + lds_byte(wr * 64 + m * 16 + fr, k * 32 + fq * 8))
; #define LDB(dst, b, h) _Pragma("unroll") for (int n = 0; n < 2; ++n) _Pragma("unroll") for (int k = 0; k < 2; ++k) \
;     dst[n][k] = *reinterpret_cast<const bf16x8*>(SB(b, h) + lds_byte(wc * 32 + n * 16 + fr, k * 32 + fq * 8))
; #define WAIT_V(n) asm volatile("s_waitcnt vmcnt(" #n ")" ::: "memory")
; #define WAIT_L(n) asm volatile("s_waitcnt lgkmcnt(" #n ")" ::: "memory")
; #define BAR __builtin_amdgcn_s_barrier()
;     ...
;       WAIT_V(6); BAR; MMA(1, 1, At, B1); BAR;
;     }
;     { LDB(B0, 0, 0); LDA(At, 0, 0); STAGE(SA(1, 1), rsA, sA1, offA, nt - 1);
;       BAR; WAIT_L(0); MMA(0, 0, At, B0); BAR;
;       LDB(B1, 0, 1); BAR; WAIT_L(0); MMA(0, 1, At, B1); BAR;
;       LDA(At, 0, 1); WAIT_V(4); BAR; WAIT_L(0); MMA(1, 0, At, B0); MMA(1, 1, At, B1); BAR; }
.Lmy_post_95:
	s_waitcnt vmcnt(6)
	s_barrier
	v_mfma_f32_16x16x32_bf16 v[28:31], v[202:205], v[170:173], v[28:31]
	v_mfma_f32_16x16x32_bf16 v[28:31], v[206:209], v[174:177], v[28:31]
	v_mfma_f32_16x16x32_bf16 v[24:27], v[214:217], v[174:177], v[24:27]
	v_mfma_f32_16x16x32_bf16 v[24:27], v[210:213], v[170:173], v[24:27]
	v_mfma_f32_16x16x32_bf16 v[16:19], v[210:213], v[178:181], v[16:19]
	v_mfma_f32_16x16x32_bf16 v[16:19], v[214:217], v[182:185], v[16:19]
	v_mfma_f32_16x16x32_bf16 v[20:23], v[206:209], v[182:185], v[20:23]
	v_mfma_f32_16x16x32_bf16 v[20:23], v[202:205], v[178:181], v[20:23]
	v_mfma_f32_16x16x32_bf16 v[12:15], v[202:205], v[186:189], v[12:15]
	v_mfma_f32_16x16x32_bf16 v[12:15], v[206:209], v[190:193], v[12:15]
	v_mfma_f32_16x16x32_bf16 v[8:11], v[214:217], v[190:193], v[8:11]
	v_mfma_f32_16x16x32_bf16 v[8:11], v[210:213], v[186:189], v[8:11]
	v_mfma_f32_16x16x32_bf16 v[0:3], v[210:213], v[194:197], v[0:3]
	v_mfma_f32_16x16x32_bf16 v[0:3], v[214:217], v[198:201], v[0:3]
	v_mfma_f32_16x16x32_bf16 v[4:7], v[206:209], v[198:201], v[4:7]
	v_mfma_f32_16x16x32_bf16 v[4:7], v[202:205], v[194:197], v[4:7]
	s_barrier
	s_add_i32 s10, s37, 0xf80
	s_mov_b32 m0, s30
	ds_read_b128 v[154:157], v149
	ds_read_b128 v[158:161], v150
	ds_read_b128 v[162:165], v151
	ds_read_b128 v[150:153], v152
	ds_read_b128 v[166:169], v131
	ds_read_b128 v[170:173], v131 offset:1024
	ds_read_b128 v[174:177], v134
	ds_read_b128 v[178:181], v134 offset:1024
	ds_read_b128 v[182:185], v133
	ds_read_b128 v[186:189], v133 offset:1024
	ds_read_b128 v[190:193], v132
	ds_read_b128 v[194:197], v132 offset:1024
	buffer_load_dwordx4 v143, s[4:7], s10 offen lds
	s_mov_b32 m0, s31
	s_nop 0
	buffer_load_dwordx4 v144, s[4:7], s10 offen lds
	s_barrier
	s_waitcnt lgkmcnt(0)
	v_mfma_f32_16x16x32_bf16 v[124:127], v[154:157], v[166:169], v[124:127]
	v_mfma_f32_16x16x32_bf16 v[124:127], v[158:161], v[170:173], v[124:127]
	v_mfma_f32_16x16x32_bf16 v[120:123], v[150:153], v[170:173], v[120:123]
	v_mfma_f32_16x16x32_bf16 v[120:123], v[162:165], v[166:169], v[120:123]
	v_mfma_f32_16x16x32_bf16 v[112:115], v[162:165], v[174:177], v[112:115]
	v_mfma_f32_16x16x32_bf16 v[112:115], v[150:153], v[178:181], v[112:115]
	v_mfma_f32_16x16x32_bf16 v[116:119], v[158:161], v[178:181], v[116:119]
	v_mfma_f32_16x16x32_bf16 v[116:119], v[154:157], v[174:177], v[116:119]
	v_mfma_f32_16x16x32_bf16 v[108:111], v[154:157], v[182:185], v[108:111]
	v_mfma_f32_16x16x32_bf16 v[108:111], v[158:161], v[186:189], v[108:111]
	v_mfma_f32_16x16x32_bf16 v[104:107], v[150:153], v[186:189], v[104:107]
	v_mfma_f32_16x16x32_bf16 v[104:107], v[162:165], v[182:185], v[104:107]
	v_mfma_f32_16x16x32_bf16 v[96:99], v[162:165], v[190:193], v[96:99]
	v_mfma_f32_16x16x32_bf16 v[96:99], v[150:153], v[194:197], v[96:99]
	v_mfma_f32_16x16x32_bf16 v[100:103], v[158:161], v[194:197], v[100:103]
	v_mfma_f32_16x16x32_bf16 v[100:103], v[154:157], v[190:193], v[100:103]
	s_barrier
	ds_read_b128 v[198:201], v145
	ds_read_b128 v[202:205], v146
	ds_read_b128 v[144:147], v147
	ds_read_b128 v[206:209], v148
	s_barrier
	s_waitcnt lgkmcnt(0)
	v_mfma_f32_16x16x32_bf16 v[92:95], v[198:201], v[166:169], v[92:95]
	v_mfma_f32_16x16x32_bf16 v[84:87], v[198:201], v[174:177], v[84:87]
	v_mfma_f32_16x16x32_bf16 v[76:79], v[198:201], v[182:185], v[76:79]
	v_mfma_f32_16x16x32_bf16 v[68:71], v[198:201], v[190:193], v[68:71]
	v_mfma_f32_16x16x32_bf16 v[88:91], v[144:147], v[166:169], v[88:91]
	v_mfma_f32_16x16x32_bf16 v[80:83], v[144:147], v[174:177], v[80:83]
	v_mfma_f32_16x16x32_bf16 v[72:75], v[144:147], v[182:185], v[72:75]
	v_mfma_f32_16x16x32_bf16 v[64:67], v[144:147], v[190:193], v[64:67]
	v_mfma_f32_16x16x32_bf16 v[92:95], v[202:205], v[170:173], v[92:95]
	v_mfma_f32_16x16x32_bf16 v[84:87], v[202:205], v[178:181], v[84:87]
	v_mfma_f32_16x16x32_bf16 v[76:79], v[202:205], v[186:189], v[76:79]
	v_mfma_f32_16x16x32_bf16 v[68:71], v[202:205], v[194:197], v[68:71]
	v_mfma_f32_16x16x32_bf16 v[166:169], v[206:209], v[170:173], v[88:91]
	v_mfma_f32_16x16x32_bf16 v[170:173], v[206:209], v[178:181], v[80:83]
	v_mfma_f32_16x16x32_bf16 v[174:177], v[206:209], v[186:189], v[72:75]
	v_mfma_f32_16x16x32_bf16 v[178:181], v[206:209], v[194:197], v[64:67]
	s_barrier
	s_nop 0
	ds_read_b128 v[64:67], v131 offset:16384
	ds_read_b128 v[72:75], v131 offset:17408
	ds_read_b128 v[80:83], v134 offset:16384
	ds_read_b128 v[88:91], v134 offset:17408
	ds_read_b128 v[182:185], v133 offset:16384
	ds_read_b128 v[186:189], v133 offset:17408
	ds_read_b128 v[190:193], v132 offset:16384
	ds_read_b128 v[194:197], v132 offset:17408
	s_waitcnt vmcnt(4)
	s_barrier
; #define LDA(dst, b, h) _Pragma("unroll") for (int m = 0; m < 4; ++m) _Pragma("unroll") for (int k = 0; k < 2; ++k) \
;     dst[m][k] = *reinterpret_cast<const bf16x8*>(SA(b, h) + lds_byte(wr * 64 + m * 16 + fr, k * 32 + fq * 8))
; #define LDB(dst, b, h) _Pragma("unroll") for (int n = 0; n < 2; ++n) _Pragma("unroll") for (int k = 0; k < 2; ++k) \
;     dst[n][k] = *reinterpret_cast<const bf16x8*>(SB(b, h) + lds_byte(wc * 32 + n * 16 + fr, k * 32 + fq * 8))
; #define WAIT_V(n) asm volatile("s_waitcnt vmcnt(" #n ")" ::: "memory")
; #define WAIT_L(n) asm volatile("s_waitcnt lgkmcnt(" #n ")" ::: "memory")
; #define BAR __builtin_amdgcn_s_barrier()
;     ...
;       LDA(At, 0, 1); WAIT_V(4); BAR; WAIT_L(0); MMA(1, 0, At, B0); MMA(1, 1, At, B1); BAR; }
;     { LDB(B0, 1, 0); LDA(At, 1, 0); WAIT_V(2); BAR; WAIT_L(0); MMA(0, 0, At, B0); BAR;
;       LDB(B1, 1, 1); WAIT_V(0); BAR; WAIT_L(0); MMA(0, 1, At, B1); BAR;
	s_waitcnt lgkmcnt(0)
	v_mfma_f32_16x16x32_bf16 v[60:63], v[154:157], v[64:67], v[60:63]
	v_mfma_f32_16x16x32_bf16 v[56:59], v[162:165], v[64:67], v[56:59]
	v_mfma_f32_16x16x32_bf16 v[52:55], v[154:157], v[80:83], v[52:55]
	v_mfma_f32_16x16x32_bf16 v[48:51], v[162:165], v[80:83], v[48:51]
	v_mfma_f32_16x16x32_bf16 v[44:47], v[154:157], v[182:185], v[44:47]
	v_mfma_f32_16x16x32_bf16 v[40:43], v[162:165], v[182:185], v[40:43]
	v_mfma_f32_16x16x32_bf16 v[36:39], v[154:157], v[190:193], v[36:39]
	v_mfma_f32_16x16x32_bf16 v[32:35], v[162:165], v[190:193], v[32:35]
	v_mfma_f32_16x16x32_bf16 v[60:63], v[158:161], v[72:75], v[60:63]
	v_mfma_f32_16x16x32_bf16 v[56:59], v[150:153], v[72:75], v[56:59]
	v_mfma_f32_16x16x32_bf16 v[52:55], v[158:161], v[88:91], v[52:55]
	v_mfma_f32_16x16x32_bf16 v[48:51], v[150:153], v[88:91], v[48:51]
	v_mfma_f32_16x16x32_bf16 v[44:47], v[158:161], v[186:189], v[44:47]
	v_mfma_f32_16x16x32_bf16 v[40:43], v[150:153], v[186:189], v[40:43]
	v_mfma_f32_16x16x32_bf16 v[36:39], v[158:161], v[194:197], v[36:39]
	v_mfma_f32_16x16x32_bf16 v[32:35], v[150:153], v[194:197], v[32:35]
	v_mfma_f32_16x16x32_bf16 v[28:31], v[198:201], v[64:67], v[28:31]
	v_mfma_f32_16x16x32_bf16 v[20:23], v[198:201], v[80:83], v[20:23]
	v_mfma_f32_16x16x32_bf16 v[12:15], v[198:201], v[182:185], v[12:15]
	v_mfma_f32_16x16x32_bf16 v[4:7], v[198:201], v[190:193], v[4:7]
	v_mfma_f32_16x16x32_bf16 v[24:27], v[144:147], v[64:67], v[24:27]
	v_mfma_f32_16x16x32_bf16 v[16:19], v[144:147], v[80:83], v[16:19]
	v_mfma_f32_16x16x32_bf16 v[8:11], v[144:147], v[182:185], v[8:11]
	v_mfma_f32_16x16x32_bf16 v[0:3], v[144:147], v[190:193], v[0:3]
	v_mfma_f32_16x16x32_bf16 v[28:31], v[202:205], v[72:75], v[28:31]
	v_mfma_f32_16x16x32_bf16 v[20:23], v[202:205], v[88:91], v[20:23]
	v_mfma_f32_16x16x32_bf16 v[12:15], v[202:205], v[186:189], v[12:15]
	v_mfma_f32_16x16x32_bf16 v[4:7], v[202:205], v[194:197], v[4:7]
	v_mfma_f32_16x16x32_bf16 v[144:147], v[206:209], v[72:75], v[24:27]
	v_mfma_f32_16x16x32_bf16 v[148:151], v[206:209], v[88:91], v[16:19]
	v_mfma_f32_16x16x32_bf16 v[152:155], v[206:209], v[186:189], v[8:11]
	v_mfma_f32_16x16x32_bf16 v[156:159], v[206:209], v[194:197], v[0:3]
	s_barrier
	s_nop 0
	ds_read_b128 v[0:3], v139
	ds_read_b128 v[8:11], v140
	ds_read_b128 v[16:19], v141
	ds_read_b128 v[140:143], v142
	ds_read_b128 v[24:27], v131 offset:32768
	ds_read_b128 v[160:163], v131 offset:33792
	ds_read_b128 v[182:185], v134 offset:32768
	ds_read_b128 v[186:189], v134 offset:33792
	ds_read_b128 v[190:193], v133 offset:32768
	ds_read_b128 v[194:197], v133 offset:33792
	ds_read_b128 v[198:201], v132 offset:32768
	ds_read_b128 v[202:205], v132 offset:33792
	s_waitcnt vmcnt(2)
	s_barrier
	s_waitcnt lgkmcnt(0)
	v_mfma_f32_16x16x32_bf16 v[64:67], v[0:3], v[24:27], v[124:127]
	v_mfma_f32_16x16x32_bf16 v[72:75], v[16:19], v[24:27], v[120:123]
	v_mfma_f32_16x16x32_bf16 v[80:83], v[0:3], v[182:185], v[116:119]
	v_mfma_f32_16x16x32_bf16 v[88:91], v[16:19], v[182:185], v[112:115]
	v_mfma_f32_16x16x32_bf16 v[108:111], v[0:3], v[190:193], v[108:111]
	v_mfma_f32_16x16x32_bf16 v[116:119], v[16:19], v[190:193], v[104:107]
	v_mfma_f32_16x16x32_bf16 v[100:103], v[0:3], v[198:201], v[100:103]
	v_mfma_f32_16x16x32_bf16 v[124:127], v[16:19], v[198:201], v[96:99]
	v_mfma_f32_16x16x32_bf16 v[120:123], v[8:11], v[160:163], v[64:67]
	v_mfma_f32_16x16x32_bf16 v[112:115], v[140:143], v[160:163], v[72:75]
	v_mfma_f32_16x16x32_bf16 v[104:107], v[8:11], v[186:189], v[80:83]
	v_mfma_f32_16x16x32_bf16 v[96:99], v[140:143], v[186:189], v[88:91]
	v_mfma_f32_16x16x32_bf16 v[88:91], v[8:11], v[194:197], v[108:111]
	v_mfma_f32_16x16x32_bf16 v[80:83], v[140:143], v[194:197], v[116:119]
	v_mfma_f32_16x16x32_bf16 v[72:75], v[8:11], v[202:205], v[100:103]
	v_mfma_f32_16x16x32_bf16 v[64:67], v[140:143], v[202:205], v[124:127]
	s_barrier
	ds_read_b128 v[206:209], v135
	ds_read_b128 v[210:213], v136
	ds_read_b128 v[214:217], v137
	ds_read_b128 v[136:139], v138
	s_waitcnt vmcnt(0)
	s_barrier
; #define LDA(dst, b, h) _Pragma("unroll") for (int m = 0; m < 4; ++m) _Pragma("unroll") for (int k = 0; k < 2; ++k) \
;     dst[m][k] = *reinterpret_cast<const bf16x8*>(SA(b, h) + lds_byte(wr * 64 + m * 16 + fr, k * 32 + fq * 8))
; #define LDB(dst, b, h) _Pragma("unroll") for (int n = 0; n < 2; ++n) _Pragma("unroll") for (int k = 0; k < 2; ++k) \
;     dst[n][k] = *reinterpret_cast<const bf16x8*>(SB(b, h) + lds_byte(wc * 32 + n * 16 + fr, k * 32 + fq * 8))
; #define WAIT_V(n) asm volatile("s_waitcnt vmcnt(" #n ")" ::: "memory")
; #define WAIT_L(n) asm volatile("s_waitcnt lgkmcnt(" #n ")" ::: "memory")
; #define BAR __builtin_amdgcn_s_barrier()
;     ...
;       LDB(B1, 1, 1); WAIT_V(0); BAR; WAIT_L(0); MMA(0, 1, At, B1); BAR;
;       LDA(At, 1, 1); BAR; WAIT_L(0); MMA(1, 0, At, B0); MMA(1, 1, At, B1); BAR; }
;     if (wr == 0) BAR;
	s_waitcnt lgkmcnt(0)
	v_mfma_f32_16x16x32_bf16 v[92:95], v[206:209], v[24:27], v[92:95]
	v_mfma_f32_16x16x32_bf16 v[24:27], v[214:217], v[24:27], v[166:169]
	v_mfma_f32_16x16x32_bf16 v[84:87], v[206:209], v[182:185], v[84:87]
	v_mfma_f32_16x16x32_bf16 v[100:103], v[214:217], v[182:185], v[170:173]
	v_mfma_f32_16x16x32_bf16 v[76:79], v[206:209], v[190:193], v[76:79]
	v_mfma_f32_16x16x32_bf16 v[164:167], v[214:217], v[190:193], v[174:177]
	v_mfma_f32_16x16x32_bf16 v[68:71], v[206:209], v[198:201], v[68:71]
	v_mfma_f32_16x16x32_bf16 v[168:171], v[214:217], v[198:201], v[178:181]
	v_mfma_f32_16x16x32_bf16 v[124:127], v[210:213], v[160:163], v[92:95]
	v_mfma_f32_16x16x32_bf16 v[116:119], v[136:139], v[160:163], v[24:27]
	v_mfma_f32_16x16x32_bf16 v[108:111], v[210:213], v[186:189], v[84:87]
	v_mfma_f32_16x16x32_bf16 v[100:103], v[136:139], v[186:189], v[100:103]
	v_mfma_f32_16x16x32_bf16 v[92:95], v[210:213], v[194:197], v[76:79]
	v_mfma_f32_16x16x32_bf16 v[84:87], v[136:139], v[194:197], v[164:167]
	v_mfma_f32_16x16x32_bf16 v[76:79], v[210:213], v[202:205], v[68:71]
	v_mfma_f32_16x16x32_bf16 v[68:71], v[136:139], v[202:205], v[168:171]
	s_barrier
	ds_read_b128 v[160:163], v131 offset:49152
	ds_read_b128 v[164:167], v131 offset:50176
	ds_read_b128 v[168:171], v134 offset:49152
	ds_read_b128 v[172:175], v134 offset:50176
	ds_read_b128 v[176:179], v133 offset:49152
	ds_read_b128 v[180:183], v133 offset:50176
	ds_read_b128 v[184:187], v132 offset:49152
	ds_read_b128 v[132:135], v132 offset:50176
	s_barrier
	s_waitcnt lgkmcnt(0)
	v_mfma_f32_16x16x32_bf16 v[24:27], v[0:3], v[160:163], v[60:63]
	v_mfma_f32_16x16x32_bf16 v[60:63], v[16:19], v[160:163], v[56:59]
	v_mfma_f32_16x16x32_bf16 v[52:55], v[0:3], v[168:171], v[52:55]
	v_mfma_f32_16x16x32_bf16 v[188:191], v[16:19], v[168:171], v[48:51]
	v_mfma_f32_16x16x32_bf16 v[44:47], v[0:3], v[176:179], v[44:47]
	v_mfma_f32_16x16x32_bf16 v[192:195], v[16:19], v[176:179], v[40:43]
	v_mfma_f32_16x16x32_bf16 v[0:3], v[0:3], v[184:187], v[36:39]
	v_mfma_f32_16x16x32_bf16 v[36:39], v[16:19], v[184:187], v[32:35]
	v_mfma_f32_16x16x32_bf16 v[56:59], v[8:11], v[164:167], v[24:27]
	v_mfma_f32_16x16x32_bf16 v[48:51], v[140:143], v[164:167], v[60:63]
	v_mfma_f32_16x16x32_bf16 v[40:43], v[8:11], v[172:175], v[52:55]
	v_mfma_f32_16x16x32_bf16 v[32:35], v[140:143], v[172:175], v[188:191]
	v_mfma_f32_16x16x32_bf16 v[24:27], v[8:11], v[180:183], v[44:47]
	v_mfma_f32_16x16x32_bf16 v[16:19], v[140:143], v[180:183], v[192:195]
	v_mfma_f32_16x16x32_bf16 v[8:11], v[8:11], v[132:135], v[0:3]
	v_mfma_f32_16x16x32_bf16 v[0:3], v[140:143], v[132:135], v[36:39]
	v_mfma_f32_16x16x32_bf16 v[28:31], v[206:209], v[160:163], v[28:31]
	v_mfma_f32_16x16x32_bf16 v[36:39], v[214:217], v[160:163], v[144:147]
	v_mfma_f32_16x16x32_bf16 v[20:23], v[206:209], v[168:171], v[20:23]
	v_mfma_f32_16x16x32_bf16 v[140:143], v[214:217], v[168:171], v[148:151]
	v_mfma_f32_16x16x32_bf16 v[12:15], v[206:209], v[176:179], v[12:15]
	v_mfma_f32_16x16x32_bf16 v[144:147], v[214:217], v[176:179], v[152:155]
	v_mfma_f32_16x16x32_bf16 v[4:7], v[206:209], v[184:187], v[4:7]
	v_mfma_f32_16x16x32_bf16 v[148:151], v[214:217], v[184:187], v[156:159]
	v_mfma_f32_16x16x32_bf16 v[60:63], v[210:213], v[164:167], v[28:31]
	v_mfma_f32_16x16x32_bf16 v[52:55], v[136:139], v[164:167], v[36:39]
	v_mfma_f32_16x16x32_bf16 v[44:47], v[210:213], v[172:175], v[20:23]
	v_mfma_f32_16x16x32_bf16 v[36:39], v[136:139], v[172:175], v[140:143]
	v_mfma_f32_16x16x32_bf16 v[28:31], v[210:213], v[180:183], v[12:15]
	v_mfma_f32_16x16x32_bf16 v[20:23], v[136:139], v[180:183], v[144:147]
	v_mfma_f32_16x16x32_bf16 v[12:15], v[210:213], v[132:135], v[4:7]
	v_mfma_f32_16x16x32_bf16 v[4:7], v[136:139], v[132:135], v[148:151]
	v_cmp_gt_u32_e32 vcc, s35, v130
	s_barrier
	s_and_saveexec_b64 s[10:11], vcc
	s_cbranch_execz .LBB0_98
	s_barrier

; #define STAGE(P, RS, SOFF, OFF, kt) do { const int _so = (SOFF) + (kt) * (BK * 2); \
;     _Pragma("unroll") for (int _i = 0; _i < 2; ++_i) { \
;       __builtin_amdgcn_raw_ptr_buffer_load_lds(RS, (__attribute__((address_space(3))) void*)((P) + wave * 1024 + _i * 8192), 16, OFF[_i], _so, 0, 0); } } while (0)
; #define LDA(dst, b, h) _Pragma("unroll") for (int m = 0; m < 4; ++m) _Pragma("unroll") for (int k = 0; k < 2; ++k) \
;     dst[m][k] = *reinterpret_cast<const bf16x8*>(SA(b, h) + lds_byte(wr * 64 + m * 16 + fr, k * 32 + fq * 8))
; #define LDB(dst, b, h) _Pragma("unroll") for (int n = 0; n < 2; ++n) _Pragma("unroll") for (int k = 0; k < 2; ++k) \
;     dst[n][k] = *reinterpret_cast<const bf16x8*>(SB(b, h) + lds_byte(wc * 32 + n * 16 + fr, k * 32 + fq * 8))
; #define WAIT_V(n) asm volatile("s_waitcnt vmcnt(" #n ")" ::: "memory")
; #define WAIT_L(n) asm volatile("s_waitcnt lgkmcnt(" #n ")" ::: "memory")
; #define BAR __builtin_amdgcn_s_barrier()
; #define SCHED __builtin_amdgcn_sched_barrier(0)
;     ...
;     const int tid = opaque_tid(wave);
;     const int wid = tid >> 6, lane = tid & 63, wr = wid >> 2, wc = wid & 3, fr = lane & 15, fq = lane >> 4;
;     int offA[2], offB[2];
;     _Pragma("unroll") for (int i = 0; i < 2; ++i) {
;       int r, c; stage_rc(tid * 16 + i * 8192, r, c);
;       offA[i] = (r * lda + c) * 2; offB[i] = (r * ldb + c) * 2;
;     }
;     const int brow = pm * BM;
;     f32x4 acc[2][2][4][2];
;     _Pragma("unroll") for (int a = 0; a < 2; ++a) _Pragma("unroll") for (int b = 0; b < 2; ++b) _Pragma("unroll") for (int m = 0; m < 4; ++m) _Pragma("unroll") for (int n = 0; n < 2; ++n)
;       acc[a][b][m][n] = f32x4{0.f, 0.f, 0.f, 0.f};
;     bf16x8 At[4][2], B0[2][2], B1[2][2];
;     if (wr == 1) BAR;
;     if (first_tile) { WAIT_V(0); }
;     else if constexpr (mode == MODE_RESID_LN) { WAIT_V(0); }
;     else if constexpr (mode == MODE_SWIGLU) { WAIT_V(6); }
;     else if constexpr (mode == MODE_V) { WAIT_V(24); }
;     else { WAIT_V(12); }
;     first_tile = false;
;     BAR;
;     BAR;
;     for (int t = 0; t < nt - 2; t += 2) {
;       LDB(B0, 0, 0); SCHED; LDA(At, 0, 0); STAGE(SA(1, 1), rsA, sA1, offA, t + 1);
;       WAIT_L(8); BAR; WAIT_L(0); MMA(0, 0, At, B0); BAR; SCHED;
.LBB0_109:
	v_bfe_i32 v4, v136, 27, 1
	v_lshlrev_b32_e32 v2, 4, v136
	v_lshrrev_b32_e32 v4, 22, v4
	v_add_u32_e32 v4, v2, v4
	v_and_b32_e32 v4, 0xfffffc00, v4
	v_sub_u32_e32 v4, v2, v4
	v_lshrrev_b32_e32 v5, 4, v4
	v_ashrrev_i32_e32 v3, 31, v136
	v_bitop3_b32 v4, v5, v4, 32 bitop3:0x6c
	v_lshrrev_b32_e32 v3, 26, v3
	v_ashrrev_i32_e32 v6, 31, v4
	v_add_u32_e32 v3, v136, v3
	v_lshrrev_b32_e32 v6, 26, v6
	v_ashrrev_i32_e32 v3, 6, v3
	v_add_u32_e32 v6, v4, v6
	v_lshlrev_b32_e32 v5, 3, v3
	v_ashrrev_i32_e32 v7, 6, v6
	v_and_b32_e32 v6, 0xc0, v6
	v_and_b32_e32 v5, -16, v5
	v_lshlrev_b32_e32 v3, 5, v3
	v_sub_u32_e32 v4, v4, v6
	v_add_u32_e32 v5, v7, v5
	v_and_b32_e32 v3, 32, v3
	v_ashrrev_i16_sdwa v4, v129, sext(v4) dst_sel:DWORD dst_unused:UNUSED_PAD src0_sel:DWORD src1_sel:BYTE_0
	v_add_u32_sdwa v3, v3, sext(v4) dst_sel:DWORD dst_unused:UNUSED_PAD src0_sel:DWORD src1_sel:WORD_0
	v_lshlrev_b32_e32 v4, 10, v5
	v_add_u32_e32 v2, 0x2000, v2
	v_lshl_add_u32 v128, v3, 1, v4
	v_ashrrev_i32_e32 v3, 31, v2
	v_lshrrev_b32_e32 v3, 22, v3
	v_add_u32_e32 v3, v2, v3
	v_ashrrev_i32_e32 v3, 10, v3
	v_mul_i32_i24_e32 v4, 0x400, v3
	v_sub_u32_e32 v2, v2, v4
	v_lshrrev_b32_e32 v4, 4, v2
	v_bitop3_b32 v2, v4, v2, 32 bitop3:0x6c
	v_mad_u64_u32 v[130:131], s[10:11], v5, s1, v[128:129]
	v_ashrrev_i32_e32 v5, 31, v2
	v_lshrrev_b32_e32 v5, 26, v5
	v_add_u32_e32 v5, v2, v5
	v_lshlrev_b32_e32 v4, 3, v3
	v_ashrrev_i32_e32 v6, 6, v5
	v_and_b32_e32 v5, 0xc0, v5
	v_and_b32_e32 v4, -16, v4
	v_lshlrev_b32_e32 v3, 5, v3
	v_sub_u32_e32 v2, v2, v5
	v_add_u32_e32 v4, v6, v4
	v_and_b32_e32 v3, 32, v3
	v_ashrrev_i16_sdwa v2, v129, sext(v2) dst_sel:DWORD dst_unused:UNUSED_PAD src0_sel:DWORD src1_sel:BYTE_0
	v_add_u32_sdwa v2, v3, sext(v2) dst_sel:DWORD dst_unused:UNUSED_PAD src0_sel:DWORD src1_sel:WORD_0
	v_lshlrev_b32_e32 v3, 10, v4
	v_lshl_add_u32 v132, v2, 1, v3
	v_and_b32_e32 v3, 15, v0
	v_lshlrev_b32_e32 v5, 2, v0
	v_and_b32_e32 v2, 48, v0
	v_lshlrev_b32_e32 v3, 6, v3
	v_and_b32_e32 v5, 32, v5
	v_lshlrev_b32_e32 v0, 6, v0
	v_mad_u64_u32 v[134:135], s[10:11], v4, s1, v[132:133]
	v_or_b32_e32 v4, v3, v2
	v_bitop3_b32 v3, v3, v5, v2 bitop3:0x36
	v_lshlrev_b32_e32 v6, 6, v136
	v_lshlrev_b32_e32 v1, 13, v1
	v_and_or_b32 v0, v0, s35, v2
	v_and_or_b32 v3, v6, s34, v3
	v_bitop3_b32 v0, v1, v0, v5 bitop3:0xf6
	v_or_b32_e32 v6, 0x400, v3
	v_or_b32_e32 v7, 0x800, v3
	v_or_b32_e32 v8, 0xc00, v3
	v_or_b32_e32 v138, 0x800, v0
	v_or_b32_e32 v137, 0x1000, v0
	v_or_b32_e32 v135, 0x1800, v0
	v_mov_b32_e32 v0, 0
	v_bitop3_b32 v131, v4, v1, v5 bitop3:0xde
	s_mov_b32 s16, -2
	s_mov_b32 s17, 0
	v_or_b32_e32 v151, 0x10000, v3
	v_or_b32_e32 v152, 0x10000, v6
	v_or_b32_e32 v153, 0x10000, v7
	v_or_b32_e32 v154, 0x10000, v8
	v_or_b32_e32 v147, 0x14000, v3
	v_or_b32_e32 v148, 0x14000, v6
	v_or_b32_e32 v149, 0x14000, v7
	v_or_b32_e32 v150, 0x14000, v8
	v_or_b32_e32 v143, 0x18000, v3
	v_or_b32_e32 v144, 0x18000, v6
	v_or_b32_e32 v145, 0x18000, v7
	v_or_b32_e32 v146, 0x18000, v8
	v_or_b32_e32 v139, 0x1c000, v3
	v_or_b32_e32 v140, 0x1c000, v6
	v_or_b32_e32 v141, 0x1c000, v7
	v_or_b32_e32 v142, 0x1c000, v8
	s_barrier
	s_barrier
	ds_read_b128 v[156:159], v151
	ds_read_b128 v[160:163], v152
	ds_read_b128 v[164:167], v153
	ds_read_b128 v[168:171], v154
	s_add_i32 s44, s38, s17
	s_add_i32 s10, s44, 0x80
	s_mov_b32 m0, s31
	ds_read_b128 v[172:175], v131
	ds_read_b128 v[176:179], v131 offset:1024
	ds_read_b128 v[180:183], v138
	ds_read_b128 v[184:187], v138 offset:1024
	ds_read_b128 v[188:191], v137
	ds_read_b128 v[192:195], v137 offset:1024
	ds_read_b128 v[196:199], v135
	ds_read_b128 v[200:203], v135 offset:1024
	buffer_load_dwordx4 v128, s[4:7], s10 offen lds
	s_mov_b32 m0, s33
	s_nop 0
	buffer_load_dwordx4 v132, s[4:7], s10 offen lds
	s_waitcnt lgkmcnt(8)
	s_barrier
	s_waitcnt lgkmcnt(0)
	v_mfma_f32_16x16x32_bf16 v[124:127], v[156:159], v[172:175], 0
	v_mfma_f32_16x16x32_bf16 v[124:127], v[160:163], v[176:179], v[124:127]
	v_mfma_f32_16x16x32_bf16 v[120:123], v[168:171], v[176:179], 0
	v_mfma_f32_16x16x32_bf16 v[120:123], v[164:167], v[172:175], v[120:123]
	v_mfma_f32_16x16x32_bf16 v[112:115], v[164:167], v[180:183], 0
	v_mfma_f32_16x16x32_bf16 v[112:115], v[168:171], v[184:187], v[112:115]
	v_mfma_f32_16x16x32_bf16 v[116:119], v[160:163], v[184:187], 0
	v_mfma_f32_16x16x32_bf16 v[116:119], v[156:159], v[180:183], v[116:119]
	v_mfma_f32_16x16x32_bf16 v[108:111], v[156:159], v[188:191], 0
	v_mfma_f32_16x16x32_bf16 v[108:111], v[160:163], v[192:195], v[108:111]
	v_mfma_f32_16x16x32_bf16 v[104:107], v[168:171], v[192:195], 0
	v_mfma_f32_16x16x32_bf16 v[104:107], v[164:167], v[188:191], v[104:107]
	v_mfma_f32_16x16x32_bf16 v[96:99], v[164:167], v[196:199], 0
	v_mfma_f32_16x16x32_bf16 v[96:99], v[168:171], v[200:203], v[96:99]
	v_mfma_f32_16x16x32_bf16 v[100:103], v[160:163], v[200:203], 0
	v_mfma_f32_16x16x32_bf16 v[100:103], v[156:159], v[196:199], v[100:103]
	s_barrier
	s_add_i32 s45, s40, s17
	s_add_i32 s46, s45, 0x100
	s_mov_b32 s10, s6
	s_mov_b32 s11, s7
	s_mov_b32 m0, s3
	ds_read_b128 v[204:207], v147
	ds_read_b128 v[208:211], v148
	ds_read_b128 v[212:215], v149
	ds_read_b128 v[216:219], v150
	buffer_load_dwordx4 v130, s[8:11], s46 offen lds
	s_mov_b32 m0, s18
	s_nop 0
	buffer_load_dwordx4 v134, s[8:11], s46 offen lds
	s_barrier
; #define STAGE(P, RS, SOFF, OFF, kt) do { const int _so = (SOFF) + (kt) * (BK * 2); \
;     _Pragma("unroll") for (int _i = 0; _i < 2; ++_i) { \
;       __builtin_amdgcn_raw_ptr_buffer_load_lds(RS, (__attribute__((address_space(3))) void*)((P) + wave * 1024 + _i * 8192), 16, OFF[_i], _so, 0, 0); } } while (0)
; #define LDA(dst, b, h) _Pragma("unroll") for (int m = 0; m < 4; ++m) _Pragma("unroll") for (int k = 0; k < 2; ++k) \
;     dst[m][k] = *reinterpret_cast<const bf16x8*>(SA(b, h) + lds_byte(wr * 64 + m * 16 + fr, k * 32 + fq * 8))
; #define LDB(dst, b, h) _Pragma("unroll") for (int n = 0; n < 2; ++n) _Pragma("unroll") for (int k = 0; k < 2; ++k) \
;     dst[n][k] = *reinterpret_cast<const bf16x8*>(SB(b, h) + lds_byte(wc * 32 + n * 16 + fr, k * 32 + fq * 8))
; #define WAIT_V(n) asm volatile("s_waitcnt vmcnt(" #n ")" ::: "memory")
; #define WAIT_L(n) asm volatile("s_waitcnt lgkmcnt(" #n ")" ::: "memory")
; #define BAR __builtin_amdgcn_s_barrier()
; #define SCHED __builtin_amdgcn_sched_barrier(0)
;     ...
;       BAR; WAIT_L(0); MMA(0, 1, At, B1); BAR;
;       LDA(At, 0, 1); STAGE(SA(0, 0), rsA, sA0, offA, t + 2);
;       BAR; WAIT_L(0); MMA(1, 0, At, B0); BAR; SCHED;
;       STAGE(SB(0, 1), rsB, sB1, offB, t + 2);
;       WAIT_V(6); BAR; MMA(1, 1, At, B1); BAR;
;       LDB(B0, 1, 0); SCHED; LDA(At, 1, 0); STAGE(SA(0, 1), rsA, sA1, offA, t + 2);
;       WAIT_L(8); BAR; WAIT_L(0); MMA(0, 0, At, B0); BAR; SCHED;
	s_waitcnt lgkmcnt(0)
	v_mfma_f32_16x16x32_bf16 v[92:95], v[204:207], v[172:175], 0
	v_mfma_f32_16x16x32_bf16 v[92:95], v[208:211], v[176:179], v[92:95]
	v_mfma_f32_16x16x32_bf16 v[88:91], v[216:219], v[176:179], 0
	v_mfma_f32_16x16x32_bf16 v[88:91], v[212:215], v[172:175], v[88:91]
	v_mfma_f32_16x16x32_bf16 v[80:83], v[212:215], v[180:183], 0
	v_mfma_f32_16x16x32_bf16 v[80:83], v[216:219], v[184:187], v[80:83]
	v_mfma_f32_16x16x32_bf16 v[84:87], v[208:211], v[184:187], 0
	v_mfma_f32_16x16x32_bf16 v[84:87], v[204:207], v[180:183], v[84:87]
	v_mfma_f32_16x16x32_bf16 v[76:79], v[204:207], v[188:191], 0
	v_mfma_f32_16x16x32_bf16 v[76:79], v[208:211], v[192:195], v[76:79]
	v_mfma_f32_16x16x32_bf16 v[72:75], v[216:219], v[192:195], 0
	v_mfma_f32_16x16x32_bf16 v[72:75], v[212:215], v[188:191], v[72:75]
	v_mfma_f32_16x16x32_bf16 v[64:67], v[212:215], v[196:199], 0
	v_mfma_f32_16x16x32_bf16 v[64:67], v[216:219], v[200:203], v[64:67]
	v_mfma_f32_16x16x32_bf16 v[68:71], v[208:211], v[200:203], 0
	v_mfma_f32_16x16x32_bf16 v[68:71], v[204:207], v[196:199], v[68:71]
	s_barrier
	s_add_i32 s46, s39, s17
	s_add_i32 s47, s46, 0x100
	s_mov_b32 m0, s0
	ds_read_b128 v[172:175], v131 offset:16384
	ds_read_b128 v[176:179], v131 offset:17408
	ds_read_b128 v[180:183], v138 offset:16384
	ds_read_b128 v[184:187], v138 offset:17408
	ds_read_b128 v[188:191], v137 offset:16384
	ds_read_b128 v[192:195], v137 offset:17408
	ds_read_b128 v[196:199], v135 offset:16384
	ds_read_b128 v[200:203], v135 offset:17408
	buffer_load_dwordx4 v128, s[4:7], s47 offen lds
	s_mov_b32 m0, s19
	s_nop 0
	buffer_load_dwordx4 v132, s[4:7], s47 offen lds
	s_barrier
	s_waitcnt lgkmcnt(0)
	v_mfma_f32_16x16x32_bf16 v[60:63], v[156:159], v[172:175], 0
	v_mfma_f32_16x16x32_bf16 v[60:63], v[160:163], v[176:179], v[60:63]
	v_mfma_f32_16x16x32_bf16 v[56:59], v[168:171], v[176:179], 0
	v_mfma_f32_16x16x32_bf16 v[56:59], v[164:167], v[172:175], v[56:59]
	v_mfma_f32_16x16x32_bf16 v[48:51], v[164:167], v[180:183], 0
	v_mfma_f32_16x16x32_bf16 v[48:51], v[168:171], v[184:187], v[48:51]
	v_mfma_f32_16x16x32_bf16 v[52:55], v[160:163], v[184:187], 0
	v_mfma_f32_16x16x32_bf16 v[52:55], v[156:159], v[180:183], v[52:55]
	v_mfma_f32_16x16x32_bf16 v[44:47], v[156:159], v[188:191], 0
	v_mfma_f32_16x16x32_bf16 v[44:47], v[160:163], v[192:195], v[44:47]
	v_mfma_f32_16x16x32_bf16 v[40:43], v[168:171], v[192:195], 0
	v_mfma_f32_16x16x32_bf16 v[40:43], v[164:167], v[188:191], v[40:43]
	v_mfma_f32_16x16x32_bf16 v[32:35], v[164:167], v[196:199], 0
	v_mfma_f32_16x16x32_bf16 v[32:35], v[168:171], v[200:203], v[32:35]
	v_mfma_f32_16x16x32_bf16 v[36:39], v[160:163], v[200:203], 0
	v_mfma_f32_16x16x32_bf16 v[36:39], v[156:159], v[196:199], v[36:39]
	s_barrier
	s_add_i32 s47, s41, s17
	s_add_i32 s48, s47, 0x100
	s_mov_b32 m0, s20
	s_nop 0
	buffer_load_dwordx4 v130, s[8:11], s48 offen lds
	s_mov_b32 m0, s21
	s_nop 0
	buffer_load_dwordx4 v134, s[8:11], s48 offen lds
	s_waitcnt vmcnt(6)
	s_barrier
	v_mfma_f32_16x16x32_bf16 v[28:31], v[204:207], v[172:175], 0
	v_mfma_f32_16x16x32_bf16 v[28:31], v[208:211], v[176:179], v[28:31]
	v_mfma_f32_16x16x32_bf16 v[24:27], v[216:219], v[176:179], 0
	v_mfma_f32_16x16x32_bf16 v[24:27], v[212:215], v[172:175], v[24:27]
	v_mfma_f32_16x16x32_bf16 v[16:19], v[212:215], v[180:183], 0
	v_mfma_f32_16x16x32_bf16 v[16:19], v[216:219], v[184:187], v[16:19]
	v_mfma_f32_16x16x32_bf16 v[20:23], v[208:211], v[184:187], 0
	v_mfma_f32_16x16x32_bf16 v[20:23], v[204:207], v[180:183], v[20:23]
	v_mfma_f32_16x16x32_bf16 v[12:15], v[204:207], v[188:191], 0
	v_mfma_f32_16x16x32_bf16 v[12:15], v[208:211], v[192:195], v[12:15]
	v_mfma_f32_16x16x32_bf16 v[8:11], v[216:219], v[192:195], 0
	v_mfma_f32_16x16x32_bf16 v[8:11], v[212:215], v[188:191], v[8:11]
	v_mfma_f32_16x16x32_bf16 v[0:3], v[212:215], v[196:199], 0
	v_mfma_f32_16x16x32_bf16 v[0:3], v[216:219], v[200:203], v[0:3]
	v_mfma_f32_16x16x32_bf16 v[4:7], v[208:211], v[200:203], 0
	v_mfma_f32_16x16x32_bf16 v[4:7], v[204:207], v[196:199], v[4:7]
	s_barrier
	ds_read_b128 v[156:159], v143
	ds_read_b128 v[160:163], v144
	ds_read_b128 v[164:167], v145
	ds_read_b128 v[168:171], v146
	s_addk_i32 s44, 0x100
	s_mov_b32 m0, s22
	ds_read_b128 v[172:175], v131 offset:32768
	ds_read_b128 v[176:179], v131 offset:33792
	ds_read_b128 v[180:183], v138 offset:32768
	ds_read_b128 v[184:187], v138 offset:33792
	ds_read_b128 v[188:191], v137 offset:32768
	ds_read_b128 v[192:195], v137 offset:33792
	ds_read_b128 v[196:199], v135 offset:32768
	ds_read_b128 v[200:203], v135 offset:33792
	buffer_load_dwordx4 v128, s[4:7], s44 offen lds
	s_mov_b32 m0, s23
	s_nop 0
	buffer_load_dwordx4 v132, s[4:7], s44 offen lds
	s_waitcnt lgkmcnt(8)
	s_barrier
; #define STAGE(P, RS, SOFF, OFF, kt) do { const int _so = (SOFF) + (kt) * (BK * 2); \
;     _Pragma("unroll") for (int _i = 0; _i < 2; ++_i) { \
;       __builtin_amdgcn_raw_ptr_buffer_load_lds(RS, (__attribute__((address_space(3))) void*)((P) + wave * 1024 + _i * 8192), 16, OFF[_i], _so, 0, 0); } } while (0)
; #define LDA(dst, b, h) _Pragma("unroll") for (int m = 0; m < 4; ++m) _Pragma("unroll") for (int k = 0; k < 2; ++k) \
;     dst[m][k] = *reinterpret_cast<const bf16x8*>(SA(b, h) + lds_byte(wr * 64 + m * 16 + fr, k * 32 + fq * 8))
; #define LDB(dst, b, h) _Pragma("unroll") for (int n = 0; n < 2; ++n) _Pragma("unroll") for (int k = 0; k < 2; ++k) \
;     dst[n][k] = *reinterpret_cast<const bf16x8*>(SB(b, h) + lds_byte(wc * 32 + n * 16 + fr, k * 32 + fq * 8))
; #define WAIT_L(n) asm volatile("s_waitcnt lgkmcnt(" #n ")" ::: "memory")
; #define BAR __builtin_amdgcn_s_barrier()
; #define SCHED __builtin_amdgcn_sched_barrier(0)
;     ...
;       WAIT_L(8); BAR; WAIT_L(0); MMA(0, 0, At, B0); BAR; SCHED;
;       LDB(B1, 1, 1); STAGE(SB(1, 0), rsB, sB0, offB, t + 3);
;       BAR; WAIT_L(0); MMA(0, 1, At, B1); BAR;
;       LDA(At, 1, 1); STAGE(SA(1, 0), rsA, sA0, offA, t + 3);
;       BAR; WAIT_L(0); MMA(1, 0, At, B0); BAR; SCHED;
;       STAGE(SB(1, 1), rsB, sB1, offB, t + 3);
	s_waitcnt lgkmcnt(0)
	v_mfma_f32_16x16x32_bf16 v[124:127], v[156:159], v[172:175], v[124:127]
	v_mfma_f32_16x16x32_bf16 v[124:127], v[160:163], v[176:179], v[124:127]
	v_mfma_f32_16x16x32_bf16 v[120:123], v[168:171], v[176:179], v[120:123]
	v_mfma_f32_16x16x32_bf16 v[120:123], v[164:167], v[172:175], v[120:123]
	v_mfma_f32_16x16x32_bf16 v[112:115], v[164:167], v[180:183], v[112:115]
	v_mfma_f32_16x16x32_bf16 v[112:115], v[168:171], v[184:187], v[112:115]
	v_mfma_f32_16x16x32_bf16 v[116:119], v[160:163], v[184:187], v[116:119]
	v_mfma_f32_16x16x32_bf16 v[116:119], v[156:159], v[180:183], v[116:119]
	v_mfma_f32_16x16x32_bf16 v[108:111], v[156:159], v[188:191], v[108:111]
	v_mfma_f32_16x16x32_bf16 v[108:111], v[160:163], v[192:195], v[108:111]
	v_mfma_f32_16x16x32_bf16 v[104:107], v[168:171], v[192:195], v[104:107]
	v_mfma_f32_16x16x32_bf16 v[104:107], v[164:167], v[188:191], v[104:107]
	v_mfma_f32_16x16x32_bf16 v[96:99], v[164:167], v[196:199], v[96:99]
	v_mfma_f32_16x16x32_bf16 v[96:99], v[168:171], v[200:203], v[96:99]
	v_mfma_f32_16x16x32_bf16 v[100:103], v[160:163], v[200:203], v[100:103]
	v_mfma_f32_16x16x32_bf16 v[100:103], v[156:159], v[196:199], v[100:103]
	s_barrier
	s_addk_i32 s45, 0x180
	s_mov_b32 m0, s24
	ds_read_b128 v[204:207], v139
	ds_read_b128 v[208:211], v140
	ds_read_b128 v[212:215], v141
	ds_read_b128 v[216:219], v142
	buffer_load_dwordx4 v130, s[8:11], s45 offen lds
	s_mov_b32 m0, s25
	s_nop 0
	buffer_load_dwordx4 v134, s[8:11], s45 offen lds
	s_barrier
	s_waitcnt lgkmcnt(0)
	v_mfma_f32_16x16x32_bf16 v[92:95], v[204:207], v[172:175], v[92:95]
	v_mfma_f32_16x16x32_bf16 v[92:95], v[208:211], v[176:179], v[92:95]
	v_mfma_f32_16x16x32_bf16 v[88:91], v[216:219], v[176:179], v[88:91]
	v_mfma_f32_16x16x32_bf16 v[88:91], v[212:215], v[172:175], v[88:91]
	v_mfma_f32_16x16x32_bf16 v[80:83], v[212:215], v[180:183], v[80:83]
	v_mfma_f32_16x16x32_bf16 v[80:83], v[216:219], v[184:187], v[80:83]
	v_mfma_f32_16x16x32_bf16 v[84:87], v[208:211], v[184:187], v[84:87]
	v_mfma_f32_16x16x32_bf16 v[84:87], v[204:207], v[180:183], v[84:87]
	v_mfma_f32_16x16x32_bf16 v[76:79], v[204:207], v[188:191], v[76:79]
	v_mfma_f32_16x16x32_bf16 v[76:79], v[208:211], v[192:195], v[76:79]
	v_mfma_f32_16x16x32_bf16 v[72:75], v[216:219], v[192:195], v[72:75]
	v_mfma_f32_16x16x32_bf16 v[72:75], v[212:215], v[188:191], v[72:75]
	v_mfma_f32_16x16x32_bf16 v[64:67], v[212:215], v[196:199], v[64:67]
	v_mfma_f32_16x16x32_bf16 v[64:67], v[216:219], v[200:203], v[64:67]
	v_mfma_f32_16x16x32_bf16 v[68:71], v[208:211], v[200:203], v[68:71]
	v_mfma_f32_16x16x32_bf16 v[68:71], v[204:207], v[196:199], v[68:71]
	s_barrier
	s_addk_i32 s46, 0x180
	s_mov_b32 m0, s26
	ds_read_b128 v[172:175], v131 offset:49152
	ds_read_b128 v[176:179], v131 offset:50176
	ds_read_b128 v[180:183], v138 offset:49152
	ds_read_b128 v[184:187], v138 offset:50176
	ds_read_b128 v[188:191], v137 offset:49152
	ds_read_b128 v[192:195], v137 offset:50176
	ds_read_b128 v[196:199], v135 offset:49152
	ds_read_b128 v[200:203], v135 offset:50176
	buffer_load_dwordx4 v128, s[4:7], s46 offen lds
	s_mov_b32 m0, s27
	s_nop 0
	buffer_load_dwordx4 v132, s[4:7], s46 offen lds
	s_barrier
	s_waitcnt lgkmcnt(0)
	v_mfma_f32_16x16x32_bf16 v[60:63], v[156:159], v[172:175], v[60:63]
	v_mfma_f32_16x16x32_bf16 v[60:63], v[160:163], v[176:179], v[60:63]
	v_mfma_f32_16x16x32_bf16 v[56:59], v[168:171], v[176:179], v[56:59]
	v_mfma_f32_16x16x32_bf16 v[56:59], v[164:167], v[172:175], v[56:59]
	v_mfma_f32_16x16x32_bf16 v[48:51], v[164:167], v[180:183], v[48:51]
	v_mfma_f32_16x16x32_bf16 v[48:51], v[168:171], v[184:187], v[48:51]
	v_mfma_f32_16x16x32_bf16 v[52:55], v[160:163], v[184:187], v[52:55]
	v_mfma_f32_16x16x32_bf16 v[52:55], v[156:159], v[180:183], v[52:55]
	v_mfma_f32_16x16x32_bf16 v[44:47], v[156:159], v[188:191], v[44:47]
	v_mfma_f32_16x16x32_bf16 v[44:47], v[160:163], v[192:195], v[44:47]
	v_mfma_f32_16x16x32_bf16 v[40:43], v[168:171], v[192:195], v[40:43]
	v_mfma_f32_16x16x32_bf16 v[40:43], v[164:167], v[188:191], v[40:43]
	v_mfma_f32_16x16x32_bf16 v[32:35], v[164:167], v[196:199], v[32:35]
	v_mfma_f32_16x16x32_bf16 v[32:35], v[168:171], v[200:203], v[32:35]
	v_mfma_f32_16x16x32_bf16 v[36:39], v[160:163], v[200:203], v[36:39]
	v_mfma_f32_16x16x32_bf16 v[36:39], v[156:159], v[196:199], v[36:39]
	s_barrier
	s_addk_i32 s47, 0x180
	s_mov_b32 m0, s28
	s_nop 0
	buffer_load_dwordx4 v130, s[8:11], s47 offen lds
	s_mov_b32 m0, s29
	s_nop 0
	buffer_load_dwordx4 v134, s[8:11], s47 offen lds
	s_add_i32 s16, s16, 2
	s_addk_i32 s17, 0x100
	s_cmp_gt_u32 s16, 3
	s_cbranch_scc0 .LBB0_110
	s_branch .Lmy_post_110

; #define STAGE(P, RS, SOFF, OFF, kt) do { const int _so = (SOFF) + (kt) * (BK * 2); \
;     _Pragma("unroll") for (int _i = 0; _i < 2; ++_i) { \
;       __builtin_amdgcn_raw_ptr_buffer_load_lds(RS, (__attribute__((address_space(3))) void*)((P) + wave * 1024 + _i * 8192), 16, OFF[_i], _so, 0, 0); } } while (0)
; #define LDA(dst, b, h) _Pragma("unroll") for (int m = 0; m < 4; ++m) _Pragma("unroll") for (int k = 0; k < 2; ++k) \
;     dst[m][k] = *reinterpret_cast<const bf16x8*>(SA(b, h) + lds_byte(wr * 64 + m * 16 + fr, k * 32 + fq * 8))
; #define LDB(dst, b, h) _Pragma("unroll") for (int n = 0; n < 2; ++n) _Pragma("unroll") for (int k = 0; k < 2; ++k) \
;     dst[n][k] = *reinterpret_cast<const bf16x8*>(SB(b, h) + lds_byte(wc * 32 + n * 16 + fr, k * 32 + fq * 8))
; #define WAIT_V(n) asm volatile("s_waitcnt vmcnt(" #n ")" ::: "memory")
; #define WAIT_L(n) asm volatile("s_waitcnt lgkmcnt(" #n ")" ::: "memory")
; #define BAR __builtin_amdgcn_s_barrier()
;     ...
;       WAIT_V(6); BAR; MMA(1, 1, At, B1); BAR;
;     }
;     { LDB(B0, 0, 0); LDA(At, 0, 0); STAGE(SA(1, 1), rsA, sA1, offA, nt - 1);
;       BAR; WAIT_L(0); MMA(0, 0, At, B0); BAR;
;       LDB(B1, 0, 1); BAR; WAIT_L(0); MMA(0, 1, At, B1); BAR;
;       LDA(At, 0, 1); WAIT_V(4); BAR; WAIT_L(0); MMA(1, 0, At, B0); MMA(1, 1, At, B1); BAR; }
.Lmy_post_110:
	s_waitcnt vmcnt(6)
	s_barrier
	v_mfma_f32_16x16x32_bf16 v[28:31], v[204:207], v[172:175], v[28:31]
	v_mfma_f32_16x16x32_bf16 v[28:31], v[208:211], v[176:179], v[28:31]
	v_mfma_f32_16x16x32_bf16 v[24:27], v[216:219], v[176:179], v[24:27]
	v_mfma_f32_16x16x32_bf16 v[24:27], v[212:215], v[172:175], v[24:27]
	v_mfma_f32_16x16x32_bf16 v[16:19], v[212:215], v[180:183], v[16:19]
	v_mfma_f32_16x16x32_bf16 v[16:19], v[216:219], v[184:187], v[16:19]
	v_mfma_f32_16x16x32_bf16 v[20:23], v[208:211], v[184:187], v[20:23]
	v_mfma_f32_16x16x32_bf16 v[20:23], v[204:207], v[180:183], v[20:23]
	v_mfma_f32_16x16x32_bf16 v[12:15], v[204:207], v[188:191], v[12:15]
	v_mfma_f32_16x16x32_bf16 v[12:15], v[208:211], v[192:195], v[12:15]
	v_mfma_f32_16x16x32_bf16 v[8:11], v[216:219], v[192:195], v[8:11]
	v_mfma_f32_16x16x32_bf16 v[8:11], v[212:215], v[188:191], v[8:11]
	v_mfma_f32_16x16x32_bf16 v[0:3], v[212:215], v[196:199], v[0:3]
	v_mfma_f32_16x16x32_bf16 v[0:3], v[216:219], v[200:203], v[0:3]
	v_mfma_f32_16x16x32_bf16 v[4:7], v[208:211], v[200:203], v[4:7]
	v_mfma_f32_16x16x32_bf16 v[4:7], v[204:207], v[196:199], v[4:7]
	s_barrier
	s_add_i32 s10, s38, 0x380
	s_mov_b32 m0, s31
	ds_read_b128 v[156:159], v151
	ds_read_b128 v[160:163], v152
	ds_read_b128 v[164:167], v153
	ds_read_b128 v[152:155], v154
	ds_read_b128 v[168:171], v131
	ds_read_b128 v[172:175], v131 offset:1024
	ds_read_b128 v[176:179], v138
	ds_read_b128 v[180:183], v138 offset:1024
	ds_read_b128 v[184:187], v137
	ds_read_b128 v[188:191], v137 offset:1024
	ds_read_b128 v[192:195], v135
	ds_read_b128 v[196:199], v135 offset:1024
	buffer_load_dwordx4 v128, s[4:7], s10 offen lds
	s_mov_b32 m0, s33
	s_nop 0
	buffer_load_dwordx4 v132, s[4:7], s10 offen lds
	s_barrier
	s_waitcnt lgkmcnt(0)
	v_mfma_f32_16x16x32_bf16 v[124:127], v[156:159], v[168:171], v[124:127]
	v_mfma_f32_16x16x32_bf16 v[124:127], v[160:163], v[172:175], v[124:127]
	v_mfma_f32_16x16x32_bf16 v[120:123], v[152:155], v[172:175], v[120:123]
	v_mfma_f32_16x16x32_bf16 v[120:123], v[164:167], v[168:171], v[120:123]
	v_mfma_f32_16x16x32_bf16 v[112:115], v[164:167], v[176:179], v[112:115]
	v_mfma_f32_16x16x32_bf16 v[112:115], v[152:155], v[180:183], v[112:115]
	v_mfma_f32_16x16x32_bf16 v[116:119], v[160:163], v[180:183], v[116:119]
	v_mfma_f32_16x16x32_bf16 v[116:119], v[156:159], v[176:179], v[116:119]
	v_mfma_f32_16x16x32_bf16 v[108:111], v[156:159], v[184:187], v[108:111]
	v_mfma_f32_16x16x32_bf16 v[108:111], v[160:163], v[188:191], v[108:111]
	v_mfma_f32_16x16x32_bf16 v[104:107], v[152:155], v[188:191], v[104:107]
	v_mfma_f32_16x16x32_bf16 v[104:107], v[164:167], v[184:187], v[104:107]
	v_mfma_f32_16x16x32_bf16 v[96:99], v[164:167], v[192:195], v[96:99]
	v_mfma_f32_16x16x32_bf16 v[96:99], v[152:155], v[196:199], v[96:99]
	v_mfma_f32_16x16x32_bf16 v[100:103], v[160:163], v[196:199], v[100:103]
	v_mfma_f32_16x16x32_bf16 v[100:103], v[156:159], v[192:195], v[100:103]
	s_barrier
	ds_read_b128 v[200:203], v147
	ds_read_b128 v[204:207], v148
	ds_read_b128 v[208:211], v149
	ds_read_b128 v[148:151], v150
	s_barrier
	s_waitcnt lgkmcnt(0)
	v_mfma_f32_16x16x32_bf16 v[92:95], v[200:203], v[168:171], v[92:95]
	v_mfma_f32_16x16x32_bf16 v[92:95], v[204:207], v[172:175], v[92:95]
	v_mfma_f32_16x16x32_bf16 v[88:91], v[148:151], v[172:175], v[88:91]
	v_mfma_f32_16x16x32_bf16 v[88:91], v[208:211], v[168:171], v[88:91]
	v_mfma_f32_16x16x32_bf16 v[80:83], v[208:211], v[176:179], v[80:83]
	v_mfma_f32_16x16x32_bf16 v[80:83], v[148:151], v[180:183], v[80:83]
	v_mfma_f32_16x16x32_bf16 v[84:87], v[204:207], v[180:183], v[84:87]
	v_mfma_f32_16x16x32_bf16 v[84:87], v[200:203], v[176:179], v[84:87]
	v_mfma_f32_16x16x32_bf16 v[76:79], v[200:203], v[184:187], v[76:79]
	v_mfma_f32_16x16x32_bf16 v[76:79], v[204:207], v[188:191], v[76:79]
	v_mfma_f32_16x16x32_bf16 v[72:75], v[148:151], v[188:191], v[72:75]
	v_mfma_f32_16x16x32_bf16 v[72:75], v[208:211], v[184:187], v[72:75]
	v_mfma_f32_16x16x32_bf16 v[64:67], v[208:211], v[192:195], v[64:67]
	v_mfma_f32_16x16x32_bf16 v[64:67], v[148:151], v[196:199], v[64:67]
	v_mfma_f32_16x16x32_bf16 v[68:71], v[204:207], v[196:199], v[68:71]
	v_mfma_f32_16x16x32_bf16 v[68:71], v[200:203], v[192:195], v[68:71]
	s_barrier
	ds_read_b128 v[168:171], v131 offset:16384
	ds_read_b128 v[172:175], v131 offset:17408
	ds_read_b128 v[176:179], v138 offset:16384
	ds_read_b128 v[180:183], v138 offset:17408
	ds_read_b128 v[184:187], v137 offset:16384
	ds_read_b128 v[188:191], v137 offset:17408
	ds_read_b128 v[192:195], v135 offset:16384
	ds_read_b128 v[196:199], v135 offset:17408
	s_waitcnt vmcnt(4)
	s_barrier
; #define LDA(dst, b, h) _Pragma("unroll") for (int m = 0; m < 4; ++m) _Pragma("unroll") for (int k = 0; k < 2; ++k) \
;     dst[m][k] = *reinterpret_cast<const bf16x8*>(SA(b, h) + lds_byte(wr * 64 + m * 16 + fr, k * 32 + fq * 8))
; #define LDB(dst, b, h) _Pragma("unroll") for (int n = 0; n < 2; ++n) _Pragma("unroll") for (int k = 0; k < 2; ++k) \
;     dst[n][k] = *reinterpret_cast<const bf16x8*>(SB(b, h) + lds_byte(wc * 32 + n * 16 + fr, k * 32 + fq * 8))
; #define WAIT_V(n) asm volatile("s_waitcnt vmcnt(" #n ")" ::: "memory")
; #define WAIT_L(n) asm volatile("s_waitcnt lgkmcnt(" #n ")" ::: "memory")
; #define BAR __builtin_amdgcn_s_barrier()
;     ...
;       LDA(At, 0, 1); WAIT_V(4); BAR; WAIT_L(0); MMA(1, 0, At, B0); MMA(1, 1, At, B1); BAR; }
;     { LDB(B0, 1, 0); LDA(At, 1, 0); WAIT_V(2); BAR; WAIT_L(0); MMA(0, 0, At, B0); BAR;
	s_waitcnt lgkmcnt(0)
	v_mfma_f32_16x16x32_bf16 v[60:63], v[156:159], v[168:171], v[60:63]
	v_mfma_f32_16x16x32_bf16 v[60:63], v[160:163], v[172:175], v[60:63]
	v_mfma_f32_16x16x32_bf16 v[56:59], v[152:155], v[172:175], v[56:59]
	v_mfma_f32_16x16x32_bf16 v[56:59], v[164:167], v[168:171], v[56:59]
	v_mfma_f32_16x16x32_bf16 v[48:51], v[164:167], v[176:179], v[48:51]
	v_mfma_f32_16x16x32_bf16 v[48:51], v[152:155], v[180:183], v[48:51]
	v_mfma_f32_16x16x32_bf16 v[52:55], v[160:163], v[180:183], v[52:55]
	v_mfma_f32_16x16x32_bf16 v[52:55], v[156:159], v[176:179], v[52:55]
	v_mfma_f32_16x16x32_bf16 v[44:47], v[156:159], v[184:187], v[44:47]
	v_mfma_f32_16x16x32_bf16 v[44:47], v[160:163], v[188:191], v[44:47]
	v_mfma_f32_16x16x32_bf16 v[40:43], v[152:155], v[188:191], v[40:43]
	v_mfma_f32_16x16x32_bf16 v[40:43], v[164:167], v[184:187], v[40:43]
	v_mfma_f32_16x16x32_bf16 v[32:35], v[164:167], v[192:195], v[32:35]
	v_mfma_f32_16x16x32_bf16 v[32:35], v[152:155], v[196:199], v[32:35]
	v_mfma_f32_16x16x32_bf16 v[36:39], v[160:163], v[196:199], v[36:39]
	v_mfma_f32_16x16x32_bf16 v[36:39], v[156:159], v[192:195], v[36:39]
	v_mfma_f32_16x16x32_bf16 v[4:7], v[200:203], v[192:195], v[4:7]
	v_mfma_f32_16x16x32_bf16 v[4:7], v[204:207], v[196:199], v[4:7]
	v_mfma_f32_16x16x32_bf16 v[28:31], v[204:207], v[172:175], v[28:31]
	v_mfma_f32_16x16x32_bf16 v[28:31], v[200:203], v[168:171], v[28:31]
	v_mfma_f32_16x16x32_bf16 v[24:27], v[208:211], v[168:171], v[24:27]
	v_mfma_f32_16x16x32_bf16 v[24:27], v[148:151], v[172:175], v[24:27]
	v_mfma_f32_16x16x32_bf16 v[16:19], v[148:151], v[180:183], v[16:19]
	v_mfma_f32_16x16x32_bf16 v[16:19], v[208:211], v[176:179], v[16:19]
	v_mfma_f32_16x16x32_bf16 v[20:23], v[200:203], v[176:179], v[20:23]
	v_mfma_f32_16x16x32_bf16 v[20:23], v[204:207], v[180:183], v[20:23]
	v_mfma_f32_16x16x32_bf16 v[12:15], v[204:207], v[188:191], v[12:15]
	v_mfma_f32_16x16x32_bf16 v[12:15], v[200:203], v[184:187], v[12:15]
	v_mfma_f32_16x16x32_bf16 v[8:11], v[208:211], v[184:187], v[8:11]
	v_mfma_f32_16x16x32_bf16 v[8:11], v[148:151], v[188:191], v[8:11]
	v_mfma_f32_16x16x32_bf16 v[0:3], v[148:151], v[196:199], v[0:3]
	v_mfma_f32_16x16x32_bf16 v[0:3], v[208:211], v[192:195], v[0:3]
	s_barrier
	ds_read_b128 v[148:151], v143
	ds_read_b128 v[152:155], v144
	ds_read_b128 v[156:159], v145
	ds_read_b128 v[144:147], v146
	ds_read_b128 v[160:163], v131 offset:32768
	ds_read_b128 v[164:167], v131 offset:33792
	ds_read_b128 v[168:171], v138 offset:32768
	ds_read_b128 v[172:175], v138 offset:33792
	ds_read_b128 v[176:179], v137 offset:32768
	ds_read_b128 v[180:183], v137 offset:33792
	ds_read_b128 v[184:187], v135 offset:32768
	ds_read_b128 v[188:191], v135 offset:33792
	s_waitcnt vmcnt(2)
	s_barrier
	s_waitcnt lgkmcnt(0)
	v_mfma_f32_16x16x32_bf16 v[124:127], v[148:151], v[160:163], v[124:127]
	v_mfma_f32_16x16x32_bf16 v[124:127], v[152:155], v[164:167], v[124:127]
	v_mfma_f32_16x16x32_bf16 v[120:123], v[144:147], v[164:167], v[120:123]
	v_mfma_f32_16x16x32_bf16 v[120:123], v[156:159], v[160:163], v[120:123]
	v_mfma_f32_16x16x32_bf16 v[112:115], v[156:159], v[168:171], v[112:115]
	v_mfma_f32_16x16x32_bf16 v[112:115], v[144:147], v[172:175], v[112:115]
	v_mfma_f32_16x16x32_bf16 v[116:119], v[152:155], v[172:175], v[116:119]
	v_mfma_f32_16x16x32_bf16 v[116:119], v[148:151], v[168:171], v[116:119]
	v_mfma_f32_16x16x32_bf16 v[108:111], v[148:151], v[176:179], v[108:111]
	v_mfma_f32_16x16x32_bf16 v[108:111], v[152:155], v[180:183], v[108:111]
	v_mfma_f32_16x16x32_bf16 v[104:107], v[144:147], v[180:183], v[104:107]
	v_mfma_f32_16x16x32_bf16 v[104:107], v[156:159], v[176:179], v[104:107]
	v_mfma_f32_16x16x32_bf16 v[96:99], v[156:159], v[184:187], v[96:99]
	v_mfma_f32_16x16x32_bf16 v[96:99], v[144:147], v[188:191], v[96:99]
	v_mfma_f32_16x16x32_bf16 v[100:103], v[152:155], v[188:191], v[100:103]
	v_mfma_f32_16x16x32_bf16 v[100:103], v[148:151], v[184:187], v[100:103]
	s_barrier
; #define LDA(dst, b, h) _Pragma("unroll") for (int m = 0; m < 4; ++m) _Pragma("unroll") for (int k = 0; k < 2; ++k) \
;     dst[m][k] = *reinterpret_cast<const bf16x8*>(SA(b, h) + lds_byte(wr * 64 + m * 16 + fr, k * 32 + fq * 8))
; #define LDB(dst, b, h) _Pragma("unroll") for (int n = 0; n < 2; ++n) _Pragma("unroll") for (int k = 0; k < 2; ++k) \
;     dst[n][k] = *reinterpret_cast<const bf16x8*>(SB(b, h) + lds_byte(wc * 32 + n * 16 + fr, k * 32 + fq * 8))
; #define WAIT_V(n) asm volatile("s_waitcnt vmcnt(" #n ")" ::: "memory")
; #define WAIT_L(n) asm volatile("s_waitcnt lgkmcnt(" #n ")" ::: "memory")
; #define BAR __builtin_amdgcn_s_barrier()
;     ...
;       LDB(B1, 1, 1); WAIT_V(0); BAR; WAIT_L(0); MMA(0, 1, At, B1); BAR;
;       LDA(At, 1, 1); BAR; WAIT_L(0); MMA(1, 0, At, B0); MMA(1, 1, At, B1); BAR; }
;     if (wr == 0) BAR;
	ds_read_b128 v[192:195], v139
	ds_read_b128 v[196:199], v140
	ds_read_b128 v[200:203], v141
	ds_read_b128 v[140:143], v142
	s_waitcnt vmcnt(0)
	s_barrier
	s_waitcnt lgkmcnt(0)
	v_mfma_f32_16x16x32_bf16 v[92:95], v[192:195], v[160:163], v[92:95]
	v_mfma_f32_16x16x32_bf16 v[92:95], v[196:199], v[164:167], v[92:95]
	v_mfma_f32_16x16x32_bf16 v[88:91], v[140:143], v[164:167], v[88:91]
	v_mfma_f32_16x16x32_bf16 v[88:91], v[200:203], v[160:163], v[88:91]
	v_mfma_f32_16x16x32_bf16 v[80:83], v[200:203], v[168:171], v[80:83]
	v_mfma_f32_16x16x32_bf16 v[80:83], v[140:143], v[172:175], v[80:83]
	v_mfma_f32_16x16x32_bf16 v[84:87], v[196:199], v[172:175], v[84:87]
	v_mfma_f32_16x16x32_bf16 v[84:87], v[192:195], v[168:171], v[84:87]
	v_mfma_f32_16x16x32_bf16 v[76:79], v[192:195], v[176:179], v[76:79]
	v_mfma_f32_16x16x32_bf16 v[76:79], v[196:199], v[180:183], v[76:79]
	v_mfma_f32_16x16x32_bf16 v[72:75], v[140:143], v[180:183], v[72:75]
	v_mfma_f32_16x16x32_bf16 v[72:75], v[200:203], v[176:179], v[72:75]
	v_mfma_f32_16x16x32_bf16 v[64:67], v[200:203], v[184:187], v[64:67]
	v_mfma_f32_16x16x32_bf16 v[64:67], v[140:143], v[188:191], v[64:67]
	v_mfma_f32_16x16x32_bf16 v[68:71], v[196:199], v[188:191], v[68:71]
	v_mfma_f32_16x16x32_bf16 v[68:71], v[192:195], v[184:187], v[68:71]
	s_barrier
	ds_read_b128 v[160:163], v131 offset:49152
	ds_read_b128 v[164:167], v131 offset:50176
	ds_read_b128 v[168:171], v138 offset:49152
	ds_read_b128 v[172:175], v138 offset:50176
	ds_read_b128 v[176:179], v137 offset:49152
	ds_read_b128 v[180:183], v137 offset:50176
	ds_read_b128 v[184:187], v135 offset:49152
	ds_read_b128 v[188:191], v135 offset:50176
	s_barrier
	s_waitcnt lgkmcnt(0)
	v_mfma_f32_16x16x32_bf16 v[60:63], v[148:151], v[160:163], v[60:63]
	v_mfma_f32_16x16x32_bf16 v[60:63], v[152:155], v[164:167], v[60:63]
	v_mfma_f32_16x16x32_bf16 v[56:59], v[144:147], v[164:167], v[56:59]
	v_mfma_f32_16x16x32_bf16 v[56:59], v[156:159], v[160:163], v[56:59]
	v_mfma_f32_16x16x32_bf16 v[48:51], v[156:159], v[168:171], v[48:51]
	v_mfma_f32_16x16x32_bf16 v[48:51], v[144:147], v[172:175], v[48:51]
	v_mfma_f32_16x16x32_bf16 v[52:55], v[152:155], v[172:175], v[52:55]
	v_mfma_f32_16x16x32_bf16 v[52:55], v[148:151], v[168:171], v[52:55]
	v_mfma_f32_16x16x32_bf16 v[44:47], v[148:151], v[176:179], v[44:47]
	v_mfma_f32_16x16x32_bf16 v[44:47], v[152:155], v[180:183], v[44:47]
	v_mfma_f32_16x16x32_bf16 v[40:43], v[144:147], v[180:183], v[40:43]
	v_mfma_f32_16x16x32_bf16 v[40:43], v[156:159], v[176:179], v[40:43]
	v_mfma_f32_16x16x32_bf16 v[32:35], v[156:159], v[184:187], v[32:35]
	v_mfma_f32_16x16x32_bf16 v[32:35], v[144:147], v[188:191], v[32:35]
	v_mfma_f32_16x16x32_bf16 v[36:39], v[152:155], v[188:191], v[36:39]
	v_mfma_f32_16x16x32_bf16 v[36:39], v[148:151], v[184:187], v[36:39]
	v_mfma_f32_16x16x32_bf16 v[4:7], v[192:195], v[184:187], v[4:7]
	v_mfma_f32_16x16x32_bf16 v[4:7], v[196:199], v[188:191], v[4:7]
	v_mfma_f32_16x16x32_bf16 v[28:31], v[196:199], v[164:167], v[28:31]
	v_mfma_f32_16x16x32_bf16 v[28:31], v[192:195], v[160:163], v[28:31]
	v_mfma_f32_16x16x32_bf16 v[24:27], v[200:203], v[160:163], v[24:27]
	v_mfma_f32_16x16x32_bf16 v[24:27], v[140:143], v[164:167], v[24:27]
	v_mfma_f32_16x16x32_bf16 v[16:19], v[140:143], v[172:175], v[16:19]
	v_mfma_f32_16x16x32_bf16 v[16:19], v[200:203], v[168:171], v[16:19]
	v_mfma_f32_16x16x32_bf16 v[20:23], v[192:195], v[168:171], v[20:23]
	v_mfma_f32_16x16x32_bf16 v[20:23], v[196:199], v[172:175], v[20:23]
	v_mfma_f32_16x16x32_bf16 v[12:15], v[196:199], v[180:183], v[12:15]
	v_mfma_f32_16x16x32_bf16 v[12:15], v[192:195], v[176:179], v[12:15]
	v_mfma_f32_16x16x32_bf16 v[8:11], v[200:203], v[176:179], v[8:11]
	v_mfma_f32_16x16x32_bf16 v[8:11], v[140:143], v[180:183], v[8:11]
	v_mfma_f32_16x16x32_bf16 v[0:3], v[140:143], v[188:191], v[0:3]
	v_mfma_f32_16x16x32_bf16 v[0:3], v[200:203], v[184:187], v[0:3]
	v_cmp_gt_u32_e32 vcc, s36, v136
	s_barrier
	s_and_saveexec_b64 s[10:11], vcc
	s_cbranch_execz .LBB0_113
	s_barrier

; #define STAGE(P, RS, SOFF, OFF, kt) do { const int _so = (SOFF) + (kt) * (BK * 2); \
;     _Pragma("unroll") for (int _i = 0; _i < 2; ++_i) { \
;       __builtin_amdgcn_raw_ptr_buffer_load_lds(RS, (__attribute__((address_space(3))) void*)((P) + wave * 1024 + _i * 8192), 16, OFF[_i], _so, 0, 0); } } while (0)
; #define LDA(dst, b, h) _Pragma("unroll") for (int m = 0; m < 4; ++m) _Pragma("unroll") for (int k = 0; k < 2; ++k) \
;     dst[m][k] = *reinterpret_cast<const bf16x8*>(SA(b, h) + lds_byte(wr * 64 + m * 16 + fr, k * 32 + fq * 8))
; #define LDB(dst, b, h) _Pragma("unroll") for (int n = 0; n < 2; ++n) _Pragma("unroll") for (int k = 0; k < 2; ++k) \
;     dst[n][k] = *reinterpret_cast<const bf16x8*>(SB(b, h) + lds_byte(wc * 32 + n * 16 + fr, k * 32 + fq * 8))
; #define WAIT_V(n) asm volatile("s_waitcnt vmcnt(" #n ")" ::: "memory")
; #define WAIT_L(n) asm volatile("s_waitcnt lgkmcnt(" #n ")" ::: "memory")
; #define BAR __builtin_amdgcn_s_barrier()
; #define SCHED __builtin_amdgcn_sched_barrier(0)
;     ...
;     const int tid = opaque_tid(wave);
;     const int wid = tid >> 6, lane = tid & 63, wr = wid >> 2, wc = wid & 3, fr = lane & 15, fq = lane >> 4;
;     int offA[2], offB[2];
;     _Pragma("unroll") for (int i = 0; i < 2; ++i) {
;       int r, c; stage_rc(tid * 16 + i * 8192, r, c);
;       offA[i] = (r * lda + c) * 2; offB[i] = (r * ldb + c) * 2;
;     }
;     const int brow = pm * BM;
;     f32x4 acc[2][2][4][2];
;     _Pragma("unroll") for (int a = 0; a < 2; ++a) _Pragma("unroll") for (int b = 0; b < 2; ++b) _Pragma("unroll") for (int m = 0; m < 4; ++m) _Pragma("unroll") for (int n = 0; n < 2; ++n)
;       acc[a][b][m][n] = f32x4{0.f, 0.f, 0.f, 0.f};
;     bf16x8 At[4][2], B0[2][2], B1[2][2];
;     if (wr == 1) BAR;
;     if (first_tile) { WAIT_V(0); }
;     else if constexpr (mode == MODE_RESID_LN) { WAIT_V(0); }
;     else if constexpr (mode == MODE_SWIGLU) { WAIT_V(6); }
;     else if constexpr (mode == MODE_V) { WAIT_V(24); }
;     else { WAIT_V(12); }
;     first_tile = false;
;     BAR;
;     BAR;
;     for (int t = 0; t < nt - 2; t += 2) {
;       LDB(B0, 0, 0); SCHED; LDA(At, 0, 0); STAGE(SA(1, 1), rsA, sA1, offA, t + 1);
;       WAIT_L(8); BAR; WAIT_L(0); MMA(0, 0, At, B0); BAR; SCHED;
.LBB0_147:
	v_bfe_i32 v4, v128, 27, 1
	v_lshlrev_b32_e32 v2, 4, v128
	v_lshrrev_b32_e32 v4, 22, v4
	v_add_u32_e32 v4, v2, v4
	v_and_b32_e32 v4, 0xfffffc00, v4
	v_sub_u32_e32 v4, v2, v4
	v_lshrrev_b32_e32 v5, 4, v4
	v_bitop3_b32 v4, v5, v4, 32 bitop3:0x6c
	v_ashrrev_i32_e32 v3, 31, v128
	v_ashrrev_i32_e32 v6, 31, v4
	v_lshrrev_b32_e32 v3, 26, v3
	v_lshrrev_b32_e32 v6, 26, v6
	v_add_u32_e32 v3, v128, v3
	v_add_u32_e32 v6, v4, v6
	v_ashrrev_i32_e32 v3, 6, v3
	v_lshrrev_b32_e32 v7, 6, v6
	v_and_b32_e32 v6, 0xc0, v6
	v_lshlrev_b32_e32 v5, 3, v3
	v_lshlrev_b32_e32 v3, 5, v3
	v_sub_u32_e32 v4, v4, v6
	v_and_b32_e32 v5, 0x7fff0, v5
	v_and_b32_e32 v3, 32, v3
	v_ashrrev_i16_sdwa v4, v244, sext(v4) dst_sel:DWORD dst_unused:UNUSED_PAD src0_sel:DWORD src1_sel:BYTE_0
	v_add_u32_sdwa v3, v3, sext(v4) dst_sel:DWORD dst_unused:UNUSED_PAD src0_sel:DWORD src1_sel:WORD_0
	v_add_lshl_u32 v4, v7, v5, 13
	v_add_u32_e32 v2, 0x2000, v2
	v_lshl_add_u32 v141, v3, 1, v4
	v_ashrrev_i32_e32 v3, 31, v2
	v_lshrrev_b32_e32 v3, 22, v3
	v_add_u32_e32 v3, v2, v3
	v_ashrrev_i32_e32 v3, 10, v3
	v_mul_i32_i24_e32 v4, 0x400, v3
	v_sub_u32_e32 v2, v2, v4
	v_lshrrev_b32_e32 v4, 4, v2
	v_bitop3_b32 v2, v4, v2, 32 bitop3:0x6c
	v_ashrrev_i32_e32 v5, 31, v2
	v_lshrrev_b32_e32 v5, 26, v5
	v_add_u32_e32 v5, v2, v5
	v_lshrrev_b32_e32 v6, 6, v5
	v_and_b32_e32 v5, 0xc0, v5
	v_lshlrev_b32_e32 v4, 3, v3
	v_lshlrev_b32_e32 v3, 5, v3
	v_sub_u32_e32 v2, v2, v5
	v_and_b32_e32 v4, 0x7fff0, v4
	v_and_b32_e32 v3, 32, v3
	v_ashrrev_i16_sdwa v2, v244, sext(v2) dst_sel:DWORD dst_unused:UNUSED_PAD src0_sel:DWORD src1_sel:BYTE_0
	v_add_u32_sdwa v2, v3, sext(v2) dst_sel:DWORD dst_unused:UNUSED_PAD src0_sel:DWORD src1_sel:WORD_0
	v_add_lshl_u32 v3, v6, v4, 13
	v_lshl_add_u32 v142, v2, 1, v3
	v_and_b32_e32 v3, 15, v0
	v_lshlrev_b32_e32 v5, 2, v0
	v_and_b32_e32 v2, 48, v0
	v_lshlrev_b32_e32 v3, 6, v3
	v_and_b32_e32 v5, 32, v5
	v_or_b32_e32 v4, v3, v2
	v_bitop3_b32 v3, v3, v5, v2 bitop3:0x36
	v_lshlrev_b32_e32 v6, 6, v128
	s_movk_i32 s1, 0x3000
	v_and_or_b32 v3, v6, s1, v3
	v_lshlrev_b32_e32 v0, 6, v0
	s_movk_i32 s1, 0x3c0
	v_lshlrev_b32_e32 v1, 13, v1
	v_and_or_b32 v0, v0, s1, v2
	v_bitop3_b32 v0, v1, v0, v5 bitop3:0xf6
	v_or_b32_e32 v6, 0x400, v3
	v_or_b32_e32 v7, 0x800, v3
	v_or_b32_e32 v8, 0xc00, v3
	v_or_b32_e32 v132, 0x800, v0
	v_or_b32_e32 v131, 0x1000, v0
	v_or_b32_e32 v130, 0x1800, v0
	v_mov_b32_e32 v0, 0
	v_bitop3_b32 v129, v4, v1, v5 bitop3:0xde
	s_mov_b32 s1, -2
	s_mov_b32 s3, 0
	v_or_b32_e32 v147, 0x10000, v3
	v_or_b32_e32 v148, 0x10000, v6
	v_or_b32_e32 v149, 0x10000, v7
	v_or_b32_e32 v150, 0x10000, v8
	v_or_b32_e32 v143, 0x14000, v3
	v_or_b32_e32 v144, 0x14000, v6
	v_or_b32_e32 v145, 0x14000, v7
	v_or_b32_e32 v146, 0x14000, v8
	v_or_b32_e32 v137, 0x18000, v3
	v_or_b32_e32 v138, 0x18000, v6
	v_or_b32_e32 v139, 0x18000, v7
	v_or_b32_e32 v140, 0x18000, v8
	v_or_b32_e32 v133, 0x1c000, v3
	v_or_b32_e32 v134, 0x1c000, v6
	v_or_b32_e32 v135, 0x1c000, v7
	v_or_b32_e32 v136, 0x1c000, v8
	s_barrier
	s_barrier
	ds_read_b128 v[152:155], v147
	ds_read_b128 v[156:159], v148
	ds_read_b128 v[160:163], v149
	ds_read_b128 v[164:167], v150
	s_add_i32 s4, s82, s3
	s_add_i32 s5, s4, 0x80
	s_mov_b32 m0, s31
	ds_read_b128 v[168:171], v129
	ds_read_b128 v[172:175], v129 offset:1024
	ds_read_b128 v[176:179], v132
	ds_read_b128 v[180:183], v132 offset:1024
	ds_read_b128 v[184:187], v131
	ds_read_b128 v[188:191], v131 offset:1024
	ds_read_b128 v[192:195], v130
	ds_read_b128 v[196:199], v130 offset:1024
	buffer_load_dwordx4 v141, s[8:11], s5 offen lds
	s_mov_b32 m0, s58
	s_nop 0
	buffer_load_dwordx4 v142, s[8:11], s5 offen lds
	s_waitcnt lgkmcnt(8)
	s_barrier
	s_waitcnt lgkmcnt(0)
	v_mfma_f32_16x16x32_bf16 v[124:127], v[152:155], v[168:171], 0
	v_mfma_f32_16x16x32_bf16 v[124:127], v[156:159], v[172:175], v[124:127]
	v_mfma_f32_16x16x32_bf16 v[120:123], v[164:167], v[172:175], 0
	v_mfma_f32_16x16x32_bf16 v[120:123], v[160:163], v[168:171], v[120:123]
	v_mfma_f32_16x16x32_bf16 v[112:115], v[160:163], v[176:179], 0
	v_mfma_f32_16x16x32_bf16 v[112:115], v[164:167], v[180:183], v[112:115]
	v_mfma_f32_16x16x32_bf16 v[116:119], v[156:159], v[180:183], 0
	v_mfma_f32_16x16x32_bf16 v[116:119], v[152:155], v[176:179], v[116:119]
	v_mfma_f32_16x16x32_bf16 v[108:111], v[152:155], v[184:187], 0
	v_mfma_f32_16x16x32_bf16 v[108:111], v[156:159], v[188:191], v[108:111]
	v_mfma_f32_16x16x32_bf16 v[104:107], v[164:167], v[188:191], 0
	v_mfma_f32_16x16x32_bf16 v[104:107], v[160:163], v[184:187], v[104:107]
	v_mfma_f32_16x16x32_bf16 v[96:99], v[160:163], v[192:195], 0
	v_mfma_f32_16x16x32_bf16 v[96:99], v[164:167], v[196:199], v[96:99]
	v_mfma_f32_16x16x32_bf16 v[100:103], v[156:159], v[196:199], 0
	v_mfma_f32_16x16x32_bf16 v[100:103], v[152:155], v[192:195], v[100:103]
	s_barrier
	s_add_i32 s5, s84, s3
	s_add_i32 s6, s5, 0x100
	s_mov_b32 s14, s10
	s_mov_b32 s15, s11
	s_mov_b32 m0, s34
	ds_read_b128 v[200:203], v143
	ds_read_b128 v[204:207], v144
	ds_read_b128 v[208:211], v145
	ds_read_b128 v[212:215], v146
	buffer_load_dwordx4 v141, s[12:15], s6 offen lds
	s_mov_b32 m0, s43
	s_nop 0
	buffer_load_dwordx4 v142, s[12:15], s6 offen lds
	s_barrier
; #define STAGE(P, RS, SOFF, OFF, kt) do { const int _so = (SOFF) + (kt) * (BK * 2); \
;     _Pragma("unroll") for (int _i = 0; _i < 2; ++_i) { \
;       __builtin_amdgcn_raw_ptr_buffer_load_lds(RS, (__attribute__((address_space(3))) void*)((P) + wave * 1024 + _i * 8192), 16, OFF[_i], _so, 0, 0); } } while (0)
; #define LDA(dst, b, h) _Pragma("unroll") for (int m = 0; m < 4; ++m) _Pragma("unroll") for (int k = 0; k < 2; ++k) \
;     dst[m][k] = *reinterpret_cast<const bf16x8*>(SA(b, h) + lds_byte(wr * 64 + m * 16 + fr, k * 32 + fq * 8))
; #define LDB(dst, b, h) _Pragma("unroll") for (int n = 0; n < 2; ++n) _Pragma("unroll") for (int k = 0; k < 2; ++k) \
;     dst[n][k] = *reinterpret_cast<const bf16x8*>(SB(b, h) + lds_byte(wc * 32 + n * 16 + fr, k * 32 + fq * 8))
; #define WAIT_V(n) asm volatile("s_waitcnt vmcnt(" #n ")" ::: "memory")
; #define WAIT_L(n) asm volatile("s_waitcnt lgkmcnt(" #n ")" ::: "memory")
; #define BAR __builtin_amdgcn_s_barrier()
; #define SCHED __builtin_amdgcn_sched_barrier(0)
;     ...
;       BAR; WAIT_L(0); MMA(0, 1, At, B1); BAR;
;       LDA(At, 0, 1); STAGE(SA(0, 0), rsA, sA0, offA, t + 2);
;       BAR; WAIT_L(0); MMA(1, 0, At, B0); BAR; SCHED;
;       STAGE(SB(0, 1), rsB, sB1, offB, t + 2);
;       WAIT_V(6); BAR; MMA(1, 1, At, B1); BAR;
;       LDB(B0, 1, 0); SCHED; LDA(At, 1, 0); STAGE(SA(0, 1), rsA, sA1, offA, t + 2);
;       WAIT_L(8); BAR; WAIT_L(0); MMA(0, 0, At, B0); BAR; SCHED;
	s_waitcnt lgkmcnt(0)
	v_mfma_f32_16x16x32_bf16 v[92:95], v[200:203], v[168:171], 0
	v_mfma_f32_16x16x32_bf16 v[92:95], v[204:207], v[172:175], v[92:95]
	v_mfma_f32_16x16x32_bf16 v[88:91], v[212:215], v[172:175], 0
	v_mfma_f32_16x16x32_bf16 v[88:91], v[208:211], v[168:171], v[88:91]
	v_mfma_f32_16x16x32_bf16 v[68:71], v[208:211], v[176:179], 0
	v_mfma_f32_16x16x32_bf16 v[68:71], v[212:215], v[180:183], v[68:71]
	v_mfma_f32_16x16x32_bf16 v[80:83], v[204:207], v[180:183], 0
	v_mfma_f32_16x16x32_bf16 v[80:83], v[200:203], v[176:179], v[80:83]
	v_mfma_f32_16x16x32_bf16 v[60:63], v[200:203], v[184:187], 0
	v_mfma_f32_16x16x32_bf16 v[60:63], v[204:207], v[188:191], v[60:63]
	v_mfma_f32_16x16x32_bf16 v[56:59], v[212:215], v[188:191], 0
	v_mfma_f32_16x16x32_bf16 v[56:59], v[208:211], v[184:187], v[56:59]
	v_mfma_f32_16x16x32_bf16 v[48:51], v[208:211], v[192:195], 0
	v_mfma_f32_16x16x32_bf16 v[48:51], v[212:215], v[196:199], v[48:51]
	v_mfma_f32_16x16x32_bf16 v[52:55], v[204:207], v[196:199], 0
	v_mfma_f32_16x16x32_bf16 v[52:55], v[200:203], v[192:195], v[52:55]
	s_barrier
	s_add_i32 s6, s83, s3
	s_add_i32 s7, s6, 0x100
	s_mov_b32 m0, s30
	ds_read_b128 v[168:171], v129 offset:16384
	ds_read_b128 v[172:175], v129 offset:17408
	ds_read_b128 v[176:179], v132 offset:16384
	ds_read_b128 v[180:183], v132 offset:17408
	ds_read_b128 v[184:187], v131 offset:16384
	ds_read_b128 v[188:191], v131 offset:17408
	ds_read_b128 v[192:195], v130 offset:16384
	ds_read_b128 v[196:199], v130 offset:17408
	buffer_load_dwordx4 v141, s[8:11], s7 offen lds
	s_mov_b32 m0, s44
	s_nop 0
	buffer_load_dwordx4 v142, s[8:11], s7 offen lds
	s_barrier
	s_waitcnt lgkmcnt(0)
	v_mfma_f32_16x16x32_bf16 v[44:47], v[152:155], v[168:171], 0
	v_mfma_f32_16x16x32_bf16 v[44:47], v[156:159], v[172:175], v[44:47]
	v_mfma_f32_16x16x32_bf16 v[40:43], v[164:167], v[172:175], 0
	v_mfma_f32_16x16x32_bf16 v[40:43], v[160:163], v[168:171], v[40:43]
	v_mfma_f32_16x16x32_bf16 v[32:35], v[160:163], v[176:179], 0
	v_mfma_f32_16x16x32_bf16 v[32:35], v[164:167], v[180:183], v[32:35]
	v_mfma_f32_16x16x32_bf16 v[36:39], v[156:159], v[180:183], 0
	v_mfma_f32_16x16x32_bf16 v[36:39], v[152:155], v[176:179], v[36:39]
	v_mfma_f32_16x16x32_bf16 v[28:31], v[152:155], v[184:187], 0
	v_mfma_f32_16x16x32_bf16 v[28:31], v[156:159], v[188:191], v[28:31]
	v_mfma_f32_16x16x32_bf16 v[24:27], v[164:167], v[188:191], 0
	v_mfma_f32_16x16x32_bf16 v[24:27], v[160:163], v[184:187], v[24:27]
	v_mfma_f32_16x16x32_bf16 v[16:19], v[160:163], v[192:195], 0
	v_mfma_f32_16x16x32_bf16 v[16:19], v[164:167], v[196:199], v[16:19]
	v_mfma_f32_16x16x32_bf16 v[20:23], v[156:159], v[196:199], 0
	v_mfma_f32_16x16x32_bf16 v[20:23], v[152:155], v[192:195], v[20:23]
	s_barrier
	s_add_i32 s7, s85, s3
	s_add_i32 s19, s7, 0x100
	s_mov_b32 m0, s35
	s_nop 0
	buffer_load_dwordx4 v141, s[12:15], s19 offen lds
	s_mov_b32 m0, s45
	s_nop 0
	buffer_load_dwordx4 v142, s[12:15], s19 offen lds
	s_waitcnt vmcnt(6)
	s_barrier
	v_mfma_f32_16x16x32_bf16 v[12:15], v[200:203], v[168:171], 0
	v_mfma_f32_16x16x32_bf16 v[12:15], v[204:207], v[172:175], v[12:15]
	v_mfma_f32_16x16x32_bf16 v[8:11], v[212:215], v[172:175], 0
	v_mfma_f32_16x16x32_bf16 v[8:11], v[208:211], v[168:171], v[8:11]
	v_mfma_f32_16x16x32_bf16 v[0:3], v[208:211], v[176:179], 0
	v_mfma_f32_16x16x32_bf16 v[0:3], v[212:215], v[180:183], v[0:3]
	v_mfma_f32_16x16x32_bf16 v[4:7], v[204:207], v[180:183], 0
	v_mfma_f32_16x16x32_bf16 v[4:7], v[200:203], v[176:179], v[4:7]
	v_mfma_f32_16x16x32_bf16 v[64:67], v[200:203], v[184:187], 0
	v_mfma_f32_16x16x32_bf16 v[64:67], v[204:207], v[188:191], v[64:67]
	v_mfma_f32_16x16x32_bf16 v[72:75], v[212:215], v[188:191], 0
	v_mfma_f32_16x16x32_bf16 v[72:75], v[208:211], v[184:187], v[72:75]
	v_mfma_f32_16x16x32_bf16 v[84:87], v[208:211], v[192:195], 0
	v_mfma_f32_16x16x32_bf16 v[84:87], v[212:215], v[196:199], v[84:87]
	v_mfma_f32_16x16x32_bf16 v[76:79], v[204:207], v[196:199], 0
	v_mfma_f32_16x16x32_bf16 v[76:79], v[200:203], v[192:195], v[76:79]
	s_barrier
	ds_read_b128 v[152:155], v137
	ds_read_b128 v[156:159], v138
	ds_read_b128 v[160:163], v139
	ds_read_b128 v[164:167], v140
	s_addk_i32 s4, 0x100
	s_mov_b32 m0, s36
	ds_read_b128 v[168:171], v129 offset:32768
	ds_read_b128 v[172:175], v129 offset:33792
	ds_read_b128 v[176:179], v132 offset:32768
	ds_read_b128 v[180:183], v132 offset:33792
	ds_read_b128 v[184:187], v131 offset:32768
	ds_read_b128 v[188:191], v131 offset:33792
	ds_read_b128 v[192:195], v130 offset:32768
	ds_read_b128 v[196:199], v130 offset:33792
	buffer_load_dwordx4 v141, s[8:11], s4 offen lds
	s_mov_b32 m0, s48
	s_nop 0
	buffer_load_dwordx4 v142, s[8:11], s4 offen lds
	s_waitcnt lgkmcnt(8)
	s_barrier
; #define STAGE(P, RS, SOFF, OFF, kt) do { const int _so = (SOFF) + (kt) * (BK * 2); \
;     _Pragma("unroll") for (int _i = 0; _i < 2; ++_i) { \
;       __builtin_amdgcn_raw_ptr_buffer_load_lds(RS, (__attribute__((address_space(3))) void*)((P) + wave * 1024 + _i * 8192), 16, OFF[_i], _so, 0, 0); } } while (0)
; #define LDA(dst, b, h) _Pragma("unroll") for (int m = 0; m < 4; ++m) _Pragma("unroll") for (int k = 0; k < 2; ++k) \
;     dst[m][k] = *reinterpret_cast<const bf16x8*>(SA(b, h) + lds_byte(wr * 64 + m * 16 + fr, k * 32 + fq * 8))
; #define LDB(dst, b, h) _Pragma("unroll") for (int n = 0; n < 2; ++n) _Pragma("unroll") for (int k = 0; k < 2; ++k) \
;     dst[n][k] = *reinterpret_cast<const bf16x8*>(SB(b, h) + lds_byte(wc * 32 + n * 16 + fr, k * 32 + fq * 8))
; #define WAIT_L(n) asm volatile("s_waitcnt lgkmcnt(" #n ")" ::: "memory")
; #define BAR __builtin_amdgcn_s_barrier()
; #define SCHED __builtin_amdgcn_sched_barrier(0)
;     ...
;       WAIT_L(8); BAR; WAIT_L(0); MMA(0, 0, At, B0); BAR; SCHED;
;       LDB(B1, 1, 1); STAGE(SB(1, 0), rsB, sB0, offB, t + 3);
;       BAR; WAIT_L(0); MMA(0, 1, At, B1); BAR;
;       LDA(At, 1, 1); STAGE(SA(1, 0), rsA, sA0, offA, t + 3);
;       BAR; WAIT_L(0); MMA(1, 0, At, B0); BAR; SCHED;
;       STAGE(SB(1, 1), rsB, sB1, offB, t + 3);
	s_waitcnt lgkmcnt(0)
	v_mfma_f32_16x16x32_bf16 v[124:127], v[152:155], v[168:171], v[124:127]
	v_mfma_f32_16x16x32_bf16 v[124:127], v[156:159], v[172:175], v[124:127]
	v_mfma_f32_16x16x32_bf16 v[120:123], v[164:167], v[172:175], v[120:123]
	v_mfma_f32_16x16x32_bf16 v[120:123], v[160:163], v[168:171], v[120:123]
	v_mfma_f32_16x16x32_bf16 v[112:115], v[160:163], v[176:179], v[112:115]
	v_mfma_f32_16x16x32_bf16 v[112:115], v[164:167], v[180:183], v[112:115]
	v_mfma_f32_16x16x32_bf16 v[116:119], v[156:159], v[180:183], v[116:119]
	v_mfma_f32_16x16x32_bf16 v[116:119], v[152:155], v[176:179], v[116:119]
	v_mfma_f32_16x16x32_bf16 v[108:111], v[152:155], v[184:187], v[108:111]
	v_mfma_f32_16x16x32_bf16 v[108:111], v[156:159], v[188:191], v[108:111]
	v_mfma_f32_16x16x32_bf16 v[104:107], v[164:167], v[188:191], v[104:107]
	v_mfma_f32_16x16x32_bf16 v[104:107], v[160:163], v[184:187], v[104:107]
	v_mfma_f32_16x16x32_bf16 v[96:99], v[160:163], v[192:195], v[96:99]
	v_mfma_f32_16x16x32_bf16 v[96:99], v[164:167], v[196:199], v[96:99]
	v_mfma_f32_16x16x32_bf16 v[100:103], v[156:159], v[196:199], v[100:103]
	v_mfma_f32_16x16x32_bf16 v[100:103], v[152:155], v[192:195], v[100:103]
	s_barrier
	s_addk_i32 s5, 0x180
	s_mov_b32 m0, s37
	ds_read_b128 v[200:203], v133
	ds_read_b128 v[204:207], v134
	ds_read_b128 v[208:211], v135
	ds_read_b128 v[212:215], v136
	buffer_load_dwordx4 v141, s[12:15], s5 offen lds
	s_mov_b32 m0, s49
	s_nop 0
	buffer_load_dwordx4 v142, s[12:15], s5 offen lds
	s_barrier
	s_waitcnt lgkmcnt(0)
	v_mfma_f32_16x16x32_bf16 v[92:95], v[200:203], v[168:171], v[92:95]
	v_mfma_f32_16x16x32_bf16 v[92:95], v[204:207], v[172:175], v[92:95]
	v_mfma_f32_16x16x32_bf16 v[88:91], v[212:215], v[172:175], v[88:91]
	v_mfma_f32_16x16x32_bf16 v[88:91], v[208:211], v[168:171], v[88:91]
	v_mfma_f32_16x16x32_bf16 v[68:71], v[208:211], v[176:179], v[68:71]
	v_mfma_f32_16x16x32_bf16 v[68:71], v[212:215], v[180:183], v[68:71]
	v_mfma_f32_16x16x32_bf16 v[80:83], v[204:207], v[180:183], v[80:83]
	v_mfma_f32_16x16x32_bf16 v[80:83], v[200:203], v[176:179], v[80:83]
	v_mfma_f32_16x16x32_bf16 v[60:63], v[200:203], v[184:187], v[60:63]
	v_mfma_f32_16x16x32_bf16 v[60:63], v[204:207], v[188:191], v[60:63]
	v_mfma_f32_16x16x32_bf16 v[56:59], v[212:215], v[188:191], v[56:59]
	v_mfma_f32_16x16x32_bf16 v[56:59], v[208:211], v[184:187], v[56:59]
	v_mfma_f32_16x16x32_bf16 v[48:51], v[208:211], v[192:195], v[48:51]
	v_mfma_f32_16x16x32_bf16 v[48:51], v[212:215], v[196:199], v[48:51]
	v_mfma_f32_16x16x32_bf16 v[52:55], v[204:207], v[196:199], v[52:55]
	v_mfma_f32_16x16x32_bf16 v[52:55], v[200:203], v[192:195], v[52:55]
	s_barrier
	s_addk_i32 s6, 0x180
	s_mov_b32 m0, s38
	ds_read_b128 v[168:171], v129 offset:49152
	ds_read_b128 v[172:175], v129 offset:50176
	ds_read_b128 v[176:179], v132 offset:49152
	ds_read_b128 v[180:183], v132 offset:50176
	ds_read_b128 v[184:187], v131 offset:49152
	ds_read_b128 v[188:191], v131 offset:50176
	ds_read_b128 v[192:195], v130 offset:49152
	ds_read_b128 v[196:199], v130 offset:50176
	buffer_load_dwordx4 v141, s[8:11], s6 offen lds
	s_mov_b32 m0, s54
	s_nop 0
	buffer_load_dwordx4 v142, s[8:11], s6 offen lds
	s_barrier
	s_waitcnt lgkmcnt(0)
	v_mfma_f32_16x16x32_bf16 v[44:47], v[152:155], v[168:171], v[44:47]
	v_mfma_f32_16x16x32_bf16 v[44:47], v[156:159], v[172:175], v[44:47]
	v_mfma_f32_16x16x32_bf16 v[40:43], v[164:167], v[172:175], v[40:43]
	v_mfma_f32_16x16x32_bf16 v[40:43], v[160:163], v[168:171], v[40:43]
	v_mfma_f32_16x16x32_bf16 v[32:35], v[160:163], v[176:179], v[32:35]
	v_mfma_f32_16x16x32_bf16 v[32:35], v[164:167], v[180:183], v[32:35]
	v_mfma_f32_16x16x32_bf16 v[36:39], v[156:159], v[180:183], v[36:39]
	v_mfma_f32_16x16x32_bf16 v[36:39], v[152:155], v[176:179], v[36:39]
	v_mfma_f32_16x16x32_bf16 v[28:31], v[152:155], v[184:187], v[28:31]
	v_mfma_f32_16x16x32_bf16 v[28:31], v[156:159], v[188:191], v[28:31]
	v_mfma_f32_16x16x32_bf16 v[24:27], v[164:167], v[188:191], v[24:27]
	v_mfma_f32_16x16x32_bf16 v[24:27], v[160:163], v[184:187], v[24:27]
	v_mfma_f32_16x16x32_bf16 v[16:19], v[160:163], v[192:195], v[16:19]
	v_mfma_f32_16x16x32_bf16 v[16:19], v[164:167], v[196:199], v[16:19]
	v_mfma_f32_16x16x32_bf16 v[20:23], v[156:159], v[196:199], v[20:23]
	v_mfma_f32_16x16x32_bf16 v[20:23], v[152:155], v[192:195], v[20:23]
	s_barrier
	s_addk_i32 s7, 0x180
	s_mov_b32 m0, s39
	s_nop 0
	buffer_load_dwordx4 v141, s[12:15], s7 offen lds
	s_mov_b32 m0, s55
	s_nop 0
	buffer_load_dwordx4 v142, s[12:15], s7 offen lds
	s_add_i32 s1, s1, 2
	s_addk_i32 s3, 0x100
	s_cmp_gt_u32 s1, 59
	s_cbranch_scc0 .LBB0_148
	s_branch .Lmy_post_148

; #define STAGE(P, RS, SOFF, OFF, kt) do { const int _so = (SOFF) + (kt) * (BK * 2); \
;     _Pragma("unroll") for (int _i = 0; _i < 2; ++_i) { \
;       __builtin_amdgcn_raw_ptr_buffer_load_lds(RS, (__attribute__((address_space(3))) void*)((P) + wave * 1024 + _i * 8192), 16, OFF[_i], _so, 0, 0); } } while (0)
; #define LDA(dst, b, h) _Pragma("unroll") for (int m = 0; m < 4; ++m) _Pragma("unroll") for (int k = 0; k < 2; ++k) \
;     dst[m][k] = *reinterpret_cast<const bf16x8*>(SA(b, h) + lds_byte(wr * 64 + m * 16 + fr, k * 32 + fq * 8))
; #define LDB(dst, b, h) _Pragma("unroll") for (int n = 0; n < 2; ++n) _Pragma("unroll") for (int k = 0; k < 2; ++k) \
;     dst[n][k] = *reinterpret_cast<const bf16x8*>(SB(b, h) + lds_byte(wc * 32 + n * 16 + fr, k * 32 + fq * 8))
; #define WAIT_V(n) asm volatile("s_waitcnt vmcnt(" #n ")" ::: "memory")
; #define WAIT_L(n) asm volatile("s_waitcnt lgkmcnt(" #n ")" ::: "memory")
; #define BAR __builtin_amdgcn_s_barrier()
;     ...
;       WAIT_V(6); BAR; MMA(1, 1, At, B1); BAR;
;     }
;     { LDB(B0, 0, 0); LDA(At, 0, 0); STAGE(SA(1, 1), rsA, sA1, offA, nt - 1);
;       BAR; WAIT_L(0); MMA(0, 0, At, B0); BAR;
;       LDB(B1, 0, 1); BAR; WAIT_L(0); MMA(0, 1, At, B1); BAR;
;       LDA(At, 0, 1); WAIT_V(4); BAR; WAIT_L(0); MMA(1, 0, At, B0); MMA(1, 1, At, B1); BAR; }
.Lmy_post_148:
	s_waitcnt vmcnt(6)
	s_barrier
	v_mfma_f32_16x16x32_bf16 v[12:15], v[200:203], v[168:171], v[12:15]
	v_mfma_f32_16x16x32_bf16 v[12:15], v[204:207], v[172:175], v[12:15]
	v_mfma_f32_16x16x32_bf16 v[8:11], v[212:215], v[172:175], v[8:11]
	v_mfma_f32_16x16x32_bf16 v[8:11], v[208:211], v[168:171], v[8:11]
	v_mfma_f32_16x16x32_bf16 v[0:3], v[208:211], v[176:179], v[0:3]
	v_mfma_f32_16x16x32_bf16 v[0:3], v[212:215], v[180:183], v[0:3]
	v_mfma_f32_16x16x32_bf16 v[4:7], v[204:207], v[180:183], v[4:7]
	v_mfma_f32_16x16x32_bf16 v[4:7], v[200:203], v[176:179], v[4:7]
	v_mfma_f32_16x16x32_bf16 v[64:67], v[200:203], v[184:187], v[64:67]
	v_mfma_f32_16x16x32_bf16 v[64:67], v[204:207], v[188:191], v[64:67]
	v_mfma_f32_16x16x32_bf16 v[72:75], v[212:215], v[188:191], v[72:75]
	v_mfma_f32_16x16x32_bf16 v[72:75], v[208:211], v[184:187], v[72:75]
	v_mfma_f32_16x16x32_bf16 v[84:87], v[208:211], v[192:195], v[84:87]
	v_mfma_f32_16x16x32_bf16 v[84:87], v[212:215], v[196:199], v[84:87]
	v_mfma_f32_16x16x32_bf16 v[76:79], v[204:207], v[196:199], v[76:79]
	v_mfma_f32_16x16x32_bf16 v[76:79], v[200:203], v[192:195], v[76:79]
	s_barrier
	s_add_i32 s1, s82, 0x1f80
	s_mov_b32 m0, s31
	ds_read_b128 v[152:155], v147
	ds_read_b128 v[156:159], v148
	ds_read_b128 v[160:163], v149
	ds_read_b128 v[148:151], v150
	ds_read_b128 v[164:167], v129
	ds_read_b128 v[168:171], v129 offset:1024
	ds_read_b128 v[172:175], v132
	ds_read_b128 v[176:179], v132 offset:1024
	ds_read_b128 v[180:183], v131
	ds_read_b128 v[184:187], v131 offset:1024
	ds_read_b128 v[188:191], v130
	ds_read_b128 v[192:195], v130 offset:1024
	buffer_load_dwordx4 v141, s[8:11], s1 offen lds
	s_mov_b32 m0, s58
	s_nop 0
	buffer_load_dwordx4 v142, s[8:11], s1 offen lds
	s_barrier
	s_waitcnt lgkmcnt(0)
	v_mfma_f32_16x16x32_bf16 v[124:127], v[152:155], v[164:167], v[124:127]
	v_mfma_f32_16x16x32_bf16 v[124:127], v[156:159], v[168:171], v[124:127]
	v_mfma_f32_16x16x32_bf16 v[120:123], v[148:151], v[168:171], v[120:123]
	v_mfma_f32_16x16x32_bf16 v[120:123], v[160:163], v[164:167], v[120:123]
	v_mfma_f32_16x16x32_bf16 v[112:115], v[160:163], v[172:175], v[112:115]
	v_mfma_f32_16x16x32_bf16 v[112:115], v[148:151], v[176:179], v[112:115]
	v_mfma_f32_16x16x32_bf16 v[116:119], v[156:159], v[176:179], v[116:119]
	v_mfma_f32_16x16x32_bf16 v[116:119], v[152:155], v[172:175], v[116:119]
	v_mfma_f32_16x16x32_bf16 v[108:111], v[152:155], v[180:183], v[108:111]
	v_mfma_f32_16x16x32_bf16 v[108:111], v[156:159], v[184:187], v[108:111]
	v_mfma_f32_16x16x32_bf16 v[104:107], v[148:151], v[184:187], v[104:107]
	v_mfma_f32_16x16x32_bf16 v[104:107], v[160:163], v[180:183], v[104:107]
	v_mfma_f32_16x16x32_bf16 v[96:99], v[160:163], v[188:191], v[96:99]
	v_mfma_f32_16x16x32_bf16 v[96:99], v[148:151], v[192:195], v[96:99]
	v_mfma_f32_16x16x32_bf16 v[100:103], v[156:159], v[192:195], v[100:103]
	v_mfma_f32_16x16x32_bf16 v[100:103], v[152:155], v[188:191], v[100:103]
	s_barrier
	ds_read_b128 v[196:199], v143
	ds_read_b128 v[200:203], v144
	ds_read_b128 v[142:145], v145
	ds_read_b128 v[204:207], v146
	s_barrier
	s_waitcnt lgkmcnt(0)
	v_mfma_f32_16x16x32_bf16 v[88:91], v[142:145], v[164:167], v[88:91]
	v_mfma_f32_16x16x32_bf16 v[80:83], v[196:199], v[172:175], v[80:83]
	v_mfma_f32_16x16x32_bf16 v[60:63], v[196:199], v[180:183], v[60:63]
	v_mfma_f32_16x16x32_bf16 v[56:59], v[142:145], v[180:183], v[56:59]
	v_mfma_f32_16x16x32_bf16 v[52:55], v[196:199], v[188:191], v[52:55]
	v_mfma_f32_16x16x32_bf16 v[48:51], v[142:145], v[188:191], v[48:51]
	v_mfma_f32_16x16x32_bf16 v[92:95], v[196:199], v[164:167], v[92:95]
	v_mfma_f32_16x16x32_bf16 v[68:71], v[142:145], v[172:175], v[68:71]
	v_mfma_f32_16x16x32_bf16 v[88:91], v[204:207], v[168:171], v[88:91]
	v_mfma_f32_16x16x32_bf16 v[80:83], v[200:203], v[176:179], v[80:83]
	v_mfma_f32_16x16x32_bf16 v[60:63], v[200:203], v[184:187], v[60:63]
	v_mfma_f32_16x16x32_bf16 v[56:59], v[204:207], v[184:187], v[56:59]
	v_mfma_f32_16x16x32_bf16 v[52:55], v[200:203], v[192:195], v[52:55]
	v_mfma_f32_16x16x32_bf16 v[48:51], v[204:207], v[192:195], v[48:51]
	v_mfma_f32_16x16x32_bf16 v[164:167], v[200:203], v[168:171], v[92:95]
	v_mfma_f32_16x16x32_bf16 v[168:171], v[204:207], v[176:179], v[68:71]
	s_barrier
	s_nop 0
	ds_read_b128 v[68:71], v129 offset:16384
	ds_read_b128 v[92:95], v129 offset:17408
	ds_read_b128 v[172:175], v132 offset:16384
	ds_read_b128 v[176:179], v132 offset:17408
	ds_read_b128 v[180:183], v131 offset:16384
	ds_read_b128 v[184:187], v131 offset:17408
	ds_read_b128 v[188:191], v130 offset:16384
	ds_read_b128 v[192:195], v130 offset:17408
	s_waitcnt vmcnt(4)
	s_barrier
; #define LDA(dst, b, h) _Pragma("unroll") for (int m = 0; m < 4; ++m) _Pragma("unroll") for (int k = 0; k < 2; ++k) \
;     dst[m][k] = *reinterpret_cast<const bf16x8*>(SA(b, h) + lds_byte(wr * 64 + m * 16 + fr, k * 32 + fq * 8))
; #define LDB(dst, b, h) _Pragma("unroll") for (int n = 0; n < 2; ++n) _Pragma("unroll") for (int k = 0; k < 2; ++k) \
;     dst[n][k] = *reinterpret_cast<const bf16x8*>(SB(b, h) + lds_byte(wc * 32 + n * 16 + fr, k * 32 + fq * 8))
; #define WAIT_V(n) asm volatile("s_waitcnt vmcnt(" #n ")" ::: "memory")
; #define WAIT_L(n) asm volatile("s_waitcnt lgkmcnt(" #n ")" ::: "memory")
; #define BAR __builtin_amdgcn_s_barrier()
;     ...
;       LDA(At, 0, 1); WAIT_V(4); BAR; WAIT_L(0); MMA(1, 0, At, B0); MMA(1, 1, At, B1); BAR; }
;     { LDB(B0, 1, 0); LDA(At, 1, 0); WAIT_V(2); BAR; WAIT_L(0); MMA(0, 0, At, B0); BAR;
	s_waitcnt lgkmcnt(0)
	v_mfma_f32_16x16x32_bf16 v[44:47], v[152:155], v[68:71], v[44:47]
	v_mfma_f32_16x16x32_bf16 v[40:43], v[160:163], v[68:71], v[40:43]
	v_mfma_f32_16x16x32_bf16 v[36:39], v[152:155], v[172:175], v[36:39]
	v_mfma_f32_16x16x32_bf16 v[32:35], v[160:163], v[172:175], v[32:35]
	v_mfma_f32_16x16x32_bf16 v[28:31], v[152:155], v[180:183], v[28:31]
	v_mfma_f32_16x16x32_bf16 v[24:27], v[160:163], v[180:183], v[24:27]
	v_mfma_f32_16x16x32_bf16 v[20:23], v[152:155], v[188:191], v[20:23]
	v_mfma_f32_16x16x32_bf16 v[16:19], v[160:163], v[188:191], v[16:19]
	v_mfma_f32_16x16x32_bf16 v[44:47], v[156:159], v[92:95], v[44:47]
	v_mfma_f32_16x16x32_bf16 v[40:43], v[148:151], v[92:95], v[40:43]
	v_mfma_f32_16x16x32_bf16 v[36:39], v[156:159], v[176:179], v[36:39]
	v_mfma_f32_16x16x32_bf16 v[32:35], v[148:151], v[176:179], v[32:35]
	v_mfma_f32_16x16x32_bf16 v[28:31], v[156:159], v[184:187], v[28:31]
	v_mfma_f32_16x16x32_bf16 v[24:27], v[148:151], v[184:187], v[24:27]
	v_mfma_f32_16x16x32_bf16 v[20:23], v[156:159], v[192:195], v[20:23]
	v_mfma_f32_16x16x32_bf16 v[16:19], v[148:151], v[192:195], v[16:19]
	v_mfma_f32_16x16x32_bf16 v[8:11], v[142:145], v[68:71], v[8:11]
	v_mfma_f32_16x16x32_bf16 v[0:3], v[142:145], v[172:175], v[0:3]
	v_mfma_f32_16x16x32_bf16 v[12:15], v[196:199], v[68:71], v[12:15]
	v_mfma_f32_16x16x32_bf16 v[4:7], v[196:199], v[172:175], v[4:7]
	v_mfma_f32_16x16x32_bf16 v[64:67], v[196:199], v[180:183], v[64:67]
	v_mfma_f32_16x16x32_bf16 v[68:71], v[142:145], v[180:183], v[72:75]
	v_mfma_f32_16x16x32_bf16 v[72:75], v[196:199], v[188:191], v[76:79]
	v_mfma_f32_16x16x32_bf16 v[76:79], v[142:145], v[188:191], v[84:87]
	v_mfma_f32_16x16x32_bf16 v[8:11], v[204:207], v[92:95], v[8:11]
	v_mfma_f32_16x16x32_bf16 v[0:3], v[204:207], v[176:179], v[0:3]
	v_mfma_f32_16x16x32_bf16 v[160:163], v[200:203], v[92:95], v[12:15]
	v_mfma_f32_16x16x32_bf16 v[172:175], v[200:203], v[176:179], v[4:7]
	v_mfma_f32_16x16x32_bf16 v[176:179], v[200:203], v[184:187], v[64:67]
	v_mfma_f32_16x16x32_bf16 v[180:183], v[204:207], v[184:187], v[68:71]
	v_mfma_f32_16x16x32_bf16 v[184:187], v[200:203], v[192:195], v[72:75]
	v_mfma_f32_16x16x32_bf16 v[188:191], v[204:207], v[192:195], v[76:79]
	s_barrier
	ds_read_b128 v[4:7], v137
	ds_read_b128 v[12:15], v138
	ds_read_b128 v[192:195], v139
	ds_read_b128 v[138:141], v140
	ds_read_b128 v[72:75], v129 offset:32768
	ds_read_b128 v[142:145], v129 offset:33792
	ds_read_b128 v[76:79], v132 offset:32768
	ds_read_b128 v[196:199], v132 offset:33792
	ds_read_b128 v[152:155], v131 offset:32768
	ds_read_b128 v[200:203], v131 offset:33792
	ds_read_b128 v[204:207], v130 offset:32768
	ds_read_b128 v[208:211], v130 offset:33792
	s_waitcnt vmcnt(2)
	s_barrier
	s_waitcnt lgkmcnt(0)
	v_mfma_f32_16x16x32_bf16 v[64:67], v[4:7], v[72:75], v[124:127]
	v_mfma_f32_16x16x32_bf16 v[84:87], v[192:195], v[72:75], v[120:123]
	v_mfma_f32_16x16x32_bf16 v[92:95], v[4:7], v[76:79], v[116:119]
	v_mfma_f32_16x16x32_bf16 v[112:115], v[192:195], v[76:79], v[112:115]
	v_mfma_f32_16x16x32_bf16 v[108:111], v[4:7], v[152:155], v[108:111]
	v_mfma_f32_16x16x32_bf16 v[104:107], v[192:195], v[152:155], v[104:107]
	v_mfma_f32_16x16x32_bf16 v[100:103], v[4:7], v[204:207], v[100:103]
	v_mfma_f32_16x16x32_bf16 v[96:99], v[192:195], v[204:207], v[96:99]
	v_mfma_f32_16x16x32_bf16 v[68:71], v[12:15], v[142:145], v[64:67]
	v_mfma_f32_16x16x32_bf16 v[64:67], v[138:141], v[142:145], v[84:87]
	v_mfma_f32_16x16x32_bf16 v[156:159], v[12:15], v[196:199], v[92:95]
	v_mfma_f32_16x16x32_bf16 v[148:151], v[138:141], v[196:199], v[112:115]
	v_mfma_f32_16x16x32_bf16 v[124:127], v[12:15], v[200:203], v[108:111]
	v_mfma_f32_16x16x32_bf16 v[116:119], v[138:141], v[200:203], v[104:107]
	v_mfma_f32_16x16x32_bf16 v[92:95], v[12:15], v[208:211], v[100:103]
	v_mfma_f32_16x16x32_bf16 v[84:87], v[138:141], v[208:211], v[96:99]
	s_barrier
; #define LDA(dst, b, h) _Pragma("unroll") for (int m = 0; m < 4; ++m) _Pragma("unroll") for (int k = 0; k < 2; ++k) \
;     dst[m][k] = *reinterpret_cast<const bf16x8*>(SA(b, h) + lds_byte(wr * 64 + m * 16 + fr, k * 32 + fq * 8))
; #define LDB(dst, b, h) _Pragma("unroll") for (int n = 0; n < 2; ++n) _Pragma("unroll") for (int k = 0; k < 2; ++k) \
;     dst[n][k] = *reinterpret_cast<const bf16x8*>(SB(b, h) + lds_byte(wc * 32 + n * 16 + fr, k * 32 + fq * 8))
; #define WAIT_V(n) asm volatile("s_waitcnt vmcnt(" #n ")" ::: "memory")
; #define WAIT_L(n) asm volatile("s_waitcnt lgkmcnt(" #n ")" ::: "memory")
; #define BAR __builtin_amdgcn_s_barrier()
;     ...
;       LDB(B1, 1, 1); WAIT_V(0); BAR; WAIT_L(0); MMA(0, 1, At, B1); BAR;
;       LDA(At, 1, 1); BAR; WAIT_L(0); MMA(1, 0, At, B0); MMA(1, 1, At, B1); BAR; }
;     if (wr == 0) BAR;
	s_nop 0
	ds_read_b128 v[96:99], v133
	ds_read_b128 v[100:103], v134
	ds_read_b128 v[104:107], v135
	ds_read_b128 v[108:111], v136
	s_waitcnt vmcnt(0)
	s_barrier
	s_waitcnt lgkmcnt(0)
	v_mfma_f32_16x16x32_bf16 v[112:115], v[96:99], v[72:75], v[164:167]
	v_mfma_f32_16x16x32_bf16 v[72:75], v[104:107], v[72:75], v[88:91]
	v_mfma_f32_16x16x32_bf16 v[80:83], v[96:99], v[76:79], v[80:83]
	v_mfma_f32_16x16x32_bf16 v[88:91], v[104:107], v[76:79], v[168:171]
	v_mfma_f32_16x16x32_bf16 v[60:63], v[96:99], v[152:155], v[60:63]
	v_mfma_f32_16x16x32_bf16 v[56:59], v[104:107], v[152:155], v[56:59]
	v_mfma_f32_16x16x32_bf16 v[52:55], v[96:99], v[204:207], v[52:55]
	v_mfma_f32_16x16x32_bf16 v[48:51], v[104:107], v[204:207], v[48:51]
	v_mfma_f32_16x16x32_bf16 v[76:79], v[100:103], v[142:145], v[112:115]
	v_mfma_f32_16x16x32_bf16 v[72:75], v[108:111], v[142:145], v[72:75]
	v_mfma_f32_16x16x32_bf16 v[152:155], v[100:103], v[196:199], v[80:83]
	v_mfma_f32_16x16x32_bf16 v[144:147], v[108:111], v[196:199], v[88:91]
	v_mfma_f32_16x16x32_bf16 v[120:123], v[100:103], v[200:203], v[60:63]
	v_mfma_f32_16x16x32_bf16 v[112:115], v[108:111], v[200:203], v[56:59]
	v_mfma_f32_16x16x32_bf16 v[88:91], v[100:103], v[208:211], v[52:55]
	v_mfma_f32_16x16x32_bf16 v[80:83], v[108:111], v[208:211], v[48:51]
	s_barrier
	s_nop 0
	ds_read_b128 v[48:51], v129 offset:49152
	ds_read_b128 v[134:137], v129 offset:50176
	ds_read_b128 v[56:59], v132 offset:49152
	ds_read_b128 v[164:167], v132 offset:50176
	ds_read_b128 v[168:171], v131 offset:49152
	ds_read_b128 v[196:199], v131 offset:50176
	ds_read_b128 v[200:203], v130 offset:49152
	ds_read_b128 v[130:133], v130 offset:50176
	s_barrier
	s_waitcnt lgkmcnt(0)
	v_mfma_f32_16x16x32_bf16 v[44:47], v[4:7], v[48:51], v[44:47]
	v_mfma_f32_16x16x32_bf16 v[40:43], v[192:195], v[48:51], v[40:43]
	v_mfma_f32_16x16x32_bf16 v[36:39], v[4:7], v[56:59], v[36:39]
	v_mfma_f32_16x16x32_bf16 v[32:35], v[192:195], v[56:59], v[32:35]
	v_mfma_f32_16x16x32_bf16 v[28:31], v[4:7], v[168:171], v[28:31]
	v_mfma_f32_16x16x32_bf16 v[24:27], v[192:195], v[168:171], v[24:27]
	v_mfma_f32_16x16x32_bf16 v[4:7], v[4:7], v[200:203], v[20:23]
	v_mfma_f32_16x16x32_bf16 v[16:19], v[192:195], v[200:203], v[16:19]
	v_mfma_f32_16x16x32_bf16 v[60:63], v[12:15], v[134:137], v[44:47]
	v_mfma_f32_16x16x32_bf16 v[52:55], v[138:141], v[134:137], v[40:43]
	v_mfma_f32_16x16x32_bf16 v[44:47], v[12:15], v[164:167], v[36:39]
	v_mfma_f32_16x16x32_bf16 v[36:39], v[138:141], v[164:167], v[32:35]
	v_mfma_f32_16x16x32_bf16 v[28:31], v[12:15], v[196:199], v[28:31]
	v_mfma_f32_16x16x32_bf16 v[20:23], v[138:141], v[196:199], v[24:27]
	v_mfma_f32_16x16x32_bf16 v[12:15], v[12:15], v[130:133], v[4:7]
	v_mfma_f32_16x16x32_bf16 v[4:7], v[138:141], v[130:133], v[16:19]
	v_mfma_f32_16x16x32_bf16 v[16:19], v[96:99], v[48:51], v[160:163]
	v_mfma_f32_16x16x32_bf16 v[8:11], v[104:107], v[48:51], v[8:11]
	v_mfma_f32_16x16x32_bf16 v[24:27], v[96:99], v[56:59], v[172:175]
	v_mfma_f32_16x16x32_bf16 v[0:3], v[104:107], v[56:59], v[0:3]
	v_mfma_f32_16x16x32_bf16 v[138:141], v[96:99], v[168:171], v[176:179]
	v_mfma_f32_16x16x32_bf16 v[160:163], v[104:107], v[168:171], v[180:183]
	v_mfma_f32_16x16x32_bf16 v[96:99], v[96:99], v[200:203], v[184:187]
	v_mfma_f32_16x16x32_bf16 v[104:107], v[104:107], v[200:203], v[188:191]
	v_mfma_f32_16x16x32_bf16 v[56:59], v[100:103], v[134:137], v[16:19]
	v_mfma_f32_16x16x32_bf16 v[48:51], v[108:111], v[134:137], v[8:11]
	v_mfma_f32_16x16x32_bf16 v[40:43], v[100:103], v[164:167], v[24:27]
	v_mfma_f32_16x16x32_bf16 v[32:35], v[108:111], v[164:167], v[0:3]
	v_mfma_f32_16x16x32_bf16 v[24:27], v[100:103], v[196:199], v[138:141]
	v_mfma_f32_16x16x32_bf16 v[16:19], v[108:111], v[196:199], v[160:163]
	v_mfma_f32_16x16x32_bf16 v[8:11], v[100:103], v[130:133], v[96:99]
	v_mfma_f32_16x16x32_bf16 v[0:3], v[108:111], v[130:133], v[104:107]
	v_cmp_gt_u32_e32 vcc, s60, v128
	s_barrier
	s_and_saveexec_b64 s[4:5], vcc
	s_cbranch_execz .LBB0_151
	s_barrier

; #define STAGE(P, RS, SOFF, OFF, kt) do { const int _so = (SOFF) + (kt) * (BK * 2); \
;     _Pragma("unroll") for (int _i = 0; _i < 2; ++_i) { \
;       __builtin_amdgcn_raw_ptr_buffer_load_lds(RS, (__attribute__((address_space(3))) void*)((P) + wave * 1024 + _i * 8192), 16, OFF[_i], _so, 0, 0); } } while (0)
; #define LDA(dst, b, h) _Pragma("unroll") for (int m = 0; m < 4; ++m) _Pragma("unroll") for (int k = 0; k < 2; ++k) \
;     dst[m][k] = *reinterpret_cast<const bf16x8*>(SA(b, h) + lds_byte(wr * 64 + m * 16 + fr, k * 32 + fq * 8))
; #define LDB(dst, b, h) _Pragma("unroll") for (int n = 0; n < 2; ++n) _Pragma("unroll") for (int k = 0; k < 2; ++k) \
;     dst[n][k] = *reinterpret_cast<const bf16x8*>(SB(b, h) + lds_byte(wc * 32 + n * 16 + fr, k * 32 + fq * 8))
; #define WAIT_V(n) asm volatile("s_waitcnt vmcnt(" #n ")" ::: "memory")
; #define WAIT_L(n) asm volatile("s_waitcnt lgkmcnt(" #n ")" ::: "memory")
; #define BAR __builtin_amdgcn_s_barrier()
; #define SCHED __builtin_amdgcn_sched_barrier(0)
;     ...
;     const int tid = opaque_tid(wave);
;     const int wid = tid >> 6, lane = tid & 63, wr = wid >> 2, wc = wid & 3, fr = lane & 15, fq = lane >> 4;
;     int offA[2], offB[2];
;     _Pragma("unroll") for (int i = 0; i < 2; ++i) {
;       int r, c; stage_rc(tid * 16 + i * 8192, r, c);
;       offA[i] = (r * lda + c) * 2; offB[i] = (r * ldb + c) * 2;
;     }
;     const int brow = pm * BM;
;     f32x4 acc[2][2][4][2];
;     _Pragma("unroll") for (int a = 0; a < 2; ++a) _Pragma("unroll") for (int b = 0; b < 2; ++b) _Pragma("unroll") for (int m = 0; m < 4; ++m) _Pragma("unroll") for (int n = 0; n < 2; ++n)
;       acc[a][b][m][n] = f32x4{0.f, 0.f, 0.f, 0.f};
;     bf16x8 At[4][2], B0[2][2], B1[2][2];
;     if (wr == 1) BAR;
;     if (first_tile) { WAIT_V(0); }
;     else if constexpr (mode == MODE_RESID_LN) { WAIT_V(0); }
;     else if constexpr (mode == MODE_SWIGLU) { WAIT_V(6); }
;     else if constexpr (mode == MODE_V) { WAIT_V(24); }
;     else { WAIT_V(12); }
;     first_tile = false;
;     BAR;
;     BAR;
;     for (int t = 0; t < nt - 2; t += 2) {
;       LDB(B0, 0, 0); SCHED; LDA(At, 0, 0); STAGE(SA(1, 1), rsA, sA1, offA, t + 1);
;       WAIT_L(8); BAR; WAIT_L(0); MMA(0, 0, At, B0); BAR; SCHED;
.LBB0_209:
	v_bfe_i32 v4, v130, 27, 1
	v_lshlrev_b32_e32 v2, 4, v130
	v_lshrrev_b32_e32 v4, 22, v4
	v_add_u32_e32 v4, v2, v4
	v_and_b32_e32 v4, 0xfffffc00, v4
	v_sub_u32_e32 v4, v2, v4
	v_lshrrev_b32_e32 v5, 4, v4
	v_bitop3_b32 v4, v5, v4, 32 bitop3:0x6c
	v_ashrrev_i32_e32 v3, 31, v130
	v_ashrrev_i32_e32 v6, 31, v4
	v_lshrrev_b32_e32 v3, 26, v3
	v_lshrrev_b32_e32 v6, 26, v6
	v_add_u32_e32 v3, v130, v3
	v_add_u32_e32 v6, v4, v6
	v_ashrrev_i32_e32 v3, 6, v3
	v_lshrrev_b32_e32 v7, 6, v6
	v_and_b32_e32 v6, 0xc0, v6
	v_lshlrev_b32_e32 v5, 3, v3
	v_lshlrev_b32_e32 v3, 5, v3
	v_sub_u32_e32 v4, v4, v6
	v_and_b32_e32 v5, 0xffff0, v5
	v_and_b32_e32 v3, 32, v3
	v_ashrrev_i16_sdwa v4, v128, sext(v4) dst_sel:DWORD dst_unused:UNUSED_PAD src0_sel:DWORD src1_sel:BYTE_0
	v_add_u32_sdwa v3, v3, sext(v4) dst_sel:DWORD dst_unused:UNUSED_PAD src0_sel:DWORD src1_sel:WORD_0
	v_add_lshl_u32 v4, v7, v5, 12
	v_add_u32_e32 v2, 0x2000, v2
	v_lshl_add_u32 v143, v3, 1, v4
	v_ashrrev_i32_e32 v3, 31, v2
	v_lshrrev_b32_e32 v3, 22, v3
	v_add_u32_e32 v3, v2, v3
	v_ashrrev_i32_e32 v3, 10, v3
	v_mul_i32_i24_e32 v4, 0x400, v3
	v_sub_u32_e32 v2, v2, v4
	v_lshrrev_b32_e32 v4, 4, v2
	v_bitop3_b32 v2, v4, v2, 32 bitop3:0x6c
	v_ashrrev_i32_e32 v5, 31, v2
	v_lshrrev_b32_e32 v5, 26, v5
	v_add_u32_e32 v5, v2, v5
	v_lshrrev_b32_e32 v6, 6, v5
	v_and_b32_e32 v5, 0xc0, v5
	v_lshlrev_b32_e32 v4, 3, v3
	v_lshlrev_b32_e32 v3, 5, v3
	v_sub_u32_e32 v2, v2, v5
	v_and_b32_e32 v4, 0xffff0, v4
	v_and_b32_e32 v3, 32, v3
	v_ashrrev_i16_sdwa v2, v128, sext(v2) dst_sel:DWORD dst_unused:UNUSED_PAD src0_sel:DWORD src1_sel:BYTE_0
	v_add_u32_sdwa v2, v3, sext(v2) dst_sel:DWORD dst_unused:UNUSED_PAD src0_sel:DWORD src1_sel:WORD_0
	v_add_lshl_u32 v3, v6, v4, 12
	v_lshl_add_u32 v144, v2, 1, v3
	v_and_b32_e32 v3, 15, v0
	v_lshlrev_b32_e32 v5, 2, v0
	v_and_b32_e32 v2, 48, v0
	v_lshlrev_b32_e32 v3, 6, v3
	v_and_b32_e32 v5, 32, v5
	v_lshlrev_b32_e32 v0, 6, v0
	v_or_b32_e32 v4, v3, v2
	v_bitop3_b32 v3, v3, v5, v2 bitop3:0x36
	v_lshlrev_b32_e32 v6, 6, v130
	v_lshlrev_b32_e32 v1, 13, v1
	v_and_or_b32 v0, v0, s34, v2
	v_and_or_b32 v3, v6, s33, v3
	v_bitop3_b32 v0, v1, v0, v5 bitop3:0xf6
	v_or_b32_e32 v6, 0x400, v3
	v_or_b32_e32 v7, 0x800, v3
	v_or_b32_e32 v8, 0xc00, v3
	v_or_b32_e32 v134, 0x800, v0
	v_or_b32_e32 v133, 0x1000, v0
	v_or_b32_e32 v132, 0x1800, v0
	v_mov_b32_e32 v0, 0
	v_bitop3_b32 v131, v4, v1, v5 bitop3:0xde
	s_mov_b32 s16, -2
	s_mov_b32 s17, 0
	v_or_b32_e32 v149, 0x10000, v3
	v_or_b32_e32 v150, 0x10000, v6
	v_or_b32_e32 v151, 0x10000, v7
	v_or_b32_e32 v152, 0x10000, v8
	v_or_b32_e32 v145, 0x14000, v3
	v_or_b32_e32 v146, 0x14000, v6
	v_or_b32_e32 v147, 0x14000, v7
	v_or_b32_e32 v148, 0x14000, v8
	v_or_b32_e32 v139, 0x18000, v3
	v_or_b32_e32 v140, 0x18000, v6
	v_or_b32_e32 v141, 0x18000, v7
	v_or_b32_e32 v142, 0x18000, v8
	v_or_b32_e32 v135, 0x1c000, v3
	v_or_b32_e32 v136, 0x1c000, v6
	v_or_b32_e32 v137, 0x1c000, v7
	v_or_b32_e32 v138, 0x1c000, v8
	s_barrier
	s_barrier
	ds_read_b128 v[154:157], v149
	ds_read_b128 v[158:161], v150
	ds_read_b128 v[162:165], v151
	ds_read_b128 v[166:169], v152
	s_add_i32 s44, s38, s17
	s_add_i32 s10, s44, 0x80
	s_mov_b32 m0, s30
	ds_read_b128 v[170:173], v131
	ds_read_b128 v[174:177], v131 offset:1024
	ds_read_b128 v[178:181], v134
	ds_read_b128 v[182:185], v134 offset:1024
	ds_read_b128 v[186:189], v133
	ds_read_b128 v[190:193], v133 offset:1024
	ds_read_b128 v[194:197], v132
	ds_read_b128 v[198:201], v132 offset:1024
	buffer_load_dwordx4 v143, s[4:7], s10 offen lds
	s_mov_b32 m0, s31
	s_nop 0
	buffer_load_dwordx4 v144, s[4:7], s10 offen lds
	s_waitcnt lgkmcnt(8)
	s_barrier
	s_waitcnt lgkmcnt(0)
	v_mfma_f32_16x16x32_bf16 v[124:127], v[154:157], v[170:173], 0
	v_mfma_f32_16x16x32_bf16 v[124:127], v[158:161], v[174:177], v[124:127]
	v_mfma_f32_16x16x32_bf16 v[120:123], v[166:169], v[174:177], 0
	v_mfma_f32_16x16x32_bf16 v[120:123], v[162:165], v[170:173], v[120:123]
	v_mfma_f32_16x16x32_bf16 v[112:115], v[162:165], v[178:181], 0
	v_mfma_f32_16x16x32_bf16 v[112:115], v[166:169], v[182:185], v[112:115]
	v_mfma_f32_16x16x32_bf16 v[116:119], v[158:161], v[182:185], 0
	v_mfma_f32_16x16x32_bf16 v[116:119], v[154:157], v[178:181], v[116:119]
	v_mfma_f32_16x16x32_bf16 v[108:111], v[154:157], v[186:189], 0
	v_mfma_f32_16x16x32_bf16 v[108:111], v[158:161], v[190:193], v[108:111]
	v_mfma_f32_16x16x32_bf16 v[104:107], v[166:169], v[190:193], 0
	v_mfma_f32_16x16x32_bf16 v[104:107], v[162:165], v[186:189], v[104:107]
	v_mfma_f32_16x16x32_bf16 v[96:99], v[162:165], v[194:197], 0
	v_mfma_f32_16x16x32_bf16 v[96:99], v[166:169], v[198:201], v[96:99]
	v_mfma_f32_16x16x32_bf16 v[100:103], v[158:161], v[198:201], 0
	v_mfma_f32_16x16x32_bf16 v[100:103], v[154:157], v[194:197], v[100:103]
	s_barrier
	s_add_i32 s45, s40, s17
	s_add_i32 s46, s45, 0x100
	s_mov_b32 s10, s6
	s_mov_b32 s11, s7
	s_mov_b32 m0, s1
	ds_read_b128 v[202:205], v145
	ds_read_b128 v[206:209], v146
	ds_read_b128 v[210:213], v147
	ds_read_b128 v[214:217], v148
	buffer_load_dwordx4 v143, s[8:11], s46 offen lds
	s_mov_b32 m0, s3
	s_nop 0
	buffer_load_dwordx4 v144, s[8:11], s46 offen lds
	s_barrier
; #define STAGE(P, RS, SOFF, OFF, kt) do { const int _so = (SOFF) + (kt) * (BK * 2); \
;     _Pragma("unroll") for (int _i = 0; _i < 2; ++_i) { \
;       __builtin_amdgcn_raw_ptr_buffer_load_lds(RS, (__attribute__((address_space(3))) void*)((P) + wave * 1024 + _i * 8192), 16, OFF[_i], _so, 0, 0); } } while (0)
; #define LDA(dst, b, h) _Pragma("unroll") for (int m = 0; m < 4; ++m) _Pragma("unroll") for (int k = 0; k < 2; ++k) \
;     dst[m][k] = *reinterpret_cast<const bf16x8*>(SA(b, h) + lds_byte(wr * 64 + m * 16 + fr, k * 32 + fq * 8))
; #define LDB(dst, b, h) _Pragma("unroll") for (int n = 0; n < 2; ++n) _Pragma("unroll") for (int k = 0; k < 2; ++k) \
;     dst[n][k] = *reinterpret_cast<const bf16x8*>(SB(b, h) + lds_byte(wc * 32 + n * 16 + fr, k * 32 + fq * 8))
; #define WAIT_V(n) asm volatile("s_waitcnt vmcnt(" #n ")" ::: "memory")
; #define WAIT_L(n) asm volatile("s_waitcnt lgkmcnt(" #n ")" ::: "memory")
; #define BAR __builtin_amdgcn_s_barrier()
; #define SCHED __builtin_amdgcn_sched_barrier(0)
;     ...
;       BAR; WAIT_L(0); MMA(0, 1, At, B1); BAR;
;       LDA(At, 0, 1); STAGE(SA(0, 0), rsA, sA0, offA, t + 2);
;       BAR; WAIT_L(0); MMA(1, 0, At, B0); BAR; SCHED;
;       STAGE(SB(0, 1), rsB, sB1, offB, t + 2);
;       WAIT_V(6); BAR; MMA(1, 1, At, B1); BAR;
;       LDB(B0, 1, 0); SCHED; LDA(At, 1, 0); STAGE(SA(0, 1), rsA, sA1, offA, t + 2);
;       WAIT_L(8); BAR; WAIT_L(0); MMA(0, 0, At, B0); BAR; SCHED;
	s_waitcnt lgkmcnt(0)
	v_mfma_f32_16x16x32_bf16 v[92:95], v[202:205], v[170:173], 0
	v_mfma_f32_16x16x32_bf16 v[92:95], v[206:209], v[174:177], v[92:95]
	v_mfma_f32_16x16x32_bf16 v[88:91], v[214:217], v[174:177], 0
	v_mfma_f32_16x16x32_bf16 v[88:91], v[210:213], v[170:173], v[88:91]
	v_mfma_f32_16x16x32_bf16 v[80:83], v[210:213], v[178:181], 0
	v_mfma_f32_16x16x32_bf16 v[80:83], v[214:217], v[182:185], v[80:83]
	v_mfma_f32_16x16x32_bf16 v[84:87], v[206:209], v[182:185], 0
	v_mfma_f32_16x16x32_bf16 v[84:87], v[202:205], v[178:181], v[84:87]
	v_mfma_f32_16x16x32_bf16 v[76:79], v[202:205], v[186:189], 0
	v_mfma_f32_16x16x32_bf16 v[76:79], v[206:209], v[190:193], v[76:79]
	v_mfma_f32_16x16x32_bf16 v[72:75], v[214:217], v[190:193], 0
	v_mfma_f32_16x16x32_bf16 v[72:75], v[210:213], v[186:189], v[72:75]
	v_mfma_f32_16x16x32_bf16 v[64:67], v[210:213], v[194:197], 0
	v_mfma_f32_16x16x32_bf16 v[64:67], v[214:217], v[198:201], v[64:67]
	v_mfma_f32_16x16x32_bf16 v[68:71], v[206:209], v[198:201], 0
	v_mfma_f32_16x16x32_bf16 v[68:71], v[202:205], v[194:197], v[68:71]
	s_barrier
	s_add_i32 s46, s39, s17
	s_add_i32 s47, s46, 0x100
	s_mov_b32 m0, s0
	ds_read_b128 v[170:173], v131 offset:16384
	ds_read_b128 v[174:177], v131 offset:17408
	ds_read_b128 v[178:181], v134 offset:16384
	ds_read_b128 v[182:185], v134 offset:17408
	ds_read_b128 v[186:189], v133 offset:16384
	ds_read_b128 v[190:193], v133 offset:17408
	ds_read_b128 v[194:197], v132 offset:16384
	ds_read_b128 v[198:201], v132 offset:17408
	buffer_load_dwordx4 v143, s[4:7], s47 offen lds
	s_mov_b32 m0, s18
	s_nop 0
	buffer_load_dwordx4 v144, s[4:7], s47 offen lds
	s_barrier
	s_waitcnt lgkmcnt(0)
	v_mfma_f32_16x16x32_bf16 v[60:63], v[154:157], v[170:173], 0
	v_mfma_f32_16x16x32_bf16 v[60:63], v[158:161], v[174:177], v[60:63]
	v_mfma_f32_16x16x32_bf16 v[56:59], v[166:169], v[174:177], 0
	v_mfma_f32_16x16x32_bf16 v[56:59], v[162:165], v[170:173], v[56:59]
	v_mfma_f32_16x16x32_bf16 v[48:51], v[162:165], v[178:181], 0
	v_mfma_f32_16x16x32_bf16 v[48:51], v[166:169], v[182:185], v[48:51]
	v_mfma_f32_16x16x32_bf16 v[52:55], v[158:161], v[182:185], 0
	v_mfma_f32_16x16x32_bf16 v[52:55], v[154:157], v[178:181], v[52:55]
	v_mfma_f32_16x16x32_bf16 v[44:47], v[154:157], v[186:189], 0
	v_mfma_f32_16x16x32_bf16 v[44:47], v[158:161], v[190:193], v[44:47]
	v_mfma_f32_16x16x32_bf16 v[40:43], v[166:169], v[190:193], 0
	v_mfma_f32_16x16x32_bf16 v[40:43], v[162:165], v[186:189], v[40:43]
	v_mfma_f32_16x16x32_bf16 v[32:35], v[162:165], v[194:197], 0
	v_mfma_f32_16x16x32_bf16 v[32:35], v[166:169], v[198:201], v[32:35]
	v_mfma_f32_16x16x32_bf16 v[36:39], v[158:161], v[198:201], 0
	v_mfma_f32_16x16x32_bf16 v[36:39], v[154:157], v[194:197], v[36:39]
	s_barrier
	s_add_i32 s47, s41, s17
	s_add_i32 s48, s47, 0x100
	s_mov_b32 m0, s19
	s_nop 0
	buffer_load_dwordx4 v143, s[8:11], s48 offen lds
	s_mov_b32 m0, s20
	s_nop 0
	buffer_load_dwordx4 v144, s[8:11], s48 offen lds
	s_waitcnt vmcnt(6)
	s_barrier
	v_mfma_f32_16x16x32_bf16 v[28:31], v[202:205], v[170:173], 0
	v_mfma_f32_16x16x32_bf16 v[28:31], v[206:209], v[174:177], v[28:31]
	v_mfma_f32_16x16x32_bf16 v[24:27], v[214:217], v[174:177], 0
	v_mfma_f32_16x16x32_bf16 v[24:27], v[210:213], v[170:173], v[24:27]
	v_mfma_f32_16x16x32_bf16 v[16:19], v[210:213], v[178:181], 0
	v_mfma_f32_16x16x32_bf16 v[16:19], v[214:217], v[182:185], v[16:19]
	v_mfma_f32_16x16x32_bf16 v[20:23], v[206:209], v[182:185], 0
	v_mfma_f32_16x16x32_bf16 v[20:23], v[202:205], v[178:181], v[20:23]
	v_mfma_f32_16x16x32_bf16 v[12:15], v[202:205], v[186:189], 0
	v_mfma_f32_16x16x32_bf16 v[12:15], v[206:209], v[190:193], v[12:15]
	v_mfma_f32_16x16x32_bf16 v[8:11], v[214:217], v[190:193], 0
	v_mfma_f32_16x16x32_bf16 v[8:11], v[210:213], v[186:189], v[8:11]
	v_mfma_f32_16x16x32_bf16 v[0:3], v[210:213], v[194:197], 0
	v_mfma_f32_16x16x32_bf16 v[0:3], v[214:217], v[198:201], v[0:3]
	v_mfma_f32_16x16x32_bf16 v[4:7], v[206:209], v[198:201], 0
	v_mfma_f32_16x16x32_bf16 v[4:7], v[202:205], v[194:197], v[4:7]
	s_barrier
	ds_read_b128 v[154:157], v139
	ds_read_b128 v[158:161], v140
	ds_read_b128 v[162:165], v141
	ds_read_b128 v[166:169], v142
	s_addk_i32 s44, 0x100
	s_mov_b32 m0, s21
	ds_read_b128 v[170:173], v131 offset:32768
	ds_read_b128 v[174:177], v131 offset:33792
	ds_read_b128 v[178:181], v134 offset:32768
	ds_read_b128 v[182:185], v134 offset:33792
	ds_read_b128 v[186:189], v133 offset:32768
	ds_read_b128 v[190:193], v133 offset:33792
	ds_read_b128 v[194:197], v132 offset:32768
	ds_read_b128 v[198:201], v132 offset:33792
	buffer_load_dwordx4 v143, s[4:7], s44 offen lds
	s_mov_b32 m0, s22
	s_nop 0
	buffer_load_dwordx4 v144, s[4:7], s44 offen lds
	s_waitcnt lgkmcnt(8)
	s_barrier
; #define STAGE(P, RS, SOFF, OFF, kt) do { const int _so = (SOFF) + (kt) * (BK * 2); \
;     _Pragma("unroll") for (int _i = 0; _i < 2; ++_i) { \
;       __builtin_amdgcn_raw_ptr_buffer_load_lds(RS, (__attribute__((address_space(3))) void*)((P) + wave * 1024 + _i * 8192), 16, OFF[_i], _so, 0, 0); } } while (0)
; #define LDA(dst, b, h) _Pragma("unroll") for (int m = 0; m < 4; ++m) _Pragma("unroll") for (int k = 0; k < 2; ++k) \
;     dst[m][k] = *reinterpret_cast<const bf16x8*>(SA(b, h) + lds_byte(wr * 64 + m * 16 + fr, k * 32 + fq * 8))
; #define LDB(dst, b, h) _Pragma("unroll") for (int n = 0; n < 2; ++n) _Pragma("unroll") for (int k = 0; k < 2; ++k) \
;     dst[n][k] = *reinterpret_cast<const bf16x8*>(SB(b, h) + lds_byte(wc * 32 + n * 16 + fr, k * 32 + fq * 8))
; #define WAIT_L(n) asm volatile("s_waitcnt lgkmcnt(" #n ")" ::: "memory")
; #define BAR __builtin_amdgcn_s_barrier()
; #define SCHED __builtin_amdgcn_sched_barrier(0)
;     ...
;       WAIT_L(8); BAR; WAIT_L(0); MMA(0, 0, At, B0); BAR; SCHED;
;       LDB(B1, 1, 1); STAGE(SB(1, 0), rsB, sB0, offB, t + 3);
;       BAR; WAIT_L(0); MMA(0, 1, At, B1); BAR;
;       LDA(At, 1, 1); STAGE(SA(1, 0), rsA, sA0, offA, t + 3);
;       BAR; WAIT_L(0); MMA(1, 0, At, B0); BAR; SCHED;
;       STAGE(SB(1, 1), rsB, sB1, offB, t + 3);
	s_waitcnt lgkmcnt(0)
	v_mfma_f32_16x16x32_bf16 v[124:127], v[154:157], v[170:173], v[124:127]
	v_mfma_f32_16x16x32_bf16 v[124:127], v[158:161], v[174:177], v[124:127]
	v_mfma_f32_16x16x32_bf16 v[120:123], v[166:169], v[174:177], v[120:123]
	v_mfma_f32_16x16x32_bf16 v[120:123], v[162:165], v[170:173], v[120:123]
	v_mfma_f32_16x16x32_bf16 v[112:115], v[162:165], v[178:181], v[112:115]
	v_mfma_f32_16x16x32_bf16 v[112:115], v[166:169], v[182:185], v[112:115]
	v_mfma_f32_16x16x32_bf16 v[116:119], v[158:161], v[182:185], v[116:119]
	v_mfma_f32_16x16x32_bf16 v[116:119], v[154:157], v[178:181], v[116:119]
	v_mfma_f32_16x16x32_bf16 v[108:111], v[154:157], v[186:189], v[108:111]
	v_mfma_f32_16x16x32_bf16 v[108:111], v[158:161], v[190:193], v[108:111]
	v_mfma_f32_16x16x32_bf16 v[104:107], v[166:169], v[190:193], v[104:107]
	v_mfma_f32_16x16x32_bf16 v[104:107], v[162:165], v[186:189], v[104:107]
	v_mfma_f32_16x16x32_bf16 v[96:99], v[162:165], v[194:197], v[96:99]
	v_mfma_f32_16x16x32_bf16 v[96:99], v[166:169], v[198:201], v[96:99]
	v_mfma_f32_16x16x32_bf16 v[100:103], v[158:161], v[198:201], v[100:103]
	v_mfma_f32_16x16x32_bf16 v[100:103], v[154:157], v[194:197], v[100:103]
	s_barrier
	s_addk_i32 s45, 0x180
	s_mov_b32 m0, s23
	ds_read_b128 v[202:205], v135
	ds_read_b128 v[206:209], v136
	ds_read_b128 v[210:213], v137
	ds_read_b128 v[214:217], v138
	buffer_load_dwordx4 v143, s[8:11], s45 offen lds
	s_mov_b32 m0, s24
	s_nop 0
	buffer_load_dwordx4 v144, s[8:11], s45 offen lds
	s_barrier
	s_waitcnt lgkmcnt(0)
	v_mfma_f32_16x16x32_bf16 v[92:95], v[202:205], v[170:173], v[92:95]
	v_mfma_f32_16x16x32_bf16 v[92:95], v[206:209], v[174:177], v[92:95]
	v_mfma_f32_16x16x32_bf16 v[88:91], v[214:217], v[174:177], v[88:91]
	v_mfma_f32_16x16x32_bf16 v[88:91], v[210:213], v[170:173], v[88:91]
	v_mfma_f32_16x16x32_bf16 v[80:83], v[210:213], v[178:181], v[80:83]
	v_mfma_f32_16x16x32_bf16 v[80:83], v[214:217], v[182:185], v[80:83]
	v_mfma_f32_16x16x32_bf16 v[84:87], v[206:209], v[182:185], v[84:87]
	v_mfma_f32_16x16x32_bf16 v[84:87], v[202:205], v[178:181], v[84:87]
	v_mfma_f32_16x16x32_bf16 v[76:79], v[202:205], v[186:189], v[76:79]
	v_mfma_f32_16x16x32_bf16 v[76:79], v[206:209], v[190:193], v[76:79]
	v_mfma_f32_16x16x32_bf16 v[72:75], v[214:217], v[190:193], v[72:75]
	v_mfma_f32_16x16x32_bf16 v[72:75], v[210:213], v[186:189], v[72:75]
	v_mfma_f32_16x16x32_bf16 v[64:67], v[210:213], v[194:197], v[64:67]
	v_mfma_f32_16x16x32_bf16 v[64:67], v[214:217], v[198:201], v[64:67]
	v_mfma_f32_16x16x32_bf16 v[68:71], v[206:209], v[198:201], v[68:71]
	v_mfma_f32_16x16x32_bf16 v[68:71], v[202:205], v[194:197], v[68:71]
	s_barrier
	s_addk_i32 s46, 0x180
	s_mov_b32 m0, s25
	ds_read_b128 v[170:173], v131 offset:49152
	ds_read_b128 v[174:177], v131 offset:50176
	ds_read_b128 v[178:181], v134 offset:49152
	ds_read_b128 v[182:185], v134 offset:50176
	ds_read_b128 v[186:189], v133 offset:49152
	ds_read_b128 v[190:193], v133 offset:50176
	ds_read_b128 v[194:197], v132 offset:49152
	ds_read_b128 v[198:201], v132 offset:50176
	buffer_load_dwordx4 v143, s[4:7], s46 offen lds
	s_mov_b32 m0, s26
	s_nop 0
	buffer_load_dwordx4 v144, s[4:7], s46 offen lds
	s_barrier
	s_waitcnt lgkmcnt(0)
	v_mfma_f32_16x16x32_bf16 v[60:63], v[154:157], v[170:173], v[60:63]
	v_mfma_f32_16x16x32_bf16 v[60:63], v[158:161], v[174:177], v[60:63]
	v_mfma_f32_16x16x32_bf16 v[56:59], v[166:169], v[174:177], v[56:59]
	v_mfma_f32_16x16x32_bf16 v[56:59], v[162:165], v[170:173], v[56:59]
	v_mfma_f32_16x16x32_bf16 v[48:51], v[162:165], v[178:181], v[48:51]
	v_mfma_f32_16x16x32_bf16 v[48:51], v[166:169], v[182:185], v[48:51]
	v_mfma_f32_16x16x32_bf16 v[52:55], v[158:161], v[182:185], v[52:55]
	v_mfma_f32_16x16x32_bf16 v[52:55], v[154:157], v[178:181], v[52:55]
	v_mfma_f32_16x16x32_bf16 v[44:47], v[154:157], v[186:189], v[44:47]
	v_mfma_f32_16x16x32_bf16 v[44:47], v[158:161], v[190:193], v[44:47]
	v_mfma_f32_16x16x32_bf16 v[40:43], v[166:169], v[190:193], v[40:43]
	v_mfma_f32_16x16x32_bf16 v[40:43], v[162:165], v[186:189], v[40:43]
	v_mfma_f32_16x16x32_bf16 v[32:35], v[162:165], v[194:197], v[32:35]
	v_mfma_f32_16x16x32_bf16 v[32:35], v[166:169], v[198:201], v[32:35]
	v_mfma_f32_16x16x32_bf16 v[36:39], v[158:161], v[198:201], v[36:39]
	v_mfma_f32_16x16x32_bf16 v[36:39], v[154:157], v[194:197], v[36:39]
	s_barrier
	s_addk_i32 s47, 0x180
	s_mov_b32 m0, s27
	s_nop 0
	buffer_load_dwordx4 v143, s[8:11], s47 offen lds
	s_mov_b32 m0, s28
	s_nop 0
	buffer_load_dwordx4 v144, s[8:11], s47 offen lds
	s_add_i32 s16, s16, 2
	s_addk_i32 s17, 0x100
	s_cmp_gt_u32 s16, 27
	s_cbranch_scc0 .LBB0_210
	s_branch .Lmy_post_210

; #define STAGE(P, RS, SOFF, OFF, kt) do { const int _so = (SOFF) + (kt) * (BK * 2); \
;     _Pragma("unroll") for (int _i = 0; _i < 2; ++_i) { \
;       __builtin_amdgcn_raw_ptr_buffer_load_lds(RS, (__attribute__((address_space(3))) void*)((P) + wave * 1024 + _i * 8192), 16, OFF[_i], _so, 0, 0); } } while (0)
; #define LDA(dst, b, h) _Pragma("unroll") for (int m = 0; m < 4; ++m) _Pragma("unroll") for (int k = 0; k < 2; ++k) \
;     dst[m][k] = *reinterpret_cast<const bf16x8*>(SA(b, h) + lds_byte(wr * 64 + m * 16 + fr, k * 32 + fq * 8))
; #define LDB(dst, b, h) _Pragma("unroll") for (int n = 0; n < 2; ++n) _Pragma("unroll") for (int k = 0; k < 2; ++k) \
;     dst[n][k] = *reinterpret_cast<const bf16x8*>(SB(b, h) + lds_byte(wc * 32 + n * 16 + fr, k * 32 + fq * 8))
; #define WAIT_V(n) asm volatile("s_waitcnt vmcnt(" #n ")" ::: "memory")
; #define WAIT_L(n) asm volatile("s_waitcnt lgkmcnt(" #n ")" ::: "memory")
; #define BAR __builtin_amdgcn_s_barrier()
;     ...
;       WAIT_V(6); BAR; MMA(1, 1, At, B1); BAR;
;     }
;     { LDB(B0, 0, 0); LDA(At, 0, 0); STAGE(SA(1, 1), rsA, sA1, offA, nt - 1);
;       BAR; WAIT_L(0); MMA(0, 0, At, B0); BAR;
;       LDB(B1, 0, 1); BAR; WAIT_L(0); MMA(0, 1, At, B1); BAR;
;       LDA(At, 0, 1); WAIT_V(4); BAR; WAIT_L(0); MMA(1, 0, At, B0); MMA(1, 1, At, B1); BAR; }
.Lmy_post_210:
	s_waitcnt vmcnt(6)
	s_barrier
	v_mfma_f32_16x16x32_bf16 v[28:31], v[202:205], v[170:173], v[28:31]
	v_mfma_f32_16x16x32_bf16 v[28:31], v[206:209], v[174:177], v[28:31]
	v_mfma_f32_16x16x32_bf16 v[24:27], v[214:217], v[174:177], v[24:27]
	v_mfma_f32_16x16x32_bf16 v[24:27], v[210:213], v[170:173], v[24:27]
	v_mfma_f32_16x16x32_bf16 v[16:19], v[210:213], v[178:181], v[16:19]
	v_mfma_f32_16x16x32_bf16 v[16:19], v[214:217], v[182:185], v[16:19]
	v_mfma_f32_16x16x32_bf16 v[20:23], v[206:209], v[182:185], v[20:23]
	v_mfma_f32_16x16x32_bf16 v[20:23], v[202:205], v[178:181], v[20:23]
	v_mfma_f32_16x16x32_bf16 v[12:15], v[202:205], v[186:189], v[12:15]
	v_mfma_f32_16x16x32_bf16 v[12:15], v[206:209], v[190:193], v[12:15]
	v_mfma_f32_16x16x32_bf16 v[8:11], v[214:217], v[190:193], v[8:11]
	v_mfma_f32_16x16x32_bf16 v[8:11], v[210:213], v[186:189], v[8:11]
	v_mfma_f32_16x16x32_bf16 v[0:3], v[210:213], v[194:197], v[0:3]
	v_mfma_f32_16x16x32_bf16 v[0:3], v[214:217], v[198:201], v[0:3]
	v_mfma_f32_16x16x32_bf16 v[4:7], v[206:209], v[198:201], v[4:7]
	v_mfma_f32_16x16x32_bf16 v[4:7], v[202:205], v[194:197], v[4:7]
	s_barrier
	s_add_i32 s10, s38, 0xf80
	s_mov_b32 m0, s30
	ds_read_b128 v[154:157], v149
	ds_read_b128 v[158:161], v150
	ds_read_b128 v[162:165], v151
	ds_read_b128 v[150:153], v152
	ds_read_b128 v[166:169], v131
	ds_read_b128 v[170:173], v131 offset:1024
	ds_read_b128 v[174:177], v134
	ds_read_b128 v[178:181], v134 offset:1024
	ds_read_b128 v[182:185], v133
	ds_read_b128 v[186:189], v133 offset:1024
	ds_read_b128 v[190:193], v132
	ds_read_b128 v[194:197], v132 offset:1024
	buffer_load_dwordx4 v143, s[4:7], s10 offen lds
	s_mov_b32 m0, s31
	s_nop 0
	buffer_load_dwordx4 v144, s[4:7], s10 offen lds
	s_barrier
	s_waitcnt lgkmcnt(0)
	v_mfma_f32_16x16x32_bf16 v[124:127], v[154:157], v[166:169], v[124:127]
	v_mfma_f32_16x16x32_bf16 v[124:127], v[158:161], v[170:173], v[124:127]
	v_mfma_f32_16x16x32_bf16 v[120:123], v[150:153], v[170:173], v[120:123]
	v_mfma_f32_16x16x32_bf16 v[120:123], v[162:165], v[166:169], v[120:123]
	v_mfma_f32_16x16x32_bf16 v[112:115], v[162:165], v[174:177], v[112:115]
	v_mfma_f32_16x16x32_bf16 v[112:115], v[150:153], v[178:181], v[112:115]
	v_mfma_f32_16x16x32_bf16 v[116:119], v[158:161], v[178:181], v[116:119]
	v_mfma_f32_16x16x32_bf16 v[116:119], v[154:157], v[174:177], v[116:119]
	v_mfma_f32_16x16x32_bf16 v[108:111], v[154:157], v[182:185], v[108:111]
	v_mfma_f32_16x16x32_bf16 v[108:111], v[158:161], v[186:189], v[108:111]
	v_mfma_f32_16x16x32_bf16 v[104:107], v[150:153], v[186:189], v[104:107]
	v_mfma_f32_16x16x32_bf16 v[104:107], v[162:165], v[182:185], v[104:107]
	v_mfma_f32_16x16x32_bf16 v[96:99], v[162:165], v[190:193], v[96:99]
	v_mfma_f32_16x16x32_bf16 v[96:99], v[150:153], v[194:197], v[96:99]
	v_mfma_f32_16x16x32_bf16 v[100:103], v[158:161], v[194:197], v[100:103]
	v_mfma_f32_16x16x32_bf16 v[100:103], v[154:157], v[190:193], v[100:103]
	s_barrier
	ds_read_b128 v[198:201], v145
	ds_read_b128 v[202:205], v146
	ds_read_b128 v[144:147], v147
	ds_read_b128 v[206:209], v148
	s_barrier
	s_waitcnt lgkmcnt(0)
	v_mfma_f32_16x16x32_bf16 v[92:95], v[198:201], v[166:169], v[92:95]
	v_mfma_f32_16x16x32_bf16 v[92:95], v[202:205], v[170:173], v[92:95]
	v_mfma_f32_16x16x32_bf16 v[88:91], v[206:209], v[170:173], v[88:91]
	v_mfma_f32_16x16x32_bf16 v[88:91], v[144:147], v[166:169], v[88:91]
	v_mfma_f32_16x16x32_bf16 v[80:83], v[144:147], v[174:177], v[80:83]
	v_mfma_f32_16x16x32_bf16 v[80:83], v[206:209], v[178:181], v[80:83]
	v_mfma_f32_16x16x32_bf16 v[84:87], v[202:205], v[178:181], v[84:87]
	v_mfma_f32_16x16x32_bf16 v[84:87], v[198:201], v[174:177], v[84:87]
	v_mfma_f32_16x16x32_bf16 v[76:79], v[198:201], v[182:185], v[76:79]
	v_mfma_f32_16x16x32_bf16 v[76:79], v[202:205], v[186:189], v[76:79]
	v_mfma_f32_16x16x32_bf16 v[72:75], v[206:209], v[186:189], v[72:75]
	v_mfma_f32_16x16x32_bf16 v[72:75], v[144:147], v[182:185], v[72:75]
	v_mfma_f32_16x16x32_bf16 v[64:67], v[144:147], v[190:193], v[64:67]
	v_mfma_f32_16x16x32_bf16 v[64:67], v[206:209], v[194:197], v[64:67]
	v_mfma_f32_16x16x32_bf16 v[68:71], v[202:205], v[194:197], v[68:71]
	v_mfma_f32_16x16x32_bf16 v[68:71], v[198:201], v[190:193], v[68:71]
	s_barrier
	ds_read_b128 v[166:169], v131 offset:16384
	ds_read_b128 v[170:173], v131 offset:17408
	ds_read_b128 v[174:177], v134 offset:16384
	ds_read_b128 v[178:181], v134 offset:17408
	ds_read_b128 v[182:185], v133 offset:16384
	ds_read_b128 v[186:189], v133 offset:17408
	ds_read_b128 v[190:193], v132 offset:16384
	ds_read_b128 v[194:197], v132 offset:17408
	s_waitcnt vmcnt(4)
	s_barrier
; #define LDA(dst, b, h) _Pragma("unroll") for (int m = 0; m < 4; ++m) _Pragma("unroll") for (int k = 0; k < 2; ++k) \
;     dst[m][k] = *reinterpret_cast<const bf16x8*>(SA(b, h) + lds_byte(wr * 64 + m * 16 + fr, k * 32 + fq * 8))
; #define LDB(dst, b, h) _Pragma("unroll") for (int n = 0; n < 2; ++n) _Pragma("unroll") for (int k = 0; k < 2; ++k) \
;     dst[n][k] = *reinterpret_cast<const bf16x8*>(SB(b, h) + lds_byte(wc * 32 + n * 16 + fr, k * 32 + fq * 8))
; #define WAIT_V(n) asm volatile("s_waitcnt vmcnt(" #n ")" ::: "memory")
; #define WAIT_L(n) asm volatile("s_waitcnt lgkmcnt(" #n ")" ::: "memory")
; #define BAR __builtin_amdgcn_s_barrier()
;     ...
;       LDA(At, 0, 1); WAIT_V(4); BAR; WAIT_L(0); MMA(1, 0, At, B0); MMA(1, 1, At, B1); BAR; }
;     { LDB(B0, 1, 0); LDA(At, 1, 0); WAIT_V(2); BAR; WAIT_L(0); MMA(0, 0, At, B0); BAR;
	s_waitcnt lgkmcnt(0)
	v_mfma_f32_16x16x32_bf16 v[60:63], v[154:157], v[166:169], v[60:63]
	v_mfma_f32_16x16x32_bf16 v[60:63], v[158:161], v[170:173], v[60:63]
	v_mfma_f32_16x16x32_bf16 v[56:59], v[150:153], v[170:173], v[56:59]
	v_mfma_f32_16x16x32_bf16 v[56:59], v[162:165], v[166:169], v[56:59]
	v_mfma_f32_16x16x32_bf16 v[48:51], v[162:165], v[174:177], v[48:51]
	v_mfma_f32_16x16x32_bf16 v[48:51], v[150:153], v[178:181], v[48:51]
	v_mfma_f32_16x16x32_bf16 v[52:55], v[158:161], v[178:181], v[52:55]
	v_mfma_f32_16x16x32_bf16 v[52:55], v[154:157], v[174:177], v[52:55]
	v_mfma_f32_16x16x32_bf16 v[44:47], v[154:157], v[182:185], v[44:47]
	v_mfma_f32_16x16x32_bf16 v[44:47], v[158:161], v[186:189], v[44:47]
	v_mfma_f32_16x16x32_bf16 v[40:43], v[150:153], v[186:189], v[40:43]
	v_mfma_f32_16x16x32_bf16 v[40:43], v[162:165], v[182:185], v[40:43]
	v_mfma_f32_16x16x32_bf16 v[32:35], v[162:165], v[190:193], v[32:35]
	v_mfma_f32_16x16x32_bf16 v[32:35], v[150:153], v[194:197], v[32:35]
	v_mfma_f32_16x16x32_bf16 v[36:39], v[158:161], v[194:197], v[36:39]
	v_mfma_f32_16x16x32_bf16 v[36:39], v[154:157], v[190:193], v[36:39]
	v_mfma_f32_16x16x32_bf16 v[4:7], v[198:201], v[190:193], v[4:7]
	v_mfma_f32_16x16x32_bf16 v[4:7], v[202:205], v[194:197], v[4:7]
	v_mfma_f32_16x16x32_bf16 v[28:31], v[202:205], v[170:173], v[28:31]
	v_mfma_f32_16x16x32_bf16 v[28:31], v[198:201], v[166:169], v[28:31]
	v_mfma_f32_16x16x32_bf16 v[24:27], v[144:147], v[166:169], v[24:27]
	v_mfma_f32_16x16x32_bf16 v[24:27], v[206:209], v[170:173], v[24:27]
	v_mfma_f32_16x16x32_bf16 v[16:19], v[206:209], v[178:181], v[16:19]
	v_mfma_f32_16x16x32_bf16 v[16:19], v[144:147], v[174:177], v[16:19]
	v_mfma_f32_16x16x32_bf16 v[20:23], v[198:201], v[174:177], v[20:23]
	v_mfma_f32_16x16x32_bf16 v[20:23], v[202:205], v[178:181], v[20:23]
	v_mfma_f32_16x16x32_bf16 v[12:15], v[202:205], v[186:189], v[12:15]
	v_mfma_f32_16x16x32_bf16 v[12:15], v[198:201], v[182:185], v[12:15]
	v_mfma_f32_16x16x32_bf16 v[8:11], v[144:147], v[182:185], v[8:11]
	v_mfma_f32_16x16x32_bf16 v[8:11], v[206:209], v[186:189], v[8:11]
	v_mfma_f32_16x16x32_bf16 v[0:3], v[206:209], v[194:197], v[0:3]
	v_mfma_f32_16x16x32_bf16 v[0:3], v[144:147], v[190:193], v[0:3]
	s_barrier
	ds_read_b128 v[144:147], v139
	ds_read_b128 v[148:151], v140
	ds_read_b128 v[152:155], v141
	ds_read_b128 v[140:143], v142
	ds_read_b128 v[156:159], v131 offset:32768
	ds_read_b128 v[160:163], v131 offset:33792
	ds_read_b128 v[164:167], v134 offset:32768
	ds_read_b128 v[168:171], v134 offset:33792
	ds_read_b128 v[172:175], v133 offset:32768
	ds_read_b128 v[176:179], v133 offset:33792
	ds_read_b128 v[180:183], v132 offset:32768
	ds_read_b128 v[184:187], v132 offset:33792
	s_waitcnt vmcnt(2)
	s_barrier
	s_waitcnt lgkmcnt(0)
	v_mfma_f32_16x16x32_bf16 v[124:127], v[144:147], v[156:159], v[124:127]
	v_mfma_f32_16x16x32_bf16 v[124:127], v[148:151], v[160:163], v[124:127]
	v_mfma_f32_16x16x32_bf16 v[120:123], v[140:143], v[160:163], v[120:123]
	v_mfma_f32_16x16x32_bf16 v[120:123], v[152:155], v[156:159], v[120:123]
	v_mfma_f32_16x16x32_bf16 v[112:115], v[152:155], v[164:167], v[112:115]
	v_mfma_f32_16x16x32_bf16 v[112:115], v[140:143], v[168:171], v[112:115]
	v_mfma_f32_16x16x32_bf16 v[116:119], v[148:151], v[168:171], v[116:119]
	v_mfma_f32_16x16x32_bf16 v[116:119], v[144:147], v[164:167], v[116:119]
	v_mfma_f32_16x16x32_bf16 v[108:111], v[144:147], v[172:175], v[108:111]
	v_mfma_f32_16x16x32_bf16 v[108:111], v[148:151], v[176:179], v[108:111]
	v_mfma_f32_16x16x32_bf16 v[104:107], v[140:143], v[176:179], v[104:107]
	v_mfma_f32_16x16x32_bf16 v[104:107], v[152:155], v[172:175], v[104:107]
	v_mfma_f32_16x16x32_bf16 v[96:99], v[152:155], v[180:183], v[96:99]
	v_mfma_f32_16x16x32_bf16 v[96:99], v[140:143], v[184:187], v[96:99]
	v_mfma_f32_16x16x32_bf16 v[100:103], v[148:151], v[184:187], v[100:103]
	v_mfma_f32_16x16x32_bf16 v[100:103], v[144:147], v[180:183], v[100:103]
	s_barrier
; #define LDA(dst, b, h) _Pragma("unroll") for (int m = 0; m < 4; ++m) _Pragma("unroll") for (int k = 0; k < 2; ++k) \
;     dst[m][k] = *reinterpret_cast<const bf16x8*>(SA(b, h) + lds_byte(wr * 64 + m * 16 + fr, k * 32 + fq * 8))
; #define LDB(dst, b, h) _Pragma("unroll") for (int n = 0; n < 2; ++n) _Pragma("unroll") for (int k = 0; k < 2; ++k) \
;     dst[n][k] = *reinterpret_cast<const bf16x8*>(SB(b, h) + lds_byte(wc * 32 + n * 16 + fr, k * 32 + fq * 8))
; #define WAIT_V(n) asm volatile("s_waitcnt vmcnt(" #n ")" ::: "memory")
; #define WAIT_L(n) asm volatile("s_waitcnt lgkmcnt(" #n ")" ::: "memory")
; #define BAR __builtin_amdgcn_s_barrier()
;     ...
;       LDB(B1, 1, 1); WAIT_V(0); BAR; WAIT_L(0); MMA(0, 1, At, B1); BAR;
;       LDA(At, 1, 1); BAR; WAIT_L(0); MMA(1, 0, At, B0); MMA(1, 1, At, B1); BAR; }
;     if (wr == 0) BAR;
	ds_read_b128 v[188:191], v135
	ds_read_b128 v[192:195], v136
	ds_read_b128 v[196:199], v137
	ds_read_b128 v[136:139], v138
	s_waitcnt vmcnt(0)
	s_barrier
	s_waitcnt lgkmcnt(0)
	v_mfma_f32_16x16x32_bf16 v[92:95], v[188:191], v[156:159], v[92:95]
	v_mfma_f32_16x16x32_bf16 v[92:95], v[192:195], v[160:163], v[92:95]
	v_mfma_f32_16x16x32_bf16 v[88:91], v[136:139], v[160:163], v[88:91]
	v_mfma_f32_16x16x32_bf16 v[88:91], v[196:199], v[156:159], v[88:91]
	v_mfma_f32_16x16x32_bf16 v[80:83], v[196:199], v[164:167], v[80:83]
	v_mfma_f32_16x16x32_bf16 v[80:83], v[136:139], v[168:171], v[80:83]
	v_mfma_f32_16x16x32_bf16 v[84:87], v[192:195], v[168:171], v[84:87]
	v_mfma_f32_16x16x32_bf16 v[84:87], v[188:191], v[164:167], v[84:87]
	v_mfma_f32_16x16x32_bf16 v[76:79], v[188:191], v[172:175], v[76:79]
	v_mfma_f32_16x16x32_bf16 v[76:79], v[192:195], v[176:179], v[76:79]
	v_mfma_f32_16x16x32_bf16 v[72:75], v[136:139], v[176:179], v[72:75]
	v_mfma_f32_16x16x32_bf16 v[72:75], v[196:199], v[172:175], v[72:75]
	v_mfma_f32_16x16x32_bf16 v[64:67], v[196:199], v[180:183], v[64:67]
	v_mfma_f32_16x16x32_bf16 v[64:67], v[136:139], v[184:187], v[64:67]
	v_mfma_f32_16x16x32_bf16 v[68:71], v[192:195], v[184:187], v[68:71]
	v_mfma_f32_16x16x32_bf16 v[68:71], v[188:191], v[180:183], v[68:71]
	s_barrier
	ds_read_b128 v[156:159], v131 offset:49152
	ds_read_b128 v[160:163], v131 offset:50176
	ds_read_b128 v[164:167], v134 offset:49152
	ds_read_b128 v[168:171], v134 offset:50176
	ds_read_b128 v[172:175], v133 offset:49152
	ds_read_b128 v[176:179], v133 offset:50176
	ds_read_b128 v[180:183], v132 offset:49152
	ds_read_b128 v[132:135], v132 offset:50176
	s_barrier
	s_waitcnt lgkmcnt(0)
	v_mfma_f32_16x16x32_bf16 v[60:63], v[144:147], v[156:159], v[60:63]
	v_mfma_f32_16x16x32_bf16 v[60:63], v[148:151], v[160:163], v[60:63]
	v_mfma_f32_16x16x32_bf16 v[56:59], v[140:143], v[160:163], v[56:59]
	v_mfma_f32_16x16x32_bf16 v[56:59], v[152:155], v[156:159], v[56:59]
	v_mfma_f32_16x16x32_bf16 v[48:51], v[152:155], v[164:167], v[48:51]
	v_mfma_f32_16x16x32_bf16 v[48:51], v[140:143], v[168:171], v[48:51]
	v_mfma_f32_16x16x32_bf16 v[52:55], v[148:151], v[168:171], v[52:55]
	v_mfma_f32_16x16x32_bf16 v[52:55], v[144:147], v[164:167], v[52:55]
	v_mfma_f32_16x16x32_bf16 v[44:47], v[144:147], v[172:175], v[44:47]
	v_mfma_f32_16x16x32_bf16 v[44:47], v[148:151], v[176:179], v[44:47]
	v_mfma_f32_16x16x32_bf16 v[40:43], v[140:143], v[176:179], v[40:43]
	v_mfma_f32_16x16x32_bf16 v[40:43], v[152:155], v[172:175], v[40:43]
	v_mfma_f32_16x16x32_bf16 v[32:35], v[152:155], v[180:183], v[32:35]
	v_mfma_f32_16x16x32_bf16 v[32:35], v[140:143], v[132:135], v[32:35]
	v_mfma_f32_16x16x32_bf16 v[36:39], v[148:151], v[132:135], v[36:39]
	v_mfma_f32_16x16x32_bf16 v[36:39], v[144:147], v[180:183], v[36:39]
	v_mfma_f32_16x16x32_bf16 v[4:7], v[188:191], v[180:183], v[4:7]
	v_mfma_f32_16x16x32_bf16 v[4:7], v[192:195], v[132:135], v[4:7]
	v_mfma_f32_16x16x32_bf16 v[28:31], v[192:195], v[160:163], v[28:31]
	v_mfma_f32_16x16x32_bf16 v[28:31], v[188:191], v[156:159], v[28:31]
	v_mfma_f32_16x16x32_bf16 v[24:27], v[196:199], v[156:159], v[24:27]
	v_mfma_f32_16x16x32_bf16 v[24:27], v[136:139], v[160:163], v[24:27]
	v_mfma_f32_16x16x32_bf16 v[16:19], v[136:139], v[168:171], v[16:19]
	v_mfma_f32_16x16x32_bf16 v[16:19], v[196:199], v[164:167], v[16:19]
	v_mfma_f32_16x16x32_bf16 v[20:23], v[188:191], v[164:167], v[20:23]
	v_mfma_f32_16x16x32_bf16 v[20:23], v[192:195], v[168:171], v[20:23]
	v_mfma_f32_16x16x32_bf16 v[12:15], v[192:195], v[176:179], v[12:15]
	v_mfma_f32_16x16x32_bf16 v[12:15], v[188:191], v[172:175], v[12:15]
	v_mfma_f32_16x16x32_bf16 v[8:11], v[196:199], v[172:175], v[8:11]
	v_mfma_f32_16x16x32_bf16 v[8:11], v[136:139], v[176:179], v[8:11]
	v_mfma_f32_16x16x32_bf16 v[0:3], v[136:139], v[132:135], v[0:3]
	v_mfma_f32_16x16x32_bf16 v[0:3], v[196:199], v[180:183], v[0:3]
	v_cmp_gt_u32_e32 vcc, s35, v130
	s_barrier
	s_and_saveexec_b64 s[10:11], vcc
	s_cbranch_execz .LBB0_213
	s_barrier

; #define STAGE(P, RS, SOFF, OFF, kt) do { const int _so = (SOFF) + (kt) * (BK * 2); \
;     _Pragma("unroll") for (int _i = 0; _i < 2; ++_i) { \
;       __builtin_amdgcn_raw_ptr_buffer_load_lds(RS, (__attribute__((address_space(3))) void*)((P) + wave * 1024 + _i * 8192), 16, OFF[_i], _so, 0, 0); } } while (0)
; #define LDA(dst, b, h) _Pragma("unroll") for (int m = 0; m < 4; ++m) _Pragma("unroll") for (int k = 0; k < 2; ++k) \
;     dst[m][k] = *reinterpret_cast<const bf16x8*>(SA(b, h) + lds_byte(wr * 64 + m * 16 + fr, k * 32 + fq * 8))
; #define LDB(dst, b, h) _Pragma("unroll") for (int n = 0; n < 2; ++n) _Pragma("unroll") for (int k = 0; k < 2; ++k) \
;     dst[n][k] = *reinterpret_cast<const bf16x8*>(SB(b, h) + lds_byte(wc * 32 + n * 16 + fr, k * 32 + fq * 8))
; #define WAIT_V(n) asm volatile("s_waitcnt vmcnt(" #n ")" ::: "memory")
; #define WAIT_L(n) asm volatile("s_waitcnt lgkmcnt(" #n ")" ::: "memory")
; #define BAR __builtin_amdgcn_s_barrier()
; #define SCHED __builtin_amdgcn_sched_barrier(0)
;     ...
;     const int tid = opaque_tid(wave);
;     const int wid = tid >> 6, lane = tid & 63, wr = wid >> 2, wc = wid & 3, fr = lane & 15, fq = lane >> 4;
;     int offA[2], offB[2];
;     _Pragma("unroll") for (int i = 0; i < 2; ++i) {
;       int r, c; stage_rc(tid * 16 + i * 8192, r, c);
;       offA[i] = (r * lda + c) * 2; offB[i] = (r * ldb + c) * 2;
;     }
;     const int brow = pm * BM;
;     f32x4 acc[2][2][4][2];
;     _Pragma("unroll") for (int a = 0; a < 2; ++a) _Pragma("unroll") for (int b = 0; b < 2; ++b) _Pragma("unroll") for (int m = 0; m < 4; ++m) _Pragma("unroll") for (int n = 0; n < 2; ++n)
;       acc[a][b][m][n] = f32x4{0.f, 0.f, 0.f, 0.f};
;     bf16x8 At[4][2], B0[2][2], B1[2][2];
;     if (wr == 1) BAR;
;     if (first_tile) { WAIT_V(0); }
;     else if constexpr (mode == MODE_RESID_LN) { WAIT_V(0); }
;     else if constexpr (mode == MODE_SWIGLU) { WAIT_V(6); }
;     else if constexpr (mode == MODE_V) { WAIT_V(24); }
;     else { WAIT_V(12); }
;     first_tile = false;
;     BAR;
;     BAR;
;     for (int t = 0; t < nt - 2; t += 2) {
;       LDB(B0, 0, 0); SCHED; LDA(At, 0, 0); STAGE(SA(1, 1), rsA, sA1, offA, t + 1);
;       WAIT_L(8); BAR; WAIT_L(0); MMA(0, 0, At, B0); BAR; SCHED;
;       LDB(B1, 0, 1); STAGE(SB(0, 0), rsB, sB0, offB, t + 2);
;       BAR; WAIT_L(0); MMA(0, 1, At, B1); BAR;
.LBB0_224:
	v_bfe_i32 v4, v129, 27, 1
	v_lshlrev_b32_e32 v2, 4, v129
	v_lshrrev_b32_e32 v4, 22, v4
	v_add_u32_e32 v4, v2, v4
	v_and_b32_e32 v4, 0xfffffc00, v4
	v_sub_u32_e32 v4, v2, v4
	v_lshrrev_b32_e32 v5, 4, v4
	v_bitop3_b32 v4, v5, v4, 32 bitop3:0x6c
	v_ashrrev_i32_e32 v3, 31, v129
	v_ashrrev_i32_e32 v6, 31, v4
	v_lshrrev_b32_e32 v3, 26, v3
	v_lshrrev_b32_e32 v6, 26, v6
	v_add_u32_e32 v3, v129, v3
	v_add_u32_e32 v6, v4, v6
	v_ashrrev_i32_e32 v3, 6, v3
	v_lshrrev_b32_e32 v7, 6, v6
	v_and_b32_e32 v6, 0xc0, v6
	v_lshlrev_b32_e32 v5, 3, v3
	v_lshlrev_b32_e32 v3, 5, v3
	v_sub_u32_e32 v4, v4, v6
	v_and_b32_e32 v5, 0xffff0, v5
	v_and_b32_e32 v3, 32, v3
	v_ashrrev_i16_sdwa v4, v128, sext(v4) dst_sel:DWORD dst_unused:UNUSED_PAD src0_sel:DWORD src1_sel:BYTE_0
	v_add_u32_sdwa v3, v3, sext(v4) dst_sel:DWORD dst_unused:UNUSED_PAD src0_sel:DWORD src1_sel:WORD_0
	v_add_lshl_u32 v4, v7, v5, 12
	v_add_u32_e32 v2, 0x2000, v2
	v_lshl_add_u32 v142, v3, 1, v4
	v_ashrrev_i32_e32 v3, 31, v2
	v_lshrrev_b32_e32 v3, 22, v3
	v_add_u32_e32 v3, v2, v3
	v_ashrrev_i32_e32 v3, 10, v3
	v_mul_i32_i24_e32 v4, 0x400, v3
	v_sub_u32_e32 v2, v2, v4
	v_lshrrev_b32_e32 v4, 4, v2
	v_bitop3_b32 v2, v4, v2, 32 bitop3:0x6c
	v_ashrrev_i32_e32 v5, 31, v2
	v_lshrrev_b32_e32 v5, 26, v5
	v_add_u32_e32 v5, v2, v5
	v_lshrrev_b32_e32 v6, 6, v5
	v_and_b32_e32 v5, 0xc0, v5
	v_lshlrev_b32_e32 v4, 3, v3
	v_lshlrev_b32_e32 v3, 5, v3
	v_sub_u32_e32 v2, v2, v5
	v_and_b32_e32 v4, 0xffff0, v4
	v_and_b32_e32 v3, 32, v3
	v_ashrrev_i16_sdwa v2, v128, sext(v2) dst_sel:DWORD dst_unused:UNUSED_PAD src0_sel:DWORD src1_sel:BYTE_0
	v_add_u32_sdwa v2, v3, sext(v2) dst_sel:DWORD dst_unused:UNUSED_PAD src0_sel:DWORD src1_sel:WORD_0
	v_add_lshl_u32 v3, v6, v4, 12
	v_lshl_add_u32 v143, v2, 1, v3
	v_and_b32_e32 v3, 15, v0
	v_lshlrev_b32_e32 v5, 2, v0
	v_and_b32_e32 v2, 48, v0
	v_lshlrev_b32_e32 v3, 6, v3
	v_and_b32_e32 v5, 32, v5
	v_lshlrev_b32_e32 v0, 6, v0
	v_or_b32_e32 v4, v3, v2
	v_bitop3_b32 v3, v3, v5, v2 bitop3:0x36
	v_lshlrev_b32_e32 v6, 6, v129
	v_lshlrev_b32_e32 v1, 13, v1
	v_and_or_b32 v0, v0, s36, v2
	v_and_or_b32 v3, v6, s35, v3
	v_bitop3_b32 v0, v1, v0, v5 bitop3:0xf6
	v_or_b32_e32 v6, 0x400, v3
	v_or_b32_e32 v7, 0x800, v3
	v_or_b32_e32 v8, 0xc00, v3
	v_or_b32_e32 v133, 0x800, v0
	v_or_b32_e32 v132, 0x1000, v0
	v_or_b32_e32 v131, 0x1800, v0
	v_mov_b32_e32 v0, 0
	v_bitop3_b32 v130, v4, v1, v5 bitop3:0xde
	s_mov_b32 s16, -2
	s_mov_b32 s17, 0
	v_or_b32_e32 v148, 0x10000, v3
	v_or_b32_e32 v149, 0x10000, v6
	v_or_b32_e32 v150, 0x10000, v7
	v_or_b32_e32 v151, 0x10000, v8
	v_or_b32_e32 v144, 0x14000, v3
	v_or_b32_e32 v145, 0x14000, v6
	v_or_b32_e32 v146, 0x14000, v7
	v_or_b32_e32 v147, 0x14000, v8
	v_or_b32_e32 v138, 0x18000, v3
	v_or_b32_e32 v139, 0x18000, v6
	v_or_b32_e32 v140, 0x18000, v7
	v_or_b32_e32 v141, 0x18000, v8
	v_or_b32_e32 v134, 0x1c000, v3
	v_or_b32_e32 v135, 0x1c000, v6
	v_or_b32_e32 v136, 0x1c000, v7
	v_or_b32_e32 v137, 0x1c000, v8
	s_barrier
	s_barrier
	ds_read_b128 v[152:155], v148
	ds_read_b128 v[156:159], v149
	ds_read_b128 v[160:163], v150
	ds_read_b128 v[164:167], v151
	s_add_i32 s18, s41, s17
	s_add_i32 s19, s18, 0x80
	s_mov_b32 m0, s33
	ds_read_b128 v[168:171], v130
	ds_read_b128 v[172:175], v130 offset:1024
	ds_read_b128 v[176:179], v133
	ds_read_b128 v[180:183], v133 offset:1024
	ds_read_b128 v[184:187], v132
	ds_read_b128 v[188:191], v132 offset:1024
	ds_read_b128 v[192:195], v131
	ds_read_b128 v[196:199], v131 offset:1024
	buffer_load_dwordx4 v142, s[4:7], s19 offen lds
	s_mov_b32 m0, s34
	s_nop 0
	buffer_load_dwordx4 v143, s[4:7], s19 offen lds
	s_waitcnt lgkmcnt(8)
	s_barrier
	s_waitcnt lgkmcnt(0)
	v_mfma_f32_16x16x32_bf16 v[124:127], v[168:171], v[152:155], 0
	v_mfma_f32_16x16x32_bf16 v[124:127], v[172:175], v[156:159], v[124:127]
	v_mfma_f32_16x16x32_bf16 v[120:123], v[172:175], v[164:167], 0
	v_mfma_f32_16x16x32_bf16 v[120:123], v[168:171], v[160:163], v[120:123]
	v_mfma_f32_16x16x32_bf16 v[112:115], v[176:179], v[160:163], 0
	v_mfma_f32_16x16x32_bf16 v[112:115], v[180:183], v[164:167], v[112:115]
	v_mfma_f32_16x16x32_bf16 v[116:119], v[180:183], v[156:159], 0
	v_mfma_f32_16x16x32_bf16 v[116:119], v[176:179], v[152:155], v[116:119]
	v_mfma_f32_16x16x32_bf16 v[108:111], v[184:187], v[152:155], 0
	v_mfma_f32_16x16x32_bf16 v[108:111], v[188:191], v[156:159], v[108:111]
	v_mfma_f32_16x16x32_bf16 v[104:107], v[188:191], v[164:167], 0
	v_mfma_f32_16x16x32_bf16 v[104:107], v[184:187], v[160:163], v[104:107]
	v_mfma_f32_16x16x32_bf16 v[96:99], v[192:195], v[160:163], 0
	v_mfma_f32_16x16x32_bf16 v[96:99], v[196:199], v[164:167], v[96:99]
	v_mfma_f32_16x16x32_bf16 v[100:103], v[196:199], v[156:159], 0
	v_mfma_f32_16x16x32_bf16 v[100:103], v[192:195], v[152:155], v[100:103]
	s_barrier
	s_add_i32 s19, s43, s17
	s_add_i32 s47, s19, 0x100
	s_mov_b32 m0, s1
	ds_read_b128 v[200:203], v144
	ds_read_b128 v[204:207], v145
	ds_read_b128 v[208:211], v146
	ds_read_b128 v[212:215], v147
	buffer_load_dwordx4 v142, s[8:11], s47 offen lds
	s_mov_b32 m0, s3
	s_nop 0
	buffer_load_dwordx4 v143, s[8:11], s47 offen lds
	s_barrier
	s_waitcnt lgkmcnt(0)
	v_mfma_f32_16x16x32_bf16 v[92:95], v[168:171], v[200:203], 0
	v_mfma_f32_16x16x32_bf16 v[92:95], v[172:175], v[204:207], v[92:95]
	v_mfma_f32_16x16x32_bf16 v[88:91], v[172:175], v[212:215], 0
	v_mfma_f32_16x16x32_bf16 v[88:91], v[168:171], v[208:211], v[88:91]
	v_mfma_f32_16x16x32_bf16 v[80:83], v[176:179], v[208:211], 0
	v_mfma_f32_16x16x32_bf16 v[80:83], v[180:183], v[212:215], v[80:83]
	v_mfma_f32_16x16x32_bf16 v[84:87], v[180:183], v[204:207], 0
	v_mfma_f32_16x16x32_bf16 v[84:87], v[176:179], v[200:203], v[84:87]
	v_mfma_f32_16x16x32_bf16 v[76:79], v[184:187], v[200:203], 0
	v_mfma_f32_16x16x32_bf16 v[76:79], v[188:191], v[204:207], v[76:79]
	v_mfma_f32_16x16x32_bf16 v[72:75], v[188:191], v[212:215], 0
	v_mfma_f32_16x16x32_bf16 v[72:75], v[184:187], v[208:211], v[72:75]
	v_mfma_f32_16x16x32_bf16 v[64:67], v[192:195], v[208:211], 0
	v_mfma_f32_16x16x32_bf16 v[64:67], v[196:199], v[212:215], v[64:67]
	v_mfma_f32_16x16x32_bf16 v[68:71], v[196:199], v[204:207], 0
	v_mfma_f32_16x16x32_bf16 v[68:71], v[192:195], v[200:203], v[68:71]
	s_barrier
; #define STAGE(P, RS, SOFF, OFF, kt) do { const int _so = (SOFF) + (kt) * (BK * 2); \
;     _Pragma("unroll") for (int _i = 0; _i < 2; ++_i) { \
;       __builtin_amdgcn_raw_ptr_buffer_load_lds(RS, (__attribute__((address_space(3))) void*)((P) + wave * 1024 + _i * 8192), 16, OFF[_i], _so, 0, 0); } } while (0)
; #define LDA(dst, b, h) _Pragma("unroll") for (int m = 0; m < 4; ++m) _Pragma("unroll") for (int k = 0; k < 2; ++k) \
;     dst[m][k] = *reinterpret_cast<const bf16x8*>(SA(b, h) + lds_byte(wr * 64 + m * 16 + fr, k * 32 + fq * 8))
; #define LDB(dst, b, h) _Pragma("unroll") for (int n = 0; n < 2; ++n) _Pragma("unroll") for (int k = 0; k < 2; ++k) \
;     dst[n][k] = *reinterpret_cast<const bf16x8*>(SB(b, h) + lds_byte(wc * 32 + n * 16 + fr, k * 32 + fq * 8))
; #define WAIT_V(n) asm volatile("s_waitcnt vmcnt(" #n ")" ::: "memory")
; #define WAIT_L(n) asm volatile("s_waitcnt lgkmcnt(" #n ")" ::: "memory")
; #define BAR __builtin_amdgcn_s_barrier()
; #define SCHED __builtin_amdgcn_sched_barrier(0)
;     ...
;       LDA(At, 0, 1); STAGE(SA(0, 0), rsA, sA0, offA, t + 2);
;       BAR; WAIT_L(0); MMA(1, 0, At, B0); BAR; SCHED;
;       STAGE(SB(0, 1), rsB, sB1, offB, t + 2);
;       WAIT_V(6); BAR; MMA(1, 1, At, B1); BAR;
;       LDB(B0, 1, 0); SCHED; LDA(At, 1, 0); STAGE(SA(0, 1), rsA, sA1, offA, t + 2);
;       WAIT_L(8); BAR; WAIT_L(0); MMA(0, 0, At, B0); BAR; SCHED;
	s_add_i32 s47, s42, s17
	s_add_i32 s48, s47, 0x100
	s_mov_b32 m0, s0
	ds_read_b128 v[168:171], v130 offset:16384
	ds_read_b128 v[172:175], v130 offset:17408
	ds_read_b128 v[176:179], v133 offset:16384
	ds_read_b128 v[180:183], v133 offset:17408
	ds_read_b128 v[184:187], v132 offset:16384
	ds_read_b128 v[188:191], v132 offset:17408
	ds_read_b128 v[192:195], v131 offset:16384
	ds_read_b128 v[196:199], v131 offset:17408
	buffer_load_dwordx4 v142, s[4:7], s48 offen lds
	s_mov_b32 m0, s20
	s_nop 0
	buffer_load_dwordx4 v143, s[4:7], s48 offen lds
	s_barrier
	s_waitcnt lgkmcnt(0)
	v_mfma_f32_16x16x32_bf16 v[60:63], v[168:171], v[152:155], 0
	v_mfma_f32_16x16x32_bf16 v[60:63], v[172:175], v[156:159], v[60:63]
	v_mfma_f32_16x16x32_bf16 v[56:59], v[172:175], v[164:167], 0
	v_mfma_f32_16x16x32_bf16 v[56:59], v[168:171], v[160:163], v[56:59]
	v_mfma_f32_16x16x32_bf16 v[48:51], v[176:179], v[160:163], 0
	v_mfma_f32_16x16x32_bf16 v[48:51], v[180:183], v[164:167], v[48:51]
	v_mfma_f32_16x16x32_bf16 v[52:55], v[180:183], v[156:159], 0
	v_mfma_f32_16x16x32_bf16 v[52:55], v[176:179], v[152:155], v[52:55]
	v_mfma_f32_16x16x32_bf16 v[44:47], v[184:187], v[152:155], 0
	v_mfma_f32_16x16x32_bf16 v[44:47], v[188:191], v[156:159], v[44:47]
	v_mfma_f32_16x16x32_bf16 v[40:43], v[188:191], v[164:167], 0
	v_mfma_f32_16x16x32_bf16 v[40:43], v[184:187], v[160:163], v[40:43]
	v_mfma_f32_16x16x32_bf16 v[32:35], v[192:195], v[160:163], 0
	v_mfma_f32_16x16x32_bf16 v[32:35], v[196:199], v[164:167], v[32:35]
	v_mfma_f32_16x16x32_bf16 v[36:39], v[196:199], v[156:159], 0
	v_mfma_f32_16x16x32_bf16 v[36:39], v[192:195], v[152:155], v[36:39]
	s_barrier
	s_add_i32 s48, s44, s17
	s_add_i32 s49, s48, 0x100
	s_mov_b32 m0, s21
	s_nop 0
	buffer_load_dwordx4 v142, s[8:11], s49 offen lds
	s_mov_b32 m0, s22
	s_nop 0
	buffer_load_dwordx4 v143, s[8:11], s49 offen lds
	s_waitcnt vmcnt(6)
	s_barrier
	v_mfma_f32_16x16x32_bf16 v[28:31], v[168:171], v[200:203], 0
	v_mfma_f32_16x16x32_bf16 v[28:31], v[172:175], v[204:207], v[28:31]
	v_mfma_f32_16x16x32_bf16 v[24:27], v[172:175], v[212:215], 0
	v_mfma_f32_16x16x32_bf16 v[24:27], v[168:171], v[208:211], v[24:27]
	v_mfma_f32_16x16x32_bf16 v[16:19], v[176:179], v[208:211], 0
	v_mfma_f32_16x16x32_bf16 v[16:19], v[180:183], v[212:215], v[16:19]
	v_mfma_f32_16x16x32_bf16 v[20:23], v[180:183], v[204:207], 0
	v_mfma_f32_16x16x32_bf16 v[20:23], v[176:179], v[200:203], v[20:23]
	v_mfma_f32_16x16x32_bf16 v[12:15], v[184:187], v[200:203], 0
	v_mfma_f32_16x16x32_bf16 v[12:15], v[188:191], v[204:207], v[12:15]
	v_mfma_f32_16x16x32_bf16 v[8:11], v[188:191], v[212:215], 0
	v_mfma_f32_16x16x32_bf16 v[8:11], v[184:187], v[208:211], v[8:11]
	v_mfma_f32_16x16x32_bf16 v[0:3], v[192:195], v[208:211], 0
	v_mfma_f32_16x16x32_bf16 v[0:3], v[196:199], v[212:215], v[0:3]
	v_mfma_f32_16x16x32_bf16 v[4:7], v[196:199], v[204:207], 0
	v_mfma_f32_16x16x32_bf16 v[4:7], v[192:195], v[200:203], v[4:7]
	s_barrier
	ds_read_b128 v[152:155], v138
	ds_read_b128 v[156:159], v139
	ds_read_b128 v[160:163], v140
	ds_read_b128 v[164:167], v141
	s_addk_i32 s18, 0x100
	s_mov_b32 m0, s23
	ds_read_b128 v[168:171], v130 offset:32768
	ds_read_b128 v[172:175], v130 offset:33792
	ds_read_b128 v[176:179], v133 offset:32768
	ds_read_b128 v[180:183], v133 offset:33792
	ds_read_b128 v[184:187], v132 offset:32768
	ds_read_b128 v[188:191], v132 offset:33792
	ds_read_b128 v[192:195], v131 offset:32768
	ds_read_b128 v[196:199], v131 offset:33792
	buffer_load_dwordx4 v142, s[4:7], s18 offen lds
	s_mov_b32 m0, s24
	s_nop 0
	buffer_load_dwordx4 v143, s[4:7], s18 offen lds
	s_waitcnt lgkmcnt(8)
	s_barrier
; #define STAGE(P, RS, SOFF, OFF, kt) do { const int _so = (SOFF) + (kt) * (BK * 2); \
;     _Pragma("unroll") for (int _i = 0; _i < 2; ++_i) { \
;       __builtin_amdgcn_raw_ptr_buffer_load_lds(RS, (__attribute__((address_space(3))) void*)((P) + wave * 1024 + _i * 8192), 16, OFF[_i], _so, 0, 0); } } while (0)
; #define LDA(dst, b, h) _Pragma("unroll") for (int m = 0; m < 4; ++m) _Pragma("unroll") for (int k = 0; k < 2; ++k) \
;     dst[m][k] = *reinterpret_cast<const bf16x8*>(SA(b, h) + lds_byte(wr * 64 + m * 16 + fr, k * 32 + fq * 8))
; #define LDB(dst, b, h) _Pragma("unroll") for (int n = 0; n < 2; ++n) _Pragma("unroll") for (int k = 0; k < 2; ++k) \
;     dst[n][k] = *reinterpret_cast<const bf16x8*>(SB(b, h) + lds_byte(wc * 32 + n * 16 + fr, k * 32 + fq * 8))
; #define WAIT_V(n) asm volatile("s_waitcnt vmcnt(" #n ")" ::: "memory")
; #define WAIT_L(n) asm volatile("s_waitcnt lgkmcnt(" #n ")" ::: "memory")
; #define BAR __builtin_amdgcn_s_barrier()
; #define SCHED __builtin_amdgcn_sched_barrier(0)
;     ...
;       WAIT_L(8); BAR; WAIT_L(0); MMA(0, 0, At, B0); BAR; SCHED;
;       LDB(B1, 1, 1); STAGE(SB(1, 0), rsB, sB0, offB, t + 3);
;       BAR; WAIT_L(0); MMA(0, 1, At, B1); BAR;
;       LDA(At, 1, 1); STAGE(SA(1, 0), rsA, sA0, offA, t + 3);
;       BAR; WAIT_L(0); MMA(1, 0, At, B0); BAR; SCHED;
;       STAGE(SB(1, 1), rsB, sB1, offB, t + 3);
;       WAIT_V(6); BAR; MMA(1, 1, At, B1); BAR;
;     }
	s_waitcnt lgkmcnt(0)
	v_mfma_f32_16x16x32_bf16 v[124:127], v[168:171], v[152:155], v[124:127]
	v_mfma_f32_16x16x32_bf16 v[124:127], v[172:175], v[156:159], v[124:127]
	v_mfma_f32_16x16x32_bf16 v[120:123], v[172:175], v[164:167], v[120:123]
	v_mfma_f32_16x16x32_bf16 v[120:123], v[168:171], v[160:163], v[120:123]
	v_mfma_f32_16x16x32_bf16 v[112:115], v[176:179], v[160:163], v[112:115]
	v_mfma_f32_16x16x32_bf16 v[112:115], v[180:183], v[164:167], v[112:115]
	v_mfma_f32_16x16x32_bf16 v[116:119], v[180:183], v[156:159], v[116:119]
	v_mfma_f32_16x16x32_bf16 v[116:119], v[176:179], v[152:155], v[116:119]
	v_mfma_f32_16x16x32_bf16 v[108:111], v[184:187], v[152:155], v[108:111]
	v_mfma_f32_16x16x32_bf16 v[108:111], v[188:191], v[156:159], v[108:111]
	v_mfma_f32_16x16x32_bf16 v[104:107], v[188:191], v[164:167], v[104:107]
	v_mfma_f32_16x16x32_bf16 v[104:107], v[184:187], v[160:163], v[104:107]
	v_mfma_f32_16x16x32_bf16 v[96:99], v[192:195], v[160:163], v[96:99]
	v_mfma_f32_16x16x32_bf16 v[96:99], v[196:199], v[164:167], v[96:99]
	v_mfma_f32_16x16x32_bf16 v[100:103], v[196:199], v[156:159], v[100:103]
	v_mfma_f32_16x16x32_bf16 v[100:103], v[192:195], v[152:155], v[100:103]
	s_barrier
	s_addk_i32 s19, 0x180
	s_mov_b32 m0, s25
	ds_read_b128 v[200:203], v134
	ds_read_b128 v[204:207], v135
	ds_read_b128 v[208:211], v136
	ds_read_b128 v[212:215], v137
	buffer_load_dwordx4 v142, s[8:11], s19 offen lds
	s_mov_b32 m0, s26
	s_nop 0
	buffer_load_dwordx4 v143, s[8:11], s19 offen lds
	s_barrier
	s_waitcnt lgkmcnt(0)
	v_mfma_f32_16x16x32_bf16 v[92:95], v[168:171], v[200:203], v[92:95]
	v_mfma_f32_16x16x32_bf16 v[92:95], v[172:175], v[204:207], v[92:95]
	v_mfma_f32_16x16x32_bf16 v[88:91], v[172:175], v[212:215], v[88:91]
	v_mfma_f32_16x16x32_bf16 v[88:91], v[168:171], v[208:211], v[88:91]
	v_mfma_f32_16x16x32_bf16 v[80:83], v[176:179], v[208:211], v[80:83]
	v_mfma_f32_16x16x32_bf16 v[80:83], v[180:183], v[212:215], v[80:83]
	v_mfma_f32_16x16x32_bf16 v[84:87], v[180:183], v[204:207], v[84:87]
	v_mfma_f32_16x16x32_bf16 v[84:87], v[176:179], v[200:203], v[84:87]
	v_mfma_f32_16x16x32_bf16 v[76:79], v[184:187], v[200:203], v[76:79]
	v_mfma_f32_16x16x32_bf16 v[76:79], v[188:191], v[204:207], v[76:79]
	v_mfma_f32_16x16x32_bf16 v[72:75], v[188:191], v[212:215], v[72:75]
	v_mfma_f32_16x16x32_bf16 v[72:75], v[184:187], v[208:211], v[72:75]
	v_mfma_f32_16x16x32_bf16 v[64:67], v[192:195], v[208:211], v[64:67]
	v_mfma_f32_16x16x32_bf16 v[64:67], v[196:199], v[212:215], v[64:67]
	v_mfma_f32_16x16x32_bf16 v[68:71], v[196:199], v[204:207], v[68:71]
	v_mfma_f32_16x16x32_bf16 v[68:71], v[192:195], v[200:203], v[68:71]
	s_barrier
	s_addk_i32 s47, 0x180
	s_mov_b32 m0, s27
	ds_read_b128 v[168:171], v130 offset:49152
	ds_read_b128 v[172:175], v130 offset:50176
	ds_read_b128 v[176:179], v133 offset:49152
	ds_read_b128 v[180:183], v133 offset:50176
	ds_read_b128 v[184:187], v132 offset:49152
	ds_read_b128 v[188:191], v132 offset:50176
	ds_read_b128 v[192:195], v131 offset:49152
	ds_read_b128 v[196:199], v131 offset:50176
	buffer_load_dwordx4 v142, s[4:7], s47 offen lds
	s_mov_b32 m0, s28
	s_nop 0
	buffer_load_dwordx4 v143, s[4:7], s47 offen lds
	s_barrier
	s_waitcnt lgkmcnt(0)
	v_mfma_f32_16x16x32_bf16 v[60:63], v[168:171], v[152:155], v[60:63]
	v_mfma_f32_16x16x32_bf16 v[60:63], v[172:175], v[156:159], v[60:63]
	v_mfma_f32_16x16x32_bf16 v[56:59], v[172:175], v[164:167], v[56:59]
	v_mfma_f32_16x16x32_bf16 v[56:59], v[168:171], v[160:163], v[56:59]
	v_mfma_f32_16x16x32_bf16 v[48:51], v[176:179], v[160:163], v[48:51]
	v_mfma_f32_16x16x32_bf16 v[48:51], v[180:183], v[164:167], v[48:51]
	v_mfma_f32_16x16x32_bf16 v[52:55], v[180:183], v[156:159], v[52:55]
	v_mfma_f32_16x16x32_bf16 v[52:55], v[176:179], v[152:155], v[52:55]
	v_mfma_f32_16x16x32_bf16 v[44:47], v[184:187], v[152:155], v[44:47]
	v_mfma_f32_16x16x32_bf16 v[44:47], v[188:191], v[156:159], v[44:47]
	v_mfma_f32_16x16x32_bf16 v[40:43], v[188:191], v[164:167], v[40:43]
	v_mfma_f32_16x16x32_bf16 v[40:43], v[184:187], v[160:163], v[40:43]
	v_mfma_f32_16x16x32_bf16 v[32:35], v[192:195], v[160:163], v[32:35]
	v_mfma_f32_16x16x32_bf16 v[32:35], v[196:199], v[164:167], v[32:35]
	v_mfma_f32_16x16x32_bf16 v[36:39], v[196:199], v[156:159], v[36:39]
	v_mfma_f32_16x16x32_bf16 v[36:39], v[192:195], v[152:155], v[36:39]
	s_barrier
	s_addk_i32 s48, 0x180
	s_mov_b32 m0, s29
	s_nop 0
	buffer_load_dwordx4 v142, s[8:11], s48 offen lds
	s_mov_b32 m0, s30
	s_nop 0
	buffer_load_dwordx4 v143, s[8:11], s48 offen lds
	s_add_i32 s16, s16, 2
	s_addk_i32 s17, 0x100
	s_cmp_gt_u32 s16, 27
	s_cbranch_scc0 .LBB0_225
	s_branch .Lmy_post_225

; #define STAGE(P, RS, SOFF, OFF, kt) do { const int _so = (SOFF) + (kt) * (BK * 2); \
;     _Pragma("unroll") for (int _i = 0; _i < 2; ++_i) { \
;       __builtin_amdgcn_raw_ptr_buffer_load_lds(RS, (__attribute__((address_space(3))) void*)((P) + wave * 1024 + _i * 8192), 16, OFF[_i], _so, 0, 0); } } while (0)
; #define LDA(dst, b, h) _Pragma("unroll") for (int m = 0; m < 4; ++m) _Pragma("unroll") for (int k = 0; k < 2; ++k) \
;     dst[m][k] = *reinterpret_cast<const bf16x8*>(SA(b, h) + lds_byte(wr * 64 + m * 16 + fr, k * 32 + fq * 8))
; #define LDB(dst, b, h) _Pragma("unroll") for (int n = 0; n < 2; ++n) _Pragma("unroll") for (int k = 0; k < 2; ++k) \
;     dst[n][k] = *reinterpret_cast<const bf16x8*>(SB(b, h) + lds_byte(wc * 32 + n * 16 + fr, k * 32 + fq * 8))
; #define WAIT_V(n) asm volatile("s_waitcnt vmcnt(" #n ")" ::: "memory")
; #define WAIT_L(n) asm volatile("s_waitcnt lgkmcnt(" #n ")" ::: "memory")
; #define BAR __builtin_amdgcn_s_barrier()
;     ...
;       WAIT_V(6); BAR; MMA(1, 1, At, B1); BAR;
;     }
;     { LDB(B0, 0, 0); LDA(At, 0, 0); STAGE(SA(1, 1), rsA, sA1, offA, nt - 1);
;       BAR; WAIT_L(0); MMA(0, 0, At, B0); BAR;
;       LDB(B1, 0, 1); BAR; WAIT_L(0); MMA(0, 1, At, B1); BAR;
;       LDA(At, 0, 1); WAIT_V(4); BAR; WAIT_L(0); MMA(1, 0, At, B0); MMA(1, 1, At, B1); BAR; }
.Lmy_post_225:
	s_waitcnt vmcnt(6)
	s_barrier
	v_mfma_f32_16x16x32_bf16 v[28:31], v[168:171], v[200:203], v[28:31]
	v_mfma_f32_16x16x32_bf16 v[28:31], v[172:175], v[204:207], v[28:31]
	v_mfma_f32_16x16x32_bf16 v[24:27], v[172:175], v[212:215], v[24:27]
	v_mfma_f32_16x16x32_bf16 v[24:27], v[168:171], v[208:211], v[24:27]
	v_mfma_f32_16x16x32_bf16 v[16:19], v[176:179], v[208:211], v[16:19]
	v_mfma_f32_16x16x32_bf16 v[16:19], v[180:183], v[212:215], v[16:19]
	v_mfma_f32_16x16x32_bf16 v[20:23], v[180:183], v[204:207], v[20:23]
	v_mfma_f32_16x16x32_bf16 v[20:23], v[176:179], v[200:203], v[20:23]
	v_mfma_f32_16x16x32_bf16 v[12:15], v[184:187], v[200:203], v[12:15]
	v_mfma_f32_16x16x32_bf16 v[12:15], v[188:191], v[204:207], v[12:15]
	v_mfma_f32_16x16x32_bf16 v[8:11], v[188:191], v[212:215], v[8:11]
	v_mfma_f32_16x16x32_bf16 v[8:11], v[184:187], v[208:211], v[8:11]
	v_mfma_f32_16x16x32_bf16 v[0:3], v[192:195], v[208:211], v[0:3]
	v_mfma_f32_16x16x32_bf16 v[0:3], v[196:199], v[212:215], v[0:3]
	v_mfma_f32_16x16x32_bf16 v[4:7], v[196:199], v[204:207], v[4:7]
	v_mfma_f32_16x16x32_bf16 v[4:7], v[192:195], v[200:203], v[4:7]
	s_barrier
	s_add_i32 s16, s41, 0xf80
	s_mov_b32 m0, s33
	ds_read_b128 v[152:155], v148
	ds_read_b128 v[156:159], v149
	ds_read_b128 v[160:163], v150
	ds_read_b128 v[148:151], v151
	ds_read_b128 v[164:167], v130
	ds_read_b128 v[168:171], v130 offset:1024
	ds_read_b128 v[172:175], v133
	ds_read_b128 v[176:179], v133 offset:1024
	ds_read_b128 v[180:183], v132
	ds_read_b128 v[184:187], v132 offset:1024
	ds_read_b128 v[188:191], v131
	ds_read_b128 v[192:195], v131 offset:1024
	buffer_load_dwordx4 v142, s[4:7], s16 offen lds
	s_mov_b32 m0, s34
	s_nop 0
	buffer_load_dwordx4 v143, s[4:7], s16 offen lds
	s_barrier
	s_waitcnt lgkmcnt(0)
	v_mfma_f32_16x16x32_bf16 v[124:127], v[164:167], v[152:155], v[124:127]
	v_mfma_f32_16x16x32_bf16 v[124:127], v[168:171], v[156:159], v[124:127]
	v_mfma_f32_16x16x32_bf16 v[120:123], v[168:171], v[148:151], v[120:123]
	v_mfma_f32_16x16x32_bf16 v[120:123], v[164:167], v[160:163], v[120:123]
	v_mfma_f32_16x16x32_bf16 v[112:115], v[172:175], v[160:163], v[112:115]
	v_mfma_f32_16x16x32_bf16 v[112:115], v[176:179], v[148:151], v[112:115]
	v_mfma_f32_16x16x32_bf16 v[116:119], v[176:179], v[156:159], v[116:119]
	v_mfma_f32_16x16x32_bf16 v[116:119], v[172:175], v[152:155], v[116:119]
	v_mfma_f32_16x16x32_bf16 v[108:111], v[180:183], v[152:155], v[108:111]
	v_mfma_f32_16x16x32_bf16 v[108:111], v[184:187], v[156:159], v[108:111]
	v_mfma_f32_16x16x32_bf16 v[104:107], v[184:187], v[148:151], v[104:107]
	v_mfma_f32_16x16x32_bf16 v[104:107], v[180:183], v[160:163], v[104:107]
	v_mfma_f32_16x16x32_bf16 v[96:99], v[188:191], v[160:163], v[96:99]
	v_mfma_f32_16x16x32_bf16 v[96:99], v[192:195], v[148:151], v[96:99]
	v_mfma_f32_16x16x32_bf16 v[100:103], v[192:195], v[156:159], v[100:103]
	v_mfma_f32_16x16x32_bf16 v[100:103], v[188:191], v[152:155], v[100:103]
	s_barrier
	ds_read_b128 v[196:199], v144
	ds_read_b128 v[142:145], v145
	ds_read_b128 v[200:203], v146
	ds_read_b128 v[204:207], v147
	s_barrier
	s_waitcnt lgkmcnt(0)
	v_mfma_f32_16x16x32_bf16 v[88:91], v[164:167], v[200:203], v[88:91]
	v_mfma_f32_16x16x32_bf16 v[84:87], v[172:175], v[196:199], v[84:87]
	v_mfma_f32_16x16x32_bf16 v[80:83], v[172:175], v[200:203], v[80:83]
	v_mfma_f32_16x16x32_bf16 v[76:79], v[180:183], v[196:199], v[76:79]
	v_mfma_f32_16x16x32_bf16 v[72:75], v[180:183], v[200:203], v[72:75]
	v_mfma_f32_16x16x32_bf16 v[68:71], v[188:191], v[196:199], v[68:71]
	v_mfma_f32_16x16x32_bf16 v[64:67], v[188:191], v[200:203], v[64:67]
	v_mfma_f32_16x16x32_bf16 v[92:95], v[164:167], v[196:199], v[92:95]
	v_mfma_f32_16x16x32_bf16 v[88:91], v[168:171], v[204:207], v[88:91]
	v_mfma_f32_16x16x32_bf16 v[84:87], v[176:179], v[142:145], v[84:87]
	v_mfma_f32_16x16x32_bf16 v[80:83], v[176:179], v[204:207], v[80:83]
	v_mfma_f32_16x16x32_bf16 v[76:79], v[184:187], v[142:145], v[76:79]
	v_mfma_f32_16x16x32_bf16 v[72:75], v[184:187], v[204:207], v[72:75]
	v_mfma_f32_16x16x32_bf16 v[68:71], v[192:195], v[142:145], v[68:71]
	v_mfma_f32_16x16x32_bf16 v[64:67], v[192:195], v[204:207], v[64:67]
	v_mfma_f32_16x16x32_bf16 v[164:167], v[168:171], v[142:145], v[92:95]
	s_barrier
	s_nop 0
	ds_read_b128 v[92:95], v130 offset:16384
	ds_read_b128 v[168:171], v130 offset:17408
	ds_read_b128 v[172:175], v133 offset:16384
	ds_read_b128 v[176:179], v133 offset:17408
	ds_read_b128 v[180:183], v132 offset:16384
	ds_read_b128 v[184:187], v132 offset:17408
	ds_read_b128 v[188:191], v131 offset:16384
	ds_read_b128 v[192:195], v131 offset:17408
	s_waitcnt vmcnt(4)
	s_barrier
; #define LDA(dst, b, h) _Pragma("unroll") for (int m = 0; m < 4; ++m) _Pragma("unroll") for (int k = 0; k < 2; ++k) \
;     dst[m][k] = *reinterpret_cast<const bf16x8*>(SA(b, h) + lds_byte(wr * 64 + m * 16 + fr, k * 32 + fq * 8))
; #define LDB(dst, b, h) _Pragma("unroll") for (int n = 0; n < 2; ++n) _Pragma("unroll") for (int k = 0; k < 2; ++k) \
;     dst[n][k] = *reinterpret_cast<const bf16x8*>(SB(b, h) + lds_byte(wc * 32 + n * 16 + fr, k * 32 + fq * 8))
; #define WAIT_V(n) asm volatile("s_waitcnt vmcnt(" #n ")" ::: "memory")
; #define WAIT_L(n) asm volatile("s_waitcnt lgkmcnt(" #n ")" ::: "memory")
; #define BAR __builtin_amdgcn_s_barrier()
;     ...
;       LDA(At, 0, 1); WAIT_V(4); BAR; WAIT_L(0); MMA(1, 0, At, B0); MMA(1, 1, At, B1); BAR; }
;     { LDB(B0, 1, 0); LDA(At, 1, 0); WAIT_V(2); BAR; WAIT_L(0); MMA(0, 0, At, B0); BAR;
	s_waitcnt lgkmcnt(0)
	v_mfma_f32_16x16x32_bf16 v[60:63], v[92:95], v[152:155], v[60:63]
	v_mfma_f32_16x16x32_bf16 v[60:63], v[168:171], v[156:159], v[60:63]
	v_mfma_f32_16x16x32_bf16 v[56:59], v[168:171], v[148:151], v[56:59]
	v_mfma_f32_16x16x32_bf16 v[56:59], v[92:95], v[160:163], v[56:59]
	v_mfma_f32_16x16x32_bf16 v[48:51], v[172:175], v[160:163], v[48:51]
	v_mfma_f32_16x16x32_bf16 v[48:51], v[176:179], v[148:151], v[48:51]
	v_mfma_f32_16x16x32_bf16 v[52:55], v[176:179], v[156:159], v[52:55]
	v_mfma_f32_16x16x32_bf16 v[52:55], v[172:175], v[152:155], v[52:55]
	v_mfma_f32_16x16x32_bf16 v[44:47], v[180:183], v[152:155], v[44:47]
	v_mfma_f32_16x16x32_bf16 v[44:47], v[184:187], v[156:159], v[44:47]
	v_mfma_f32_16x16x32_bf16 v[40:43], v[184:187], v[148:151], v[40:43]
	v_mfma_f32_16x16x32_bf16 v[40:43], v[180:183], v[160:163], v[40:43]
	v_mfma_f32_16x16x32_bf16 v[32:35], v[188:191], v[160:163], v[32:35]
	v_mfma_f32_16x16x32_bf16 v[32:35], v[192:195], v[148:151], v[32:35]
	v_mfma_f32_16x16x32_bf16 v[36:39], v[192:195], v[156:159], v[36:39]
	v_mfma_f32_16x16x32_bf16 v[36:39], v[188:191], v[152:155], v[36:39]
	v_mfma_f32_16x16x32_bf16 v[4:7], v[188:191], v[196:199], v[4:7]
	v_mfma_f32_16x16x32_bf16 v[4:7], v[192:195], v[142:145], v[4:7]
	v_mfma_f32_16x16x32_bf16 v[28:31], v[168:171], v[142:145], v[28:31]
	v_mfma_f32_16x16x32_bf16 v[28:31], v[92:95], v[196:199], v[28:31]
	v_mfma_f32_16x16x32_bf16 v[24:27], v[92:95], v[200:203], v[24:27]
	v_mfma_f32_16x16x32_bf16 v[24:27], v[168:171], v[204:207], v[24:27]
	v_mfma_f32_16x16x32_bf16 v[16:19], v[176:179], v[204:207], v[16:19]
	v_mfma_f32_16x16x32_bf16 v[16:19], v[172:175], v[200:203], v[16:19]
	v_mfma_f32_16x16x32_bf16 v[20:23], v[172:175], v[196:199], v[20:23]
	v_mfma_f32_16x16x32_bf16 v[20:23], v[176:179], v[142:145], v[20:23]
	v_mfma_f32_16x16x32_bf16 v[12:15], v[184:187], v[142:145], v[12:15]
	v_mfma_f32_16x16x32_bf16 v[12:15], v[180:183], v[196:199], v[12:15]
	v_mfma_f32_16x16x32_bf16 v[8:11], v[180:183], v[200:203], v[8:11]
	v_mfma_f32_16x16x32_bf16 v[8:11], v[184:187], v[204:207], v[8:11]
	v_mfma_f32_16x16x32_bf16 v[0:3], v[192:195], v[204:207], v[0:3]
	v_mfma_f32_16x16x32_bf16 v[0:3], v[188:191], v[200:203], v[0:3]
	s_barrier
	ds_read_b128 v[142:145], v138
	ds_read_b128 v[146:149], v139
	ds_read_b128 v[150:153], v140
	ds_read_b128 v[138:141], v141
	ds_read_b128 v[154:157], v130 offset:32768
	ds_read_b128 v[158:161], v130 offset:33792
	ds_read_b128 v[168:171], v133 offset:32768
	ds_read_b128 v[172:175], v133 offset:33792
	ds_read_b128 v[176:179], v132 offset:32768
	ds_read_b128 v[180:183], v132 offset:33792
	ds_read_b128 v[184:187], v131 offset:32768
	ds_read_b128 v[188:191], v131 offset:33792
	s_waitcnt vmcnt(2)
	s_barrier
	s_waitcnt lgkmcnt(0)
	v_mfma_f32_16x16x32_bf16 v[92:95], v[154:157], v[142:145], v[124:127]
	v_mfma_f32_16x16x32_bf16 v[120:123], v[154:157], v[150:153], v[120:123]
	v_mfma_f32_16x16x32_bf16 v[116:119], v[168:171], v[142:145], v[116:119]
	v_mfma_f32_16x16x32_bf16 v[112:115], v[168:171], v[150:153], v[112:115]
	v_mfma_f32_16x16x32_bf16 v[108:111], v[176:179], v[142:145], v[108:111]
	v_mfma_f32_16x16x32_bf16 v[104:107], v[176:179], v[150:153], v[104:107]
	v_mfma_f32_16x16x32_bf16 v[100:103], v[184:187], v[142:145], v[100:103]
	v_mfma_f32_16x16x32_bf16 v[96:99], v[184:187], v[150:153], v[96:99]
	v_mfma_f32_16x16x32_bf16 v[124:127], v[158:161], v[146:149], v[92:95]
	v_mfma_f32_16x16x32_bf16 v[120:123], v[158:161], v[138:141], v[120:123]
	v_mfma_f32_16x16x32_bf16 v[116:119], v[172:175], v[146:149], v[116:119]
	v_mfma_f32_16x16x32_bf16 v[112:115], v[172:175], v[138:141], v[112:115]
	v_mfma_f32_16x16x32_bf16 v[108:111], v[180:183], v[146:149], v[108:111]
	v_mfma_f32_16x16x32_bf16 v[104:107], v[180:183], v[138:141], v[104:107]
	v_mfma_f32_16x16x32_bf16 v[100:103], v[188:191], v[146:149], v[100:103]
	v_mfma_f32_16x16x32_bf16 v[92:95], v[188:191], v[138:141], v[96:99]
	s_barrier
; #define LDA(dst, b, h) _Pragma("unroll") for (int m = 0; m < 4; ++m) _Pragma("unroll") for (int k = 0; k < 2; ++k) \
;     dst[m][k] = *reinterpret_cast<const bf16x8*>(SA(b, h) + lds_byte(wr * 64 + m * 16 + fr, k * 32 + fq * 8))
; #define LDB(dst, b, h) _Pragma("unroll") for (int n = 0; n < 2; ++n) _Pragma("unroll") for (int k = 0; k < 2; ++k) \
;     dst[n][k] = *reinterpret_cast<const bf16x8*>(SB(b, h) + lds_byte(wc * 32 + n * 16 + fr, k * 32 + fq * 8))
; #define WAIT_V(n) asm volatile("s_waitcnt vmcnt(" #n ")" ::: "memory")
; #define WAIT_L(n) asm volatile("s_waitcnt lgkmcnt(" #n ")" ::: "memory")
; #define BAR __builtin_amdgcn_s_barrier()
;     ...
;       LDB(B1, 1, 1); WAIT_V(0); BAR; WAIT_L(0); MMA(0, 1, At, B1); BAR;
;       LDA(At, 1, 1); BAR; WAIT_L(0); MMA(1, 0, At, B0); MMA(1, 1, At, B1); BAR; }
;     if (wr == 0) BAR;
	ds_read_b128 v[192:195], v134
	ds_read_b128 v[196:199], v135
	ds_read_b128 v[200:203], v136
	ds_read_b128 v[134:137], v137
	s_waitcnt vmcnt(0)
	s_barrier
	s_waitcnt lgkmcnt(0)
	v_mfma_f32_16x16x32_bf16 v[96:99], v[154:157], v[192:195], v[164:167]
	v_mfma_f32_16x16x32_bf16 v[88:91], v[154:157], v[200:203], v[88:91]
	v_mfma_f32_16x16x32_bf16 v[84:87], v[168:171], v[192:195], v[84:87]
	v_mfma_f32_16x16x32_bf16 v[80:83], v[168:171], v[200:203], v[80:83]
	v_mfma_f32_16x16x32_bf16 v[76:79], v[176:179], v[192:195], v[76:79]
	v_mfma_f32_16x16x32_bf16 v[72:75], v[176:179], v[200:203], v[72:75]
	v_mfma_f32_16x16x32_bf16 v[68:71], v[184:187], v[192:195], v[68:71]
	v_mfma_f32_16x16x32_bf16 v[64:67], v[184:187], v[200:203], v[64:67]
	v_mfma_f32_16x16x32_bf16 v[96:99], v[158:161], v[196:199], v[96:99]
	v_mfma_f32_16x16x32_bf16 v[88:91], v[158:161], v[134:137], v[88:91]
	v_mfma_f32_16x16x32_bf16 v[84:87], v[172:175], v[196:199], v[84:87]
	v_mfma_f32_16x16x32_bf16 v[80:83], v[172:175], v[134:137], v[80:83]
	v_mfma_f32_16x16x32_bf16 v[76:79], v[180:183], v[196:199], v[76:79]
	v_mfma_f32_16x16x32_bf16 v[72:75], v[180:183], v[134:137], v[72:75]
	v_mfma_f32_16x16x32_bf16 v[68:71], v[188:191], v[196:199], v[68:71]
	v_mfma_f32_16x16x32_bf16 v[64:67], v[188:191], v[134:137], v[64:67]
	s_barrier
	ds_read_b128 v[154:157], v130 offset:49152
	ds_read_b128 v[158:161], v130 offset:50176
	ds_read_b128 v[162:165], v133 offset:49152
	ds_read_b128 v[166:169], v133 offset:50176
	ds_read_b128 v[170:173], v132 offset:49152
	ds_read_b128 v[174:177], v132 offset:50176
	ds_read_b128 v[178:181], v131 offset:49152
	ds_read_b128 v[130:133], v131 offset:50176
	s_barrier
	s_waitcnt lgkmcnt(0)
	v_mfma_f32_16x16x32_bf16 v[60:63], v[154:157], v[142:145], v[60:63]
	v_mfma_f32_16x16x32_bf16 v[60:63], v[158:161], v[146:149], v[60:63]
	v_mfma_f32_16x16x32_bf16 v[56:59], v[158:161], v[138:141], v[56:59]
	v_mfma_f32_16x16x32_bf16 v[56:59], v[154:157], v[150:153], v[56:59]
	v_mfma_f32_16x16x32_bf16 v[48:51], v[162:165], v[150:153], v[48:51]
	v_mfma_f32_16x16x32_bf16 v[48:51], v[166:169], v[138:141], v[48:51]
	v_mfma_f32_16x16x32_bf16 v[52:55], v[166:169], v[146:149], v[52:55]
	v_mfma_f32_16x16x32_bf16 v[52:55], v[162:165], v[142:145], v[52:55]
	v_mfma_f32_16x16x32_bf16 v[44:47], v[170:173], v[142:145], v[44:47]
	v_mfma_f32_16x16x32_bf16 v[44:47], v[174:177], v[146:149], v[44:47]
	v_mfma_f32_16x16x32_bf16 v[40:43], v[174:177], v[138:141], v[40:43]
	v_mfma_f32_16x16x32_bf16 v[40:43], v[170:173], v[150:153], v[40:43]
	v_mfma_f32_16x16x32_bf16 v[32:35], v[178:181], v[150:153], v[32:35]
	v_mfma_f32_16x16x32_bf16 v[32:35], v[130:133], v[138:141], v[32:35]
	v_mfma_f32_16x16x32_bf16 v[36:39], v[130:133], v[146:149], v[36:39]
	v_mfma_f32_16x16x32_bf16 v[36:39], v[178:181], v[142:145], v[36:39]
	v_mfma_f32_16x16x32_bf16 v[4:7], v[178:181], v[192:195], v[4:7]
	v_mfma_f32_16x16x32_bf16 v[4:7], v[130:133], v[196:199], v[4:7]
	v_mfma_f32_16x16x32_bf16 v[28:31], v[158:161], v[196:199], v[28:31]
	v_mfma_f32_16x16x32_bf16 v[28:31], v[154:157], v[192:195], v[28:31]
	v_mfma_f32_16x16x32_bf16 v[24:27], v[154:157], v[200:203], v[24:27]
	v_mfma_f32_16x16x32_bf16 v[24:27], v[158:161], v[134:137], v[24:27]
	v_mfma_f32_16x16x32_bf16 v[16:19], v[166:169], v[134:137], v[16:19]
	v_mfma_f32_16x16x32_bf16 v[16:19], v[162:165], v[200:203], v[16:19]
	v_mfma_f32_16x16x32_bf16 v[20:23], v[162:165], v[192:195], v[20:23]
	v_mfma_f32_16x16x32_bf16 v[20:23], v[166:169], v[196:199], v[20:23]
	v_mfma_f32_16x16x32_bf16 v[12:15], v[174:177], v[196:199], v[12:15]
	v_mfma_f32_16x16x32_bf16 v[12:15], v[170:173], v[192:195], v[12:15]
	v_mfma_f32_16x16x32_bf16 v[8:11], v[170:173], v[200:203], v[8:11]
	v_mfma_f32_16x16x32_bf16 v[8:11], v[174:177], v[134:137], v[8:11]
	v_mfma_f32_16x16x32_bf16 v[0:3], v[130:133], v[134:137], v[0:3]
	v_mfma_f32_16x16x32_bf16 v[0:3], v[178:181], v[200:203], v[0:3]
	v_cmp_gt_u32_e32 vcc, s37, v129
	s_barrier
	s_and_saveexec_b64 s[16:17], vcc
	s_cbranch_execz .LBB0_228
	s_barrier

; #define STAGE(P, RS, SOFF, OFF, kt) do { const int _so = (SOFF) + (kt) * (BK * 2); \
;     _Pragma("unroll") for (int _i = 0; _i < 2; ++_i) { \
;       __builtin_amdgcn_raw_ptr_buffer_load_lds(RS, (__attribute__((address_space(3))) void*)((P) + wave * 1024 + _i * 8192), 16, OFF[_i], _so, 0, 0); } } while (0)
; #define LDA(dst, b, h) _Pragma("unroll") for (int m = 0; m < 4; ++m) _Pragma("unroll") for (int k = 0; k < 2; ++k) \
;     dst[m][k] = *reinterpret_cast<const bf16x8*>(SA(b, h) + lds_byte(wr * 64 + m * 16 + fr, k * 32 + fq * 8))
; #define LDB(dst, b, h) _Pragma("unroll") for (int n = 0; n < 2; ++n) _Pragma("unroll") for (int k = 0; k < 2; ++k) \
;     dst[n][k] = *reinterpret_cast<const bf16x8*>(SB(b, h) + lds_byte(wc * 32 + n * 16 + fr, k * 32 + fq * 8))
; #define WAIT_V(n) asm volatile("s_waitcnt vmcnt(" #n ")" ::: "memory")
; #define WAIT_L(n) asm volatile("s_waitcnt lgkmcnt(" #n ")" ::: "memory")
; #define BAR __builtin_amdgcn_s_barrier()
; #define SCHED __builtin_amdgcn_sched_barrier(0)
;     ...
;     const int tid = opaque_tid(wave);
;     const int wid = tid >> 6, lane = tid & 63, wr = wid >> 2, wc = wid & 3, fr = lane & 15, fq = lane >> 4;
;     int offA[2], offB[2];
;     _Pragma("unroll") for (int i = 0; i < 2; ++i) {
;       int r, c; stage_rc(tid * 16 + i * 8192, r, c);
;       offA[i] = (r * lda + c) * 2; offB[i] = (r * ldb + c) * 2;
;     }
;     const int brow = pm * BM;
;     f32x4 acc[2][2][4][2];
;     _Pragma("unroll") for (int a = 0; a < 2; ++a) _Pragma("unroll") for (int b = 0; b < 2; ++b) _Pragma("unroll") for (int m = 0; m < 4; ++m) _Pragma("unroll") for (int n = 0; n < 2; ++n)
;       acc[a][b][m][n] = f32x4{0.f, 0.f, 0.f, 0.f};
;     bf16x8 At[4][2], B0[2][2], B1[2][2];
;     if (wr == 1) BAR;
;     if (first_tile) { WAIT_V(0); }
;     else if constexpr (mode == MODE_RESID_LN) { WAIT_V(0); }
;     else if constexpr (mode == MODE_SWIGLU) { WAIT_V(6); }
;     else if constexpr (mode == MODE_V) { WAIT_V(24); }
;     else { WAIT_V(12); }
;     first_tile = false;
;     BAR;
;     BAR;
;     for (int t = 0; t < nt - 2; t += 2) {
;       LDB(B0, 0, 0); SCHED; LDA(At, 0, 0); STAGE(SA(1, 1), rsA, sA1, offA, t + 1);
;       WAIT_L(8); BAR; WAIT_L(0); MMA(0, 0, At, B0); BAR; SCHED;
;       LDB(B1, 0, 1); STAGE(SB(0, 0), rsB, sB0, offB, t + 2);
;       BAR; WAIT_L(0); MMA(0, 1, At, B1); BAR;
.LBB0_290:
	v_bfe_i32 v4, v128, 27, 1
	v_lshlrev_b32_e32 v2, 4, v128
	v_lshrrev_b32_e32 v4, 22, v4
	v_add_u32_e32 v4, v2, v4
	v_and_b32_e32 v4, 0xfffffc00, v4
	v_sub_u32_e32 v4, v2, v4
	v_lshrrev_b32_e32 v5, 4, v4
	v_bitop3_b32 v4, v5, v4, 32 bitop3:0x6c
	v_ashrrev_i32_e32 v3, 31, v128
	v_ashrrev_i32_e32 v6, 31, v4
	v_lshrrev_b32_e32 v3, 26, v3
	v_lshrrev_b32_e32 v6, 26, v6
	v_add_u32_e32 v3, v128, v3
	v_add_u32_e32 v6, v4, v6
	v_ashrrev_i32_e32 v3, 6, v3
	v_lshrrev_b32_e32 v7, 6, v6
	v_and_b32_e32 v6, 0xc0, v6
	v_lshlrev_b32_e32 v5, 3, v3
	v_lshlrev_b32_e32 v3, 5, v3
	v_sub_u32_e32 v4, v4, v6
	v_and_b32_e32 v5, 0x1ffff0, v5
	v_and_b32_e32 v3, 32, v3
	v_ashrrev_i16_sdwa v4, v216, sext(v4) dst_sel:DWORD dst_unused:UNUSED_PAD src0_sel:DWORD src1_sel:BYTE_0
	v_add_u32_sdwa v3, v3, sext(v4) dst_sel:DWORD dst_unused:UNUSED_PAD src0_sel:DWORD src1_sel:WORD_0
	v_add_lshl_u32 v4, v7, v5, 11
	v_add_u32_e32 v2, 0x2000, v2
	v_lshl_add_u32 v141, v3, 1, v4
	v_ashrrev_i32_e32 v3, 31, v2
	v_lshrrev_b32_e32 v3, 22, v3
	v_add_u32_e32 v3, v2, v3
	v_ashrrev_i32_e32 v3, 10, v3
	v_mul_i32_i24_e32 v4, 0x400, v3
	v_sub_u32_e32 v2, v2, v4
	v_lshrrev_b32_e32 v4, 4, v2
	v_bitop3_b32 v2, v4, v2, 32 bitop3:0x6c
	v_ashrrev_i32_e32 v5, 31, v2
	v_lshrrev_b32_e32 v5, 26, v5
	v_add_u32_e32 v5, v2, v5
	v_lshrrev_b32_e32 v6, 6, v5
	v_and_b32_e32 v5, 0xc0, v5
	v_lshlrev_b32_e32 v4, 3, v3
	v_lshlrev_b32_e32 v3, 5, v3
	v_sub_u32_e32 v2, v2, v5
	v_and_b32_e32 v4, 0x1ffff0, v4
	v_and_b32_e32 v3, 32, v3
	v_ashrrev_i16_sdwa v2, v216, sext(v2) dst_sel:DWORD dst_unused:UNUSED_PAD src0_sel:DWORD src1_sel:BYTE_0
	v_add_u32_sdwa v2, v3, sext(v2) dst_sel:DWORD dst_unused:UNUSED_PAD src0_sel:DWORD src1_sel:WORD_0
	v_add_lshl_u32 v3, v6, v4, 11
	v_lshl_add_u32 v142, v2, 1, v3
	v_and_b32_e32 v3, 15, v0
	v_lshlrev_b32_e32 v5, 2, v0
	v_and_b32_e32 v2, 48, v0
	v_lshlrev_b32_e32 v3, 6, v3
	v_and_b32_e32 v5, 32, v5
	v_or_b32_e32 v4, v3, v2
	v_bitop3_b32 v3, v3, v5, v2 bitop3:0x36
	v_lshlrev_b32_e32 v6, 6, v128
	s_movk_i32 s1, 0x3000
	v_and_or_b32 v3, v6, s1, v3
	v_lshlrev_b32_e32 v0, 6, v0
	s_movk_i32 s1, 0x3c0
	v_lshlrev_b32_e32 v1, 13, v1
	v_and_or_b32 v0, v0, s1, v2
	v_bitop3_b32 v0, v1, v0, v5 bitop3:0xf6
	v_or_b32_e32 v6, 0x400, v3
	v_or_b32_e32 v7, 0x800, v3
	v_or_b32_e32 v8, 0xc00, v3
	v_or_b32_e32 v132, 0x800, v0
	v_or_b32_e32 v131, 0x1000, v0
	v_or_b32_e32 v130, 0x1800, v0
	v_mov_b32_e32 v0, 0
	v_bitop3_b32 v129, v4, v1, v5 bitop3:0xde
	s_mov_b32 s1, -2
	s_mov_b32 s3, 0
	v_or_b32_e32 v147, 0x10000, v3
	v_or_b32_e32 v148, 0x10000, v6
	v_or_b32_e32 v149, 0x10000, v7
	v_or_b32_e32 v150, 0x10000, v8
	v_or_b32_e32 v143, 0x14000, v3
	v_or_b32_e32 v144, 0x14000, v6
	v_or_b32_e32 v145, 0x14000, v7
	v_or_b32_e32 v146, 0x14000, v8
	v_or_b32_e32 v137, 0x18000, v3
	v_or_b32_e32 v138, 0x18000, v6
	v_or_b32_e32 v139, 0x18000, v7
	v_or_b32_e32 v140, 0x18000, v8
	v_or_b32_e32 v133, 0x1c000, v3
	v_or_b32_e32 v134, 0x1c000, v6
	v_or_b32_e32 v135, 0x1c000, v7
	v_or_b32_e32 v136, 0x1c000, v8
	s_barrier
	s_barrier
	ds_read_b128 v[152:155], v147
	ds_read_b128 v[156:159], v148
	ds_read_b128 v[160:163], v149
	ds_read_b128 v[164:167], v150
	s_add_i32 s5, s94, s3
	s_add_i32 s6, s5, 0x80
	s_mov_b32 m0, s36
	ds_read_b128 v[168:171], v129
	ds_read_b128 v[172:175], v129 offset:1024
	ds_read_b128 v[176:179], v132
	ds_read_b128 v[180:183], v132 offset:1024
	ds_read_b128 v[184:187], v131
	ds_read_b128 v[188:191], v131 offset:1024
	ds_read_b128 v[192:195], v130
	ds_read_b128 v[196:199], v130 offset:1024
	buffer_load_dwordx4 v141, s[8:11], s6 offen lds
	s_mov_b32 m0, s61
	s_nop 0
	buffer_load_dwordx4 v142, s[8:11], s6 offen lds
	s_waitcnt lgkmcnt(8)
	s_barrier
	s_waitcnt lgkmcnt(0)
	v_mfma_f32_16x16x32_bf16 v[124:127], v[152:155], v[168:171], 0
	v_mfma_f32_16x16x32_bf16 v[124:127], v[156:159], v[172:175], v[124:127]
	v_mfma_f32_16x16x32_bf16 v[120:123], v[164:167], v[172:175], 0
	v_mfma_f32_16x16x32_bf16 v[120:123], v[160:163], v[168:171], v[120:123]
	v_mfma_f32_16x16x32_bf16 v[112:115], v[160:163], v[176:179], 0
	v_mfma_f32_16x16x32_bf16 v[112:115], v[164:167], v[180:183], v[112:115]
	v_mfma_f32_16x16x32_bf16 v[116:119], v[156:159], v[180:183], 0
	v_mfma_f32_16x16x32_bf16 v[116:119], v[152:155], v[176:179], v[116:119]
	v_mfma_f32_16x16x32_bf16 v[108:111], v[152:155], v[184:187], 0
	v_mfma_f32_16x16x32_bf16 v[108:111], v[156:159], v[188:191], v[108:111]
	v_mfma_f32_16x16x32_bf16 v[104:107], v[164:167], v[188:191], 0
	v_mfma_f32_16x16x32_bf16 v[104:107], v[160:163], v[184:187], v[104:107]
	v_mfma_f32_16x16x32_bf16 v[96:99], v[160:163], v[192:195], 0
	v_mfma_f32_16x16x32_bf16 v[96:99], v[164:167], v[196:199], v[96:99]
	v_mfma_f32_16x16x32_bf16 v[100:103], v[156:159], v[196:199], 0
	v_mfma_f32_16x16x32_bf16 v[100:103], v[152:155], v[192:195], v[100:103]
	s_barrier
	s_add_i32 s6, s96, s3
	s_add_i32 s7, s6, 0x100
	s_mov_b32 s14, s10
	s_mov_b32 s15, s11
	s_mov_b32 m0, s37
	ds_read_b128 v[200:203], v143
	ds_read_b128 v[204:207], v144
	ds_read_b128 v[208:211], v145
	ds_read_b128 v[212:215], v146
	buffer_load_dwordx4 v141, s[12:15], s7 offen lds
	s_mov_b32 m0, s48
	s_nop 0
	buffer_load_dwordx4 v142, s[12:15], s7 offen lds
	s_barrier
; #define STAGE(P, RS, SOFF, OFF, kt) do { const int _so = (SOFF) + (kt) * (BK * 2); \
;     _Pragma("unroll") for (int _i = 0; _i < 2; ++_i) { \
;       __builtin_amdgcn_raw_ptr_buffer_load_lds(RS, (__attribute__((address_space(3))) void*)((P) + wave * 1024 + _i * 8192), 16, OFF[_i], _so, 0, 0); } } while (0)
; #define LDA(dst, b, h) _Pragma("unroll") for (int m = 0; m < 4; ++m) _Pragma("unroll") for (int k = 0; k < 2; ++k) \
;     dst[m][k] = *reinterpret_cast<const bf16x8*>(SA(b, h) + lds_byte(wr * 64 + m * 16 + fr, k * 32 + fq * 8))
; #define LDB(dst, b, h) _Pragma("unroll") for (int n = 0; n < 2; ++n) _Pragma("unroll") for (int k = 0; k < 2; ++k) \
;     dst[n][k] = *reinterpret_cast<const bf16x8*>(SB(b, h) + lds_byte(wc * 32 + n * 16 + fr, k * 32 + fq * 8))
; #define WAIT_V(n) asm volatile("s_waitcnt vmcnt(" #n ")" ::: "memory")
; #define WAIT_L(n) asm volatile("s_waitcnt lgkmcnt(" #n ")" ::: "memory")
; #define BAR __builtin_amdgcn_s_barrier()
; #define SCHED __builtin_amdgcn_sched_barrier(0)
;     ...
;       BAR; WAIT_L(0); MMA(0, 1, At, B1); BAR;
;       LDA(At, 0, 1); STAGE(SA(0, 0), rsA, sA0, offA, t + 2);
;       BAR; WAIT_L(0); MMA(1, 0, At, B0); BAR; SCHED;
;       STAGE(SB(0, 1), rsB, sB1, offB, t + 2);
;       WAIT_V(6); BAR; MMA(1, 1, At, B1); BAR;
;       LDB(B0, 1, 0); SCHED; LDA(At, 1, 0); STAGE(SA(0, 1), rsA, sA1, offA, t + 2);
;       WAIT_L(8); BAR; WAIT_L(0); MMA(0, 0, At, B0); BAR; SCHED;
	s_waitcnt lgkmcnt(0)
	v_mfma_f32_16x16x32_bf16 v[92:95], v[200:203], v[168:171], 0
	v_mfma_f32_16x16x32_bf16 v[92:95], v[204:207], v[172:175], v[92:95]
	v_mfma_f32_16x16x32_bf16 v[88:91], v[212:215], v[172:175], 0
	v_mfma_f32_16x16x32_bf16 v[88:91], v[208:211], v[168:171], v[88:91]
	v_mfma_f32_16x16x32_bf16 v[68:71], v[208:211], v[176:179], 0
	v_mfma_f32_16x16x32_bf16 v[68:71], v[212:215], v[180:183], v[68:71]
	v_mfma_f32_16x16x32_bf16 v[80:83], v[204:207], v[180:183], 0
	v_mfma_f32_16x16x32_bf16 v[80:83], v[200:203], v[176:179], v[80:83]
	v_mfma_f32_16x16x32_bf16 v[60:63], v[200:203], v[184:187], 0
	v_mfma_f32_16x16x32_bf16 v[60:63], v[204:207], v[188:191], v[60:63]
	v_mfma_f32_16x16x32_bf16 v[56:59], v[212:215], v[188:191], 0
	v_mfma_f32_16x16x32_bf16 v[56:59], v[208:211], v[184:187], v[56:59]
	v_mfma_f32_16x16x32_bf16 v[48:51], v[208:211], v[192:195], 0
	v_mfma_f32_16x16x32_bf16 v[48:51], v[212:215], v[196:199], v[48:51]
	v_mfma_f32_16x16x32_bf16 v[52:55], v[204:207], v[196:199], 0
	v_mfma_f32_16x16x32_bf16 v[52:55], v[200:203], v[192:195], v[52:55]
	s_barrier
	s_add_i32 s7, s95, s3
	s_add_i32 s22, s7, 0x100
	s_mov_b32 m0, s35
	ds_read_b128 v[168:171], v129 offset:16384
	ds_read_b128 v[172:175], v129 offset:17408
	ds_read_b128 v[176:179], v132 offset:16384
	ds_read_b128 v[180:183], v132 offset:17408
	ds_read_b128 v[184:187], v131 offset:16384
	ds_read_b128 v[188:191], v131 offset:17408
	ds_read_b128 v[192:195], v130 offset:16384
	ds_read_b128 v[196:199], v130 offset:17408
	buffer_load_dwordx4 v141, s[8:11], s22 offen lds
	s_mov_b32 m0, s49
	s_nop 0
	buffer_load_dwordx4 v142, s[8:11], s22 offen lds
	s_barrier
	s_waitcnt lgkmcnt(0)
	v_mfma_f32_16x16x32_bf16 v[44:47], v[152:155], v[168:171], 0
	v_mfma_f32_16x16x32_bf16 v[44:47], v[156:159], v[172:175], v[44:47]
	v_mfma_f32_16x16x32_bf16 v[40:43], v[164:167], v[172:175], 0
	v_mfma_f32_16x16x32_bf16 v[40:43], v[160:163], v[168:171], v[40:43]
	v_mfma_f32_16x16x32_bf16 v[32:35], v[160:163], v[176:179], 0
	v_mfma_f32_16x16x32_bf16 v[32:35], v[164:167], v[180:183], v[32:35]
	v_mfma_f32_16x16x32_bf16 v[36:39], v[156:159], v[180:183], 0
	v_mfma_f32_16x16x32_bf16 v[36:39], v[152:155], v[176:179], v[36:39]
	v_mfma_f32_16x16x32_bf16 v[28:31], v[152:155], v[184:187], 0
	v_mfma_f32_16x16x32_bf16 v[28:31], v[156:159], v[188:191], v[28:31]
	v_mfma_f32_16x16x32_bf16 v[24:27], v[164:167], v[188:191], 0
	v_mfma_f32_16x16x32_bf16 v[24:27], v[160:163], v[184:187], v[24:27]
	v_mfma_f32_16x16x32_bf16 v[16:19], v[160:163], v[192:195], 0
	v_mfma_f32_16x16x32_bf16 v[16:19], v[164:167], v[196:199], v[16:19]
	v_mfma_f32_16x16x32_bf16 v[20:23], v[156:159], v[196:199], 0
	v_mfma_f32_16x16x32_bf16 v[20:23], v[152:155], v[192:195], v[20:23]
	s_barrier
	s_add_i32 s22, s97, s3
	s_add_i32 s23, s22, 0x100
	s_mov_b32 m0, s38
	s_nop 0
	buffer_load_dwordx4 v141, s[12:15], s23 offen lds
	s_mov_b32 m0, s54
	s_nop 0
	buffer_load_dwordx4 v142, s[12:15], s23 offen lds
	s_waitcnt vmcnt(6)
	s_barrier
	v_mfma_f32_16x16x32_bf16 v[12:15], v[200:203], v[168:171], 0
	v_mfma_f32_16x16x32_bf16 v[12:15], v[204:207], v[172:175], v[12:15]
	v_mfma_f32_16x16x32_bf16 v[8:11], v[212:215], v[172:175], 0
	v_mfma_f32_16x16x32_bf16 v[8:11], v[208:211], v[168:171], v[8:11]
	v_mfma_f32_16x16x32_bf16 v[0:3], v[208:211], v[176:179], 0
	v_mfma_f32_16x16x32_bf16 v[0:3], v[212:215], v[180:183], v[0:3]
	v_mfma_f32_16x16x32_bf16 v[4:7], v[204:207], v[180:183], 0
	v_mfma_f32_16x16x32_bf16 v[4:7], v[200:203], v[176:179], v[4:7]
	v_mfma_f32_16x16x32_bf16 v[64:67], v[200:203], v[184:187], 0
	v_mfma_f32_16x16x32_bf16 v[64:67], v[204:207], v[188:191], v[64:67]
	v_mfma_f32_16x16x32_bf16 v[72:75], v[212:215], v[188:191], 0
	v_mfma_f32_16x16x32_bf16 v[72:75], v[208:211], v[184:187], v[72:75]
	v_mfma_f32_16x16x32_bf16 v[84:87], v[208:211], v[192:195], 0
	v_mfma_f32_16x16x32_bf16 v[84:87], v[212:215], v[196:199], v[84:87]
	v_mfma_f32_16x16x32_bf16 v[76:79], v[204:207], v[196:199], 0
	v_mfma_f32_16x16x32_bf16 v[76:79], v[200:203], v[192:195], v[76:79]
	s_barrier
	ds_read_b128 v[152:155], v137
	ds_read_b128 v[156:159], v138
	ds_read_b128 v[160:163], v139
	ds_read_b128 v[164:167], v140
	s_addk_i32 s5, 0x100
	s_mov_b32 m0, s39
	ds_read_b128 v[168:171], v129 offset:32768
	ds_read_b128 v[172:175], v129 offset:33792
	ds_read_b128 v[176:179], v132 offset:32768
	ds_read_b128 v[180:183], v132 offset:33792
	ds_read_b128 v[184:187], v131 offset:32768
	ds_read_b128 v[188:191], v131 offset:33792
	ds_read_b128 v[192:195], v130 offset:32768
	ds_read_b128 v[196:199], v130 offset:33792
	buffer_load_dwordx4 v141, s[8:11], s5 offen lds
	s_mov_b32 m0, s55
	s_nop 0
	buffer_load_dwordx4 v142, s[8:11], s5 offen lds
	s_waitcnt lgkmcnt(8)
	s_barrier
; #define STAGE(P, RS, SOFF, OFF, kt) do { const int _so = (SOFF) + (kt) * (BK * 2); \
;     _Pragma("unroll") for (int _i = 0; _i < 2; ++_i) { \
;       __builtin_amdgcn_raw_ptr_buffer_load_lds(RS, (__attribute__((address_space(3))) void*)((P) + wave * 1024 + _i * 8192), 16, OFF[_i], _so, 0, 0); } } while (0)
; #define LDA(dst, b, h) _Pragma("unroll") for (int m = 0; m < 4; ++m) _Pragma("unroll") for (int k = 0; k < 2; ++k) \
;     dst[m][k] = *reinterpret_cast<const bf16x8*>(SA(b, h) + lds_byte(wr * 64 + m * 16 + fr, k * 32 + fq * 8))
; #define LDB(dst, b, h) _Pragma("unroll") for (int n = 0; n < 2; ++n) _Pragma("unroll") for (int k = 0; k < 2; ++k) \
;     dst[n][k] = *reinterpret_cast<const bf16x8*>(SB(b, h) + lds_byte(wc * 32 + n * 16 + fr, k * 32 + fq * 8))
; #define WAIT_V(n) asm volatile("s_waitcnt vmcnt(" #n ")" ::: "memory")
; #define WAIT_L(n) asm volatile("s_waitcnt lgkmcnt(" #n ")" ::: "memory")
; #define BAR __builtin_amdgcn_s_barrier()
; #define SCHED __builtin_amdgcn_sched_barrier(0)
;     ...
;       WAIT_L(8); BAR; WAIT_L(0); MMA(0, 0, At, B0); BAR; SCHED;
;       LDB(B1, 1, 1); STAGE(SB(1, 0), rsB, sB0, offB, t + 3);
;       BAR; WAIT_L(0); MMA(0, 1, At, B1); BAR;
;       LDA(At, 1, 1); STAGE(SA(1, 0), rsA, sA0, offA, t + 3);
;       BAR; WAIT_L(0); MMA(1, 0, At, B0); BAR; SCHED;
;       STAGE(SB(1, 1), rsB, sB1, offB, t + 3);
;       WAIT_V(6); BAR; MMA(1, 1, At, B1); BAR;
;     }
	s_waitcnt lgkmcnt(0)
	v_mfma_f32_16x16x32_bf16 v[124:127], v[152:155], v[168:171], v[124:127]
	v_mfma_f32_16x16x32_bf16 v[124:127], v[156:159], v[172:175], v[124:127]
	v_mfma_f32_16x16x32_bf16 v[120:123], v[164:167], v[172:175], v[120:123]
	v_mfma_f32_16x16x32_bf16 v[120:123], v[160:163], v[168:171], v[120:123]
	v_mfma_f32_16x16x32_bf16 v[112:115], v[160:163], v[176:179], v[112:115]
	v_mfma_f32_16x16x32_bf16 v[112:115], v[164:167], v[180:183], v[112:115]
	v_mfma_f32_16x16x32_bf16 v[116:119], v[156:159], v[180:183], v[116:119]
	v_mfma_f32_16x16x32_bf16 v[116:119], v[152:155], v[176:179], v[116:119]
	v_mfma_f32_16x16x32_bf16 v[108:111], v[152:155], v[184:187], v[108:111]
	v_mfma_f32_16x16x32_bf16 v[108:111], v[156:159], v[188:191], v[108:111]
	v_mfma_f32_16x16x32_bf16 v[104:107], v[164:167], v[188:191], v[104:107]
	v_mfma_f32_16x16x32_bf16 v[104:107], v[160:163], v[184:187], v[104:107]
	v_mfma_f32_16x16x32_bf16 v[96:99], v[160:163], v[192:195], v[96:99]
	v_mfma_f32_16x16x32_bf16 v[96:99], v[164:167], v[196:199], v[96:99]
	v_mfma_f32_16x16x32_bf16 v[100:103], v[156:159], v[196:199], v[100:103]
	v_mfma_f32_16x16x32_bf16 v[100:103], v[152:155], v[192:195], v[100:103]
	s_barrier
	s_addk_i32 s6, 0x180
	s_mov_b32 m0, s42
	ds_read_b128 v[200:203], v133
	ds_read_b128 v[204:207], v134
	ds_read_b128 v[208:211], v135
	ds_read_b128 v[212:215], v136
	buffer_load_dwordx4 v141, s[12:15], s6 offen lds
	s_mov_b32 m0, s58
	s_nop 0
	buffer_load_dwordx4 v142, s[12:15], s6 offen lds
	s_barrier
	s_waitcnt lgkmcnt(0)
	v_mfma_f32_16x16x32_bf16 v[92:95], v[200:203], v[168:171], v[92:95]
	v_mfma_f32_16x16x32_bf16 v[92:95], v[204:207], v[172:175], v[92:95]
	v_mfma_f32_16x16x32_bf16 v[88:91], v[212:215], v[172:175], v[88:91]
	v_mfma_f32_16x16x32_bf16 v[88:91], v[208:211], v[168:171], v[88:91]
	v_mfma_f32_16x16x32_bf16 v[68:71], v[208:211], v[176:179], v[68:71]
	v_mfma_f32_16x16x32_bf16 v[68:71], v[212:215], v[180:183], v[68:71]
	v_mfma_f32_16x16x32_bf16 v[80:83], v[204:207], v[180:183], v[80:83]
	v_mfma_f32_16x16x32_bf16 v[80:83], v[200:203], v[176:179], v[80:83]
	v_mfma_f32_16x16x32_bf16 v[60:63], v[200:203], v[184:187], v[60:63]
	v_mfma_f32_16x16x32_bf16 v[60:63], v[204:207], v[188:191], v[60:63]
	v_mfma_f32_16x16x32_bf16 v[56:59], v[212:215], v[188:191], v[56:59]
	v_mfma_f32_16x16x32_bf16 v[56:59], v[208:211], v[184:187], v[56:59]
	v_mfma_f32_16x16x32_bf16 v[48:51], v[208:211], v[192:195], v[48:51]
	v_mfma_f32_16x16x32_bf16 v[48:51], v[212:215], v[196:199], v[48:51]
	v_mfma_f32_16x16x32_bf16 v[52:55], v[204:207], v[196:199], v[52:55]
	v_mfma_f32_16x16x32_bf16 v[52:55], v[200:203], v[192:195], v[52:55]
	s_barrier
	s_addk_i32 s7, 0x180
	s_mov_b32 m0, s43
	ds_read_b128 v[168:171], v129 offset:49152
	ds_read_b128 v[172:175], v129 offset:50176
	ds_read_b128 v[176:179], v132 offset:49152
	ds_read_b128 v[180:183], v132 offset:50176
	ds_read_b128 v[184:187], v131 offset:49152
	ds_read_b128 v[188:191], v131 offset:50176
	ds_read_b128 v[192:195], v130 offset:49152
	ds_read_b128 v[196:199], v130 offset:50176
	buffer_load_dwordx4 v141, s[8:11], s7 offen lds
	s_mov_b32 m0, s59
	s_nop 0
	buffer_load_dwordx4 v142, s[8:11], s7 offen lds
	s_barrier
	s_waitcnt lgkmcnt(0)
	v_mfma_f32_16x16x32_bf16 v[44:47], v[152:155], v[168:171], v[44:47]
	v_mfma_f32_16x16x32_bf16 v[44:47], v[156:159], v[172:175], v[44:47]
	v_mfma_f32_16x16x32_bf16 v[40:43], v[164:167], v[172:175], v[40:43]
	v_mfma_f32_16x16x32_bf16 v[40:43], v[160:163], v[168:171], v[40:43]
	v_mfma_f32_16x16x32_bf16 v[32:35], v[160:163], v[176:179], v[32:35]
	v_mfma_f32_16x16x32_bf16 v[32:35], v[164:167], v[180:183], v[32:35]
	v_mfma_f32_16x16x32_bf16 v[36:39], v[156:159], v[180:183], v[36:39]
	v_mfma_f32_16x16x32_bf16 v[36:39], v[152:155], v[176:179], v[36:39]
	v_mfma_f32_16x16x32_bf16 v[28:31], v[152:155], v[184:187], v[28:31]
	v_mfma_f32_16x16x32_bf16 v[28:31], v[156:159], v[188:191], v[28:31]
	v_mfma_f32_16x16x32_bf16 v[24:27], v[164:167], v[188:191], v[24:27]
	v_mfma_f32_16x16x32_bf16 v[24:27], v[160:163], v[184:187], v[24:27]
	v_mfma_f32_16x16x32_bf16 v[16:19], v[160:163], v[192:195], v[16:19]
	v_mfma_f32_16x16x32_bf16 v[16:19], v[164:167], v[196:199], v[16:19]
	v_mfma_f32_16x16x32_bf16 v[20:23], v[156:159], v[196:199], v[20:23]
	v_mfma_f32_16x16x32_bf16 v[20:23], v[152:155], v[192:195], v[20:23]
	s_barrier
	s_addk_i32 s22, 0x180
	s_mov_b32 m0, s44
	s_nop 0
	buffer_load_dwordx4 v141, s[12:15], s22 offen lds
	s_mov_b32 m0, s60
	s_nop 0
	buffer_load_dwordx4 v142, s[12:15], s22 offen lds
	s_add_i32 s1, s1, 2
	s_addk_i32 s3, 0x100
	s_cmp_gt_u32 s1, 11
	s_cbranch_scc0 .LBB0_291
	s_branch .Lmy_post_291

; #define STAGE(P, RS, SOFF, OFF, kt) do { const int _so = (SOFF) + (kt) * (BK * 2); \
;     _Pragma("unroll") for (int _i = 0; _i < 2; ++_i) { \
;       __builtin_amdgcn_raw_ptr_buffer_load_lds(RS, (__attribute__((address_space(3))) void*)((P) + wave * 1024 + _i * 8192), 16, OFF[_i], _so, 0, 0); } } while (0)
; #define LDA(dst, b, h) _Pragma("unroll") for (int m = 0; m < 4; ++m) _Pragma("unroll") for (int k = 0; k < 2; ++k) \
;     dst[m][k] = *reinterpret_cast<const bf16x8*>(SA(b, h) + lds_byte(wr * 64 + m * 16 + fr, k * 32 + fq * 8))
; #define LDB(dst, b, h) _Pragma("unroll") for (int n = 0; n < 2; ++n) _Pragma("unroll") for (int k = 0; k < 2; ++k) \
;     dst[n][k] = *reinterpret_cast<const bf16x8*>(SB(b, h) + lds_byte(wc * 32 + n * 16 + fr, k * 32 + fq * 8))
; #define WAIT_V(n) asm volatile("s_waitcnt vmcnt(" #n ")" ::: "memory")
; #define WAIT_L(n) asm volatile("s_waitcnt lgkmcnt(" #n ")" ::: "memory")
; #define BAR __builtin_amdgcn_s_barrier()
;     ...
;       WAIT_V(6); BAR; MMA(1, 1, At, B1); BAR;
;     }
;     { LDB(B0, 0, 0); LDA(At, 0, 0); STAGE(SA(1, 1), rsA, sA1, offA, nt - 1);
;       BAR; WAIT_L(0); MMA(0, 0, At, B0); BAR;
;       LDB(B1, 0, 1); BAR; WAIT_L(0); MMA(0, 1, At, B1); BAR;
;       LDA(At, 0, 1); WAIT_V(4); BAR; WAIT_L(0); MMA(1, 0, At, B0); MMA(1, 1, At, B1); BAR; }
.Lmy_post_291:
	s_waitcnt vmcnt(6)
	s_barrier
	v_mfma_f32_16x16x32_bf16 v[12:15], v[200:203], v[168:171], v[12:15]
	v_mfma_f32_16x16x32_bf16 v[12:15], v[204:207], v[172:175], v[12:15]
	v_mfma_f32_16x16x32_bf16 v[8:11], v[212:215], v[172:175], v[8:11]
	v_mfma_f32_16x16x32_bf16 v[8:11], v[208:211], v[168:171], v[8:11]
	v_mfma_f32_16x16x32_bf16 v[0:3], v[208:211], v[176:179], v[0:3]
	v_mfma_f32_16x16x32_bf16 v[0:3], v[212:215], v[180:183], v[0:3]
	v_mfma_f32_16x16x32_bf16 v[4:7], v[204:207], v[180:183], v[4:7]
	v_mfma_f32_16x16x32_bf16 v[4:7], v[200:203], v[176:179], v[4:7]
	v_mfma_f32_16x16x32_bf16 v[64:67], v[200:203], v[184:187], v[64:67]
	v_mfma_f32_16x16x32_bf16 v[64:67], v[204:207], v[188:191], v[64:67]
	v_mfma_f32_16x16x32_bf16 v[72:75], v[212:215], v[188:191], v[72:75]
	v_mfma_f32_16x16x32_bf16 v[72:75], v[208:211], v[184:187], v[72:75]
	v_mfma_f32_16x16x32_bf16 v[84:87], v[208:211], v[192:195], v[84:87]
	v_mfma_f32_16x16x32_bf16 v[84:87], v[212:215], v[196:199], v[84:87]
	v_mfma_f32_16x16x32_bf16 v[76:79], v[204:207], v[196:199], v[76:79]
	v_mfma_f32_16x16x32_bf16 v[76:79], v[200:203], v[192:195], v[76:79]
	s_barrier
	s_add_i32 s1, s94, 0x780
	s_mov_b32 m0, s36
	ds_read_b128 v[152:155], v147
	ds_read_b128 v[156:159], v148
	ds_read_b128 v[160:163], v149
	ds_read_b128 v[148:151], v150
	ds_read_b128 v[164:167], v129
	ds_read_b128 v[168:171], v129 offset:1024
	ds_read_b128 v[172:175], v132
	ds_read_b128 v[176:179], v132 offset:1024
	ds_read_b128 v[180:183], v131
	ds_read_b128 v[184:187], v131 offset:1024
	ds_read_b128 v[188:191], v130
	ds_read_b128 v[192:195], v130 offset:1024
	buffer_load_dwordx4 v141, s[8:11], s1 offen lds
	s_mov_b32 m0, s61
	s_nop 0
	buffer_load_dwordx4 v142, s[8:11], s1 offen lds
	s_barrier
	s_waitcnt lgkmcnt(0)
	v_mfma_f32_16x16x32_bf16 v[124:127], v[152:155], v[164:167], v[124:127]
	v_mfma_f32_16x16x32_bf16 v[124:127], v[156:159], v[168:171], v[124:127]
	v_mfma_f32_16x16x32_bf16 v[120:123], v[148:151], v[168:171], v[120:123]
	v_mfma_f32_16x16x32_bf16 v[120:123], v[160:163], v[164:167], v[120:123]
	v_mfma_f32_16x16x32_bf16 v[112:115], v[160:163], v[172:175], v[112:115]
	v_mfma_f32_16x16x32_bf16 v[112:115], v[148:151], v[176:179], v[112:115]
	v_mfma_f32_16x16x32_bf16 v[116:119], v[156:159], v[176:179], v[116:119]
	v_mfma_f32_16x16x32_bf16 v[116:119], v[152:155], v[172:175], v[116:119]
	v_mfma_f32_16x16x32_bf16 v[108:111], v[152:155], v[180:183], v[108:111]
	v_mfma_f32_16x16x32_bf16 v[108:111], v[156:159], v[184:187], v[108:111]
	v_mfma_f32_16x16x32_bf16 v[104:107], v[148:151], v[184:187], v[104:107]
	v_mfma_f32_16x16x32_bf16 v[104:107], v[160:163], v[180:183], v[104:107]
	v_mfma_f32_16x16x32_bf16 v[96:99], v[160:163], v[188:191], v[96:99]
	v_mfma_f32_16x16x32_bf16 v[96:99], v[148:151], v[192:195], v[96:99]
	v_mfma_f32_16x16x32_bf16 v[100:103], v[156:159], v[192:195], v[100:103]
	v_mfma_f32_16x16x32_bf16 v[100:103], v[152:155], v[188:191], v[100:103]
	s_barrier
	ds_read_b128 v[196:199], v143
	ds_read_b128 v[200:203], v144
	ds_read_b128 v[142:145], v145
	ds_read_b128 v[204:207], v146
	s_barrier
	s_waitcnt lgkmcnt(0)
	v_mfma_f32_16x16x32_bf16 v[88:91], v[142:145], v[164:167], v[88:91]
	v_mfma_f32_16x16x32_bf16 v[80:83], v[196:199], v[172:175], v[80:83]
	v_mfma_f32_16x16x32_bf16 v[60:63], v[196:199], v[180:183], v[60:63]
	v_mfma_f32_16x16x32_bf16 v[56:59], v[142:145], v[180:183], v[56:59]
	v_mfma_f32_16x16x32_bf16 v[52:55], v[196:199], v[188:191], v[52:55]
	v_mfma_f32_16x16x32_bf16 v[48:51], v[142:145], v[188:191], v[48:51]
	v_mfma_f32_16x16x32_bf16 v[92:95], v[196:199], v[164:167], v[92:95]
	v_mfma_f32_16x16x32_bf16 v[68:71], v[142:145], v[172:175], v[68:71]
	v_mfma_f32_16x16x32_bf16 v[88:91], v[204:207], v[168:171], v[88:91]
	v_mfma_f32_16x16x32_bf16 v[80:83], v[200:203], v[176:179], v[80:83]
	v_mfma_f32_16x16x32_bf16 v[60:63], v[200:203], v[184:187], v[60:63]
	v_mfma_f32_16x16x32_bf16 v[56:59], v[204:207], v[184:187], v[56:59]
	v_mfma_f32_16x16x32_bf16 v[52:55], v[200:203], v[192:195], v[52:55]
	v_mfma_f32_16x16x32_bf16 v[48:51], v[204:207], v[192:195], v[48:51]
	v_mfma_f32_16x16x32_bf16 v[164:167], v[200:203], v[168:171], v[92:95]
	v_mfma_f32_16x16x32_bf16 v[168:171], v[204:207], v[176:179], v[68:71]
	s_barrier
	s_nop 0
	ds_read_b128 v[68:71], v129 offset:16384
	ds_read_b128 v[92:95], v129 offset:17408
	ds_read_b128 v[172:175], v132 offset:16384
	ds_read_b128 v[176:179], v132 offset:17408
	ds_read_b128 v[180:183], v131 offset:16384
	ds_read_b128 v[184:187], v131 offset:17408
	ds_read_b128 v[188:191], v130 offset:16384
	ds_read_b128 v[192:195], v130 offset:17408
	s_waitcnt vmcnt(4)
	s_barrier
; #define LDA(dst, b, h) _Pragma("unroll") for (int m = 0; m < 4; ++m) _Pragma("unroll") for (int k = 0; k < 2; ++k) \
;     dst[m][k] = *reinterpret_cast<const bf16x8*>(SA(b, h) + lds_byte(wr * 64 + m * 16 + fr, k * 32 + fq * 8))
; #define LDB(dst, b, h) _Pragma("unroll") for (int n = 0; n < 2; ++n) _Pragma("unroll") for (int k = 0; k < 2; ++k) \
;     dst[n][k] = *reinterpret_cast<const bf16x8*>(SB(b, h) + lds_byte(wc * 32 + n * 16 + fr, k * 32 + fq * 8))
; #define WAIT_V(n) asm volatile("s_waitcnt vmcnt(" #n ")" ::: "memory")
; #define WAIT_L(n) asm volatile("s_waitcnt lgkmcnt(" #n ")" ::: "memory")
; #define BAR __builtin_amdgcn_s_barrier()
;     ...
;       LDA(At, 0, 1); WAIT_V(4); BAR; WAIT_L(0); MMA(1, 0, At, B0); MMA(1, 1, At, B1); BAR; }
;     { LDB(B0, 1, 0); LDA(At, 1, 0); WAIT_V(2); BAR; WAIT_L(0); MMA(0, 0, At, B0); BAR;
	s_waitcnt lgkmcnt(0)
	v_mfma_f32_16x16x32_bf16 v[44:47], v[152:155], v[68:71], v[44:47]
	v_mfma_f32_16x16x32_bf16 v[40:43], v[160:163], v[68:71], v[40:43]
	v_mfma_f32_16x16x32_bf16 v[36:39], v[152:155], v[172:175], v[36:39]
	v_mfma_f32_16x16x32_bf16 v[32:35], v[160:163], v[172:175], v[32:35]
	v_mfma_f32_16x16x32_bf16 v[28:31], v[152:155], v[180:183], v[28:31]
	v_mfma_f32_16x16x32_bf16 v[24:27], v[160:163], v[180:183], v[24:27]
	v_mfma_f32_16x16x32_bf16 v[20:23], v[152:155], v[188:191], v[20:23]
	v_mfma_f32_16x16x32_bf16 v[16:19], v[160:163], v[188:191], v[16:19]
	v_mfma_f32_16x16x32_bf16 v[44:47], v[156:159], v[92:95], v[44:47]
	v_mfma_f32_16x16x32_bf16 v[40:43], v[148:151], v[92:95], v[40:43]
	v_mfma_f32_16x16x32_bf16 v[36:39], v[156:159], v[176:179], v[36:39]
	v_mfma_f32_16x16x32_bf16 v[32:35], v[148:151], v[176:179], v[32:35]
	v_mfma_f32_16x16x32_bf16 v[28:31], v[156:159], v[184:187], v[28:31]
	v_mfma_f32_16x16x32_bf16 v[24:27], v[148:151], v[184:187], v[24:27]
	v_mfma_f32_16x16x32_bf16 v[20:23], v[156:159], v[192:195], v[20:23]
	v_mfma_f32_16x16x32_bf16 v[16:19], v[148:151], v[192:195], v[16:19]
	v_mfma_f32_16x16x32_bf16 v[4:7], v[196:199], v[172:175], v[4:7]
	v_mfma_f32_16x16x32_bf16 v[0:3], v[142:145], v[172:175], v[0:3]
	v_mfma_f32_16x16x32_bf16 v[12:15], v[196:199], v[68:71], v[12:15]
	v_mfma_f32_16x16x32_bf16 v[8:11], v[142:145], v[68:71], v[8:11]
	v_mfma_f32_16x16x32_bf16 v[64:67], v[196:199], v[180:183], v[64:67]
	v_mfma_f32_16x16x32_bf16 v[68:71], v[142:145], v[180:183], v[72:75]
	v_mfma_f32_16x16x32_bf16 v[72:75], v[196:199], v[188:191], v[76:79]
	v_mfma_f32_16x16x32_bf16 v[76:79], v[142:145], v[188:191], v[84:87]
	v_mfma_f32_16x16x32_bf16 v[4:7], v[200:203], v[176:179], v[4:7]
	v_mfma_f32_16x16x32_bf16 v[0:3], v[204:207], v[176:179], v[0:3]
	v_mfma_f32_16x16x32_bf16 v[142:145], v[200:203], v[92:95], v[12:15]
	v_mfma_f32_16x16x32_bf16 v[146:149], v[204:207], v[92:95], v[8:11]
	v_mfma_f32_16x16x32_bf16 v[150:153], v[200:203], v[184:187], v[64:67]
	v_mfma_f32_16x16x32_bf16 v[154:157], v[204:207], v[184:187], v[68:71]
	v_mfma_f32_16x16x32_bf16 v[158:161], v[200:203], v[192:195], v[72:75]
	v_mfma_f32_16x16x32_bf16 v[172:175], v[204:207], v[192:195], v[76:79]
	s_barrier
	ds_read_b128 v[8:11], v137
	ds_read_b128 v[12:15], v138
	ds_read_b128 v[176:179], v139
	ds_read_b128 v[138:141], v140
	ds_read_b128 v[64:67], v129 offset:32768
	ds_read_b128 v[72:75], v129 offset:33792
	ds_read_b128 v[180:183], v132 offset:32768
	ds_read_b128 v[184:187], v132 offset:33792
	ds_read_b128 v[188:191], v131 offset:32768
	ds_read_b128 v[192:195], v131 offset:33792
	ds_read_b128 v[196:199], v130 offset:32768
	ds_read_b128 v[200:203], v130 offset:33792
	s_waitcnt vmcnt(2)
	s_barrier
	s_waitcnt lgkmcnt(0)
	v_mfma_f32_16x16x32_bf16 v[68:71], v[8:11], v[64:67], v[124:127]
	v_mfma_f32_16x16x32_bf16 v[76:79], v[176:179], v[64:67], v[120:123]
	v_mfma_f32_16x16x32_bf16 v[84:87], v[8:11], v[180:183], v[116:119]
	v_mfma_f32_16x16x32_bf16 v[92:95], v[176:179], v[180:183], v[112:115]
	v_mfma_f32_16x16x32_bf16 v[112:115], v[8:11], v[188:191], v[108:111]
	v_mfma_f32_16x16x32_bf16 v[104:107], v[176:179], v[188:191], v[104:107]
	v_mfma_f32_16x16x32_bf16 v[120:123], v[8:11], v[196:199], v[100:103]
	v_mfma_f32_16x16x32_bf16 v[96:99], v[176:179], v[196:199], v[96:99]
	v_mfma_f32_16x16x32_bf16 v[124:127], v[12:15], v[72:75], v[68:71]
	v_mfma_f32_16x16x32_bf16 v[116:119], v[138:141], v[72:75], v[76:79]
	v_mfma_f32_16x16x32_bf16 v[108:111], v[12:15], v[184:187], v[84:87]
	v_mfma_f32_16x16x32_bf16 v[100:103], v[138:141], v[184:187], v[92:95]
	v_mfma_f32_16x16x32_bf16 v[92:95], v[12:15], v[192:195], v[112:115]
	v_mfma_f32_16x16x32_bf16 v[84:87], v[138:141], v[192:195], v[104:107]
	v_mfma_f32_16x16x32_bf16 v[76:79], v[12:15], v[200:203], v[120:123]
	v_mfma_f32_16x16x32_bf16 v[68:71], v[138:141], v[200:203], v[96:99]
	s_barrier
; #define LDA(dst, b, h) _Pragma("unroll") for (int m = 0; m < 4; ++m) _Pragma("unroll") for (int k = 0; k < 2; ++k) \
;     dst[m][k] = *reinterpret_cast<const bf16x8*>(SA(b, h) + lds_byte(wr * 64 + m * 16 + fr, k * 32 + fq * 8))
; #define LDB(dst, b, h) _Pragma("unroll") for (int n = 0; n < 2; ++n) _Pragma("unroll") for (int k = 0; k < 2; ++k) \
;     dst[n][k] = *reinterpret_cast<const bf16x8*>(SB(b, h) + lds_byte(wc * 32 + n * 16 + fr, k * 32 + fq * 8))
; #define WAIT_V(n) asm volatile("s_waitcnt vmcnt(" #n ")" ::: "memory")
; #define WAIT_L(n) asm volatile("s_waitcnt lgkmcnt(" #n ")" ::: "memory")
; #define BAR __builtin_amdgcn_s_barrier()
;     ...
;       LDB(B1, 1, 1); WAIT_V(0); BAR; WAIT_L(0); MMA(0, 1, At, B1); BAR;
;       LDA(At, 1, 1); BAR; WAIT_L(0); MMA(1, 0, At, B0); MMA(1, 1, At, B1); BAR; }
;     if (wr == 0) BAR;
	ds_read_b128 v[204:207], v133
	ds_read_b128 v[208:211], v134
	ds_read_b128 v[212:215], v135
	ds_read_b128 v[134:137], v136
	s_waitcnt vmcnt(0)
	s_barrier
	s_waitcnt lgkmcnt(0)
	v_mfma_f32_16x16x32_bf16 v[96:99], v[204:207], v[64:67], v[164:167]
	v_mfma_f32_16x16x32_bf16 v[64:67], v[212:215], v[64:67], v[88:91]
	v_mfma_f32_16x16x32_bf16 v[80:83], v[204:207], v[180:183], v[80:83]
	v_mfma_f32_16x16x32_bf16 v[88:91], v[212:215], v[180:183], v[168:171]
	v_mfma_f32_16x16x32_bf16 v[60:63], v[204:207], v[188:191], v[60:63]
	v_mfma_f32_16x16x32_bf16 v[56:59], v[212:215], v[188:191], v[56:59]
	v_mfma_f32_16x16x32_bf16 v[52:55], v[204:207], v[196:199], v[52:55]
	v_mfma_f32_16x16x32_bf16 v[48:51], v[212:215], v[196:199], v[48:51]
	v_mfma_f32_16x16x32_bf16 v[120:123], v[208:211], v[72:75], v[96:99]
	v_mfma_f32_16x16x32_bf16 v[112:115], v[134:137], v[72:75], v[64:67]
	v_mfma_f32_16x16x32_bf16 v[104:107], v[208:211], v[184:187], v[80:83]
	v_mfma_f32_16x16x32_bf16 v[96:99], v[134:137], v[184:187], v[88:91]
	v_mfma_f32_16x16x32_bf16 v[88:91], v[208:211], v[192:195], v[60:63]
	v_mfma_f32_16x16x32_bf16 v[80:83], v[134:137], v[192:195], v[56:59]
	v_mfma_f32_16x16x32_bf16 v[72:75], v[208:211], v[200:203], v[52:55]
	v_mfma_f32_16x16x32_bf16 v[64:67], v[134:137], v[200:203], v[48:51]
	s_barrier
	s_nop 0
	ds_read_b128 v[48:51], v129 offset:49152
	ds_read_b128 v[162:165], v129 offset:50176
	ds_read_b128 v[52:55], v132 offset:49152
	ds_read_b128 v[166:169], v132 offset:50176
	ds_read_b128 v[180:183], v131 offset:49152
	ds_read_b128 v[184:187], v131 offset:50176
	ds_read_b128 v[188:191], v130 offset:49152
	ds_read_b128 v[130:133], v130 offset:50176
	s_barrier
	s_waitcnt lgkmcnt(0)
	v_mfma_f32_16x16x32_bf16 v[44:47], v[8:11], v[48:51], v[44:47]
	v_mfma_f32_16x16x32_bf16 v[40:43], v[176:179], v[48:51], v[40:43]
	v_mfma_f32_16x16x32_bf16 v[36:39], v[8:11], v[52:55], v[36:39]
	v_mfma_f32_16x16x32_bf16 v[32:35], v[176:179], v[52:55], v[32:35]
	v_mfma_f32_16x16x32_bf16 v[28:31], v[8:11], v[180:183], v[28:31]
	v_mfma_f32_16x16x32_bf16 v[24:27], v[176:179], v[180:183], v[24:27]
	v_mfma_f32_16x16x32_bf16 v[8:11], v[8:11], v[188:191], v[20:23]
	v_mfma_f32_16x16x32_bf16 v[16:19], v[176:179], v[188:191], v[16:19]
	v_mfma_f32_16x16x32_bf16 v[60:63], v[12:15], v[162:165], v[44:47]
	v_mfma_f32_16x16x32_bf16 v[56:59], v[138:141], v[162:165], v[40:43]
	v_mfma_f32_16x16x32_bf16 v[44:47], v[12:15], v[166:169], v[36:39]
	v_mfma_f32_16x16x32_bf16 v[40:43], v[138:141], v[166:169], v[32:35]
	v_mfma_f32_16x16x32_bf16 v[28:31], v[12:15], v[184:187], v[28:31]
	v_mfma_f32_16x16x32_bf16 v[24:27], v[138:141], v[184:187], v[24:27]
	v_mfma_f32_16x16x32_bf16 v[12:15], v[12:15], v[130:133], v[8:11]
	v_mfma_f32_16x16x32_bf16 v[8:11], v[138:141], v[130:133], v[16:19]
	v_mfma_f32_16x16x32_bf16 v[16:19], v[204:207], v[48:51], v[142:145]
	v_mfma_f32_16x16x32_bf16 v[20:23], v[212:215], v[48:51], v[146:149]
	v_mfma_f32_16x16x32_bf16 v[4:7], v[204:207], v[52:55], v[4:7]
	v_mfma_f32_16x16x32_bf16 v[0:3], v[212:215], v[52:55], v[0:3]
	v_mfma_f32_16x16x32_bf16 v[138:141], v[204:207], v[180:183], v[150:153]
	v_mfma_f32_16x16x32_bf16 v[142:145], v[212:215], v[180:183], v[154:157]
	v_mfma_f32_16x16x32_bf16 v[146:149], v[204:207], v[188:191], v[158:161]
	v_mfma_f32_16x16x32_bf16 v[150:153], v[212:215], v[188:191], v[172:175]
	v_mfma_f32_16x16x32_bf16 v[52:55], v[208:211], v[162:165], v[16:19]
	v_mfma_f32_16x16x32_bf16 v[48:51], v[134:137], v[162:165], v[20:23]
	v_mfma_f32_16x16x32_bf16 v[36:39], v[208:211], v[166:169], v[4:7]
	v_mfma_f32_16x16x32_bf16 v[32:35], v[134:137], v[166:169], v[0:3]
	v_mfma_f32_16x16x32_bf16 v[20:23], v[208:211], v[184:187], v[138:141]
	v_mfma_f32_16x16x32_bf16 v[16:19], v[134:137], v[184:187], v[142:145]
	v_mfma_f32_16x16x32_bf16 v[4:7], v[208:211], v[130:133], v[146:149]
	v_mfma_f32_16x16x32_bf16 v[0:3], v[134:137], v[130:133], v[150:153]
	v_cmp_gt_u32_e32 vcc, s46, v128
	s_barrier
	s_and_saveexec_b64 s[6:7], vcc
	s_cbranch_execz .LBB0_294
	s_barrier

; #define STAGE(P, RS, SOFF, OFF, kt) do { const int _so = (SOFF) + (kt) * (BK * 2); \
;     _Pragma("unroll") for (int _i = 0; _i < 2; ++_i) { \
;       __builtin_amdgcn_raw_ptr_buffer_load_lds(RS, (__attribute__((address_space(3))) void*)((P) + wave * 1024 + _i * 8192), 16, OFF[_i], _so, 0, 0); } } while (0)
; #define LDA(dst, b, h) _Pragma("unroll") for (int m = 0; m < 4; ++m) _Pragma("unroll") for (int k = 0; k < 2; ++k) \
;     dst[m][k] = *reinterpret_cast<const bf16x8*>(SA(b, h) + lds_byte(wr * 64 + m * 16 + fr, k * 32 + fq * 8))
; #define LDB(dst, b, h) _Pragma("unroll") for (int n = 0; n < 2; ++n) _Pragma("unroll") for (int k = 0; k < 2; ++k) \
;     dst[n][k] = *reinterpret_cast<const bf16x8*>(SB(b, h) + lds_byte(wc * 32 + n * 16 + fr, k * 32 + fq * 8))
; #define WAIT_V(n) asm volatile("s_waitcnt vmcnt(" #n ")" ::: "memory")
; #define WAIT_L(n) asm volatile("s_waitcnt lgkmcnt(" #n ")" ::: "memory")
; #define BAR __builtin_amdgcn_s_barrier()
; #define SCHED __builtin_amdgcn_sched_barrier(0)
;     ...
;     const int tid = opaque_tid(wave);
;     const int wid = tid >> 6, lane = tid & 63, wr = wid >> 2, wc = wid & 3, fr = lane & 15, fq = lane >> 4;
;     int offA[2], offB[2];
;     _Pragma("unroll") for (int i = 0; i < 2; ++i) {
;       int r, c; stage_rc(tid * 16 + i * 8192, r, c);
;       offA[i] = (r * lda + c) * 2; offB[i] = (r * ldb + c) * 2;
;     }
;     const int brow = pm * BM;
;     f32x4 acc[2][2][4][2];
;     _Pragma("unroll") for (int a = 0; a < 2; ++a) _Pragma("unroll") for (int b = 0; b < 2; ++b) _Pragma("unroll") for (int m = 0; m < 4; ++m) _Pragma("unroll") for (int n = 0; n < 2; ++n)
;       acc[a][b][m][n] = f32x4{0.f, 0.f, 0.f, 0.f};
;     bf16x8 At[4][2], B0[2][2], B1[2][2];
;     if (wr == 1) BAR;
;     if (first_tile) { WAIT_V(0); }
;     else if constexpr (mode == MODE_RESID_LN) { WAIT_V(0); }
;     else if constexpr (mode == MODE_SWIGLU) { WAIT_V(6); }
;     else if constexpr (mode == MODE_V) { WAIT_V(24); }
;     else { WAIT_V(12); }
;     first_tile = false;
;     BAR;
;     BAR;
;     for (int t = 0; t < nt - 2; t += 2) {
;       LDB(B0, 0, 0); SCHED; LDA(At, 0, 0); STAGE(SA(1, 1), rsA, sA1, offA, t + 1);
;       WAIT_L(8); BAR; WAIT_L(0); MMA(0, 0, At, B0); BAR; SCHED;
;       LDB(B1, 0, 1); STAGE(SB(0, 0), rsB, sB0, offB, t + 2);
;       BAR; WAIT_L(0); MMA(0, 1, At, B1); BAR;
.LBB0_353:
	v_bfe_i32 v4, v130, 27, 1
	v_lshlrev_b32_e32 v2, 4, v130
	v_lshrrev_b32_e32 v4, 22, v4
	v_add_u32_e32 v4, v2, v4
	v_and_b32_e32 v4, 0xfffffc00, v4
	v_sub_u32_e32 v4, v2, v4
	v_lshrrev_b32_e32 v5, 4, v4
	v_bitop3_b32 v4, v5, v4, 32 bitop3:0x6c
	v_ashrrev_i32_e32 v3, 31, v130
	v_ashrrev_i32_e32 v6, 31, v4
	v_lshrrev_b32_e32 v3, 26, v3
	v_lshrrev_b32_e32 v6, 26, v6
	v_add_u32_e32 v3, v130, v3
	v_add_u32_e32 v6, v4, v6
	v_ashrrev_i32_e32 v3, 6, v3
	v_lshrrev_b32_e32 v7, 6, v6
	v_and_b32_e32 v6, 0xc0, v6
	v_lshlrev_b32_e32 v5, 3, v3
	v_lshlrev_b32_e32 v3, 5, v3
	v_sub_u32_e32 v4, v4, v6
	v_and_b32_e32 v5, 0xffff0, v5
	v_and_b32_e32 v3, 32, v3
	v_ashrrev_i16_sdwa v4, v128, sext(v4) dst_sel:DWORD dst_unused:UNUSED_PAD src0_sel:DWORD src1_sel:BYTE_0
	v_add_u32_sdwa v3, v3, sext(v4) dst_sel:DWORD dst_unused:UNUSED_PAD src0_sel:DWORD src1_sel:WORD_0
	v_add_lshl_u32 v4, v7, v5, 12
	v_add_u32_e32 v2, 0x2000, v2
	v_lshl_add_u32 v143, v3, 1, v4
	v_ashrrev_i32_e32 v3, 31, v2
	v_lshrrev_b32_e32 v3, 22, v3
	v_add_u32_e32 v3, v2, v3
	v_ashrrev_i32_e32 v3, 10, v3
	v_mul_i32_i24_e32 v4, 0x400, v3
	v_sub_u32_e32 v2, v2, v4
	v_lshrrev_b32_e32 v4, 4, v2
	v_bitop3_b32 v2, v4, v2, 32 bitop3:0x6c
	v_ashrrev_i32_e32 v5, 31, v2
	v_lshrrev_b32_e32 v5, 26, v5
	v_add_u32_e32 v5, v2, v5
	v_lshrrev_b32_e32 v6, 6, v5
	v_and_b32_e32 v5, 0xc0, v5
	v_lshlrev_b32_e32 v4, 3, v3
	v_lshlrev_b32_e32 v3, 5, v3
	v_sub_u32_e32 v2, v2, v5
	v_and_b32_e32 v4, 0xffff0, v4
	v_and_b32_e32 v3, 32, v3
	v_ashrrev_i16_sdwa v2, v128, sext(v2) dst_sel:DWORD dst_unused:UNUSED_PAD src0_sel:DWORD src1_sel:BYTE_0
	v_add_u32_sdwa v2, v3, sext(v2) dst_sel:DWORD dst_unused:UNUSED_PAD src0_sel:DWORD src1_sel:WORD_0
	v_add_lshl_u32 v3, v6, v4, 12
	v_lshl_add_u32 v144, v2, 1, v3
	v_and_b32_e32 v3, 15, v0
	v_lshlrev_b32_e32 v5, 2, v0
	v_and_b32_e32 v2, 48, v0
	v_lshlrev_b32_e32 v3, 6, v3
	v_and_b32_e32 v5, 32, v5
	v_lshlrev_b32_e32 v0, 6, v0
	v_or_b32_e32 v4, v3, v2
	v_bitop3_b32 v3, v3, v5, v2 bitop3:0x36
	v_lshlrev_b32_e32 v6, 6, v130
	v_lshlrev_b32_e32 v1, 13, v1
	v_and_or_b32 v0, v0, s34, v2
	v_and_or_b32 v3, v6, s33, v3
	v_bitop3_b32 v0, v1, v0, v5 bitop3:0xf6
	v_or_b32_e32 v6, 0x400, v3
	v_or_b32_e32 v7, 0x800, v3
	v_or_b32_e32 v8, 0xc00, v3
	v_or_b32_e32 v134, 0x800, v0
	v_or_b32_e32 v133, 0x1000, v0
	v_or_b32_e32 v132, 0x1800, v0
	v_mov_b32_e32 v0, 0
	v_bitop3_b32 v131, v4, v1, v5 bitop3:0xde
	s_mov_b32 s16, -2
	s_mov_b32 s17, 0
	v_or_b32_e32 v149, 0x10000, v3
	v_or_b32_e32 v150, 0x10000, v6
	v_or_b32_e32 v151, 0x10000, v7
	v_or_b32_e32 v152, 0x10000, v8
	v_or_b32_e32 v145, 0x14000, v3
	v_or_b32_e32 v146, 0x14000, v6
	v_or_b32_e32 v147, 0x14000, v7
	v_or_b32_e32 v148, 0x14000, v8
	v_or_b32_e32 v139, 0x18000, v3
	v_or_b32_e32 v140, 0x18000, v6
	v_or_b32_e32 v141, 0x18000, v7
	v_or_b32_e32 v142, 0x18000, v8
	v_or_b32_e32 v135, 0x1c000, v3
	v_or_b32_e32 v136, 0x1c000, v6
	v_or_b32_e32 v137, 0x1c000, v7
	v_or_b32_e32 v138, 0x1c000, v8
	s_barrier
	s_barrier
	ds_read_b128 v[154:157], v149
	ds_read_b128 v[158:161], v150
	ds_read_b128 v[162:165], v151
	ds_read_b128 v[166:169], v152
	s_add_i32 s43, s37, s17
	s_add_i32 s10, s43, 0x80
	s_mov_b32 m0, s30
	ds_read_b128 v[170:173], v131
	ds_read_b128 v[174:177], v131 offset:1024
	ds_read_b128 v[178:181], v134
	ds_read_b128 v[182:185], v134 offset:1024
	ds_read_b128 v[186:189], v133
	ds_read_b128 v[190:193], v133 offset:1024
	ds_read_b128 v[194:197], v132
	ds_read_b128 v[198:201], v132 offset:1024
	buffer_load_dwordx4 v143, s[4:7], s10 offen lds
	s_mov_b32 m0, s31
	s_nop 0
	buffer_load_dwordx4 v144, s[4:7], s10 offen lds
	s_waitcnt lgkmcnt(8)
	s_barrier
	s_waitcnt lgkmcnt(0)
	v_mfma_f32_16x16x32_bf16 v[124:127], v[154:157], v[170:173], 0
	v_mfma_f32_16x16x32_bf16 v[124:127], v[158:161], v[174:177], v[124:127]
	v_mfma_f32_16x16x32_bf16 v[120:123], v[166:169], v[174:177], 0
	v_mfma_f32_16x16x32_bf16 v[120:123], v[162:165], v[170:173], v[120:123]
	v_mfma_f32_16x16x32_bf16 v[112:115], v[162:165], v[178:181], 0
	v_mfma_f32_16x16x32_bf16 v[112:115], v[166:169], v[182:185], v[112:115]
	v_mfma_f32_16x16x32_bf16 v[116:119], v[158:161], v[182:185], 0
	v_mfma_f32_16x16x32_bf16 v[116:119], v[154:157], v[178:181], v[116:119]
	v_mfma_f32_16x16x32_bf16 v[108:111], v[154:157], v[186:189], 0
	v_mfma_f32_16x16x32_bf16 v[108:111], v[158:161], v[190:193], v[108:111]
	v_mfma_f32_16x16x32_bf16 v[104:107], v[166:169], v[190:193], 0
	v_mfma_f32_16x16x32_bf16 v[104:107], v[162:165], v[186:189], v[104:107]
	v_mfma_f32_16x16x32_bf16 v[96:99], v[162:165], v[194:197], 0
	v_mfma_f32_16x16x32_bf16 v[96:99], v[166:169], v[198:201], v[96:99]
	v_mfma_f32_16x16x32_bf16 v[100:103], v[158:161], v[198:201], 0
	v_mfma_f32_16x16x32_bf16 v[100:103], v[154:157], v[194:197], v[100:103]
	s_barrier
	s_add_i32 s44, s39, s17
	s_add_i32 s45, s44, 0x100
	s_mov_b32 s10, s6
	s_mov_b32 s11, s7
	s_mov_b32 m0, s1
	ds_read_b128 v[202:205], v145
	ds_read_b128 v[206:209], v146
	ds_read_b128 v[210:213], v147
	ds_read_b128 v[214:217], v148
	buffer_load_dwordx4 v143, s[8:11], s45 offen lds
	s_mov_b32 m0, s3
	s_nop 0
	buffer_load_dwordx4 v144, s[8:11], s45 offen lds
	s_barrier
; #define STAGE(P, RS, SOFF, OFF, kt) do { const int _so = (SOFF) + (kt) * (BK * 2); \
;     _Pragma("unroll") for (int _i = 0; _i < 2; ++_i) { \
;       __builtin_amdgcn_raw_ptr_buffer_load_lds(RS, (__attribute__((address_space(3))) void*)((P) + wave * 1024 + _i * 8192), 16, OFF[_i], _so, 0, 0); } } while (0)
; #define LDA(dst, b, h) _Pragma("unroll") for (int m = 0; m < 4; ++m) _Pragma("unroll") for (int k = 0; k < 2; ++k) \
;     dst[m][k] = *reinterpret_cast<const bf16x8*>(SA(b, h) + lds_byte(wr * 64 + m * 16 + fr, k * 32 + fq * 8))
; #define LDB(dst, b, h) _Pragma("unroll") for (int n = 0; n < 2; ++n) _Pragma("unroll") for (int k = 0; k < 2; ++k) \
;     dst[n][k] = *reinterpret_cast<const bf16x8*>(SB(b, h) + lds_byte(wc * 32 + n * 16 + fr, k * 32 + fq * 8))
; #define WAIT_V(n) asm volatile("s_waitcnt vmcnt(" #n ")" ::: "memory")
; #define WAIT_L(n) asm volatile("s_waitcnt lgkmcnt(" #n ")" ::: "memory")
; #define BAR __builtin_amdgcn_s_barrier()
; #define SCHED __builtin_amdgcn_sched_barrier(0)
;     ...
;       BAR; WAIT_L(0); MMA(0, 1, At, B1); BAR;
;       LDA(At, 0, 1); STAGE(SA(0, 0), rsA, sA0, offA, t + 2);
;       BAR; WAIT_L(0); MMA(1, 0, At, B0); BAR; SCHED;
;       STAGE(SB(0, 1), rsB, sB1, offB, t + 2);
;       WAIT_V(6); BAR; MMA(1, 1, At, B1); BAR;
;       LDB(B0, 1, 0); SCHED; LDA(At, 1, 0); STAGE(SA(0, 1), rsA, sA1, offA, t + 2);
;       WAIT_L(8); BAR; WAIT_L(0); MMA(0, 0, At, B0); BAR; SCHED;
	s_waitcnt lgkmcnt(0)
	v_mfma_f32_16x16x32_bf16 v[92:95], v[202:205], v[170:173], 0
	v_mfma_f32_16x16x32_bf16 v[92:95], v[206:209], v[174:177], v[92:95]
	v_mfma_f32_16x16x32_bf16 v[88:91], v[214:217], v[174:177], 0
	v_mfma_f32_16x16x32_bf16 v[88:91], v[210:213], v[170:173], v[88:91]
	v_mfma_f32_16x16x32_bf16 v[80:83], v[210:213], v[178:181], 0
	v_mfma_f32_16x16x32_bf16 v[80:83], v[214:217], v[182:185], v[80:83]
	v_mfma_f32_16x16x32_bf16 v[84:87], v[206:209], v[182:185], 0
	v_mfma_f32_16x16x32_bf16 v[84:87], v[202:205], v[178:181], v[84:87]
	v_mfma_f32_16x16x32_bf16 v[76:79], v[202:205], v[186:189], 0
	v_mfma_f32_16x16x32_bf16 v[76:79], v[206:209], v[190:193], v[76:79]
	v_mfma_f32_16x16x32_bf16 v[72:75], v[214:217], v[190:193], 0
	v_mfma_f32_16x16x32_bf16 v[72:75], v[210:213], v[186:189], v[72:75]
	v_mfma_f32_16x16x32_bf16 v[64:67], v[210:213], v[194:197], 0
	v_mfma_f32_16x16x32_bf16 v[64:67], v[214:217], v[198:201], v[64:67]
	v_mfma_f32_16x16x32_bf16 v[68:71], v[206:209], v[198:201], 0
	v_mfma_f32_16x16x32_bf16 v[68:71], v[202:205], v[194:197], v[68:71]
	s_barrier
	s_add_i32 s45, s38, s17
	s_add_i32 s46, s45, 0x100
	s_mov_b32 m0, s0
	ds_read_b128 v[170:173], v131 offset:16384
	ds_read_b128 v[174:177], v131 offset:17408
	ds_read_b128 v[178:181], v134 offset:16384
	ds_read_b128 v[182:185], v134 offset:17408
	ds_read_b128 v[186:189], v133 offset:16384
	ds_read_b128 v[190:193], v133 offset:17408
	ds_read_b128 v[194:197], v132 offset:16384
	ds_read_b128 v[198:201], v132 offset:17408
	buffer_load_dwordx4 v143, s[4:7], s46 offen lds
	s_mov_b32 m0, s18
	s_nop 0
	buffer_load_dwordx4 v144, s[4:7], s46 offen lds
	s_barrier
	s_waitcnt lgkmcnt(0)
	v_mfma_f32_16x16x32_bf16 v[60:63], v[154:157], v[170:173], 0
	v_mfma_f32_16x16x32_bf16 v[60:63], v[158:161], v[174:177], v[60:63]
	v_mfma_f32_16x16x32_bf16 v[56:59], v[166:169], v[174:177], 0
	v_mfma_f32_16x16x32_bf16 v[56:59], v[162:165], v[170:173], v[56:59]
	v_mfma_f32_16x16x32_bf16 v[48:51], v[162:165], v[178:181], 0
	v_mfma_f32_16x16x32_bf16 v[48:51], v[166:169], v[182:185], v[48:51]
	v_mfma_f32_16x16x32_bf16 v[52:55], v[158:161], v[182:185], 0
	v_mfma_f32_16x16x32_bf16 v[52:55], v[154:157], v[178:181], v[52:55]
	v_mfma_f32_16x16x32_bf16 v[44:47], v[154:157], v[186:189], 0
	v_mfma_f32_16x16x32_bf16 v[44:47], v[158:161], v[190:193], v[44:47]
	v_mfma_f32_16x16x32_bf16 v[40:43], v[166:169], v[190:193], 0
	v_mfma_f32_16x16x32_bf16 v[40:43], v[162:165], v[186:189], v[40:43]
	v_mfma_f32_16x16x32_bf16 v[32:35], v[162:165], v[194:197], 0
	v_mfma_f32_16x16x32_bf16 v[32:35], v[166:169], v[198:201], v[32:35]
	v_mfma_f32_16x16x32_bf16 v[36:39], v[158:161], v[198:201], 0
	v_mfma_f32_16x16x32_bf16 v[36:39], v[154:157], v[194:197], v[36:39]
	s_barrier
	s_add_i32 s46, s40, s17
	s_add_i32 s47, s46, 0x100
	s_mov_b32 m0, s19
	s_nop 0
	buffer_load_dwordx4 v143, s[8:11], s47 offen lds
	s_mov_b32 m0, s20
	s_nop 0
	buffer_load_dwordx4 v144, s[8:11], s47 offen lds
	s_waitcnt vmcnt(6)
	s_barrier
	v_mfma_f32_16x16x32_bf16 v[28:31], v[202:205], v[170:173], 0
	v_mfma_f32_16x16x32_bf16 v[28:31], v[206:209], v[174:177], v[28:31]
	v_mfma_f32_16x16x32_bf16 v[24:27], v[214:217], v[174:177], 0
	v_mfma_f32_16x16x32_bf16 v[24:27], v[210:213], v[170:173], v[24:27]
	v_mfma_f32_16x16x32_bf16 v[16:19], v[210:213], v[178:181], 0
	v_mfma_f32_16x16x32_bf16 v[16:19], v[214:217], v[182:185], v[16:19]
	v_mfma_f32_16x16x32_bf16 v[20:23], v[206:209], v[182:185], 0
	v_mfma_f32_16x16x32_bf16 v[20:23], v[202:205], v[178:181], v[20:23]
	v_mfma_f32_16x16x32_bf16 v[12:15], v[202:205], v[186:189], 0
	v_mfma_f32_16x16x32_bf16 v[12:15], v[206:209], v[190:193], v[12:15]
	v_mfma_f32_16x16x32_bf16 v[8:11], v[214:217], v[190:193], 0
	v_mfma_f32_16x16x32_bf16 v[8:11], v[210:213], v[186:189], v[8:11]
	v_mfma_f32_16x16x32_bf16 v[0:3], v[210:213], v[194:197], 0
	v_mfma_f32_16x16x32_bf16 v[0:3], v[214:217], v[198:201], v[0:3]
	v_mfma_f32_16x16x32_bf16 v[4:7], v[206:209], v[198:201], 0
	v_mfma_f32_16x16x32_bf16 v[4:7], v[202:205], v[194:197], v[4:7]
	s_barrier
	ds_read_b128 v[154:157], v139
	ds_read_b128 v[158:161], v140
	ds_read_b128 v[162:165], v141
	ds_read_b128 v[166:169], v142
	s_addk_i32 s43, 0x100
	s_mov_b32 m0, s21
	ds_read_b128 v[170:173], v131 offset:32768
	ds_read_b128 v[174:177], v131 offset:33792
	ds_read_b128 v[178:181], v134 offset:32768
	ds_read_b128 v[182:185], v134 offset:33792
	ds_read_b128 v[186:189], v133 offset:32768
	ds_read_b128 v[190:193], v133 offset:33792
	ds_read_b128 v[194:197], v132 offset:32768
	ds_read_b128 v[198:201], v132 offset:33792
	buffer_load_dwordx4 v143, s[4:7], s43 offen lds
	s_mov_b32 m0, s22
	s_nop 0
	buffer_load_dwordx4 v144, s[4:7], s43 offen lds
	s_waitcnt lgkmcnt(8)
	s_barrier
; #define STAGE(P, RS, SOFF, OFF, kt) do { const int _so = (SOFF) + (kt) * (BK * 2); \
;     _Pragma("unroll") for (int _i = 0; _i < 2; ++_i) { \
;       __builtin_amdgcn_raw_ptr_buffer_load_lds(RS, (__attribute__((address_space(3))) void*)((P) + wave * 1024 + _i * 8192), 16, OFF[_i], _so, 0, 0); } } while (0)
; #define LDA(dst, b, h) _Pragma("unroll") for (int m = 0; m < 4; ++m) _Pragma("unroll") for (int k = 0; k < 2; ++k) \
;     dst[m][k] = *reinterpret_cast<const bf16x8*>(SA(b, h) + lds_byte(wr * 64 + m * 16 + fr, k * 32 + fq * 8))
; #define LDB(dst, b, h) _Pragma("unroll") for (int n = 0; n < 2; ++n) _Pragma("unroll") for (int k = 0; k < 2; ++k) \
;     dst[n][k] = *reinterpret_cast<const bf16x8*>(SB(b, h) + lds_byte(wc * 32 + n * 16 + fr, k * 32 + fq * 8))
; #define WAIT_V(n) asm volatile("s_waitcnt vmcnt(" #n ")" ::: "memory")
; #define WAIT_L(n) asm volatile("s_waitcnt lgkmcnt(" #n ")" ::: "memory")
; #define BAR __builtin_amdgcn_s_barrier()
; #define SCHED __builtin_amdgcn_sched_barrier(0)
;     ...
;       WAIT_L(8); BAR; WAIT_L(0); MMA(0, 0, At, B0); BAR; SCHED;
;       LDB(B1, 1, 1); STAGE(SB(1, 0), rsB, sB0, offB, t + 3);
;       BAR; WAIT_L(0); MMA(0, 1, At, B1); BAR;
;       LDA(At, 1, 1); STAGE(SA(1, 0), rsA, sA0, offA, t + 3);
;       BAR; WAIT_L(0); MMA(1, 0, At, B0); BAR; SCHED;
;       STAGE(SB(1, 1), rsB, sB1, offB, t + 3);
;       WAIT_V(6); BAR; MMA(1, 1, At, B1); BAR;
;     }
	s_waitcnt lgkmcnt(0)
	v_mfma_f32_16x16x32_bf16 v[124:127], v[154:157], v[170:173], v[124:127]
	v_mfma_f32_16x16x32_bf16 v[124:127], v[158:161], v[174:177], v[124:127]
	v_mfma_f32_16x16x32_bf16 v[120:123], v[166:169], v[174:177], v[120:123]
	v_mfma_f32_16x16x32_bf16 v[120:123], v[162:165], v[170:173], v[120:123]
	v_mfma_f32_16x16x32_bf16 v[112:115], v[162:165], v[178:181], v[112:115]
	v_mfma_f32_16x16x32_bf16 v[112:115], v[166:169], v[182:185], v[112:115]
	v_mfma_f32_16x16x32_bf16 v[116:119], v[158:161], v[182:185], v[116:119]
	v_mfma_f32_16x16x32_bf16 v[116:119], v[154:157], v[178:181], v[116:119]
	v_mfma_f32_16x16x32_bf16 v[108:111], v[154:157], v[186:189], v[108:111]
	v_mfma_f32_16x16x32_bf16 v[108:111], v[158:161], v[190:193], v[108:111]
	v_mfma_f32_16x16x32_bf16 v[104:107], v[166:169], v[190:193], v[104:107]
	v_mfma_f32_16x16x32_bf16 v[104:107], v[162:165], v[186:189], v[104:107]
	v_mfma_f32_16x16x32_bf16 v[96:99], v[162:165], v[194:197], v[96:99]
	v_mfma_f32_16x16x32_bf16 v[96:99], v[166:169], v[198:201], v[96:99]
	v_mfma_f32_16x16x32_bf16 v[100:103], v[158:161], v[198:201], v[100:103]
	v_mfma_f32_16x16x32_bf16 v[100:103], v[154:157], v[194:197], v[100:103]
	s_barrier
	s_addk_i32 s44, 0x180
	s_mov_b32 m0, s23
	ds_read_b128 v[202:205], v135
	ds_read_b128 v[206:209], v136
	ds_read_b128 v[210:213], v137
	ds_read_b128 v[214:217], v138
	buffer_load_dwordx4 v143, s[8:11], s44 offen lds
	s_mov_b32 m0, s24
	s_nop 0
	buffer_load_dwordx4 v144, s[8:11], s44 offen lds
	s_barrier
	s_waitcnt lgkmcnt(0)
	v_mfma_f32_16x16x32_bf16 v[92:95], v[202:205], v[170:173], v[92:95]
	v_mfma_f32_16x16x32_bf16 v[92:95], v[206:209], v[174:177], v[92:95]
	v_mfma_f32_16x16x32_bf16 v[88:91], v[214:217], v[174:177], v[88:91]
	v_mfma_f32_16x16x32_bf16 v[88:91], v[210:213], v[170:173], v[88:91]
	v_mfma_f32_16x16x32_bf16 v[80:83], v[210:213], v[178:181], v[80:83]
	v_mfma_f32_16x16x32_bf16 v[80:83], v[214:217], v[182:185], v[80:83]
	v_mfma_f32_16x16x32_bf16 v[84:87], v[206:209], v[182:185], v[84:87]
	v_mfma_f32_16x16x32_bf16 v[84:87], v[202:205], v[178:181], v[84:87]
	v_mfma_f32_16x16x32_bf16 v[76:79], v[202:205], v[186:189], v[76:79]
	v_mfma_f32_16x16x32_bf16 v[76:79], v[206:209], v[190:193], v[76:79]
	v_mfma_f32_16x16x32_bf16 v[72:75], v[214:217], v[190:193], v[72:75]
	v_mfma_f32_16x16x32_bf16 v[72:75], v[210:213], v[186:189], v[72:75]
	v_mfma_f32_16x16x32_bf16 v[64:67], v[210:213], v[194:197], v[64:67]
	v_mfma_f32_16x16x32_bf16 v[64:67], v[214:217], v[198:201], v[64:67]
	v_mfma_f32_16x16x32_bf16 v[68:71], v[206:209], v[198:201], v[68:71]
	v_mfma_f32_16x16x32_bf16 v[68:71], v[202:205], v[194:197], v[68:71]
	s_barrier
	s_addk_i32 s45, 0x180
	s_mov_b32 m0, s25
	ds_read_b128 v[170:173], v131 offset:49152
	ds_read_b128 v[174:177], v131 offset:50176
	ds_read_b128 v[178:181], v134 offset:49152
	ds_read_b128 v[182:185], v134 offset:50176
	ds_read_b128 v[186:189], v133 offset:49152
	ds_read_b128 v[190:193], v133 offset:50176
	ds_read_b128 v[194:197], v132 offset:49152
	ds_read_b128 v[198:201], v132 offset:50176
	buffer_load_dwordx4 v143, s[4:7], s45 offen lds
	s_mov_b32 m0, s26
	s_nop 0
	buffer_load_dwordx4 v144, s[4:7], s45 offen lds
	s_barrier
	s_waitcnt lgkmcnt(0)
	v_mfma_f32_16x16x32_bf16 v[60:63], v[154:157], v[170:173], v[60:63]
	v_mfma_f32_16x16x32_bf16 v[60:63], v[158:161], v[174:177], v[60:63]
	v_mfma_f32_16x16x32_bf16 v[56:59], v[166:169], v[174:177], v[56:59]
	v_mfma_f32_16x16x32_bf16 v[56:59], v[162:165], v[170:173], v[56:59]
	v_mfma_f32_16x16x32_bf16 v[48:51], v[162:165], v[178:181], v[48:51]
	v_mfma_f32_16x16x32_bf16 v[48:51], v[166:169], v[182:185], v[48:51]
	v_mfma_f32_16x16x32_bf16 v[52:55], v[158:161], v[182:185], v[52:55]
	v_mfma_f32_16x16x32_bf16 v[52:55], v[154:157], v[178:181], v[52:55]
	v_mfma_f32_16x16x32_bf16 v[44:47], v[154:157], v[186:189], v[44:47]
	v_mfma_f32_16x16x32_bf16 v[44:47], v[158:161], v[190:193], v[44:47]
	v_mfma_f32_16x16x32_bf16 v[40:43], v[166:169], v[190:193], v[40:43]
	v_mfma_f32_16x16x32_bf16 v[40:43], v[162:165], v[186:189], v[40:43]
	v_mfma_f32_16x16x32_bf16 v[32:35], v[162:165], v[194:197], v[32:35]
	v_mfma_f32_16x16x32_bf16 v[32:35], v[166:169], v[198:201], v[32:35]
	v_mfma_f32_16x16x32_bf16 v[36:39], v[158:161], v[198:201], v[36:39]
	v_mfma_f32_16x16x32_bf16 v[36:39], v[154:157], v[194:197], v[36:39]
	s_barrier
	s_addk_i32 s46, 0x180
	s_mov_b32 m0, s27
	s_nop 0
	buffer_load_dwordx4 v143, s[8:11], s46 offen lds
	s_mov_b32 m0, s28
	s_nop 0
	buffer_load_dwordx4 v144, s[8:11], s46 offen lds
	s_add_i32 s16, s16, 2
	s_addk_i32 s17, 0x100
	s_cmp_gt_u32 s16, 27
	s_cbranch_scc0 .LBB0_354
	s_branch .Lmy_post_354

; #define STAGE(P, RS, SOFF, OFF, kt) do { const int _so = (SOFF) + (kt) * (BK * 2); \
;     _Pragma("unroll") for (int _i = 0; _i < 2; ++_i) { \
;       __builtin_amdgcn_raw_ptr_buffer_load_lds(RS, (__attribute__((address_space(3))) void*)((P) + wave * 1024 + _i * 8192), 16, OFF[_i], _so, 0, 0); } } while (0)
; #define LDA(dst, b, h) _Pragma("unroll") for (int m = 0; m < 4; ++m) _Pragma("unroll") for (int k = 0; k < 2; ++k) \
;     dst[m][k] = *reinterpret_cast<const bf16x8*>(SA(b, h) + lds_byte(wr * 64 + m * 16 + fr, k * 32 + fq * 8))
; #define LDB(dst, b, h) _Pragma("unroll") for (int n = 0; n < 2; ++n) _Pragma("unroll") for (int k = 0; k < 2; ++k) \
;     dst[n][k] = *reinterpret_cast<const bf16x8*>(SB(b, h) + lds_byte(wc * 32 + n * 16 + fr, k * 32 + fq * 8))
; #define WAIT_V(n) asm volatile("s_waitcnt vmcnt(" #n ")" ::: "memory")
; #define WAIT_L(n) asm volatile("s_waitcnt lgkmcnt(" #n ")" ::: "memory")
; #define BAR __builtin_amdgcn_s_barrier()
; #define SCHED __builtin_amdgcn_sched_barrier(0)
;     ...
;     const int tid = opaque_tid(wave);
;     const int wid = tid >> 6, lane = tid & 63, wr = wid >> 2, wc = wid & 3, fr = lane & 15, fq = lane >> 4;
;     int offA[2], offB[2];
;     _Pragma("unroll") for (int i = 0; i < 2; ++i) {
;       int r, c; stage_rc(tid * 16 + i * 8192, r, c);
;       offA[i] = (r * lda + c) * 2; offB[i] = (r * ldb + c) * 2;
;     }
;     const int brow = pm * BM;
;     f32x4 acc[2][2][4][2];
;     _Pragma("unroll") for (int a = 0; a < 2; ++a) _Pragma("unroll") for (int b = 0; b < 2; ++b) _Pragma("unroll") for (int m = 0; m < 4; ++m) _Pragma("unroll") for (int n = 0; n < 2; ++n)
;       acc[a][b][m][n] = f32x4{0.f, 0.f, 0.f, 0.f};
;     bf16x8 At[4][2], B0[2][2], B1[2][2];
;     if (wr == 1) BAR;
;     if (first_tile) { WAIT_V(0); }
;     else if constexpr (mode == MODE_RESID_LN) { WAIT_V(0); }
;     else if constexpr (mode == MODE_SWIGLU) { WAIT_V(6); }
;     else if constexpr (mode == MODE_V) { WAIT_V(24); }
;     else { WAIT_V(12); }
;     first_tile = false;
;     BAR;
;     BAR;
;     for (int t = 0; t < nt - 2; t += 2) {
;       LDB(B0, 0, 0); SCHED; LDA(At, 0, 0); STAGE(SA(1, 1), rsA, sA1, offA, t + 1);
;       WAIT_L(8); BAR; WAIT_L(0); MMA(0, 0, At, B0); BAR; SCHED;
;       LDB(B1, 0, 1); STAGE(SB(0, 0), rsB, sB0, offB, t + 2);
;       BAR; WAIT_L(0); MMA(0, 1, At, B1); BAR;
.LBB0_391:
	v_bfe_i32 v4, v128, 27, 1
	v_lshlrev_b32_e32 v2, 4, v128
	v_lshrrev_b32_e32 v4, 22, v4
	v_add_u32_e32 v4, v2, v4
	v_and_b32_e32 v4, 0xfffffc00, v4
	v_sub_u32_e32 v4, v2, v4
	v_lshrrev_b32_e32 v5, 4, v4
	v_bitop3_b32 v4, v5, v4, 32 bitop3:0x6c
	v_ashrrev_i32_e32 v3, 31, v128
	v_ashrrev_i32_e32 v6, 31, v4
	v_lshrrev_b32_e32 v3, 26, v3
	v_lshrrev_b32_e32 v6, 26, v6
	v_add_u32_e32 v3, v128, v3
	v_add_u32_e32 v6, v4, v6
	v_ashrrev_i32_e32 v3, 6, v3
	v_lshrrev_b32_e32 v7, 6, v6
	v_and_b32_e32 v6, 0xc0, v6
	v_lshlrev_b32_e32 v5, 3, v3
	v_lshlrev_b32_e32 v3, 5, v3
	v_sub_u32_e32 v4, v4, v6
	v_and_b32_e32 v5, 0x7fff0, v5
	v_and_b32_e32 v3, 32, v3
	v_ashrrev_i16_sdwa v4, v216, sext(v4) dst_sel:DWORD dst_unused:UNUSED_PAD src0_sel:DWORD src1_sel:BYTE_0
	v_add_u32_sdwa v3, v3, sext(v4) dst_sel:DWORD dst_unused:UNUSED_PAD src0_sel:DWORD src1_sel:WORD_0
	v_add_lshl_u32 v4, v7, v5, 13
	v_add_u32_e32 v2, 0x2000, v2
	v_lshl_add_u32 v141, v3, 1, v4
	v_ashrrev_i32_e32 v3, 31, v2
	v_lshrrev_b32_e32 v3, 22, v3
	v_add_u32_e32 v3, v2, v3
	v_ashrrev_i32_e32 v3, 10, v3
	v_mul_i32_i24_e32 v4, 0x400, v3
	v_sub_u32_e32 v2, v2, v4
	v_lshrrev_b32_e32 v4, 4, v2
	v_bitop3_b32 v2, v4, v2, 32 bitop3:0x6c
	v_ashrrev_i32_e32 v5, 31, v2
	v_lshrrev_b32_e32 v5, 26, v5
	v_add_u32_e32 v5, v2, v5
	v_lshrrev_b32_e32 v6, 6, v5
	v_and_b32_e32 v5, 0xc0, v5
	v_lshlrev_b32_e32 v4, 3, v3
	v_lshlrev_b32_e32 v3, 5, v3
	v_sub_u32_e32 v2, v2, v5
	v_and_b32_e32 v4, 0x7fff0, v4
	v_and_b32_e32 v3, 32, v3
	v_ashrrev_i16_sdwa v2, v216, sext(v2) dst_sel:DWORD dst_unused:UNUSED_PAD src0_sel:DWORD src1_sel:BYTE_0
	v_add_u32_sdwa v2, v3, sext(v2) dst_sel:DWORD dst_unused:UNUSED_PAD src0_sel:DWORD src1_sel:WORD_0
	v_add_lshl_u32 v3, v6, v4, 13
	v_lshl_add_u32 v142, v2, 1, v3
	v_and_b32_e32 v3, 15, v0
	v_lshlrev_b32_e32 v5, 2, v0
	v_and_b32_e32 v2, 48, v0
	v_lshlrev_b32_e32 v3, 6, v3
	v_and_b32_e32 v5, 32, v5
	v_or_b32_e32 v4, v3, v2
	v_bitop3_b32 v3, v3, v5, v2 bitop3:0x36
	v_lshlrev_b32_e32 v6, 6, v128
	s_movk_i32 s1, 0x3000
	v_and_or_b32 v3, v6, s1, v3
	v_lshlrev_b32_e32 v0, 6, v0
	s_movk_i32 s1, 0x3c0
	v_lshlrev_b32_e32 v1, 13, v1
	v_and_or_b32 v0, v0, s1, v2
	v_bitop3_b32 v0, v1, v0, v5 bitop3:0xf6
	v_or_b32_e32 v6, 0x400, v3
	v_or_b32_e32 v7, 0x800, v3
	v_or_b32_e32 v8, 0xc00, v3
	v_or_b32_e32 v132, 0x800, v0
	v_or_b32_e32 v131, 0x1000, v0
	v_or_b32_e32 v130, 0x1800, v0
	v_mov_b32_e32 v0, 0
	v_bitop3_b32 v129, v4, v1, v5 bitop3:0xde
	s_mov_b32 s1, -2
	s_mov_b32 s3, 0
	v_or_b32_e32 v147, 0x10000, v3
	v_or_b32_e32 v148, 0x10000, v6
	v_or_b32_e32 v149, 0x10000, v7
	v_or_b32_e32 v150, 0x10000, v8
	v_or_b32_e32 v143, 0x14000, v3
	v_or_b32_e32 v144, 0x14000, v6
	v_or_b32_e32 v145, 0x14000, v7
	v_or_b32_e32 v146, 0x14000, v8
	v_or_b32_e32 v137, 0x18000, v3
	v_or_b32_e32 v138, 0x18000, v6
	v_or_b32_e32 v139, 0x18000, v7
	v_or_b32_e32 v140, 0x18000, v8
	v_or_b32_e32 v133, 0x1c000, v3
	v_or_b32_e32 v134, 0x1c000, v6
	v_or_b32_e32 v135, 0x1c000, v7
	v_or_b32_e32 v136, 0x1c000, v8
	s_barrier
	s_barrier
	ds_read_b128 v[152:155], v147
	ds_read_b128 v[156:159], v148
	ds_read_b128 v[160:163], v149
	ds_read_b128 v[164:167], v150
	s_add_i32 s5, s86, s3
	s_add_i32 s6, s5, 0x80
	s_mov_b32 m0, s36
	ds_read_b128 v[168:171], v129
	ds_read_b128 v[172:175], v129 offset:1024
	ds_read_b128 v[176:179], v132
	ds_read_b128 v[180:183], v132 offset:1024
	ds_read_b128 v[184:187], v131
	ds_read_b128 v[188:191], v131 offset:1024
	ds_read_b128 v[192:195], v130
	ds_read_b128 v[196:199], v130 offset:1024
	buffer_load_dwordx4 v141, s[8:11], s6 offen lds
	s_mov_b32 m0, s59
	s_nop 0
	buffer_load_dwordx4 v142, s[8:11], s6 offen lds
	s_waitcnt lgkmcnt(8)
	s_barrier
	s_waitcnt lgkmcnt(0)
	v_mfma_f32_16x16x32_bf16 v[124:127], v[152:155], v[168:171], 0
	v_mfma_f32_16x16x32_bf16 v[124:127], v[156:159], v[172:175], v[124:127]
	v_mfma_f32_16x16x32_bf16 v[120:123], v[164:167], v[172:175], 0
	v_mfma_f32_16x16x32_bf16 v[120:123], v[160:163], v[168:171], v[120:123]
	v_mfma_f32_16x16x32_bf16 v[112:115], v[160:163], v[176:179], 0
	v_mfma_f32_16x16x32_bf16 v[112:115], v[164:167], v[180:183], v[112:115]
	v_mfma_f32_16x16x32_bf16 v[116:119], v[156:159], v[180:183], 0
	v_mfma_f32_16x16x32_bf16 v[116:119], v[152:155], v[176:179], v[116:119]
	v_mfma_f32_16x16x32_bf16 v[108:111], v[152:155], v[184:187], 0
	v_mfma_f32_16x16x32_bf16 v[108:111], v[156:159], v[188:191], v[108:111]
	v_mfma_f32_16x16x32_bf16 v[104:107], v[164:167], v[188:191], 0
	v_mfma_f32_16x16x32_bf16 v[104:107], v[160:163], v[184:187], v[104:107]
	v_mfma_f32_16x16x32_bf16 v[96:99], v[160:163], v[192:195], 0
	v_mfma_f32_16x16x32_bf16 v[96:99], v[164:167], v[196:199], v[96:99]
	v_mfma_f32_16x16x32_bf16 v[100:103], v[156:159], v[196:199], 0
	v_mfma_f32_16x16x32_bf16 v[100:103], v[152:155], v[192:195], v[100:103]
	s_barrier
	s_add_i32 s6, s92, s3
	s_add_i32 s7, s6, 0x100
	s_mov_b32 s14, s10
	s_mov_b32 s15, s11
	s_mov_b32 m0, s37
	ds_read_b128 v[200:203], v143
	ds_read_b128 v[204:207], v144
	ds_read_b128 v[208:211], v145
	ds_read_b128 v[212:215], v146
	buffer_load_dwordx4 v141, s[12:15], s7 offen lds
	s_mov_b32 m0, s48
	s_nop 0
	buffer_load_dwordx4 v142, s[12:15], s7 offen lds
	s_barrier
; #define STAGE(P, RS, SOFF, OFF, kt) do { const int _so = (SOFF) + (kt) * (BK * 2); \
;     _Pragma("unroll") for (int _i = 0; _i < 2; ++_i) { \
;       __builtin_amdgcn_raw_ptr_buffer_load_lds(RS, (__attribute__((address_space(3))) void*)((P) + wave * 1024 + _i * 8192), 16, OFF[_i], _so, 0, 0); } } while (0)
; #define LDA(dst, b, h) _Pragma("unroll") for (int m = 0; m < 4; ++m) _Pragma("unroll") for (int k = 0; k < 2; ++k) \
;     dst[m][k] = *reinterpret_cast<const bf16x8*>(SA(b, h) + lds_byte(wr * 64 + m * 16 + fr, k * 32 + fq * 8))
; #define LDB(dst, b, h) _Pragma("unroll") for (int n = 0; n < 2; ++n) _Pragma("unroll") for (int k = 0; k < 2; ++k) \
;     dst[n][k] = *reinterpret_cast<const bf16x8*>(SB(b, h) + lds_byte(wc * 32 + n * 16 + fr, k * 32 + fq * 8))
; #define WAIT_V(n) asm volatile("s_waitcnt vmcnt(" #n ")" ::: "memory")
; #define WAIT_L(n) asm volatile("s_waitcnt lgkmcnt(" #n ")" ::: "memory")
; #define BAR __builtin_amdgcn_s_barrier()
; #define SCHED __builtin_amdgcn_sched_barrier(0)
;     ...
;       BAR; WAIT_L(0); MMA(0, 1, At, B1); BAR;
;       LDA(At, 0, 1); STAGE(SA(0, 0), rsA, sA0, offA, t + 2);
;       BAR; WAIT_L(0); MMA(1, 0, At, B0); BAR; SCHED;
;       STAGE(SB(0, 1), rsB, sB1, offB, t + 2);
;       WAIT_V(6); BAR; MMA(1, 1, At, B1); BAR;
;       LDB(B0, 1, 0); SCHED; LDA(At, 1, 0); STAGE(SA(0, 1), rsA, sA1, offA, t + 2);
;       WAIT_L(8); BAR; WAIT_L(0); MMA(0, 0, At, B0); BAR; SCHED;
	s_waitcnt lgkmcnt(0)
	v_mfma_f32_16x16x32_bf16 v[92:95], v[200:203], v[168:171], 0
	v_mfma_f32_16x16x32_bf16 v[92:95], v[204:207], v[172:175], v[92:95]
	v_mfma_f32_16x16x32_bf16 v[88:91], v[212:215], v[172:175], 0
	v_mfma_f32_16x16x32_bf16 v[88:91], v[208:211], v[168:171], v[88:91]
	v_mfma_f32_16x16x32_bf16 v[68:71], v[208:211], v[176:179], 0
	v_mfma_f32_16x16x32_bf16 v[68:71], v[212:215], v[180:183], v[68:71]
	v_mfma_f32_16x16x32_bf16 v[80:83], v[204:207], v[180:183], 0
	v_mfma_f32_16x16x32_bf16 v[80:83], v[200:203], v[176:179], v[80:83]
	v_mfma_f32_16x16x32_bf16 v[60:63], v[200:203], v[184:187], 0
	v_mfma_f32_16x16x32_bf16 v[60:63], v[204:207], v[188:191], v[60:63]
	v_mfma_f32_16x16x32_bf16 v[56:59], v[212:215], v[188:191], 0
	v_mfma_f32_16x16x32_bf16 v[56:59], v[208:211], v[184:187], v[56:59]
	v_mfma_f32_16x16x32_bf16 v[48:51], v[208:211], v[192:195], 0
	v_mfma_f32_16x16x32_bf16 v[48:51], v[212:215], v[196:199], v[48:51]
	v_mfma_f32_16x16x32_bf16 v[52:55], v[204:207], v[196:199], 0
	v_mfma_f32_16x16x32_bf16 v[52:55], v[200:203], v[192:195], v[52:55]
	s_barrier
	s_add_i32 s7, s87, s3
	s_add_i32 s22, s7, 0x100
	s_mov_b32 m0, s35
	ds_read_b128 v[168:171], v129 offset:16384
	ds_read_b128 v[172:175], v129 offset:17408
	ds_read_b128 v[176:179], v132 offset:16384
	ds_read_b128 v[180:183], v132 offset:17408
	ds_read_b128 v[184:187], v131 offset:16384
	ds_read_b128 v[188:191], v131 offset:17408
	ds_read_b128 v[192:195], v130 offset:16384
	ds_read_b128 v[196:199], v130 offset:17408
	buffer_load_dwordx4 v141, s[8:11], s22 offen lds
	s_mov_b32 m0, s49
	s_nop 0
	buffer_load_dwordx4 v142, s[8:11], s22 offen lds
	s_barrier
	s_waitcnt lgkmcnt(0)
	v_mfma_f32_16x16x32_bf16 v[44:47], v[152:155], v[168:171], 0
	v_mfma_f32_16x16x32_bf16 v[44:47], v[156:159], v[172:175], v[44:47]
	v_mfma_f32_16x16x32_bf16 v[40:43], v[164:167], v[172:175], 0
	v_mfma_f32_16x16x32_bf16 v[40:43], v[160:163], v[168:171], v[40:43]
	v_mfma_f32_16x16x32_bf16 v[32:35], v[160:163], v[176:179], 0
	v_mfma_f32_16x16x32_bf16 v[32:35], v[164:167], v[180:183], v[32:35]
	v_mfma_f32_16x16x32_bf16 v[36:39], v[156:159], v[180:183], 0
	v_mfma_f32_16x16x32_bf16 v[36:39], v[152:155], v[176:179], v[36:39]
	v_mfma_f32_16x16x32_bf16 v[28:31], v[152:155], v[184:187], 0
	v_mfma_f32_16x16x32_bf16 v[28:31], v[156:159], v[188:191], v[28:31]
	v_mfma_f32_16x16x32_bf16 v[24:27], v[164:167], v[188:191], 0
	v_mfma_f32_16x16x32_bf16 v[24:27], v[160:163], v[184:187], v[24:27]
	v_mfma_f32_16x16x32_bf16 v[16:19], v[160:163], v[192:195], 0
	v_mfma_f32_16x16x32_bf16 v[16:19], v[164:167], v[196:199], v[16:19]
	v_mfma_f32_16x16x32_bf16 v[20:23], v[156:159], v[196:199], 0
	v_mfma_f32_16x16x32_bf16 v[20:23], v[152:155], v[192:195], v[20:23]
	s_barrier
	s_add_i32 s22, s93, s3
	s_add_i32 s23, s22, 0x100
	s_mov_b32 m0, s38
	s_nop 0
	buffer_load_dwordx4 v141, s[12:15], s23 offen lds
	s_mov_b32 m0, s54
	s_nop 0
	buffer_load_dwordx4 v142, s[12:15], s23 offen lds
	s_waitcnt vmcnt(6)
	s_barrier
	v_mfma_f32_16x16x32_bf16 v[12:15], v[200:203], v[168:171], 0
	v_mfma_f32_16x16x32_bf16 v[12:15], v[204:207], v[172:175], v[12:15]
	v_mfma_f32_16x16x32_bf16 v[8:11], v[212:215], v[172:175], 0
	v_mfma_f32_16x16x32_bf16 v[8:11], v[208:211], v[168:171], v[8:11]
	v_mfma_f32_16x16x32_bf16 v[0:3], v[208:211], v[176:179], 0
	v_mfma_f32_16x16x32_bf16 v[0:3], v[212:215], v[180:183], v[0:3]
	v_mfma_f32_16x16x32_bf16 v[4:7], v[204:207], v[180:183], 0
	v_mfma_f32_16x16x32_bf16 v[4:7], v[200:203], v[176:179], v[4:7]
	v_mfma_f32_16x16x32_bf16 v[64:67], v[200:203], v[184:187], 0
	v_mfma_f32_16x16x32_bf16 v[64:67], v[204:207], v[188:191], v[64:67]
	v_mfma_f32_16x16x32_bf16 v[72:75], v[212:215], v[188:191], 0
	v_mfma_f32_16x16x32_bf16 v[72:75], v[208:211], v[184:187], v[72:75]
	v_mfma_f32_16x16x32_bf16 v[84:87], v[208:211], v[192:195], 0
	v_mfma_f32_16x16x32_bf16 v[84:87], v[212:215], v[196:199], v[84:87]
	v_mfma_f32_16x16x32_bf16 v[76:79], v[204:207], v[196:199], 0
	v_mfma_f32_16x16x32_bf16 v[76:79], v[200:203], v[192:195], v[76:79]
	s_barrier
	ds_read_b128 v[152:155], v137
	ds_read_b128 v[156:159], v138
	ds_read_b128 v[160:163], v139
	ds_read_b128 v[164:167], v140
	s_addk_i32 s5, 0x100
	s_mov_b32 m0, s39
	ds_read_b128 v[168:171], v129 offset:32768
	ds_read_b128 v[172:175], v129 offset:33792
	ds_read_b128 v[176:179], v132 offset:32768
	ds_read_b128 v[180:183], v132 offset:33792
	ds_read_b128 v[184:187], v131 offset:32768
	ds_read_b128 v[188:191], v131 offset:33792
	ds_read_b128 v[192:195], v130 offset:32768
	ds_read_b128 v[196:199], v130 offset:33792
	buffer_load_dwordx4 v141, s[8:11], s5 offen lds
	s_mov_b32 m0, s55
	s_nop 0
	buffer_load_dwordx4 v142, s[8:11], s5 offen lds
	s_waitcnt lgkmcnt(8)
	s_barrier
; #define STAGE(P, RS, SOFF, OFF, kt) do { const int _so = (SOFF) + (kt) * (BK * 2); \
;     _Pragma("unroll") for (int _i = 0; _i < 2; ++_i) { \
;       __builtin_amdgcn_raw_ptr_buffer_load_lds(RS, (__attribute__((address_space(3))) void*)((P) + wave * 1024 + _i * 8192), 16, OFF[_i], _so, 0, 0); } } while (0)
; #define LDA(dst, b, h) _Pragma("unroll") for (int m = 0; m < 4; ++m) _Pragma("unroll") for (int k = 0; k < 2; ++k) \
;     dst[m][k] = *reinterpret_cast<const bf16x8*>(SA(b, h) + lds_byte(wr * 64 + m * 16 + fr, k * 32 + fq * 8))
; #define LDB(dst, b, h) _Pragma("unroll") for (int n = 0; n < 2; ++n) _Pragma("unroll") for (int k = 0; k < 2; ++k) \
;     dst[n][k] = *reinterpret_cast<const bf16x8*>(SB(b, h) + lds_byte(wc * 32 + n * 16 + fr, k * 32 + fq * 8))
; #define WAIT_V(n) asm volatile("s_waitcnt vmcnt(" #n ")" ::: "memory")
; #define WAIT_L(n) asm volatile("s_waitcnt lgkmcnt(" #n ")" ::: "memory")
; #define BAR __builtin_amdgcn_s_barrier()
; #define SCHED __builtin_amdgcn_sched_barrier(0)
;     ...
;       WAIT_L(8); BAR; WAIT_L(0); MMA(0, 0, At, B0); BAR; SCHED;
;       LDB(B1, 1, 1); STAGE(SB(1, 0), rsB, sB0, offB, t + 3);
;       BAR; WAIT_L(0); MMA(0, 1, At, B1); BAR;
;       LDA(At, 1, 1); STAGE(SA(1, 0), rsA, sA0, offA, t + 3);
;       BAR; WAIT_L(0); MMA(1, 0, At, B0); BAR; SCHED;
;       STAGE(SB(1, 1), rsB, sB1, offB, t + 3);
;       WAIT_V(6); BAR; MMA(1, 1, At, B1); BAR;
;     }
	s_waitcnt lgkmcnt(0)
	v_mfma_f32_16x16x32_bf16 v[124:127], v[152:155], v[168:171], v[124:127]
	v_mfma_f32_16x16x32_bf16 v[124:127], v[156:159], v[172:175], v[124:127]
	v_mfma_f32_16x16x32_bf16 v[120:123], v[164:167], v[172:175], v[120:123]
	v_mfma_f32_16x16x32_bf16 v[120:123], v[160:163], v[168:171], v[120:123]
	v_mfma_f32_16x16x32_bf16 v[112:115], v[160:163], v[176:179], v[112:115]
	v_mfma_f32_16x16x32_bf16 v[112:115], v[164:167], v[180:183], v[112:115]
	v_mfma_f32_16x16x32_bf16 v[116:119], v[156:159], v[180:183], v[116:119]
	v_mfma_f32_16x16x32_bf16 v[116:119], v[152:155], v[176:179], v[116:119]
	v_mfma_f32_16x16x32_bf16 v[108:111], v[152:155], v[184:187], v[108:111]
	v_mfma_f32_16x16x32_bf16 v[108:111], v[156:159], v[188:191], v[108:111]
	v_mfma_f32_16x16x32_bf16 v[104:107], v[164:167], v[188:191], v[104:107]
	v_mfma_f32_16x16x32_bf16 v[104:107], v[160:163], v[184:187], v[104:107]
	v_mfma_f32_16x16x32_bf16 v[96:99], v[160:163], v[192:195], v[96:99]
	v_mfma_f32_16x16x32_bf16 v[96:99], v[164:167], v[196:199], v[96:99]
	v_mfma_f32_16x16x32_bf16 v[100:103], v[156:159], v[196:199], v[100:103]
	v_mfma_f32_16x16x32_bf16 v[100:103], v[152:155], v[192:195], v[100:103]
	s_barrier
	s_addk_i32 s6, 0x180
	s_mov_b32 m0, s42
	ds_read_b128 v[200:203], v133
	ds_read_b128 v[204:207], v134
	ds_read_b128 v[208:211], v135
	ds_read_b128 v[212:215], v136
	buffer_load_dwordx4 v141, s[12:15], s6 offen lds
	s_mov_b32 m0, s56
	s_nop 0
	buffer_load_dwordx4 v142, s[12:15], s6 offen lds
	s_barrier
	s_waitcnt lgkmcnt(0)
	v_mfma_f32_16x16x32_bf16 v[92:95], v[200:203], v[168:171], v[92:95]
	v_mfma_f32_16x16x32_bf16 v[92:95], v[204:207], v[172:175], v[92:95]
	v_mfma_f32_16x16x32_bf16 v[88:91], v[212:215], v[172:175], v[88:91]
	v_mfma_f32_16x16x32_bf16 v[88:91], v[208:211], v[168:171], v[88:91]
	v_mfma_f32_16x16x32_bf16 v[68:71], v[208:211], v[176:179], v[68:71]
	v_mfma_f32_16x16x32_bf16 v[68:71], v[212:215], v[180:183], v[68:71]
	v_mfma_f32_16x16x32_bf16 v[80:83], v[204:207], v[180:183], v[80:83]
	v_mfma_f32_16x16x32_bf16 v[80:83], v[200:203], v[176:179], v[80:83]
	v_mfma_f32_16x16x32_bf16 v[60:63], v[200:203], v[184:187], v[60:63]
	v_mfma_f32_16x16x32_bf16 v[60:63], v[204:207], v[188:191], v[60:63]
	v_mfma_f32_16x16x32_bf16 v[56:59], v[212:215], v[188:191], v[56:59]
	v_mfma_f32_16x16x32_bf16 v[56:59], v[208:211], v[184:187], v[56:59]
	v_mfma_f32_16x16x32_bf16 v[48:51], v[208:211], v[192:195], v[48:51]
	v_mfma_f32_16x16x32_bf16 v[48:51], v[212:215], v[196:199], v[48:51]
	v_mfma_f32_16x16x32_bf16 v[52:55], v[204:207], v[196:199], v[52:55]
	v_mfma_f32_16x16x32_bf16 v[52:55], v[200:203], v[192:195], v[52:55]
	s_barrier
	s_addk_i32 s7, 0x180
	s_mov_b32 m0, s43
	ds_read_b128 v[168:171], v129 offset:49152
	ds_read_b128 v[172:175], v129 offset:50176
	ds_read_b128 v[176:179], v132 offset:49152
	ds_read_b128 v[180:183], v132 offset:50176
	ds_read_b128 v[184:187], v131 offset:49152
	ds_read_b128 v[188:191], v131 offset:50176
	ds_read_b128 v[192:195], v130 offset:49152
	ds_read_b128 v[196:199], v130 offset:50176
	buffer_load_dwordx4 v141, s[8:11], s7 offen lds
	s_mov_b32 m0, s57
	s_nop 0
	buffer_load_dwordx4 v142, s[8:11], s7 offen lds
	s_barrier
	s_waitcnt lgkmcnt(0)
	v_mfma_f32_16x16x32_bf16 v[44:47], v[152:155], v[168:171], v[44:47]
	v_mfma_f32_16x16x32_bf16 v[44:47], v[156:159], v[172:175], v[44:47]
	v_mfma_f32_16x16x32_bf16 v[40:43], v[164:167], v[172:175], v[40:43]
	v_mfma_f32_16x16x32_bf16 v[40:43], v[160:163], v[168:171], v[40:43]
	v_mfma_f32_16x16x32_bf16 v[32:35], v[160:163], v[176:179], v[32:35]
	v_mfma_f32_16x16x32_bf16 v[32:35], v[164:167], v[180:183], v[32:35]
	v_mfma_f32_16x16x32_bf16 v[36:39], v[156:159], v[180:183], v[36:39]
	v_mfma_f32_16x16x32_bf16 v[36:39], v[152:155], v[176:179], v[36:39]
	v_mfma_f32_16x16x32_bf16 v[28:31], v[152:155], v[184:187], v[28:31]
	v_mfma_f32_16x16x32_bf16 v[28:31], v[156:159], v[188:191], v[28:31]
	v_mfma_f32_16x16x32_bf16 v[24:27], v[164:167], v[188:191], v[24:27]
	v_mfma_f32_16x16x32_bf16 v[24:27], v[160:163], v[184:187], v[24:27]
	v_mfma_f32_16x16x32_bf16 v[16:19], v[160:163], v[192:195], v[16:19]
	v_mfma_f32_16x16x32_bf16 v[16:19], v[164:167], v[196:199], v[16:19]
	v_mfma_f32_16x16x32_bf16 v[20:23], v[156:159], v[196:199], v[20:23]
	v_mfma_f32_16x16x32_bf16 v[20:23], v[152:155], v[192:195], v[20:23]
	s_barrier
	s_addk_i32 s22, 0x180
	s_mov_b32 m0, s44
	s_nop 0
	buffer_load_dwordx4 v141, s[12:15], s22 offen lds
	s_mov_b32 m0, s58
	s_nop 0
	buffer_load_dwordx4 v142, s[12:15], s22 offen lds
	s_add_i32 s1, s1, 2
	s_addk_i32 s3, 0x100
	s_cmp_gt_u32 s1, 59
	s_cbranch_scc0 .LBB0_392
	s_branch .Lmy_post_392

; #define STAGE(P, RS, SOFF, OFF, kt) do { const int _so = (SOFF) + (kt) * (BK * 2); \
;     _Pragma("unroll") for (int _i = 0; _i < 2; ++_i) { \
;       __builtin_amdgcn_raw_ptr_buffer_load_lds(RS, (__attribute__((address_space(3))) void*)((P) + wave * 1024 + _i * 8192), 16, OFF[_i], _so, 0, 0); } } while (0)
; #define LDA(dst, b, h) _Pragma("unroll") for (int m = 0; m < 4; ++m) _Pragma("unroll") for (int k = 0; k < 2; ++k) \
;     dst[m][k] = *reinterpret_cast<const bf16x8*>(SA(b, h) + lds_byte(wr * 64 + m * 16 + fr, k * 32 + fq * 8))
; #define LDB(dst, b, h) _Pragma("unroll") for (int n = 0; n < 2; ++n) _Pragma("unroll") for (int k = 0; k < 2; ++k) \
;     dst[n][k] = *reinterpret_cast<const bf16x8*>(SB(b, h) + lds_byte(wc * 32 + n * 16 + fr, k * 32 + fq * 8))
; #define WAIT_V(n) asm volatile("s_waitcnt vmcnt(" #n ")" ::: "memory")
; #define WAIT_L(n) asm volatile("s_waitcnt lgkmcnt(" #n ")" ::: "memory")
; #define BAR __builtin_amdgcn_s_barrier()
;     ...
;       WAIT_V(6); BAR; MMA(1, 1, At, B1); BAR;
;     }
;     { LDB(B0, 0, 0); LDA(At, 0, 0); STAGE(SA(1, 1), rsA, sA1, offA, nt - 1);
;       BAR; WAIT_L(0); MMA(0, 0, At, B0); BAR;
;       LDB(B1, 0, 1); BAR; WAIT_L(0); MMA(0, 1, At, B1); BAR;
;       LDA(At, 0, 1); WAIT_V(4); BAR; WAIT_L(0); MMA(1, 0, At, B0); MMA(1, 1, At, B1); BAR; }
.Lmy_post_392:
	s_waitcnt vmcnt(6)
	s_barrier
	v_mfma_f32_16x16x32_bf16 v[12:15], v[200:203], v[168:171], v[12:15]
	v_mfma_f32_16x16x32_bf16 v[12:15], v[204:207], v[172:175], v[12:15]
	v_mfma_f32_16x16x32_bf16 v[8:11], v[212:215], v[172:175], v[8:11]
	v_mfma_f32_16x16x32_bf16 v[8:11], v[208:211], v[168:171], v[8:11]
	v_mfma_f32_16x16x32_bf16 v[0:3], v[208:211], v[176:179], v[0:3]
	v_mfma_f32_16x16x32_bf16 v[0:3], v[212:215], v[180:183], v[0:3]
	v_mfma_f32_16x16x32_bf16 v[4:7], v[204:207], v[180:183], v[4:7]
	v_mfma_f32_16x16x32_bf16 v[4:7], v[200:203], v[176:179], v[4:7]
	v_mfma_f32_16x16x32_bf16 v[64:67], v[200:203], v[184:187], v[64:67]
	v_mfma_f32_16x16x32_bf16 v[64:67], v[204:207], v[188:191], v[64:67]
	v_mfma_f32_16x16x32_bf16 v[72:75], v[212:215], v[188:191], v[72:75]
	v_mfma_f32_16x16x32_bf16 v[72:75], v[208:211], v[184:187], v[72:75]
	v_mfma_f32_16x16x32_bf16 v[84:87], v[208:211], v[192:195], v[84:87]
	v_mfma_f32_16x16x32_bf16 v[84:87], v[212:215], v[196:199], v[84:87]
	v_mfma_f32_16x16x32_bf16 v[76:79], v[204:207], v[196:199], v[76:79]
	v_mfma_f32_16x16x32_bf16 v[76:79], v[200:203], v[192:195], v[76:79]
	s_barrier
	s_add_i32 s1, s86, 0x1f80
	s_mov_b32 m0, s36
	ds_read_b128 v[152:155], v147
	ds_read_b128 v[156:159], v148
	ds_read_b128 v[160:163], v149
	ds_read_b128 v[148:151], v150
	ds_read_b128 v[164:167], v129
	ds_read_b128 v[168:171], v129 offset:1024
	ds_read_b128 v[172:175], v132
	ds_read_b128 v[176:179], v132 offset:1024
	ds_read_b128 v[180:183], v131
	ds_read_b128 v[184:187], v131 offset:1024
	ds_read_b128 v[188:191], v130
	ds_read_b128 v[192:195], v130 offset:1024
	buffer_load_dwordx4 v141, s[8:11], s1 offen lds
	s_mov_b32 m0, s59
	s_nop 0
	buffer_load_dwordx4 v142, s[8:11], s1 offen lds
	s_barrier
	s_waitcnt lgkmcnt(0)
	v_mfma_f32_16x16x32_bf16 v[124:127], v[152:155], v[164:167], v[124:127]
	v_mfma_f32_16x16x32_bf16 v[124:127], v[156:159], v[168:171], v[124:127]
	v_mfma_f32_16x16x32_bf16 v[120:123], v[148:151], v[168:171], v[120:123]
	v_mfma_f32_16x16x32_bf16 v[120:123], v[160:163], v[164:167], v[120:123]
	v_mfma_f32_16x16x32_bf16 v[112:115], v[160:163], v[172:175], v[112:115]
	v_mfma_f32_16x16x32_bf16 v[112:115], v[148:151], v[176:179], v[112:115]
	v_mfma_f32_16x16x32_bf16 v[116:119], v[156:159], v[176:179], v[116:119]
	v_mfma_f32_16x16x32_bf16 v[116:119], v[152:155], v[172:175], v[116:119]
	v_mfma_f32_16x16x32_bf16 v[108:111], v[152:155], v[180:183], v[108:111]
	v_mfma_f32_16x16x32_bf16 v[108:111], v[156:159], v[184:187], v[108:111]
	v_mfma_f32_16x16x32_bf16 v[104:107], v[148:151], v[184:187], v[104:107]
	v_mfma_f32_16x16x32_bf16 v[104:107], v[160:163], v[180:183], v[104:107]
	v_mfma_f32_16x16x32_bf16 v[96:99], v[160:163], v[188:191], v[96:99]
	v_mfma_f32_16x16x32_bf16 v[96:99], v[148:151], v[192:195], v[96:99]
	v_mfma_f32_16x16x32_bf16 v[100:103], v[156:159], v[192:195], v[100:103]
	v_mfma_f32_16x16x32_bf16 v[100:103], v[152:155], v[188:191], v[100:103]
	s_barrier
	ds_read_b128 v[196:199], v143
	ds_read_b128 v[200:203], v144
	ds_read_b128 v[142:145], v145
	ds_read_b128 v[204:207], v146
	s_barrier
	s_waitcnt lgkmcnt(0)
	v_mfma_f32_16x16x32_bf16 v[80:83], v[196:199], v[172:175], v[80:83]
	v_mfma_f32_16x16x32_bf16 v[68:71], v[142:145], v[172:175], v[68:71]
	v_mfma_f32_16x16x32_bf16 v[60:63], v[196:199], v[180:183], v[60:63]
	v_mfma_f32_16x16x32_bf16 v[56:59], v[142:145], v[180:183], v[56:59]
	v_mfma_f32_16x16x32_bf16 v[52:55], v[196:199], v[188:191], v[52:55]
	v_mfma_f32_16x16x32_bf16 v[48:51], v[142:145], v[188:191], v[48:51]
	v_mfma_f32_16x16x32_bf16 v[92:95], v[196:199], v[164:167], v[92:95]
	v_mfma_f32_16x16x32_bf16 v[88:91], v[142:145], v[164:167], v[88:91]
	v_mfma_f32_16x16x32_bf16 v[80:83], v[200:203], v[176:179], v[80:83]
	v_mfma_f32_16x16x32_bf16 v[68:71], v[204:207], v[176:179], v[68:71]
	v_mfma_f32_16x16x32_bf16 v[60:63], v[200:203], v[184:187], v[60:63]
	v_mfma_f32_16x16x32_bf16 v[56:59], v[204:207], v[184:187], v[56:59]
	v_mfma_f32_16x16x32_bf16 v[52:55], v[200:203], v[192:195], v[52:55]
	v_mfma_f32_16x16x32_bf16 v[48:51], v[204:207], v[192:195], v[48:51]
	v_mfma_f32_16x16x32_bf16 v[164:167], v[200:203], v[168:171], v[92:95]
	v_mfma_f32_16x16x32_bf16 v[168:171], v[204:207], v[168:171], v[88:91]
	s_barrier
	s_nop 0
	ds_read_b128 v[88:91], v129 offset:16384
	ds_read_b128 v[92:95], v129 offset:17408
	ds_read_b128 v[172:175], v132 offset:16384
	ds_read_b128 v[176:179], v132 offset:17408
	ds_read_b128 v[180:183], v131 offset:16384
	ds_read_b128 v[184:187], v131 offset:17408
	ds_read_b128 v[188:191], v130 offset:16384
	ds_read_b128 v[192:195], v130 offset:17408
	s_waitcnt vmcnt(4)
	s_barrier
; #define LDA(dst, b, h) _Pragma("unroll") for (int m = 0; m < 4; ++m) _Pragma("unroll") for (int k = 0; k < 2; ++k) \
;     dst[m][k] = *reinterpret_cast<const bf16x8*>(SA(b, h) + lds_byte(wr * 64 + m * 16 + fr, k * 32 + fq * 8))
; #define LDB(dst, b, h) _Pragma("unroll") for (int n = 0; n < 2; ++n) _Pragma("unroll") for (int k = 0; k < 2; ++k) \
;     dst[n][k] = *reinterpret_cast<const bf16x8*>(SB(b, h) + lds_byte(wc * 32 + n * 16 + fr, k * 32 + fq * 8))
; #define WAIT_V(n) asm volatile("s_waitcnt vmcnt(" #n ")" ::: "memory")
; #define WAIT_L(n) asm volatile("s_waitcnt lgkmcnt(" #n ")" ::: "memory")
; #define BAR __builtin_amdgcn_s_barrier()
;     ...
;       LDA(At, 0, 1); WAIT_V(4); BAR; WAIT_L(0); MMA(1, 0, At, B0); MMA(1, 1, At, B1); BAR; }
;     { LDB(B0, 1, 0); LDA(At, 1, 0); WAIT_V(2); BAR; WAIT_L(0); MMA(0, 0, At, B0); BAR;
	s_waitcnt lgkmcnt(0)
	v_mfma_f32_16x16x32_bf16 v[44:47], v[152:155], v[88:91], v[44:47]
	v_mfma_f32_16x16x32_bf16 v[40:43], v[160:163], v[88:91], v[40:43]
	v_mfma_f32_16x16x32_bf16 v[36:39], v[152:155], v[172:175], v[36:39]
	v_mfma_f32_16x16x32_bf16 v[32:35], v[160:163], v[172:175], v[32:35]
	v_mfma_f32_16x16x32_bf16 v[28:31], v[152:155], v[180:183], v[28:31]
	v_mfma_f32_16x16x32_bf16 v[24:27], v[160:163], v[180:183], v[24:27]
	v_mfma_f32_16x16x32_bf16 v[20:23], v[152:155], v[188:191], v[20:23]
	v_mfma_f32_16x16x32_bf16 v[16:19], v[160:163], v[188:191], v[16:19]
	v_mfma_f32_16x16x32_bf16 v[44:47], v[156:159], v[92:95], v[44:47]
	v_mfma_f32_16x16x32_bf16 v[40:43], v[148:151], v[92:95], v[40:43]
	v_mfma_f32_16x16x32_bf16 v[36:39], v[156:159], v[176:179], v[36:39]
	v_mfma_f32_16x16x32_bf16 v[32:35], v[148:151], v[176:179], v[32:35]
	v_mfma_f32_16x16x32_bf16 v[28:31], v[156:159], v[184:187], v[28:31]
	v_mfma_f32_16x16x32_bf16 v[24:27], v[148:151], v[184:187], v[24:27]
	v_mfma_f32_16x16x32_bf16 v[20:23], v[156:159], v[192:195], v[20:23]
	v_mfma_f32_16x16x32_bf16 v[16:19], v[148:151], v[192:195], v[16:19]
	v_mfma_f32_16x16x32_bf16 v[4:7], v[196:199], v[172:175], v[4:7]
	v_mfma_f32_16x16x32_bf16 v[0:3], v[142:145], v[172:175], v[0:3]
	v_mfma_f32_16x16x32_bf16 v[12:15], v[196:199], v[88:91], v[12:15]
	v_mfma_f32_16x16x32_bf16 v[8:11], v[142:145], v[88:91], v[8:11]
	v_mfma_f32_16x16x32_bf16 v[64:67], v[196:199], v[180:183], v[64:67]
	v_mfma_f32_16x16x32_bf16 v[72:75], v[142:145], v[180:183], v[72:75]
	v_mfma_f32_16x16x32_bf16 v[76:79], v[196:199], v[188:191], v[76:79]
	v_mfma_f32_16x16x32_bf16 v[84:87], v[142:145], v[188:191], v[84:87]
	v_mfma_f32_16x16x32_bf16 v[4:7], v[200:203], v[176:179], v[4:7]
	v_mfma_f32_16x16x32_bf16 v[0:3], v[204:207], v[176:179], v[0:3]
	v_mfma_f32_16x16x32_bf16 v[142:145], v[200:203], v[92:95], v[12:15]
	v_mfma_f32_16x16x32_bf16 v[146:149], v[204:207], v[92:95], v[8:11]
	v_mfma_f32_16x16x32_bf16 v[150:153], v[200:203], v[184:187], v[64:67]
	v_mfma_f32_16x16x32_bf16 v[154:157], v[204:207], v[184:187], v[72:75]
	v_mfma_f32_16x16x32_bf16 v[158:161], v[200:203], v[192:195], v[76:79]
	v_mfma_f32_16x16x32_bf16 v[172:175], v[204:207], v[192:195], v[84:87]
	s_barrier
	ds_read_b128 v[8:11], v137
	ds_read_b128 v[12:15], v138
	ds_read_b128 v[176:179], v139
	ds_read_b128 v[138:141], v140
	ds_read_b128 v[64:67], v129 offset:32768
	ds_read_b128 v[84:87], v129 offset:33792
	ds_read_b128 v[180:183], v132 offset:32768
	ds_read_b128 v[184:187], v132 offset:33792
	ds_read_b128 v[188:191], v131 offset:32768
	ds_read_b128 v[192:195], v131 offset:33792
	ds_read_b128 v[196:199], v130 offset:32768
	ds_read_b128 v[200:203], v130 offset:33792
	s_waitcnt vmcnt(2)
	s_barrier
	s_waitcnt lgkmcnt(0)
	v_mfma_f32_16x16x32_bf16 v[72:75], v[8:11], v[64:67], v[124:127]
	v_mfma_f32_16x16x32_bf16 v[76:79], v[176:179], v[64:67], v[120:123]
	v_mfma_f32_16x16x32_bf16 v[88:91], v[8:11], v[180:183], v[116:119]
	v_mfma_f32_16x16x32_bf16 v[92:95], v[176:179], v[180:183], v[112:115]
	v_mfma_f32_16x16x32_bf16 v[112:115], v[8:11], v[188:191], v[108:111]
	v_mfma_f32_16x16x32_bf16 v[120:123], v[176:179], v[188:191], v[104:107]
	v_mfma_f32_16x16x32_bf16 v[100:103], v[8:11], v[196:199], v[100:103]
	v_mfma_f32_16x16x32_bf16 v[96:99], v[176:179], v[196:199], v[96:99]
	v_mfma_f32_16x16x32_bf16 v[124:127], v[12:15], v[84:87], v[72:75]
	v_mfma_f32_16x16x32_bf16 v[116:119], v[138:141], v[84:87], v[76:79]
	v_mfma_f32_16x16x32_bf16 v[108:111], v[12:15], v[184:187], v[88:91]
	v_mfma_f32_16x16x32_bf16 v[104:107], v[138:141], v[184:187], v[92:95]
	v_mfma_f32_16x16x32_bf16 v[92:95], v[12:15], v[192:195], v[112:115]
	v_mfma_f32_16x16x32_bf16 v[88:91], v[138:141], v[192:195], v[120:123]
	v_mfma_f32_16x16x32_bf16 v[76:79], v[12:15], v[200:203], v[100:103]
	v_mfma_f32_16x16x32_bf16 v[72:75], v[138:141], v[200:203], v[96:99]
	s_barrier
; #define LDA(dst, b, h) _Pragma("unroll") for (int m = 0; m < 4; ++m) _Pragma("unroll") for (int k = 0; k < 2; ++k) \
;     dst[m][k] = *reinterpret_cast<const bf16x8*>(SA(b, h) + lds_byte(wr * 64 + m * 16 + fr, k * 32 + fq * 8))
; #define LDB(dst, b, h) _Pragma("unroll") for (int n = 0; n < 2; ++n) _Pragma("unroll") for (int k = 0; k < 2; ++k) \
;     dst[n][k] = *reinterpret_cast<const bf16x8*>(SB(b, h) + lds_byte(wc * 32 + n * 16 + fr, k * 32 + fq * 8))
; #define WAIT_V(n) asm volatile("s_waitcnt vmcnt(" #n ")" ::: "memory")
; #define WAIT_L(n) asm volatile("s_waitcnt lgkmcnt(" #n ")" ::: "memory")
; #define BAR __builtin_amdgcn_s_barrier()
;     ...
;       LDB(B1, 1, 1); WAIT_V(0); BAR; WAIT_L(0); MMA(0, 1, At, B1); BAR;
;       LDA(At, 1, 1); BAR; WAIT_L(0); MMA(1, 0, At, B0); MMA(1, 1, At, B1); BAR; }
;     if (wr == 0) BAR;
	ds_read_b128 v[204:207], v133
	ds_read_b128 v[208:211], v134
	ds_read_b128 v[212:215], v135
	ds_read_b128 v[134:137], v136
	s_waitcnt vmcnt(0)
	s_barrier
	s_waitcnt lgkmcnt(0)
	v_mfma_f32_16x16x32_bf16 v[96:99], v[204:207], v[64:67], v[164:167]
	v_mfma_f32_16x16x32_bf16 v[64:67], v[212:215], v[64:67], v[168:171]
	v_mfma_f32_16x16x32_bf16 v[80:83], v[204:207], v[180:183], v[80:83]
	v_mfma_f32_16x16x32_bf16 v[68:71], v[212:215], v[180:183], v[68:71]
	v_mfma_f32_16x16x32_bf16 v[60:63], v[204:207], v[188:191], v[60:63]
	v_mfma_f32_16x16x32_bf16 v[56:59], v[212:215], v[188:191], v[56:59]
	v_mfma_f32_16x16x32_bf16 v[52:55], v[204:207], v[196:199], v[52:55]
	v_mfma_f32_16x16x32_bf16 v[48:51], v[212:215], v[196:199], v[48:51]
	v_mfma_f32_16x16x32_bf16 v[120:123], v[208:211], v[84:87], v[96:99]
	v_mfma_f32_16x16x32_bf16 v[112:115], v[134:137], v[84:87], v[64:67]
	v_mfma_f32_16x16x32_bf16 v[100:103], v[208:211], v[184:187], v[80:83]
	v_mfma_f32_16x16x32_bf16 v[96:99], v[134:137], v[184:187], v[68:71]
	v_mfma_f32_16x16x32_bf16 v[84:87], v[208:211], v[192:195], v[60:63]
	v_mfma_f32_16x16x32_bf16 v[80:83], v[134:137], v[192:195], v[56:59]
	v_mfma_f32_16x16x32_bf16 v[68:71], v[208:211], v[200:203], v[52:55]
	v_mfma_f32_16x16x32_bf16 v[64:67], v[134:137], v[200:203], v[48:51]
	s_barrier
	s_nop 0
	ds_read_b128 v[48:51], v129 offset:49152
	ds_read_b128 v[162:165], v129 offset:50176
	ds_read_b128 v[52:55], v132 offset:49152
	ds_read_b128 v[166:169], v132 offset:50176
	ds_read_b128 v[180:183], v131 offset:49152
	ds_read_b128 v[184:187], v131 offset:50176
	ds_read_b128 v[188:191], v130 offset:49152
	ds_read_b128 v[130:133], v130 offset:50176
	s_barrier
	s_waitcnt lgkmcnt(0)
	v_mfma_f32_16x16x32_bf16 v[44:47], v[8:11], v[48:51], v[44:47]
	v_mfma_f32_16x16x32_bf16 v[40:43], v[176:179], v[48:51], v[40:43]
	v_mfma_f32_16x16x32_bf16 v[36:39], v[8:11], v[52:55], v[36:39]
	v_mfma_f32_16x16x32_bf16 v[32:35], v[176:179], v[52:55], v[32:35]
	v_mfma_f32_16x16x32_bf16 v[28:31], v[8:11], v[180:183], v[28:31]
	v_mfma_f32_16x16x32_bf16 v[24:27], v[176:179], v[180:183], v[24:27]
	v_mfma_f32_16x16x32_bf16 v[8:11], v[8:11], v[188:191], v[20:23]
	v_mfma_f32_16x16x32_bf16 v[16:19], v[176:179], v[188:191], v[16:19]
	v_mfma_f32_16x16x32_bf16 v[60:63], v[12:15], v[162:165], v[44:47]
	v_mfma_f32_16x16x32_bf16 v[56:59], v[138:141], v[162:165], v[40:43]
	v_mfma_f32_16x16x32_bf16 v[44:47], v[12:15], v[166:169], v[36:39]
	v_mfma_f32_16x16x32_bf16 v[40:43], v[138:141], v[166:169], v[32:35]
	v_mfma_f32_16x16x32_bf16 v[28:31], v[12:15], v[184:187], v[28:31]
	v_mfma_f32_16x16x32_bf16 v[24:27], v[138:141], v[184:187], v[24:27]
	v_mfma_f32_16x16x32_bf16 v[12:15], v[12:15], v[130:133], v[8:11]
	v_mfma_f32_16x16x32_bf16 v[8:11], v[138:141], v[130:133], v[16:19]
	v_mfma_f32_16x16x32_bf16 v[16:19], v[204:207], v[48:51], v[142:145]
	v_mfma_f32_16x16x32_bf16 v[20:23], v[212:215], v[48:51], v[146:149]
	v_mfma_f32_16x16x32_bf16 v[4:7], v[204:207], v[52:55], v[4:7]
	v_mfma_f32_16x16x32_bf16 v[0:3], v[212:215], v[52:55], v[0:3]
	v_mfma_f32_16x16x32_bf16 v[138:141], v[204:207], v[180:183], v[150:153]
	v_mfma_f32_16x16x32_bf16 v[142:145], v[212:215], v[180:183], v[154:157]
	v_mfma_f32_16x16x32_bf16 v[146:149], v[204:207], v[188:191], v[158:161]
	v_mfma_f32_16x16x32_bf16 v[150:153], v[212:215], v[188:191], v[172:175]
	v_mfma_f32_16x16x32_bf16 v[52:55], v[208:211], v[162:165], v[16:19]
	v_mfma_f32_16x16x32_bf16 v[48:51], v[134:137], v[162:165], v[20:23]
	v_mfma_f32_16x16x32_bf16 v[36:39], v[208:211], v[166:169], v[4:7]
	v_mfma_f32_16x16x32_bf16 v[32:35], v[134:137], v[166:169], v[0:3]
	v_mfma_f32_16x16x32_bf16 v[20:23], v[208:211], v[184:187], v[138:141]
	v_mfma_f32_16x16x32_bf16 v[16:19], v[134:137], v[184:187], v[142:145]
	v_mfma_f32_16x16x32_bf16 v[4:7], v[208:211], v[130:133], v[146:149]
	v_mfma_f32_16x16x32_bf16 v[0:3], v[134:137], v[130:133], v[150:153]
	v_cmp_gt_u32_e32 vcc, s40, v128
	s_barrier
	s_and_saveexec_b64 s[6:7], vcc
	s_cbranch_execz .LBB0_395
	s_barrier

; #define STAGE(P, RS, SOFF, OFF, kt) do { const int _so = (SOFF) + (kt) * (BK * 2); \
;     _Pragma("unroll") for (int _i = 0; _i < 2; ++_i) { \
;       __builtin_amdgcn_raw_ptr_buffer_load_lds(RS, (__attribute__((address_space(3))) void*)((P) + wave * 1024 + _i * 8192), 16, OFF[_i], _so, 0, 0); } } while (0)
; #define LDA(dst, b, h) _Pragma("unroll") for (int m = 0; m < 4; ++m) _Pragma("unroll") for (int k = 0; k < 2; ++k) \
;     dst[m][k] = *reinterpret_cast<const bf16x8*>(SA(b, h) + lds_byte(wr * 64 + m * 16 + fr, k * 32 + fq * 8))
; #define LDB(dst, b, h) _Pragma("unroll") for (int n = 0; n < 2; ++n) _Pragma("unroll") for (int k = 0; k < 2; ++k) \
;     dst[n][k] = *reinterpret_cast<const bf16x8*>(SB(b, h) + lds_byte(wc * 32 + n * 16 + fr, k * 32 + fq * 8))
; #define WAIT_V(n) asm volatile("s_waitcnt vmcnt(" #n ")" ::: "memory")
; #define WAIT_L(n) asm volatile("s_waitcnt lgkmcnt(" #n ")" ::: "memory")
; #define BAR __builtin_amdgcn_s_barrier()
; #define SCHED __builtin_amdgcn_sched_barrier(0)
;     ...
;     const int tid = opaque_tid(wave);
;     const int wid = tid >> 6, lane = tid & 63, wr = wid >> 2, wc = wid & 3, fr = lane & 15, fq = lane >> 4;
;     int offA[2], offB[2];
;     _Pragma("unroll") for (int i = 0; i < 2; ++i) {
;       int r, c; stage_rc(tid * 16 + i * 8192, r, c);
;       offA[i] = (r * lda + c) * 2; offB[i] = (r * ldb + c) * 2;
;     }
;     const int brow = pm * BM;
;     f32x4 acc[2][2][4][2];
;     _Pragma("unroll") for (int a = 0; a < 2; ++a) _Pragma("unroll") for (int b = 0; b < 2; ++b) _Pragma("unroll") for (int m = 0; m < 4; ++m) _Pragma("unroll") for (int n = 0; n < 2; ++n)
;       acc[a][b][m][n] = f32x4{0.f, 0.f, 0.f, 0.f};
;     bf16x8 At[4][2], B0[2][2], B1[2][2];
;     if (wr == 1) BAR;
;     if (first_tile) { WAIT_V(0); }
;     else if constexpr (mode == MODE_RESID_LN) { WAIT_V(0); }
;     else if constexpr (mode == MODE_SWIGLU) { WAIT_V(6); }
;     else if constexpr (mode == MODE_V) { WAIT_V(24); }
;     else { WAIT_V(12); }
;     first_tile = false;
;     BAR;
;     BAR;
;     for (int t = 0; t < nt - 2; t += 2) {
;       LDB(B0, 0, 0); SCHED; LDA(At, 0, 0); STAGE(SA(1, 1), rsA, sA1, offA, t + 1);
;       WAIT_L(8); BAR; WAIT_L(0); MMA(0, 0, At, B0); BAR; SCHED;
;       LDB(B1, 0, 1); STAGE(SB(0, 0), rsB, sB0, offB, t + 2);
;       BAR; WAIT_L(0); MMA(0, 1, At, B1); BAR;
.LBB0_493:
	v_bfe_i32 v4, v128, 27, 1
	v_lshlrev_b32_e32 v2, 4, v128
	v_lshrrev_b32_e32 v4, 22, v4
	v_add_u32_e32 v4, v2, v4
	v_and_b32_e32 v4, 0xfffffc00, v4
	v_sub_u32_e32 v4, v2, v4
	v_lshrrev_b32_e32 v5, 4, v4
	v_bitop3_b32 v4, v5, v4, 32 bitop3:0x6c
	v_ashrrev_i32_e32 v3, 31, v128
	v_ashrrev_i32_e32 v6, 31, v4
	v_lshrrev_b32_e32 v3, 26, v3
	v_lshrrev_b32_e32 v6, 26, v6
	v_add_u32_e32 v3, v128, v3
	v_add_u32_e32 v6, v4, v6
	v_ashrrev_i32_e32 v3, 6, v3
	v_lshrrev_b32_e32 v7, 6, v6
	v_and_b32_e32 v6, 0xc0, v6
	v_lshlrev_b32_e32 v5, 3, v3
	v_lshlrev_b32_e32 v3, 5, v3
	v_sub_u32_e32 v4, v4, v6
	v_and_b32_e32 v5, 0x7fff0, v5
	v_and_b32_e32 v3, 32, v3
	v_ashrrev_i16_sdwa v4, v216, sext(v4) dst_sel:DWORD dst_unused:UNUSED_PAD src0_sel:DWORD src1_sel:BYTE_0
	v_add_u32_sdwa v3, v3, sext(v4) dst_sel:DWORD dst_unused:UNUSED_PAD src0_sel:DWORD src1_sel:WORD_0
	v_add_lshl_u32 v4, v7, v5, 13
	v_add_u32_e32 v2, 0x2000, v2
	v_lshl_add_u32 v141, v3, 1, v4
	v_ashrrev_i32_e32 v3, 31, v2
	v_lshrrev_b32_e32 v3, 22, v3
	v_add_u32_e32 v3, v2, v3
	v_ashrrev_i32_e32 v3, 10, v3
	v_mul_i32_i24_e32 v4, 0x400, v3
	v_sub_u32_e32 v2, v2, v4
	v_lshrrev_b32_e32 v4, 4, v2
	v_bitop3_b32 v2, v4, v2, 32 bitop3:0x6c
	v_ashrrev_i32_e32 v5, 31, v2
	v_lshrrev_b32_e32 v5, 26, v5
	v_add_u32_e32 v5, v2, v5
	v_lshrrev_b32_e32 v6, 6, v5
	v_and_b32_e32 v5, 0xc0, v5
	v_lshlrev_b32_e32 v4, 3, v3
	v_lshlrev_b32_e32 v3, 5, v3
	v_sub_u32_e32 v2, v2, v5
	v_and_b32_e32 v4, 0x7fff0, v4
	v_and_b32_e32 v3, 32, v3
	v_ashrrev_i16_sdwa v2, v216, sext(v2) dst_sel:DWORD dst_unused:UNUSED_PAD src0_sel:DWORD src1_sel:BYTE_0
	v_add_u32_sdwa v2, v3, sext(v2) dst_sel:DWORD dst_unused:UNUSED_PAD src0_sel:DWORD src1_sel:WORD_0
	v_add_lshl_u32 v3, v6, v4, 13
	v_lshl_add_u32 v142, v2, 1, v3
	v_and_b32_e32 v3, 15, v0
	v_lshlrev_b32_e32 v5, 2, v0
	v_and_b32_e32 v2, 48, v0
	v_lshlrev_b32_e32 v3, 6, v3
	v_and_b32_e32 v5, 32, v5
	v_or_b32_e32 v4, v3, v2
	v_bitop3_b32 v3, v3, v5, v2 bitop3:0x36
	v_lshlrev_b32_e32 v6, 6, v128
	s_movk_i32 s1, 0x3000
	v_and_or_b32 v3, v6, s1, v3
	v_lshlrev_b32_e32 v0, 6, v0
	s_movk_i32 s1, 0x3c0
	v_lshlrev_b32_e32 v1, 13, v1
	v_and_or_b32 v0, v0, s1, v2
	v_bitop3_b32 v0, v1, v0, v5 bitop3:0xf6
	v_or_b32_e32 v6, 0x400, v3
	v_or_b32_e32 v7, 0x800, v3
	v_or_b32_e32 v8, 0xc00, v3
	v_or_b32_e32 v132, 0x800, v0
	v_or_b32_e32 v131, 0x1000, v0
	v_or_b32_e32 v130, 0x1800, v0
	v_mov_b32_e32 v0, 0
	v_bitop3_b32 v129, v4, v1, v5 bitop3:0xde
	s_mov_b32 s1, -2
	s_mov_b32 s3, 0
	v_or_b32_e32 v147, 0x10000, v3
	v_or_b32_e32 v148, 0x10000, v6
	v_or_b32_e32 v149, 0x10000, v7
	v_or_b32_e32 v150, 0x10000, v8
	v_or_b32_e32 v143, 0x14000, v3
	v_or_b32_e32 v144, 0x14000, v6
	v_or_b32_e32 v145, 0x14000, v7
	v_or_b32_e32 v146, 0x14000, v8
	v_or_b32_e32 v137, 0x18000, v3
	v_or_b32_e32 v138, 0x18000, v6
	v_or_b32_e32 v139, 0x18000, v7
	v_or_b32_e32 v140, 0x18000, v8
	v_or_b32_e32 v133, 0x1c000, v3
	v_or_b32_e32 v134, 0x1c000, v6
	v_or_b32_e32 v135, 0x1c000, v7
	v_or_b32_e32 v136, 0x1c000, v8
	s_barrier
	s_barrier
	ds_read_b128 v[152:155], v147
	ds_read_b128 v[156:159], v148
	ds_read_b128 v[160:163], v149
	ds_read_b128 v[164:167], v150
	s_add_i32 s5, s82, s3
	s_add_i32 s6, s5, 0x80
	s_mov_b32 m0, s36
	ds_read_b128 v[168:171], v129
	ds_read_b128 v[172:175], v129 offset:1024
	ds_read_b128 v[176:179], v132
	ds_read_b128 v[180:183], v132 offset:1024
	ds_read_b128 v[184:187], v131
	ds_read_b128 v[188:191], v131 offset:1024
	ds_read_b128 v[192:195], v130
	ds_read_b128 v[196:199], v130 offset:1024
	buffer_load_dwordx4 v141, s[8:11], s6 offen lds
	s_mov_b32 m0, s59
	s_nop 0
	buffer_load_dwordx4 v142, s[8:11], s6 offen lds
	s_waitcnt lgkmcnt(8)
	s_barrier
	s_waitcnt lgkmcnt(0)
	v_mfma_f32_16x16x32_bf16 v[124:127], v[152:155], v[168:171], 0
	v_mfma_f32_16x16x32_bf16 v[124:127], v[156:159], v[172:175], v[124:127]
	v_mfma_f32_16x16x32_bf16 v[120:123], v[164:167], v[172:175], 0
	v_mfma_f32_16x16x32_bf16 v[120:123], v[160:163], v[168:171], v[120:123]
	v_mfma_f32_16x16x32_bf16 v[112:115], v[160:163], v[176:179], 0
	v_mfma_f32_16x16x32_bf16 v[112:115], v[164:167], v[180:183], v[112:115]
	v_mfma_f32_16x16x32_bf16 v[116:119], v[156:159], v[180:183], 0
	v_mfma_f32_16x16x32_bf16 v[116:119], v[152:155], v[176:179], v[116:119]
	v_mfma_f32_16x16x32_bf16 v[108:111], v[152:155], v[184:187], 0
	v_mfma_f32_16x16x32_bf16 v[108:111], v[156:159], v[188:191], v[108:111]
	v_mfma_f32_16x16x32_bf16 v[104:107], v[164:167], v[188:191], 0
	v_mfma_f32_16x16x32_bf16 v[104:107], v[160:163], v[184:187], v[104:107]
	v_mfma_f32_16x16x32_bf16 v[96:99], v[160:163], v[192:195], 0
	v_mfma_f32_16x16x32_bf16 v[96:99], v[164:167], v[196:199], v[96:99]
	v_mfma_f32_16x16x32_bf16 v[100:103], v[156:159], v[196:199], 0
	v_mfma_f32_16x16x32_bf16 v[100:103], v[152:155], v[192:195], v[100:103]
	s_barrier
	s_add_i32 s6, s84, s3
	s_add_i32 s7, s6, 0x100
	s_mov_b32 s14, s10
	s_mov_b32 s15, s11
	s_mov_b32 m0, s37
	ds_read_b128 v[200:203], v143
	ds_read_b128 v[204:207], v144
	ds_read_b128 v[208:211], v145
	ds_read_b128 v[212:215], v146
	buffer_load_dwordx4 v141, s[12:15], s7 offen lds
	s_mov_b32 m0, s70
	s_nop 0
	buffer_load_dwordx4 v142, s[12:15], s7 offen lds
	s_barrier
; #define STAGE(P, RS, SOFF, OFF, kt) do { const int _so = (SOFF) + (kt) * (BK * 2); \
;     _Pragma("unroll") for (int _i = 0; _i < 2; ++_i) { \
;       __builtin_amdgcn_raw_ptr_buffer_load_lds(RS, (__attribute__((address_space(3))) void*)((P) + wave * 1024 + _i * 8192), 16, OFF[_i], _so, 0, 0); } } while (0)
; #define LDA(dst, b, h) _Pragma("unroll") for (int m = 0; m < 4; ++m) _Pragma("unroll") for (int k = 0; k < 2; ++k) \
;     dst[m][k] = *reinterpret_cast<const bf16x8*>(SA(b, h) + lds_byte(wr * 64 + m * 16 + fr, k * 32 + fq * 8))
; #define LDB(dst, b, h) _Pragma("unroll") for (int n = 0; n < 2; ++n) _Pragma("unroll") for (int k = 0; k < 2; ++k) \
;     dst[n][k] = *reinterpret_cast<const bf16x8*>(SB(b, h) + lds_byte(wc * 32 + n * 16 + fr, k * 32 + fq * 8))
; #define WAIT_V(n) asm volatile("s_waitcnt vmcnt(" #n ")" ::: "memory")
; #define WAIT_L(n) asm volatile("s_waitcnt lgkmcnt(" #n ")" ::: "memory")
; #define BAR __builtin_amdgcn_s_barrier()
; #define SCHED __builtin_amdgcn_sched_barrier(0)
;     ...
;       BAR; WAIT_L(0); MMA(0, 1, At, B1); BAR;
;       LDA(At, 0, 1); STAGE(SA(0, 0), rsA, sA0, offA, t + 2);
;       BAR; WAIT_L(0); MMA(1, 0, At, B0); BAR; SCHED;
;       STAGE(SB(0, 1), rsB, sB1, offB, t + 2);
;       WAIT_V(6); BAR; MMA(1, 1, At, B1); BAR;
;       LDB(B0, 1, 0); SCHED; LDA(At, 1, 0); STAGE(SA(0, 1), rsA, sA1, offA, t + 2);
;       WAIT_L(8); BAR; WAIT_L(0); MMA(0, 0, At, B0); BAR; SCHED;
	s_waitcnt lgkmcnt(0)
	v_mfma_f32_16x16x32_bf16 v[92:95], v[200:203], v[168:171], 0
	v_mfma_f32_16x16x32_bf16 v[92:95], v[204:207], v[172:175], v[92:95]
	v_mfma_f32_16x16x32_bf16 v[88:91], v[212:215], v[172:175], 0
	v_mfma_f32_16x16x32_bf16 v[88:91], v[208:211], v[168:171], v[88:91]
	v_mfma_f32_16x16x32_bf16 v[68:71], v[208:211], v[176:179], 0
	v_mfma_f32_16x16x32_bf16 v[68:71], v[212:215], v[180:183], v[68:71]
	v_mfma_f32_16x16x32_bf16 v[80:83], v[204:207], v[180:183], 0
	v_mfma_f32_16x16x32_bf16 v[80:83], v[200:203], v[176:179], v[80:83]
	v_mfma_f32_16x16x32_bf16 v[60:63], v[200:203], v[184:187], 0
	v_mfma_f32_16x16x32_bf16 v[60:63], v[204:207], v[188:191], v[60:63]
	v_mfma_f32_16x16x32_bf16 v[56:59], v[212:215], v[188:191], 0
	v_mfma_f32_16x16x32_bf16 v[56:59], v[208:211], v[184:187], v[56:59]
	v_mfma_f32_16x16x32_bf16 v[48:51], v[208:211], v[192:195], 0
	v_mfma_f32_16x16x32_bf16 v[48:51], v[212:215], v[196:199], v[48:51]
	v_mfma_f32_16x16x32_bf16 v[52:55], v[204:207], v[196:199], 0
	v_mfma_f32_16x16x32_bf16 v[52:55], v[200:203], v[192:195], v[52:55]
	s_barrier
	s_add_i32 s7, s83, s3
	s_add_i32 s22, s7, 0x100
	s_mov_b32 m0, s35
	ds_read_b128 v[168:171], v129 offset:16384
	ds_read_b128 v[172:175], v129 offset:17408
	ds_read_b128 v[176:179], v132 offset:16384
	ds_read_b128 v[180:183], v132 offset:17408
	ds_read_b128 v[184:187], v131 offset:16384
	ds_read_b128 v[188:191], v131 offset:17408
	ds_read_b128 v[192:195], v130 offset:16384
	ds_read_b128 v[196:199], v130 offset:17408
	buffer_load_dwordx4 v141, s[8:11], s22 offen lds
	s_mov_b32 m0, s95
	s_nop 0
	buffer_load_dwordx4 v142, s[8:11], s22 offen lds
	s_barrier
	s_waitcnt lgkmcnt(0)
	v_mfma_f32_16x16x32_bf16 v[44:47], v[152:155], v[168:171], 0
	v_mfma_f32_16x16x32_bf16 v[44:47], v[156:159], v[172:175], v[44:47]
	v_mfma_f32_16x16x32_bf16 v[40:43], v[164:167], v[172:175], 0
	v_mfma_f32_16x16x32_bf16 v[40:43], v[160:163], v[168:171], v[40:43]
	v_mfma_f32_16x16x32_bf16 v[32:35], v[160:163], v[176:179], 0
	v_mfma_f32_16x16x32_bf16 v[32:35], v[164:167], v[180:183], v[32:35]
	v_mfma_f32_16x16x32_bf16 v[36:39], v[156:159], v[180:183], 0
	v_mfma_f32_16x16x32_bf16 v[36:39], v[152:155], v[176:179], v[36:39]
	v_mfma_f32_16x16x32_bf16 v[28:31], v[152:155], v[184:187], 0
	v_mfma_f32_16x16x32_bf16 v[28:31], v[156:159], v[188:191], v[28:31]
	v_mfma_f32_16x16x32_bf16 v[24:27], v[164:167], v[188:191], 0
	v_mfma_f32_16x16x32_bf16 v[24:27], v[160:163], v[184:187], v[24:27]
	v_mfma_f32_16x16x32_bf16 v[16:19], v[160:163], v[192:195], 0
	v_mfma_f32_16x16x32_bf16 v[16:19], v[164:167], v[196:199], v[16:19]
	v_mfma_f32_16x16x32_bf16 v[20:23], v[156:159], v[196:199], 0
	v_mfma_f32_16x16x32_bf16 v[20:23], v[152:155], v[192:195], v[20:23]
	s_barrier
	s_add_i32 s22, s85, s3
	s_add_i32 s23, s22, 0x100
	s_mov_b32 m0, s38
	s_nop 0
	buffer_load_dwordx4 v141, s[12:15], s23 offen lds
	s_mov_b32 m0, s71
	s_nop 0
	buffer_load_dwordx4 v142, s[12:15], s23 offen lds
	s_waitcnt vmcnt(6)
	s_barrier
	v_mfma_f32_16x16x32_bf16 v[12:15], v[200:203], v[168:171], 0
	v_mfma_f32_16x16x32_bf16 v[12:15], v[204:207], v[172:175], v[12:15]
	v_mfma_f32_16x16x32_bf16 v[8:11], v[212:215], v[172:175], 0
	v_mfma_f32_16x16x32_bf16 v[8:11], v[208:211], v[168:171], v[8:11]
	v_mfma_f32_16x16x32_bf16 v[0:3], v[208:211], v[176:179], 0
	v_mfma_f32_16x16x32_bf16 v[0:3], v[212:215], v[180:183], v[0:3]
	v_mfma_f32_16x16x32_bf16 v[4:7], v[204:207], v[180:183], 0
	v_mfma_f32_16x16x32_bf16 v[4:7], v[200:203], v[176:179], v[4:7]
	v_mfma_f32_16x16x32_bf16 v[64:67], v[200:203], v[184:187], 0
	v_mfma_f32_16x16x32_bf16 v[64:67], v[204:207], v[188:191], v[64:67]
	v_mfma_f32_16x16x32_bf16 v[72:75], v[212:215], v[188:191], 0
	v_mfma_f32_16x16x32_bf16 v[72:75], v[208:211], v[184:187], v[72:75]
	v_mfma_f32_16x16x32_bf16 v[84:87], v[208:211], v[192:195], 0
	v_mfma_f32_16x16x32_bf16 v[84:87], v[212:215], v[196:199], v[84:87]
	v_mfma_f32_16x16x32_bf16 v[76:79], v[204:207], v[196:199], 0
	v_mfma_f32_16x16x32_bf16 v[76:79], v[200:203], v[192:195], v[76:79]
	s_barrier
	ds_read_b128 v[152:155], v137
	ds_read_b128 v[156:159], v138
	ds_read_b128 v[160:163], v139
	ds_read_b128 v[164:167], v140
	s_addk_i32 s5, 0x100
	s_mov_b32 m0, s39
	ds_read_b128 v[168:171], v129 offset:32768
	ds_read_b128 v[172:175], v129 offset:33792
	ds_read_b128 v[176:179], v132 offset:32768
	ds_read_b128 v[180:183], v132 offset:33792
	ds_read_b128 v[184:187], v131 offset:32768
	ds_read_b128 v[188:191], v131 offset:33792
	ds_read_b128 v[192:195], v130 offset:32768
	ds_read_b128 v[196:199], v130 offset:33792
	buffer_load_dwordx4 v141, s[8:11], s5 offen lds
	s_mov_b32 m0, s97
	s_nop 0
	buffer_load_dwordx4 v142, s[8:11], s5 offen lds
	s_waitcnt lgkmcnt(8)
	s_barrier
; #define STAGE(P, RS, SOFF, OFF, kt) do { const int _so = (SOFF) + (kt) * (BK * 2); \
;     _Pragma("unroll") for (int _i = 0; _i < 2; ++_i) { \
;       __builtin_amdgcn_raw_ptr_buffer_load_lds(RS, (__attribute__((address_space(3))) void*)((P) + wave * 1024 + _i * 8192), 16, OFF[_i], _so, 0, 0); } } while (0)
; #define LDA(dst, b, h) _Pragma("unroll") for (int m = 0; m < 4; ++m) _Pragma("unroll") for (int k = 0; k < 2; ++k) \
;     dst[m][k] = *reinterpret_cast<const bf16x8*>(SA(b, h) + lds_byte(wr * 64 + m * 16 + fr, k * 32 + fq * 8))
; #define LDB(dst, b, h) _Pragma("unroll") for (int n = 0; n < 2; ++n) _Pragma("unroll") for (int k = 0; k < 2; ++k) \
;     dst[n][k] = *reinterpret_cast<const bf16x8*>(SB(b, h) + lds_byte(wc * 32 + n * 16 + fr, k * 32 + fq * 8))
; #define WAIT_V(n) asm volatile("s_waitcnt vmcnt(" #n ")" ::: "memory")
; #define WAIT_L(n) asm volatile("s_waitcnt lgkmcnt(" #n ")" ::: "memory")
; #define BAR __builtin_amdgcn_s_barrier()
; #define SCHED __builtin_amdgcn_sched_barrier(0)
;     ...
;       WAIT_L(8); BAR; WAIT_L(0); MMA(0, 0, At, B0); BAR; SCHED;
;       LDB(B1, 1, 1); STAGE(SB(1, 0), rsB, sB0, offB, t + 3);
;       BAR; WAIT_L(0); MMA(0, 1, At, B1); BAR;
;       LDA(At, 1, 1); STAGE(SA(1, 0), rsA, sA0, offA, t + 3);
;       BAR; WAIT_L(0); MMA(1, 0, At, B0); BAR; SCHED;
;       STAGE(SB(1, 1), rsB, sB1, offB, t + 3);
;       WAIT_V(6); BAR; MMA(1, 1, At, B1); BAR;
;     }
	s_waitcnt lgkmcnt(0)
	v_mfma_f32_16x16x32_bf16 v[124:127], v[152:155], v[168:171], v[124:127]
	v_mfma_f32_16x16x32_bf16 v[124:127], v[156:159], v[172:175], v[124:127]
	v_mfma_f32_16x16x32_bf16 v[120:123], v[164:167], v[172:175], v[120:123]
	v_mfma_f32_16x16x32_bf16 v[120:123], v[160:163], v[168:171], v[120:123]
	v_mfma_f32_16x16x32_bf16 v[112:115], v[160:163], v[176:179], v[112:115]
	v_mfma_f32_16x16x32_bf16 v[112:115], v[164:167], v[180:183], v[112:115]
	v_mfma_f32_16x16x32_bf16 v[116:119], v[156:159], v[180:183], v[116:119]
	v_mfma_f32_16x16x32_bf16 v[116:119], v[152:155], v[176:179], v[116:119]
	v_mfma_f32_16x16x32_bf16 v[108:111], v[152:155], v[184:187], v[108:111]
	v_mfma_f32_16x16x32_bf16 v[108:111], v[156:159], v[188:191], v[108:111]
	v_mfma_f32_16x16x32_bf16 v[104:107], v[164:167], v[188:191], v[104:107]
	v_mfma_f32_16x16x32_bf16 v[104:107], v[160:163], v[184:187], v[104:107]
	v_mfma_f32_16x16x32_bf16 v[96:99], v[160:163], v[192:195], v[96:99]
	v_mfma_f32_16x16x32_bf16 v[96:99], v[164:167], v[196:199], v[96:99]
	v_mfma_f32_16x16x32_bf16 v[100:103], v[156:159], v[196:199], v[100:103]
	v_mfma_f32_16x16x32_bf16 v[100:103], v[152:155], v[192:195], v[100:103]
	s_barrier
	s_addk_i32 s6, 0x180
	s_mov_b32 m0, s92
	ds_read_b128 v[200:203], v133
	ds_read_b128 v[204:207], v134
	ds_read_b128 v[208:211], v135
	ds_read_b128 v[212:215], v136
	buffer_load_dwordx4 v141, s[12:15], s6 offen lds
	s_mov_b32 m0, s56
	s_nop 0
	buffer_load_dwordx4 v142, s[12:15], s6 offen lds
	s_barrier
	s_waitcnt lgkmcnt(0)
	v_mfma_f32_16x16x32_bf16 v[92:95], v[200:203], v[168:171], v[92:95]
	v_mfma_f32_16x16x32_bf16 v[92:95], v[204:207], v[172:175], v[92:95]
	v_mfma_f32_16x16x32_bf16 v[88:91], v[212:215], v[172:175], v[88:91]
	v_mfma_f32_16x16x32_bf16 v[88:91], v[208:211], v[168:171], v[88:91]
	v_mfma_f32_16x16x32_bf16 v[68:71], v[208:211], v[176:179], v[68:71]
	v_mfma_f32_16x16x32_bf16 v[68:71], v[212:215], v[180:183], v[68:71]
	v_mfma_f32_16x16x32_bf16 v[80:83], v[204:207], v[180:183], v[80:83]
	v_mfma_f32_16x16x32_bf16 v[80:83], v[200:203], v[176:179], v[80:83]
	v_mfma_f32_16x16x32_bf16 v[60:63], v[200:203], v[184:187], v[60:63]
	v_mfma_f32_16x16x32_bf16 v[60:63], v[204:207], v[188:191], v[60:63]
	v_mfma_f32_16x16x32_bf16 v[56:59], v[212:215], v[188:191], v[56:59]
	v_mfma_f32_16x16x32_bf16 v[56:59], v[208:211], v[184:187], v[56:59]
	v_mfma_f32_16x16x32_bf16 v[48:51], v[208:211], v[192:195], v[48:51]
	v_mfma_f32_16x16x32_bf16 v[48:51], v[212:215], v[196:199], v[48:51]
	v_mfma_f32_16x16x32_bf16 v[52:55], v[204:207], v[196:199], v[52:55]
	v_mfma_f32_16x16x32_bf16 v[52:55], v[200:203], v[192:195], v[52:55]
	s_barrier
	s_addk_i32 s7, 0x180
	s_mov_b32 m0, s93
	ds_read_b128 v[168:171], v129 offset:49152
	ds_read_b128 v[172:175], v129 offset:50176
	ds_read_b128 v[176:179], v132 offset:49152
	ds_read_b128 v[180:183], v132 offset:50176
	ds_read_b128 v[184:187], v131 offset:49152
	ds_read_b128 v[188:191], v131 offset:50176
	ds_read_b128 v[192:195], v130 offset:49152
	ds_read_b128 v[196:199], v130 offset:50176
	buffer_load_dwordx4 v141, s[8:11], s7 offen lds
	s_mov_b32 m0, s57
	s_nop 0
	buffer_load_dwordx4 v142, s[8:11], s7 offen lds
	s_barrier
	s_waitcnt lgkmcnt(0)
	v_mfma_f32_16x16x32_bf16 v[44:47], v[152:155], v[168:171], v[44:47]
	v_mfma_f32_16x16x32_bf16 v[44:47], v[156:159], v[172:175], v[44:47]
	v_mfma_f32_16x16x32_bf16 v[40:43], v[164:167], v[172:175], v[40:43]
	v_mfma_f32_16x16x32_bf16 v[40:43], v[160:163], v[168:171], v[40:43]
	v_mfma_f32_16x16x32_bf16 v[32:35], v[160:163], v[176:179], v[32:35]
	v_mfma_f32_16x16x32_bf16 v[32:35], v[164:167], v[180:183], v[32:35]
	v_mfma_f32_16x16x32_bf16 v[36:39], v[156:159], v[180:183], v[36:39]
	v_mfma_f32_16x16x32_bf16 v[36:39], v[152:155], v[176:179], v[36:39]
	v_mfma_f32_16x16x32_bf16 v[28:31], v[152:155], v[184:187], v[28:31]
	v_mfma_f32_16x16x32_bf16 v[28:31], v[156:159], v[188:191], v[28:31]
	v_mfma_f32_16x16x32_bf16 v[24:27], v[164:167], v[188:191], v[24:27]
	v_mfma_f32_16x16x32_bf16 v[24:27], v[160:163], v[184:187], v[24:27]
	v_mfma_f32_16x16x32_bf16 v[16:19], v[160:163], v[192:195], v[16:19]
	v_mfma_f32_16x16x32_bf16 v[16:19], v[164:167], v[196:199], v[16:19]
	v_mfma_f32_16x16x32_bf16 v[20:23], v[156:159], v[196:199], v[20:23]
	v_mfma_f32_16x16x32_bf16 v[20:23], v[152:155], v[192:195], v[20:23]
	s_barrier
	s_addk_i32 s22, 0x180
	s_mov_b32 m0, s94
	s_nop 0
	buffer_load_dwordx4 v141, s[12:15], s22 offen lds
	s_mov_b32 m0, s58
	s_nop 0
	buffer_load_dwordx4 v142, s[12:15], s22 offen lds
	s_add_i32 s1, s1, 2
	s_addk_i32 s3, 0x100
	s_cmp_gt_u32 s1, 59
	s_cbranch_scc0 .LBB0_494
	s_branch .Lmy_post_494

; #define STAGE(P, RS, SOFF, OFF, kt) do { const int _so = (SOFF) + (kt) * (BK * 2); \
;     _Pragma("unroll") for (int _i = 0; _i < 2; ++_i) { \
;       __builtin_amdgcn_raw_ptr_buffer_load_lds(RS, (__attribute__((address_space(3))) void*)((P) + wave * 1024 + _i * 8192), 16, OFF[_i], _so, 0, 0); } } while (0)
; #define LDA(dst, b, h) _Pragma("unroll") for (int m = 0; m < 4; ++m) _Pragma("unroll") for (int k = 0; k < 2; ++k) \
;     dst[m][k] = *reinterpret_cast<const bf16x8*>(SA(b, h) + lds_byte(wr * 64 + m * 16 + fr, k * 32 + fq * 8))
; #define LDB(dst, b, h) _Pragma("unroll") for (int n = 0; n < 2; ++n) _Pragma("unroll") for (int k = 0; k < 2; ++k) \
;     dst[n][k] = *reinterpret_cast<const bf16x8*>(SB(b, h) + lds_byte(wc * 32 + n * 16 + fr, k * 32 + fq * 8))
; #define WAIT_V(n) asm volatile("s_waitcnt vmcnt(" #n ")" ::: "memory")
; #define WAIT_L(n) asm volatile("s_waitcnt lgkmcnt(" #n ")" ::: "memory")
; #define BAR __builtin_amdgcn_s_barrier()
;     ...
;       WAIT_V(6); BAR; MMA(1, 1, At, B1); BAR;
;     }
;     { LDB(B0, 0, 0); LDA(At, 0, 0); STAGE(SA(1, 1), rsA, sA1, offA, nt - 1);
;       BAR; WAIT_L(0); MMA(0, 0, At, B0); BAR;
;       LDB(B1, 0, 1); BAR; WAIT_L(0); MMA(0, 1, At, B1); BAR;
;       LDA(At, 0, 1); WAIT_V(4); BAR; WAIT_L(0); MMA(1, 0, At, B0); MMA(1, 1, At, B1); BAR; }
.Lmy_post_494:
	s_waitcnt vmcnt(6)
	s_barrier
	v_mfma_f32_16x16x32_bf16 v[12:15], v[200:203], v[168:171], v[12:15]
	v_mfma_f32_16x16x32_bf16 v[12:15], v[204:207], v[172:175], v[12:15]
	v_mfma_f32_16x16x32_bf16 v[8:11], v[212:215], v[172:175], v[8:11]
	v_mfma_f32_16x16x32_bf16 v[8:11], v[208:211], v[168:171], v[8:11]
	v_mfma_f32_16x16x32_bf16 v[0:3], v[208:211], v[176:179], v[0:3]
	v_mfma_f32_16x16x32_bf16 v[0:3], v[212:215], v[180:183], v[0:3]
	v_mfma_f32_16x16x32_bf16 v[4:7], v[204:207], v[180:183], v[4:7]
	v_mfma_f32_16x16x32_bf16 v[4:7], v[200:203], v[176:179], v[4:7]
	v_mfma_f32_16x16x32_bf16 v[64:67], v[200:203], v[184:187], v[64:67]
	v_mfma_f32_16x16x32_bf16 v[64:67], v[204:207], v[188:191], v[64:67]
	v_mfma_f32_16x16x32_bf16 v[72:75], v[212:215], v[188:191], v[72:75]
	v_mfma_f32_16x16x32_bf16 v[72:75], v[208:211], v[184:187], v[72:75]
	v_mfma_f32_16x16x32_bf16 v[84:87], v[208:211], v[192:195], v[84:87]
	v_mfma_f32_16x16x32_bf16 v[84:87], v[212:215], v[196:199], v[84:87]
	v_mfma_f32_16x16x32_bf16 v[76:79], v[204:207], v[196:199], v[76:79]
	v_mfma_f32_16x16x32_bf16 v[76:79], v[200:203], v[192:195], v[76:79]
	s_barrier
	s_add_i32 s1, s82, 0x1f80
	s_mov_b32 m0, s36
	ds_read_b128 v[152:155], v147
	ds_read_b128 v[156:159], v148
	ds_read_b128 v[160:163], v149
	ds_read_b128 v[148:151], v150
	ds_read_b128 v[164:167], v129
	ds_read_b128 v[168:171], v129 offset:1024
	ds_read_b128 v[172:175], v132
	ds_read_b128 v[176:179], v132 offset:1024
	ds_read_b128 v[180:183], v131
	ds_read_b128 v[184:187], v131 offset:1024
	ds_read_b128 v[188:191], v130
	ds_read_b128 v[192:195], v130 offset:1024
	buffer_load_dwordx4 v141, s[8:11], s1 offen lds
	s_mov_b32 m0, s59
	s_nop 0
	buffer_load_dwordx4 v142, s[8:11], s1 offen lds
	s_barrier
	s_waitcnt lgkmcnt(0)
	v_mfma_f32_16x16x32_bf16 v[124:127], v[152:155], v[164:167], v[124:127]
	v_mfma_f32_16x16x32_bf16 v[124:127], v[156:159], v[168:171], v[124:127]
	v_mfma_f32_16x16x32_bf16 v[120:123], v[148:151], v[168:171], v[120:123]
	v_mfma_f32_16x16x32_bf16 v[120:123], v[160:163], v[164:167], v[120:123]
	v_mfma_f32_16x16x32_bf16 v[112:115], v[160:163], v[172:175], v[112:115]
	v_mfma_f32_16x16x32_bf16 v[112:115], v[148:151], v[176:179], v[112:115]
	v_mfma_f32_16x16x32_bf16 v[116:119], v[156:159], v[176:179], v[116:119]
	v_mfma_f32_16x16x32_bf16 v[116:119], v[152:155], v[172:175], v[116:119]
	v_mfma_f32_16x16x32_bf16 v[108:111], v[152:155], v[180:183], v[108:111]
	v_mfma_f32_16x16x32_bf16 v[108:111], v[156:159], v[184:187], v[108:111]
	v_mfma_f32_16x16x32_bf16 v[104:107], v[148:151], v[184:187], v[104:107]
	v_mfma_f32_16x16x32_bf16 v[104:107], v[160:163], v[180:183], v[104:107]
	v_mfma_f32_16x16x32_bf16 v[96:99], v[160:163], v[188:191], v[96:99]
	v_mfma_f32_16x16x32_bf16 v[96:99], v[148:151], v[192:195], v[96:99]
	v_mfma_f32_16x16x32_bf16 v[100:103], v[156:159], v[192:195], v[100:103]
	v_mfma_f32_16x16x32_bf16 v[100:103], v[152:155], v[188:191], v[100:103]
	s_barrier
	ds_read_b128 v[196:199], v143
	ds_read_b128 v[200:203], v144
	ds_read_b128 v[142:145], v145
	ds_read_b128 v[204:207], v146
	s_barrier
	s_waitcnt lgkmcnt(0)
	v_mfma_f32_16x16x32_bf16 v[80:83], v[196:199], v[172:175], v[80:83]
	v_mfma_f32_16x16x32_bf16 v[68:71], v[142:145], v[172:175], v[68:71]
	v_mfma_f32_16x16x32_bf16 v[60:63], v[196:199], v[180:183], v[60:63]
	v_mfma_f32_16x16x32_bf16 v[56:59], v[142:145], v[180:183], v[56:59]
	v_mfma_f32_16x16x32_bf16 v[52:55], v[196:199], v[188:191], v[52:55]
	v_mfma_f32_16x16x32_bf16 v[48:51], v[142:145], v[188:191], v[48:51]
	v_mfma_f32_16x16x32_bf16 v[92:95], v[196:199], v[164:167], v[92:95]
	v_mfma_f32_16x16x32_bf16 v[88:91], v[142:145], v[164:167], v[88:91]
	v_mfma_f32_16x16x32_bf16 v[80:83], v[200:203], v[176:179], v[80:83]
	v_mfma_f32_16x16x32_bf16 v[68:71], v[204:207], v[176:179], v[68:71]
	v_mfma_f32_16x16x32_bf16 v[60:63], v[200:203], v[184:187], v[60:63]
	v_mfma_f32_16x16x32_bf16 v[56:59], v[204:207], v[184:187], v[56:59]
	v_mfma_f32_16x16x32_bf16 v[52:55], v[200:203], v[192:195], v[52:55]
	v_mfma_f32_16x16x32_bf16 v[48:51], v[204:207], v[192:195], v[48:51]
	v_mfma_f32_16x16x32_bf16 v[164:167], v[200:203], v[168:171], v[92:95]
	v_mfma_f32_16x16x32_bf16 v[168:171], v[204:207], v[168:171], v[88:91]
	s_barrier
	s_nop 0
	ds_read_b128 v[88:91], v129 offset:16384
	ds_read_b128 v[92:95], v129 offset:17408
	ds_read_b128 v[172:175], v132 offset:16384
	ds_read_b128 v[176:179], v132 offset:17408
	ds_read_b128 v[180:183], v131 offset:16384
	ds_read_b128 v[184:187], v131 offset:17408
	ds_read_b128 v[188:191], v130 offset:16384
	ds_read_b128 v[192:195], v130 offset:17408
	s_waitcnt vmcnt(4)
	s_barrier
; #define LDA(dst, b, h) _Pragma("unroll") for (int m = 0; m < 4; ++m) _Pragma("unroll") for (int k = 0; k < 2; ++k) \
;     dst[m][k] = *reinterpret_cast<const bf16x8*>(SA(b, h) + lds_byte(wr * 64 + m * 16 + fr, k * 32 + fq * 8))
; #define LDB(dst, b, h) _Pragma("unroll") for (int n = 0; n < 2; ++n) _Pragma("unroll") for (int k = 0; k < 2; ++k) \
;     dst[n][k] = *reinterpret_cast<const bf16x8*>(SB(b, h) + lds_byte(wc * 32 + n * 16 + fr, k * 32 + fq * 8))
; #define WAIT_V(n) asm volatile("s_waitcnt vmcnt(" #n ")" ::: "memory")
; #define WAIT_L(n) asm volatile("s_waitcnt lgkmcnt(" #n ")" ::: "memory")
; #define BAR __builtin_amdgcn_s_barrier()
;     ...
;       LDA(At, 0, 1); WAIT_V(4); BAR; WAIT_L(0); MMA(1, 0, At, B0); MMA(1, 1, At, B1); BAR; }
;     { LDB(B0, 1, 0); LDA(At, 1, 0); WAIT_V(2); BAR; WAIT_L(0); MMA(0, 0, At, B0); BAR;
	s_waitcnt lgkmcnt(0)
	v_mfma_f32_16x16x32_bf16 v[44:47], v[152:155], v[88:91], v[44:47]
	v_mfma_f32_16x16x32_bf16 v[40:43], v[160:163], v[88:91], v[40:43]
	v_mfma_f32_16x16x32_bf16 v[36:39], v[152:155], v[172:175], v[36:39]
	v_mfma_f32_16x16x32_bf16 v[32:35], v[160:163], v[172:175], v[32:35]
	v_mfma_f32_16x16x32_bf16 v[28:31], v[152:155], v[180:183], v[28:31]
	v_mfma_f32_16x16x32_bf16 v[24:27], v[160:163], v[180:183], v[24:27]
	v_mfma_f32_16x16x32_bf16 v[20:23], v[152:155], v[188:191], v[20:23]
	v_mfma_f32_16x16x32_bf16 v[16:19], v[160:163], v[188:191], v[16:19]
	v_mfma_f32_16x16x32_bf16 v[44:47], v[156:159], v[92:95], v[44:47]
	v_mfma_f32_16x16x32_bf16 v[40:43], v[148:151], v[92:95], v[40:43]
	v_mfma_f32_16x16x32_bf16 v[36:39], v[156:159], v[176:179], v[36:39]
	v_mfma_f32_16x16x32_bf16 v[32:35], v[148:151], v[176:179], v[32:35]
	v_mfma_f32_16x16x32_bf16 v[28:31], v[156:159], v[184:187], v[28:31]
	v_mfma_f32_16x16x32_bf16 v[24:27], v[148:151], v[184:187], v[24:27]
	v_mfma_f32_16x16x32_bf16 v[20:23], v[156:159], v[192:195], v[20:23]
	v_mfma_f32_16x16x32_bf16 v[16:19], v[148:151], v[192:195], v[16:19]
	v_mfma_f32_16x16x32_bf16 v[4:7], v[196:199], v[172:175], v[4:7]
	v_mfma_f32_16x16x32_bf16 v[0:3], v[142:145], v[172:175], v[0:3]
	v_mfma_f32_16x16x32_bf16 v[12:15], v[196:199], v[88:91], v[12:15]
	v_mfma_f32_16x16x32_bf16 v[8:11], v[142:145], v[88:91], v[8:11]
	v_mfma_f32_16x16x32_bf16 v[64:67], v[196:199], v[180:183], v[64:67]
	v_mfma_f32_16x16x32_bf16 v[72:75], v[142:145], v[180:183], v[72:75]
	v_mfma_f32_16x16x32_bf16 v[76:79], v[196:199], v[188:191], v[76:79]
	v_mfma_f32_16x16x32_bf16 v[84:87], v[142:145], v[188:191], v[84:87]
	v_mfma_f32_16x16x32_bf16 v[4:7], v[200:203], v[176:179], v[4:7]
	v_mfma_f32_16x16x32_bf16 v[0:3], v[204:207], v[176:179], v[0:3]
	v_mfma_f32_16x16x32_bf16 v[142:145], v[200:203], v[92:95], v[12:15]
	v_mfma_f32_16x16x32_bf16 v[146:149], v[204:207], v[92:95], v[8:11]
	v_mfma_f32_16x16x32_bf16 v[150:153], v[200:203], v[184:187], v[64:67]
	v_mfma_f32_16x16x32_bf16 v[154:157], v[204:207], v[184:187], v[72:75]
	v_mfma_f32_16x16x32_bf16 v[158:161], v[200:203], v[192:195], v[76:79]
	v_mfma_f32_16x16x32_bf16 v[172:175], v[204:207], v[192:195], v[84:87]
	s_barrier
	ds_read_b128 v[8:11], v137
	ds_read_b128 v[12:15], v138
	ds_read_b128 v[176:179], v139
	ds_read_b128 v[138:141], v140
	ds_read_b128 v[64:67], v129 offset:32768
	ds_read_b128 v[84:87], v129 offset:33792
	ds_read_b128 v[180:183], v132 offset:32768
	ds_read_b128 v[184:187], v132 offset:33792
	ds_read_b128 v[188:191], v131 offset:32768
	ds_read_b128 v[192:195], v131 offset:33792
	ds_read_b128 v[196:199], v130 offset:32768
	ds_read_b128 v[200:203], v130 offset:33792
	s_waitcnt vmcnt(2)
	s_barrier
	s_waitcnt lgkmcnt(0)
	v_mfma_f32_16x16x32_bf16 v[72:75], v[8:11], v[64:67], v[124:127]
	v_mfma_f32_16x16x32_bf16 v[76:79], v[176:179], v[64:67], v[120:123]
	v_mfma_f32_16x16x32_bf16 v[88:91], v[8:11], v[180:183], v[116:119]
	v_mfma_f32_16x16x32_bf16 v[92:95], v[176:179], v[180:183], v[112:115]
	v_mfma_f32_16x16x32_bf16 v[112:115], v[8:11], v[188:191], v[108:111]
	v_mfma_f32_16x16x32_bf16 v[120:123], v[176:179], v[188:191], v[104:107]
	v_mfma_f32_16x16x32_bf16 v[100:103], v[8:11], v[196:199], v[100:103]
	v_mfma_f32_16x16x32_bf16 v[96:99], v[176:179], v[196:199], v[96:99]
	v_mfma_f32_16x16x32_bf16 v[124:127], v[12:15], v[84:87], v[72:75]
	v_mfma_f32_16x16x32_bf16 v[116:119], v[138:141], v[84:87], v[76:79]
	v_mfma_f32_16x16x32_bf16 v[108:111], v[12:15], v[184:187], v[88:91]
	v_mfma_f32_16x16x32_bf16 v[104:107], v[138:141], v[184:187], v[92:95]
	v_mfma_f32_16x16x32_bf16 v[92:95], v[12:15], v[192:195], v[112:115]
	v_mfma_f32_16x16x32_bf16 v[88:91], v[138:141], v[192:195], v[120:123]
	v_mfma_f32_16x16x32_bf16 v[76:79], v[12:15], v[200:203], v[100:103]
	v_mfma_f32_16x16x32_bf16 v[72:75], v[138:141], v[200:203], v[96:99]
	s_barrier
; #define LDA(dst, b, h) _Pragma("unroll") for (int m = 0; m < 4; ++m) _Pragma("unroll") for (int k = 0; k < 2; ++k) \
;     dst[m][k] = *reinterpret_cast<const bf16x8*>(SA(b, h) + lds_byte(wr * 64 + m * 16 + fr, k * 32 + fq * 8))
; #define LDB(dst, b, h) _Pragma("unroll") for (int n = 0; n < 2; ++n) _Pragma("unroll") for (int k = 0; k < 2; ++k) \
;     dst[n][k] = *reinterpret_cast<const bf16x8*>(SB(b, h) + lds_byte(wc * 32 + n * 16 + fr, k * 32 + fq * 8))
; #define WAIT_V(n) asm volatile("s_waitcnt vmcnt(" #n ")" ::: "memory")
; #define WAIT_L(n) asm volatile("s_waitcnt lgkmcnt(" #n ")" ::: "memory")
; #define BAR __builtin_amdgcn_s_barrier()
;     ...
;     { LDB(B0, 1, 0); LDA(At, 1, 0); WAIT_V(2); BAR; WAIT_L(0); MMA(0, 0, At, B0); BAR;
;       LDB(B1, 1, 1); WAIT_V(0); BAR; WAIT_L(0); MMA(0, 1, At, B1); BAR;
;       LDA(At, 1, 1); BAR; WAIT_L(0); MMA(1, 0, At, B0); MMA(1, 1, At, B1); BAR; }
;     if (wr == 0) BAR;
	ds_read_b128 v[204:207], v133
	ds_read_b128 v[208:211], v134
	ds_read_b128 v[212:215], v135
	ds_read_b128 v[134:137], v136
	s_waitcnt vmcnt(0)
	s_barrier
	s_waitcnt lgkmcnt(0)
	v_mfma_f32_16x16x32_bf16 v[96:99], v[204:207], v[64:67], v[164:167]
	v_mfma_f32_16x16x32_bf16 v[64:67], v[212:215], v[64:67], v[168:171]
	v_mfma_f32_16x16x32_bf16 v[80:83], v[204:207], v[180:183], v[80:83]
	v_mfma_f32_16x16x32_bf16 v[68:71], v[212:215], v[180:183], v[68:71]
	v_mfma_f32_16x16x32_bf16 v[60:63], v[204:207], v[188:191], v[60:63]
	v_mfma_f32_16x16x32_bf16 v[56:59], v[212:215], v[188:191], v[56:59]
	v_mfma_f32_16x16x32_bf16 v[52:55], v[204:207], v[196:199], v[52:55]
	v_mfma_f32_16x16x32_bf16 v[48:51], v[212:215], v[196:199], v[48:51]
	v_mfma_f32_16x16x32_bf16 v[120:123], v[208:211], v[84:87], v[96:99]
	v_mfma_f32_16x16x32_bf16 v[112:115], v[134:137], v[84:87], v[64:67]
	v_mfma_f32_16x16x32_bf16 v[100:103], v[208:211], v[184:187], v[80:83]
	v_mfma_f32_16x16x32_bf16 v[96:99], v[134:137], v[184:187], v[68:71]
	v_mfma_f32_16x16x32_bf16 v[84:87], v[208:211], v[192:195], v[60:63]
	v_mfma_f32_16x16x32_bf16 v[80:83], v[134:137], v[192:195], v[56:59]
	v_mfma_f32_16x16x32_bf16 v[68:71], v[208:211], v[200:203], v[52:55]
	v_mfma_f32_16x16x32_bf16 v[64:67], v[134:137], v[200:203], v[48:51]
	s_barrier
	s_nop 0
	ds_read_b128 v[48:51], v129 offset:49152
	ds_read_b128 v[162:165], v129 offset:50176
	ds_read_b128 v[52:55], v132 offset:49152
	ds_read_b128 v[166:169], v132 offset:50176
	ds_read_b128 v[180:183], v131 offset:49152
	ds_read_b128 v[184:187], v131 offset:50176
	ds_read_b128 v[188:191], v130 offset:49152
	ds_read_b128 v[130:133], v130 offset:50176
	s_barrier
	s_waitcnt lgkmcnt(0)
	v_mfma_f32_16x16x32_bf16 v[44:47], v[8:11], v[48:51], v[44:47]
	v_mfma_f32_16x16x32_bf16 v[40:43], v[176:179], v[48:51], v[40:43]
	v_mfma_f32_16x16x32_bf16 v[36:39], v[8:11], v[52:55], v[36:39]
	v_mfma_f32_16x16x32_bf16 v[32:35], v[176:179], v[52:55], v[32:35]
	v_mfma_f32_16x16x32_bf16 v[28:31], v[8:11], v[180:183], v[28:31]
	v_mfma_f32_16x16x32_bf16 v[24:27], v[176:179], v[180:183], v[24:27]
	v_mfma_f32_16x16x32_bf16 v[8:11], v[8:11], v[188:191], v[20:23]
	v_mfma_f32_16x16x32_bf16 v[16:19], v[176:179], v[188:191], v[16:19]
	v_mfma_f32_16x16x32_bf16 v[60:63], v[12:15], v[162:165], v[44:47]
	v_mfma_f32_16x16x32_bf16 v[56:59], v[138:141], v[162:165], v[40:43]
	v_mfma_f32_16x16x32_bf16 v[44:47], v[12:15], v[166:169], v[36:39]
	v_mfma_f32_16x16x32_bf16 v[40:43], v[138:141], v[166:169], v[32:35]
	v_mfma_f32_16x16x32_bf16 v[28:31], v[12:15], v[184:187], v[28:31]
	v_mfma_f32_16x16x32_bf16 v[24:27], v[138:141], v[184:187], v[24:27]
	v_mfma_f32_16x16x32_bf16 v[12:15], v[12:15], v[130:133], v[8:11]
	v_mfma_f32_16x16x32_bf16 v[8:11], v[138:141], v[130:133], v[16:19]
	v_mfma_f32_16x16x32_bf16 v[16:19], v[204:207], v[48:51], v[142:145]
	v_mfma_f32_16x16x32_bf16 v[20:23], v[212:215], v[48:51], v[146:149]
	v_mfma_f32_16x16x32_bf16 v[4:7], v[204:207], v[52:55], v[4:7]
	v_mfma_f32_16x16x32_bf16 v[0:3], v[212:215], v[52:55], v[0:3]
	v_mfma_f32_16x16x32_bf16 v[138:141], v[204:207], v[180:183], v[150:153]
	v_mfma_f32_16x16x32_bf16 v[142:145], v[212:215], v[180:183], v[154:157]
	v_mfma_f32_16x16x32_bf16 v[146:149], v[204:207], v[188:191], v[158:161]
	v_mfma_f32_16x16x32_bf16 v[150:153], v[212:215], v[188:191], v[172:175]
	v_mfma_f32_16x16x32_bf16 v[52:55], v[208:211], v[162:165], v[16:19]
	v_mfma_f32_16x16x32_bf16 v[48:51], v[134:137], v[162:165], v[20:23]
	v_mfma_f32_16x16x32_bf16 v[36:39], v[208:211], v[166:169], v[4:7]
	v_mfma_f32_16x16x32_bf16 v[32:35], v[134:137], v[166:169], v[0:3]
	v_mfma_f32_16x16x32_bf16 v[20:23], v[208:211], v[184:187], v[138:141]
	v_mfma_f32_16x16x32_bf16 v[16:19], v[134:137], v[184:187], v[142:145]
	v_mfma_f32_16x16x32_bf16 v[4:7], v[208:211], v[130:133], v[146:149]
	v_mfma_f32_16x16x32_bf16 v[0:3], v[134:137], v[130:133], v[150:153]
	v_cmp_gt_u32_e32 vcc, s76, v128
	s_barrier
	s_and_saveexec_b64 s[6:7], vcc
	s_cbranch_execz .LBB0_497
	s_barrier

; #define STAGE(P, RS, SOFF, OFF, kt) do { const int _so = (SOFF) + (kt) * (BK * 2); \
;     _Pragma("unroll") for (int _i = 0; _i < 2; ++_i) { \
;       __builtin_amdgcn_raw_ptr_buffer_load_lds(RS, (__attribute__((address_space(3))) void*)((P) + wave * 1024 + _i * 8192), 16, OFF[_i], _so, 0, 0); } } while (0)
; #define LDA(dst, b, h) _Pragma("unroll") for (int m = 0; m < 4; ++m) _Pragma("unroll") for (int k = 0; k < 2; ++k) \
;     dst[m][k] = *reinterpret_cast<const bf16x8*>(SA(b, h) + lds_byte(wr * 64 + m * 16 + fr, k * 32 + fq * 8))
; #define LDB(dst, b, h) _Pragma("unroll") for (int n = 0; n < 2; ++n) _Pragma("unroll") for (int k = 0; k < 2; ++k) \
;     dst[n][k] = *reinterpret_cast<const bf16x8*>(SB(b, h) + lds_byte(wc * 32 + n * 16 + fr, k * 32 + fq * 8))
; #define WAIT_V(n) asm volatile("s_waitcnt vmcnt(" #n ")" ::: "memory")
; #define WAIT_L(n) asm volatile("s_waitcnt lgkmcnt(" #n ")" ::: "memory")
; #define BAR __builtin_amdgcn_s_barrier()
;     ...
;       WAIT_V(6); BAR; MMA(1, 1, At, B1); BAR;
;     }
;     { LDB(B0, 0, 0); LDA(At, 0, 0); STAGE(SA(1, 1), rsA, sA1, offA, nt - 1);
;       BAR; WAIT_L(0); MMA(0, 0, At, B0); BAR;
;       LDB(B1, 0, 1); BAR; WAIT_L(0); MMA(0, 1, At, B1); BAR;
;       LDA(At, 0, 1); WAIT_V(4); BAR; WAIT_L(0); MMA(1, 0, At, B0); MMA(1, 1, At, B1); BAR; }
.Lmy_post_556:
	s_waitcnt vmcnt(6)
	s_barrier
	v_mfma_f32_16x16x32_bf16 v[28:31], v[202:205], v[170:173], v[28:31]
	v_mfma_f32_16x16x32_bf16 v[28:31], v[206:209], v[174:177], v[28:31]
	v_mfma_f32_16x16x32_bf16 v[24:27], v[214:217], v[174:177], v[24:27]
	v_mfma_f32_16x16x32_bf16 v[24:27], v[210:213], v[170:173], v[24:27]
	v_mfma_f32_16x16x32_bf16 v[16:19], v[210:213], v[178:181], v[16:19]
	v_mfma_f32_16x16x32_bf16 v[16:19], v[214:217], v[182:185], v[16:19]
	v_mfma_f32_16x16x32_bf16 v[20:23], v[206:209], v[182:185], v[20:23]
	v_mfma_f32_16x16x32_bf16 v[20:23], v[202:205], v[178:181], v[20:23]
	v_mfma_f32_16x16x32_bf16 v[12:15], v[202:205], v[186:189], v[12:15]
	v_mfma_f32_16x16x32_bf16 v[12:15], v[206:209], v[190:193], v[12:15]
	v_mfma_f32_16x16x32_bf16 v[8:11], v[214:217], v[190:193], v[8:11]
	v_mfma_f32_16x16x32_bf16 v[8:11], v[210:213], v[186:189], v[8:11]
	v_mfma_f32_16x16x32_bf16 v[0:3], v[210:213], v[194:197], v[0:3]
	v_mfma_f32_16x16x32_bf16 v[0:3], v[214:217], v[198:201], v[0:3]
	v_mfma_f32_16x16x32_bf16 v[4:7], v[206:209], v[198:201], v[4:7]
	v_mfma_f32_16x16x32_bf16 v[4:7], v[202:205], v[194:197], v[4:7]
	s_barrier
	s_add_i32 s10, s37, 0xf80
	s_mov_b32 m0, s30
	ds_read_b128 v[154:157], v149
	ds_read_b128 v[158:161], v150
	ds_read_b128 v[162:165], v151
	ds_read_b128 v[150:153], v152
	ds_read_b128 v[166:169], v131
	ds_read_b128 v[170:173], v131 offset:1024
	ds_read_b128 v[174:177], v134
	ds_read_b128 v[178:181], v134 offset:1024
	ds_read_b128 v[182:185], v133
	ds_read_b128 v[186:189], v133 offset:1024
	ds_read_b128 v[190:193], v132
	ds_read_b128 v[194:197], v132 offset:1024
	buffer_load_dwordx4 v143, s[4:7], s10 offen lds
	s_mov_b32 m0, s31
	s_nop 0
	buffer_load_dwordx4 v144, s[4:7], s10 offen lds
	s_barrier
	s_waitcnt lgkmcnt(0)
	v_mfma_f32_16x16x32_bf16 v[124:127], v[154:157], v[166:169], v[124:127]
	v_mfma_f32_16x16x32_bf16 v[124:127], v[158:161], v[170:173], v[124:127]
	v_mfma_f32_16x16x32_bf16 v[120:123], v[150:153], v[170:173], v[120:123]
	v_mfma_f32_16x16x32_bf16 v[120:123], v[162:165], v[166:169], v[120:123]
	v_mfma_f32_16x16x32_bf16 v[112:115], v[162:165], v[174:177], v[112:115]
	v_mfma_f32_16x16x32_bf16 v[112:115], v[150:153], v[178:181], v[112:115]
	v_mfma_f32_16x16x32_bf16 v[116:119], v[158:161], v[178:181], v[116:119]
	v_mfma_f32_16x16x32_bf16 v[116:119], v[154:157], v[174:177], v[116:119]
	v_mfma_f32_16x16x32_bf16 v[108:111], v[154:157], v[182:185], v[108:111]
	v_mfma_f32_16x16x32_bf16 v[108:111], v[158:161], v[186:189], v[108:111]
	v_mfma_f32_16x16x32_bf16 v[104:107], v[150:153], v[186:189], v[104:107]
	v_mfma_f32_16x16x32_bf16 v[104:107], v[162:165], v[182:185], v[104:107]
	v_mfma_f32_16x16x32_bf16 v[96:99], v[162:165], v[190:193], v[96:99]
	v_mfma_f32_16x16x32_bf16 v[96:99], v[150:153], v[194:197], v[96:99]
	v_mfma_f32_16x16x32_bf16 v[100:103], v[158:161], v[194:197], v[100:103]
	v_mfma_f32_16x16x32_bf16 v[100:103], v[154:157], v[190:193], v[100:103]
	s_barrier
	ds_read_b128 v[198:201], v145
	ds_read_b128 v[202:205], v146
	ds_read_b128 v[144:147], v147
	ds_read_b128 v[206:209], v148
	s_barrier
	s_waitcnt lgkmcnt(0)
	v_mfma_f32_16x16x32_bf16 v[92:95], v[198:201], v[166:169], v[92:95]
	v_mfma_f32_16x16x32_bf16 v[92:95], v[202:205], v[170:173], v[92:95]
	v_mfma_f32_16x16x32_bf16 v[88:91], v[206:209], v[170:173], v[88:91]
	v_mfma_f32_16x16x32_bf16 v[88:91], v[144:147], v[166:169], v[88:91]
	v_mfma_f32_16x16x32_bf16 v[80:83], v[144:147], v[174:177], v[80:83]
	v_mfma_f32_16x16x32_bf16 v[80:83], v[206:209], v[178:181], v[80:83]
	v_mfma_f32_16x16x32_bf16 v[84:87], v[202:205], v[178:181], v[84:87]
	v_mfma_f32_16x16x32_bf16 v[84:87], v[198:201], v[174:177], v[84:87]
	v_mfma_f32_16x16x32_bf16 v[76:79], v[198:201], v[182:185], v[76:79]
	v_mfma_f32_16x16x32_bf16 v[76:79], v[202:205], v[186:189], v[76:79]
	v_mfma_f32_16x16x32_bf16 v[72:75], v[206:209], v[186:189], v[72:75]
	v_mfma_f32_16x16x32_bf16 v[72:75], v[144:147], v[182:185], v[72:75]
	v_mfma_f32_16x16x32_bf16 v[64:67], v[144:147], v[190:193], v[64:67]
	v_mfma_f32_16x16x32_bf16 v[64:67], v[206:209], v[194:197], v[64:67]
	v_mfma_f32_16x16x32_bf16 v[68:71], v[202:205], v[194:197], v[68:71]
	v_mfma_f32_16x16x32_bf16 v[68:71], v[198:201], v[190:193], v[68:71]
	s_barrier
	ds_read_b128 v[166:169], v131 offset:16384
	ds_read_b128 v[170:173], v131 offset:17408
	ds_read_b128 v[174:177], v134 offset:16384
	ds_read_b128 v[178:181], v134 offset:17408
	ds_read_b128 v[182:185], v133 offset:16384
	ds_read_b128 v[186:189], v133 offset:17408
	ds_read_b128 v[190:193], v132 offset:16384
	ds_read_b128 v[194:197], v132 offset:17408
	s_waitcnt vmcnt(4)
	s_barrier
; #define LDA(dst, b, h) _Pragma("unroll") for (int m = 0; m < 4; ++m) _Pragma("unroll") for (int k = 0; k < 2; ++k) \
;     dst[m][k] = *reinterpret_cast<const bf16x8*>(SA(b, h) + lds_byte(wr * 64 + m * 16 + fr, k * 32 + fq * 8))
; #define LDB(dst, b, h) _Pragma("unroll") for (int n = 0; n < 2; ++n) _Pragma("unroll") for (int k = 0; k < 2; ++k) \
;     dst[n][k] = *reinterpret_cast<const bf16x8*>(SB(b, h) + lds_byte(wc * 32 + n * 16 + fr, k * 32 + fq * 8))
; #define WAIT_V(n) asm volatile("s_waitcnt vmcnt(" #n ")" ::: "memory")
; #define WAIT_L(n) asm volatile("s_waitcnt lgkmcnt(" #n ")" ::: "memory")
; #define BAR __builtin_amdgcn_s_barrier()
;     ...
;       LDA(At, 0, 1); WAIT_V(4); BAR; WAIT_L(0); MMA(1, 0, At, B0); MMA(1, 1, At, B1); BAR; }
;     { LDB(B0, 1, 0); LDA(At, 1, 0); WAIT_V(2); BAR; WAIT_L(0); MMA(0, 0, At, B0); BAR;
	s_waitcnt lgkmcnt(0)
	v_mfma_f32_16x16x32_bf16 v[60:63], v[154:157], v[166:169], v[60:63]
	v_mfma_f32_16x16x32_bf16 v[60:63], v[158:161], v[170:173], v[60:63]
	v_mfma_f32_16x16x32_bf16 v[56:59], v[150:153], v[170:173], v[56:59]
	v_mfma_f32_16x16x32_bf16 v[56:59], v[162:165], v[166:169], v[56:59]
	v_mfma_f32_16x16x32_bf16 v[48:51], v[162:165], v[174:177], v[48:51]
	v_mfma_f32_16x16x32_bf16 v[48:51], v[150:153], v[178:181], v[48:51]
	v_mfma_f32_16x16x32_bf16 v[52:55], v[158:161], v[178:181], v[52:55]
	v_mfma_f32_16x16x32_bf16 v[52:55], v[154:157], v[174:177], v[52:55]
	v_mfma_f32_16x16x32_bf16 v[44:47], v[154:157], v[182:185], v[44:47]
	v_mfma_f32_16x16x32_bf16 v[44:47], v[158:161], v[186:189], v[44:47]
	v_mfma_f32_16x16x32_bf16 v[40:43], v[150:153], v[186:189], v[40:43]
	v_mfma_f32_16x16x32_bf16 v[40:43], v[162:165], v[182:185], v[40:43]
	v_mfma_f32_16x16x32_bf16 v[32:35], v[162:165], v[190:193], v[32:35]
	v_mfma_f32_16x16x32_bf16 v[32:35], v[150:153], v[194:197], v[32:35]
	v_mfma_f32_16x16x32_bf16 v[36:39], v[158:161], v[194:197], v[36:39]
	v_mfma_f32_16x16x32_bf16 v[36:39], v[154:157], v[190:193], v[36:39]
	v_mfma_f32_16x16x32_bf16 v[4:7], v[198:201], v[190:193], v[4:7]
	v_mfma_f32_16x16x32_bf16 v[4:7], v[202:205], v[194:197], v[4:7]
	v_mfma_f32_16x16x32_bf16 v[28:31], v[202:205], v[170:173], v[28:31]
	v_mfma_f32_16x16x32_bf16 v[28:31], v[198:201], v[166:169], v[28:31]
	v_mfma_f32_16x16x32_bf16 v[24:27], v[144:147], v[166:169], v[24:27]
	v_mfma_f32_16x16x32_bf16 v[24:27], v[206:209], v[170:173], v[24:27]
	v_mfma_f32_16x16x32_bf16 v[16:19], v[206:209], v[178:181], v[16:19]
	v_mfma_f32_16x16x32_bf16 v[16:19], v[144:147], v[174:177], v[16:19]
	v_mfma_f32_16x16x32_bf16 v[20:23], v[198:201], v[174:177], v[20:23]
	v_mfma_f32_16x16x32_bf16 v[20:23], v[202:205], v[178:181], v[20:23]
	v_mfma_f32_16x16x32_bf16 v[12:15], v[202:205], v[186:189], v[12:15]
	v_mfma_f32_16x16x32_bf16 v[12:15], v[198:201], v[182:185], v[12:15]
	v_mfma_f32_16x16x32_bf16 v[8:11], v[144:147], v[182:185], v[8:11]
	v_mfma_f32_16x16x32_bf16 v[8:11], v[206:209], v[186:189], v[8:11]
	v_mfma_f32_16x16x32_bf16 v[0:3], v[206:209], v[194:197], v[0:3]
	v_mfma_f32_16x16x32_bf16 v[0:3], v[144:147], v[190:193], v[0:3]
	s_barrier
	ds_read_b128 v[144:147], v139
	ds_read_b128 v[148:151], v140
	ds_read_b128 v[152:155], v141
	ds_read_b128 v[140:143], v142
	ds_read_b128 v[156:159], v131 offset:32768
	ds_read_b128 v[160:163], v131 offset:33792
	ds_read_b128 v[164:167], v134 offset:32768
	ds_read_b128 v[168:171], v134 offset:33792
	ds_read_b128 v[172:175], v133 offset:32768
	ds_read_b128 v[176:179], v133 offset:33792
	ds_read_b128 v[180:183], v132 offset:32768
	ds_read_b128 v[184:187], v132 offset:33792
	s_waitcnt vmcnt(2)
	s_barrier
	s_waitcnt lgkmcnt(0)
	v_mfma_f32_16x16x32_bf16 v[124:127], v[144:147], v[156:159], v[124:127]
	v_mfma_f32_16x16x32_bf16 v[124:127], v[148:151], v[160:163], v[124:127]
	v_mfma_f32_16x16x32_bf16 v[120:123], v[140:143], v[160:163], v[120:123]
	v_mfma_f32_16x16x32_bf16 v[120:123], v[152:155], v[156:159], v[120:123]
	v_mfma_f32_16x16x32_bf16 v[112:115], v[152:155], v[164:167], v[112:115]
	v_mfma_f32_16x16x32_bf16 v[112:115], v[140:143], v[168:171], v[112:115]
	v_mfma_f32_16x16x32_bf16 v[116:119], v[148:151], v[168:171], v[116:119]
	v_mfma_f32_16x16x32_bf16 v[116:119], v[144:147], v[164:167], v[116:119]
	v_mfma_f32_16x16x32_bf16 v[108:111], v[144:147], v[172:175], v[108:111]
	v_mfma_f32_16x16x32_bf16 v[108:111], v[148:151], v[176:179], v[108:111]
	v_mfma_f32_16x16x32_bf16 v[104:107], v[140:143], v[176:179], v[104:107]
	v_mfma_f32_16x16x32_bf16 v[104:107], v[152:155], v[172:175], v[104:107]
	v_mfma_f32_16x16x32_bf16 v[96:99], v[152:155], v[180:183], v[96:99]
	v_mfma_f32_16x16x32_bf16 v[96:99], v[140:143], v[184:187], v[96:99]
	v_mfma_f32_16x16x32_bf16 v[100:103], v[148:151], v[184:187], v[100:103]
	v_mfma_f32_16x16x32_bf16 v[100:103], v[144:147], v[180:183], v[100:103]
	s_barrier
; #define LDA(dst, b, h) _Pragma("unroll") for (int m = 0; m < 4; ++m) _Pragma("unroll") for (int k = 0; k < 2; ++k) \
;     dst[m][k] = *reinterpret_cast<const bf16x8*>(SA(b, h) + lds_byte(wr * 64 + m * 16 + fr, k * 32 + fq * 8))
; #define LDB(dst, b, h) _Pragma("unroll") for (int n = 0; n < 2; ++n) _Pragma("unroll") for (int k = 0; k < 2; ++k) \
;     dst[n][k] = *reinterpret_cast<const bf16x8*>(SB(b, h) + lds_byte(wc * 32 + n * 16 + fr, k * 32 + fq * 8))
; #define WAIT_V(n) asm volatile("s_waitcnt vmcnt(" #n ")" ::: "memory")
; #define WAIT_L(n) asm volatile("s_waitcnt lgkmcnt(" #n ")" ::: "memory")
; #define BAR __builtin_amdgcn_s_barrier()
;     ...
;     { LDB(B0, 1, 0); LDA(At, 1, 0); WAIT_V(2); BAR; WAIT_L(0); MMA(0, 0, At, B0); BAR;
;       LDB(B1, 1, 1); WAIT_V(0); BAR; WAIT_L(0); MMA(0, 1, At, B1); BAR;
;       LDA(At, 1, 1); BAR; WAIT_L(0); MMA(1, 0, At, B0); MMA(1, 1, At, B1); BAR; }
;     if (wr == 0) BAR;
	ds_read_b128 v[188:191], v135
	ds_read_b128 v[192:195], v136
	ds_read_b128 v[196:199], v137
	ds_read_b128 v[136:139], v138
	s_waitcnt vmcnt(0)
	s_barrier
	s_waitcnt lgkmcnt(0)
	v_mfma_f32_16x16x32_bf16 v[92:95], v[188:191], v[156:159], v[92:95]
	v_mfma_f32_16x16x32_bf16 v[92:95], v[192:195], v[160:163], v[92:95]
	v_mfma_f32_16x16x32_bf16 v[88:91], v[136:139], v[160:163], v[88:91]
	v_mfma_f32_16x16x32_bf16 v[88:91], v[196:199], v[156:159], v[88:91]
	v_mfma_f32_16x16x32_bf16 v[80:83], v[196:199], v[164:167], v[80:83]
	v_mfma_f32_16x16x32_bf16 v[80:83], v[136:139], v[168:171], v[80:83]
	v_mfma_f32_16x16x32_bf16 v[84:87], v[192:195], v[168:171], v[84:87]
	v_mfma_f32_16x16x32_bf16 v[84:87], v[188:191], v[164:167], v[84:87]
	v_mfma_f32_16x16x32_bf16 v[76:79], v[188:191], v[172:175], v[76:79]
	v_mfma_f32_16x16x32_bf16 v[76:79], v[192:195], v[176:179], v[76:79]
	v_mfma_f32_16x16x32_bf16 v[72:75], v[136:139], v[176:179], v[72:75]
	v_mfma_f32_16x16x32_bf16 v[72:75], v[196:199], v[172:175], v[72:75]
	v_mfma_f32_16x16x32_bf16 v[64:67], v[196:199], v[180:183], v[64:67]
	v_mfma_f32_16x16x32_bf16 v[64:67], v[136:139], v[184:187], v[64:67]
	v_mfma_f32_16x16x32_bf16 v[68:71], v[192:195], v[184:187], v[68:71]
	v_mfma_f32_16x16x32_bf16 v[68:71], v[188:191], v[180:183], v[68:71]
	s_barrier
	ds_read_b128 v[156:159], v131 offset:49152
	ds_read_b128 v[160:163], v131 offset:50176
	ds_read_b128 v[164:167], v134 offset:49152
	ds_read_b128 v[168:171], v134 offset:50176
	ds_read_b128 v[172:175], v133 offset:49152
	ds_read_b128 v[176:179], v133 offset:50176
	ds_read_b128 v[180:183], v132 offset:49152
	ds_read_b128 v[132:135], v132 offset:50176
	s_barrier
	s_waitcnt lgkmcnt(0)
	v_mfma_f32_16x16x32_bf16 v[60:63], v[144:147], v[156:159], v[60:63]
	v_mfma_f32_16x16x32_bf16 v[60:63], v[148:151], v[160:163], v[60:63]
	v_mfma_f32_16x16x32_bf16 v[56:59], v[140:143], v[160:163], v[56:59]
	v_mfma_f32_16x16x32_bf16 v[56:59], v[152:155], v[156:159], v[56:59]
	v_mfma_f32_16x16x32_bf16 v[48:51], v[152:155], v[164:167], v[48:51]
	v_mfma_f32_16x16x32_bf16 v[48:51], v[140:143], v[168:171], v[48:51]
	v_mfma_f32_16x16x32_bf16 v[52:55], v[148:151], v[168:171], v[52:55]
	v_mfma_f32_16x16x32_bf16 v[52:55], v[144:147], v[164:167], v[52:55]
	v_mfma_f32_16x16x32_bf16 v[44:47], v[144:147], v[172:175], v[44:47]
	v_mfma_f32_16x16x32_bf16 v[44:47], v[148:151], v[176:179], v[44:47]
	v_mfma_f32_16x16x32_bf16 v[40:43], v[140:143], v[176:179], v[40:43]
	v_mfma_f32_16x16x32_bf16 v[40:43], v[152:155], v[172:175], v[40:43]
	v_mfma_f32_16x16x32_bf16 v[32:35], v[152:155], v[180:183], v[32:35]
	v_mfma_f32_16x16x32_bf16 v[32:35], v[140:143], v[132:135], v[32:35]
	v_mfma_f32_16x16x32_bf16 v[36:39], v[148:151], v[132:135], v[36:39]
	v_mfma_f32_16x16x32_bf16 v[36:39], v[144:147], v[180:183], v[36:39]
	v_mfma_f32_16x16x32_bf16 v[4:7], v[188:191], v[180:183], v[4:7]
	v_mfma_f32_16x16x32_bf16 v[4:7], v[192:195], v[132:135], v[4:7]
	v_mfma_f32_16x16x32_bf16 v[28:31], v[192:195], v[160:163], v[28:31]
	v_mfma_f32_16x16x32_bf16 v[28:31], v[188:191], v[156:159], v[28:31]
	v_mfma_f32_16x16x32_bf16 v[24:27], v[196:199], v[156:159], v[24:27]
	v_mfma_f32_16x16x32_bf16 v[24:27], v[136:139], v[160:163], v[24:27]
	v_mfma_f32_16x16x32_bf16 v[16:19], v[136:139], v[168:171], v[16:19]
	v_mfma_f32_16x16x32_bf16 v[16:19], v[196:199], v[164:167], v[16:19]
	v_mfma_f32_16x16x32_bf16 v[20:23], v[188:191], v[164:167], v[20:23]
	v_mfma_f32_16x16x32_bf16 v[20:23], v[192:195], v[168:171], v[20:23]
	v_mfma_f32_16x16x32_bf16 v[12:15], v[192:195], v[176:179], v[12:15]
	v_mfma_f32_16x16x32_bf16 v[12:15], v[188:191], v[172:175], v[12:15]
	v_mfma_f32_16x16x32_bf16 v[8:11], v[196:199], v[172:175], v[8:11]
	v_mfma_f32_16x16x32_bf16 v[8:11], v[136:139], v[176:179], v[8:11]
	v_mfma_f32_16x16x32_bf16 v[0:3], v[136:139], v[132:135], v[0:3]
	v_mfma_f32_16x16x32_bf16 v[0:3], v[196:199], v[180:183], v[0:3]
	v_cmp_gt_u32_e32 vcc, s35, v130
	s_barrier
	s_and_saveexec_b64 s[10:11], vcc
	s_cbranch_execz .LBB0_559
	s_barrier

; #define STAGE(P, RS, SOFF, OFF, kt) do { const int _so = (SOFF) + (kt) * (BK * 2); \
;     _Pragma("unroll") for (int _i = 0; _i < 2; ++_i) { \
;       __builtin_amdgcn_raw_ptr_buffer_load_lds(RS, (__attribute__((address_space(3))) void*)((P) + wave * 1024 + _i * 8192), 16, OFF[_i], _so, 0, 0); } } while (0)
; #define LDA(dst, b, h) _Pragma("unroll") for (int m = 0; m < 4; ++m) _Pragma("unroll") for (int k = 0; k < 2; ++k) \
;     dst[m][k] = *reinterpret_cast<const bf16x8*>(SA(b, h) + lds_byte(wr * 64 + m * 16 + fr, k * 32 + fq * 8))
; #define LDB(dst, b, h) _Pragma("unroll") for (int n = 0; n < 2; ++n) _Pragma("unroll") for (int k = 0; k < 2; ++k) \
;     dst[n][k] = *reinterpret_cast<const bf16x8*>(SB(b, h) + lds_byte(wc * 32 + n * 16 + fr, k * 32 + fq * 8))
; #define WAIT_V(n) asm volatile("s_waitcnt vmcnt(" #n ")" ::: "memory")
; #define WAIT_L(n) asm volatile("s_waitcnt lgkmcnt(" #n ")" ::: "memory")
; #define BAR __builtin_amdgcn_s_barrier()
; #define SCHED __builtin_amdgcn_sched_barrier(0)
;     ...
;     const int tid = opaque_tid(wave);
;     const int wid = tid >> 6, lane = tid & 63, wr = wid >> 2, wc = wid & 3, fr = lane & 15, fq = lane >> 4;
;     int offA[2], offB[2];
;     _Pragma("unroll") for (int i = 0; i < 2; ++i) {
;       int r, c; stage_rc(tid * 16 + i * 8192, r, c);
;       offA[i] = (r * lda + c) * 2; offB[i] = (r * ldb + c) * 2;
;     }
;     const int brow = pm * BM;
;     f32x4 acc[2][2][4][2];
;     _Pragma("unroll") for (int a = 0; a < 2; ++a) _Pragma("unroll") for (int b = 0; b < 2; ++b) _Pragma("unroll") for (int m = 0; m < 4; ++m) _Pragma("unroll") for (int n = 0; n < 2; ++n)
;       acc[a][b][m][n] = f32x4{0.f, 0.f, 0.f, 0.f};
;     bf16x8 At[4][2], B0[2][2], B1[2][2];
;     if (wr == 1) BAR;
;     if (first_tile) { WAIT_V(0); }
;     else if constexpr (mode == MODE_RESID_LN) { WAIT_V(0); }
;     else if constexpr (mode == MODE_SWIGLU) { WAIT_V(6); }
;     else if constexpr (mode == MODE_V) { WAIT_V(24); }
;     else { WAIT_V(12); }
;     first_tile = false;
;     BAR;
;     BAR;
;     for (int t = 0; t < nt - 2; t += 2) {
;       LDB(B0, 0, 0); SCHED; LDA(At, 0, 0); STAGE(SA(1, 1), rsA, sA1, offA, t + 1);
;       WAIT_L(8); BAR; WAIT_L(0); MMA(0, 0, At, B0); BAR; SCHED;
;       LDB(B1, 0, 1); STAGE(SB(0, 0), rsB, sB0, offB, t + 2);
.LBB0_656:
	v_bfe_i32 v4, v128, 27, 1
	v_lshlrev_b32_e32 v2, 4, v128
	v_lshrrev_b32_e32 v4, 22, v4
	v_add_u32_e32 v4, v2, v4
	v_and_b32_e32 v4, 0xfffffc00, v4
	v_sub_u32_e32 v4, v2, v4
	v_lshrrev_b32_e32 v5, 4, v4
	v_bitop3_b32 v4, v5, v4, 32 bitop3:0x6c
	v_ashrrev_i32_e32 v3, 31, v128
	v_ashrrev_i32_e32 v6, 31, v4
	v_lshrrev_b32_e32 v3, 26, v3
	v_lshrrev_b32_e32 v6, 26, v6
	v_add_u32_e32 v3, v128, v3
	v_add_u32_e32 v6, v4, v6
	v_ashrrev_i32_e32 v3, 6, v3
	v_lshrrev_b32_e32 v7, 6, v6
	v_and_b32_e32 v6, 0xc0, v6
	v_lshlrev_b32_e32 v5, 3, v3
	v_lshlrev_b32_e32 v3, 5, v3
	v_sub_u32_e32 v4, v4, v6
	v_and_b32_e32 v5, 0xffff0, v5
	v_and_b32_e32 v3, 32, v3
	v_ashrrev_i16_sdwa v4, v216, sext(v4) dst_sel:DWORD dst_unused:UNUSED_PAD src0_sel:DWORD src1_sel:BYTE_0
	v_add_u32_sdwa v3, v3, sext(v4) dst_sel:DWORD dst_unused:UNUSED_PAD src0_sel:DWORD src1_sel:WORD_0
	v_add_lshl_u32 v4, v7, v5, 12
	v_add_u32_e32 v2, 0x2000, v2
	v_lshl_add_u32 v141, v3, 1, v4
	v_ashrrev_i32_e32 v3, 31, v2
	v_lshrrev_b32_e32 v3, 22, v3
	v_add_u32_e32 v3, v2, v3
	v_ashrrev_i32_e32 v3, 10, v3
	v_mul_i32_i24_e32 v4, 0x400, v3
	v_sub_u32_e32 v2, v2, v4
	v_lshrrev_b32_e32 v4, 4, v2
	v_bitop3_b32 v2, v4, v2, 32 bitop3:0x6c
	v_ashrrev_i32_e32 v5, 31, v2
	v_lshrrev_b32_e32 v5, 26, v5
	v_add_u32_e32 v5, v2, v5
	v_lshrrev_b32_e32 v6, 6, v5
	v_and_b32_e32 v5, 0xc0, v5
	v_lshlrev_b32_e32 v4, 3, v3
	v_lshlrev_b32_e32 v3, 5, v3
	v_sub_u32_e32 v2, v2, v5
	v_and_b32_e32 v4, 0xffff0, v4
	v_and_b32_e32 v3, 32, v3
	v_ashrrev_i16_sdwa v2, v216, sext(v2) dst_sel:DWORD dst_unused:UNUSED_PAD src0_sel:DWORD src1_sel:BYTE_0
	v_add_u32_sdwa v2, v3, sext(v2) dst_sel:DWORD dst_unused:UNUSED_PAD src0_sel:DWORD src1_sel:WORD_0
	v_add_lshl_u32 v3, v6, v4, 12
	v_lshl_add_u32 v142, v2, 1, v3
	v_and_b32_e32 v3, 15, v0
	v_lshlrev_b32_e32 v5, 2, v0
	v_and_b32_e32 v2, 48, v0
	v_lshlrev_b32_e32 v3, 6, v3
	v_and_b32_e32 v5, 32, v5
	v_or_b32_e32 v4, v3, v2
	v_bitop3_b32 v3, v3, v5, v2 bitop3:0x36
	v_lshlrev_b32_e32 v6, 6, v128
	s_movk_i32 s1, 0x3000
	v_and_or_b32 v3, v6, s1, v3
	v_lshlrev_b32_e32 v0, 6, v0
	s_movk_i32 s1, 0x3c0
	v_lshlrev_b32_e32 v1, 13, v1
	v_and_or_b32 v0, v0, s1, v2
	v_bitop3_b32 v0, v1, v0, v5 bitop3:0xf6
	v_or_b32_e32 v6, 0x400, v3
	v_or_b32_e32 v7, 0x800, v3
	v_or_b32_e32 v8, 0xc00, v3
	v_or_b32_e32 v132, 0x800, v0
	v_or_b32_e32 v131, 0x1000, v0
	v_or_b32_e32 v130, 0x1800, v0
	v_mov_b32_e32 v0, 0
	v_bitop3_b32 v129, v4, v1, v5 bitop3:0xde
	s_mov_b32 s1, -2
	s_mov_b32 s3, 0
	v_or_b32_e32 v147, 0x10000, v3
	v_or_b32_e32 v148, 0x10000, v6
	v_or_b32_e32 v149, 0x10000, v7
	v_or_b32_e32 v150, 0x10000, v8
	v_or_b32_e32 v143, 0x14000, v3
	v_or_b32_e32 v144, 0x14000, v6
	v_or_b32_e32 v145, 0x14000, v7
	v_or_b32_e32 v146, 0x14000, v8
	v_or_b32_e32 v137, 0x18000, v3
	v_or_b32_e32 v138, 0x18000, v6
	v_or_b32_e32 v139, 0x18000, v7
	v_or_b32_e32 v140, 0x18000, v8
	v_or_b32_e32 v133, 0x1c000, v3
	v_or_b32_e32 v134, 0x1c000, v6
	v_or_b32_e32 v135, 0x1c000, v7
	v_or_b32_e32 v136, 0x1c000, v8
	s_barrier
	s_barrier
	ds_read_b128 v[152:155], v147
	ds_read_b128 v[156:159], v148
	ds_read_b128 v[160:163], v149
	ds_read_b128 v[164:167], v150
	s_add_i32 s5, s81, s3
	s_add_i32 s6, s5, 0x80
	s_mov_b32 m0, s39
	ds_read_b128 v[168:171], v129
	ds_read_b128 v[172:175], v129 offset:1024
	ds_read_b128 v[176:179], v132
	ds_read_b128 v[180:183], v132 offset:1024
	ds_read_b128 v[184:187], v131
	ds_read_b128 v[188:191], v131 offset:1024
	ds_read_b128 v[192:195], v130
	ds_read_b128 v[196:199], v130 offset:1024
	buffer_load_dwordx4 v141, s[8:11], s6 offen lds
	s_mov_b32 m0, s58
	s_nop 0
	buffer_load_dwordx4 v142, s[8:11], s6 offen lds
	s_waitcnt lgkmcnt(8)
	s_barrier
	s_waitcnt lgkmcnt(0)
	v_mfma_f32_16x16x32_bf16 v[124:127], v[152:155], v[168:171], 0
	v_mfma_f32_16x16x32_bf16 v[124:127], v[156:159], v[172:175], v[124:127]
	v_mfma_f32_16x16x32_bf16 v[120:123], v[164:167], v[172:175], 0
	v_mfma_f32_16x16x32_bf16 v[120:123], v[160:163], v[168:171], v[120:123]
	v_mfma_f32_16x16x32_bf16 v[112:115], v[160:163], v[176:179], 0
	v_mfma_f32_16x16x32_bf16 v[112:115], v[164:167], v[180:183], v[112:115]
	v_mfma_f32_16x16x32_bf16 v[116:119], v[156:159], v[180:183], 0
	v_mfma_f32_16x16x32_bf16 v[116:119], v[152:155], v[176:179], v[116:119]
	v_mfma_f32_16x16x32_bf16 v[108:111], v[152:155], v[184:187], 0
	v_mfma_f32_16x16x32_bf16 v[108:111], v[156:159], v[188:191], v[108:111]
	v_mfma_f32_16x16x32_bf16 v[104:107], v[164:167], v[188:191], 0
	v_mfma_f32_16x16x32_bf16 v[104:107], v[160:163], v[184:187], v[104:107]
	v_mfma_f32_16x16x32_bf16 v[96:99], v[160:163], v[192:195], 0
	v_mfma_f32_16x16x32_bf16 v[96:99], v[164:167], v[196:199], v[96:99]
	v_mfma_f32_16x16x32_bf16 v[100:103], v[156:159], v[196:199], 0
	v_mfma_f32_16x16x32_bf16 v[100:103], v[152:155], v[192:195], v[100:103]
	s_barrier
	s_add_i32 s6, s83, s3
	s_add_i32 s7, s6, 0x100
	s_mov_b32 s14, s10
	s_mov_b32 s15, s11
	s_mov_b32 m0, s85
	ds_read_b128 v[200:203], v143
	ds_read_b128 v[204:207], v144
	ds_read_b128 v[208:211], v145
	ds_read_b128 v[212:215], v146
	buffer_load_dwordx4 v141, s[12:15], s7 offen lds
	s_mov_b32 m0, s75
	s_nop 0
	buffer_load_dwordx4 v142, s[12:15], s7 offen lds
	s_barrier
; #define STAGE(P, RS, SOFF, OFF, kt) do { const int _so = (SOFF) + (kt) * (BK * 2); \
;     _Pragma("unroll") for (int _i = 0; _i < 2; ++_i) { \
;       __builtin_amdgcn_raw_ptr_buffer_load_lds(RS, (__attribute__((address_space(3))) void*)((P) + wave * 1024 + _i * 8192), 16, OFF[_i], _so, 0, 0); } } while (0)
; #define LDA(dst, b, h) _Pragma("unroll") for (int m = 0; m < 4; ++m) _Pragma("unroll") for (int k = 0; k < 2; ++k) \
;     dst[m][k] = *reinterpret_cast<const bf16x8*>(SA(b, h) + lds_byte(wr * 64 + m * 16 + fr, k * 32 + fq * 8))
; #define LDB(dst, b, h) _Pragma("unroll") for (int n = 0; n < 2; ++n) _Pragma("unroll") for (int k = 0; k < 2; ++k) \
;     dst[n][k] = *reinterpret_cast<const bf16x8*>(SB(b, h) + lds_byte(wc * 32 + n * 16 + fr, k * 32 + fq * 8))
; #define WAIT_V(n) asm volatile("s_waitcnt vmcnt(" #n ")" ::: "memory")
; #define WAIT_L(n) asm volatile("s_waitcnt lgkmcnt(" #n ")" ::: "memory")
; #define BAR __builtin_amdgcn_s_barrier()
; #define SCHED __builtin_amdgcn_sched_barrier(0)
;     ...
;       BAR; WAIT_L(0); MMA(0, 1, At, B1); BAR;
;       LDA(At, 0, 1); STAGE(SA(0, 0), rsA, sA0, offA, t + 2);
;       BAR; WAIT_L(0); MMA(1, 0, At, B0); BAR; SCHED;
;       STAGE(SB(0, 1), rsB, sB1, offB, t + 2);
;       WAIT_V(6); BAR; MMA(1, 1, At, B1); BAR;
;       LDB(B0, 1, 0); SCHED; LDA(At, 1, 0); STAGE(SA(0, 1), rsA, sA1, offA, t + 2);
;       WAIT_L(8); BAR; WAIT_L(0); MMA(0, 0, At, B0); BAR; SCHED;
	s_waitcnt lgkmcnt(0)
	v_mfma_f32_16x16x32_bf16 v[92:95], v[200:203], v[168:171], 0
	v_mfma_f32_16x16x32_bf16 v[92:95], v[204:207], v[172:175], v[92:95]
	v_mfma_f32_16x16x32_bf16 v[88:91], v[212:215], v[172:175], 0
	v_mfma_f32_16x16x32_bf16 v[88:91], v[208:211], v[168:171], v[88:91]
	v_mfma_f32_16x16x32_bf16 v[68:71], v[208:211], v[176:179], 0
	v_mfma_f32_16x16x32_bf16 v[68:71], v[212:215], v[180:183], v[68:71]
	v_mfma_f32_16x16x32_bf16 v[80:83], v[204:207], v[180:183], 0
	v_mfma_f32_16x16x32_bf16 v[80:83], v[200:203], v[176:179], v[80:83]
	v_mfma_f32_16x16x32_bf16 v[60:63], v[200:203], v[184:187], 0
	v_mfma_f32_16x16x32_bf16 v[60:63], v[204:207], v[188:191], v[60:63]
	v_mfma_f32_16x16x32_bf16 v[56:59], v[212:215], v[188:191], 0
	v_mfma_f32_16x16x32_bf16 v[56:59], v[208:211], v[184:187], v[56:59]
	v_mfma_f32_16x16x32_bf16 v[48:51], v[208:211], v[192:195], 0
	v_mfma_f32_16x16x32_bf16 v[48:51], v[212:215], v[196:199], v[48:51]
	v_mfma_f32_16x16x32_bf16 v[52:55], v[204:207], v[196:199], 0
	v_mfma_f32_16x16x32_bf16 v[52:55], v[200:203], v[192:195], v[52:55]
	s_barrier
	s_add_i32 s7, s82, s3
	s_add_i32 s22, s7, 0x100
	s_mov_b32 m0, s38
	ds_read_b128 v[168:171], v129 offset:16384
	ds_read_b128 v[172:175], v129 offset:17408
	ds_read_b128 v[176:179], v132 offset:16384
	ds_read_b128 v[180:183], v132 offset:17408
	ds_read_b128 v[184:187], v131 offset:16384
	ds_read_b128 v[188:191], v131 offset:17408
	ds_read_b128 v[192:195], v130 offset:16384
	ds_read_b128 v[196:199], v130 offset:17408
	buffer_load_dwordx4 v141, s[8:11], s22 offen lds
	s_mov_b32 m0, s95
	s_nop 0
	buffer_load_dwordx4 v142, s[8:11], s22 offen lds
	s_barrier
	s_waitcnt lgkmcnt(0)
	v_mfma_f32_16x16x32_bf16 v[44:47], v[152:155], v[168:171], 0
	v_mfma_f32_16x16x32_bf16 v[44:47], v[156:159], v[172:175], v[44:47]
	v_mfma_f32_16x16x32_bf16 v[40:43], v[164:167], v[172:175], 0
	v_mfma_f32_16x16x32_bf16 v[40:43], v[160:163], v[168:171], v[40:43]
	v_mfma_f32_16x16x32_bf16 v[32:35], v[160:163], v[176:179], 0
	v_mfma_f32_16x16x32_bf16 v[32:35], v[164:167], v[180:183], v[32:35]
	v_mfma_f32_16x16x32_bf16 v[36:39], v[156:159], v[180:183], 0
	v_mfma_f32_16x16x32_bf16 v[36:39], v[152:155], v[176:179], v[36:39]
	v_mfma_f32_16x16x32_bf16 v[28:31], v[152:155], v[184:187], 0
	v_mfma_f32_16x16x32_bf16 v[28:31], v[156:159], v[188:191], v[28:31]
	v_mfma_f32_16x16x32_bf16 v[24:27], v[164:167], v[188:191], 0
	v_mfma_f32_16x16x32_bf16 v[24:27], v[160:163], v[184:187], v[24:27]
	v_mfma_f32_16x16x32_bf16 v[16:19], v[160:163], v[192:195], 0
	v_mfma_f32_16x16x32_bf16 v[16:19], v[164:167], v[196:199], v[16:19]
	v_mfma_f32_16x16x32_bf16 v[20:23], v[156:159], v[196:199], 0
	v_mfma_f32_16x16x32_bf16 v[20:23], v[152:155], v[192:195], v[20:23]
	s_barrier
	s_add_i32 s22, s84, s3
	s_add_i32 s23, s22, 0x100
	s_mov_b32 m0, s86
	s_nop 0
	buffer_load_dwordx4 v141, s[12:15], s23 offen lds
	s_mov_b32 m0, s28
	s_nop 0
	buffer_load_dwordx4 v142, s[12:15], s23 offen lds
	s_waitcnt vmcnt(6)
	s_barrier
	v_mfma_f32_16x16x32_bf16 v[12:15], v[200:203], v[168:171], 0
	v_mfma_f32_16x16x32_bf16 v[12:15], v[204:207], v[172:175], v[12:15]
	v_mfma_f32_16x16x32_bf16 v[8:11], v[212:215], v[172:175], 0
	v_mfma_f32_16x16x32_bf16 v[8:11], v[208:211], v[168:171], v[8:11]
	v_mfma_f32_16x16x32_bf16 v[0:3], v[208:211], v[176:179], 0
	v_mfma_f32_16x16x32_bf16 v[0:3], v[212:215], v[180:183], v[0:3]
	v_mfma_f32_16x16x32_bf16 v[4:7], v[204:207], v[180:183], 0
	v_mfma_f32_16x16x32_bf16 v[4:7], v[200:203], v[176:179], v[4:7]
	v_mfma_f32_16x16x32_bf16 v[64:67], v[200:203], v[184:187], 0
	v_mfma_f32_16x16x32_bf16 v[64:67], v[204:207], v[188:191], v[64:67]
	v_mfma_f32_16x16x32_bf16 v[72:75], v[212:215], v[188:191], 0
	v_mfma_f32_16x16x32_bf16 v[72:75], v[208:211], v[184:187], v[72:75]
	v_mfma_f32_16x16x32_bf16 v[84:87], v[208:211], v[192:195], 0
	v_mfma_f32_16x16x32_bf16 v[84:87], v[212:215], v[196:199], v[84:87]
	v_mfma_f32_16x16x32_bf16 v[76:79], v[204:207], v[196:199], 0
	v_mfma_f32_16x16x32_bf16 v[76:79], v[200:203], v[192:195], v[76:79]
	s_barrier
	ds_read_b128 v[152:155], v137
	ds_read_b128 v[156:159], v138
	ds_read_b128 v[160:163], v139
	ds_read_b128 v[164:167], v140
	s_addk_i32 s5, 0x100
	s_mov_b32 m0, s87
	ds_read_b128 v[168:171], v129 offset:32768
	ds_read_b128 v[172:175], v129 offset:33792
	ds_read_b128 v[176:179], v132 offset:32768
	ds_read_b128 v[180:183], v132 offset:33792
	ds_read_b128 v[184:187], v131 offset:32768
	ds_read_b128 v[188:191], v131 offset:33792
	ds_read_b128 v[192:195], v130 offset:32768
	ds_read_b128 v[196:199], v130 offset:33792
	buffer_load_dwordx4 v141, s[8:11], s5 offen lds
	s_mov_b32 m0, s97
	s_nop 0
	buffer_load_dwordx4 v142, s[8:11], s5 offen lds
	s_waitcnt lgkmcnt(8)
	s_barrier
; #define STAGE(P, RS, SOFF, OFF, kt) do { const int _so = (SOFF) + (kt) * (BK * 2); \
;     _Pragma("unroll") for (int _i = 0; _i < 2; ++_i) { \
;       __builtin_amdgcn_raw_ptr_buffer_load_lds(RS, (__attribute__((address_space(3))) void*)((P) + wave * 1024 + _i * 8192), 16, OFF[_i], _so, 0, 0); } } while (0)
; #define LDA(dst, b, h) _Pragma("unroll") for (int m = 0; m < 4; ++m) _Pragma("unroll") for (int k = 0; k < 2; ++k) \
;     dst[m][k] = *reinterpret_cast<const bf16x8*>(SA(b, h) + lds_byte(wr * 64 + m * 16 + fr, k * 32 + fq * 8))
; #define LDB(dst, b, h) _Pragma("unroll") for (int n = 0; n < 2; ++n) _Pragma("unroll") for (int k = 0; k < 2; ++k) \
;     dst[n][k] = *reinterpret_cast<const bf16x8*>(SB(b, h) + lds_byte(wc * 32 + n * 16 + fr, k * 32 + fq * 8))
; #define WAIT_V(n) asm volatile("s_waitcnt vmcnt(" #n ")" ::: "memory")
; #define WAIT_L(n) asm volatile("s_waitcnt lgkmcnt(" #n ")" ::: "memory")
; #define BAR __builtin_amdgcn_s_barrier()
; #define SCHED __builtin_amdgcn_sched_barrier(0)
;     ...
;       WAIT_L(8); BAR; WAIT_L(0); MMA(0, 0, At, B0); BAR; SCHED;
;       LDB(B1, 1, 1); STAGE(SB(1, 0), rsB, sB0, offB, t + 3);
;       BAR; WAIT_L(0); MMA(0, 1, At, B1); BAR;
;       LDA(At, 1, 1); STAGE(SA(1, 0), rsA, sA0, offA, t + 3);
;       BAR; WAIT_L(0); MMA(1, 0, At, B0); BAR; SCHED;
;       STAGE(SB(1, 1), rsB, sB1, offB, t + 3);
;       WAIT_V(6); BAR; MMA(1, 1, At, B1); BAR;
;     }
	s_waitcnt lgkmcnt(0)
	v_mfma_f32_16x16x32_bf16 v[124:127], v[152:155], v[168:171], v[124:127]
	v_mfma_f32_16x16x32_bf16 v[124:127], v[156:159], v[172:175], v[124:127]
	v_mfma_f32_16x16x32_bf16 v[120:123], v[164:167], v[172:175], v[120:123]
	v_mfma_f32_16x16x32_bf16 v[120:123], v[160:163], v[168:171], v[120:123]
	v_mfma_f32_16x16x32_bf16 v[112:115], v[160:163], v[176:179], v[112:115]
	v_mfma_f32_16x16x32_bf16 v[112:115], v[164:167], v[180:183], v[112:115]
	v_mfma_f32_16x16x32_bf16 v[116:119], v[156:159], v[180:183], v[116:119]
	v_mfma_f32_16x16x32_bf16 v[116:119], v[152:155], v[176:179], v[116:119]
	v_mfma_f32_16x16x32_bf16 v[108:111], v[152:155], v[184:187], v[108:111]
	v_mfma_f32_16x16x32_bf16 v[108:111], v[156:159], v[188:191], v[108:111]
	v_mfma_f32_16x16x32_bf16 v[104:107], v[164:167], v[188:191], v[104:107]
	v_mfma_f32_16x16x32_bf16 v[104:107], v[160:163], v[184:187], v[104:107]
	v_mfma_f32_16x16x32_bf16 v[96:99], v[160:163], v[192:195], v[96:99]
	v_mfma_f32_16x16x32_bf16 v[96:99], v[164:167], v[196:199], v[96:99]
	v_mfma_f32_16x16x32_bf16 v[100:103], v[156:159], v[196:199], v[100:103]
	v_mfma_f32_16x16x32_bf16 v[100:103], v[152:155], v[192:195], v[100:103]
	s_barrier
	s_addk_i32 s6, 0x180
	s_mov_b32 m0, s92
	ds_read_b128 v[200:203], v133
	ds_read_b128 v[204:207], v134
	ds_read_b128 v[208:211], v135
	ds_read_b128 v[212:215], v136
	buffer_load_dwordx4 v141, s[12:15], s6 offen lds
	s_mov_b32 m0, s29
	s_nop 0
	buffer_load_dwordx4 v142, s[12:15], s6 offen lds
	s_barrier
	s_waitcnt lgkmcnt(0)
	v_mfma_f32_16x16x32_bf16 v[92:95], v[200:203], v[168:171], v[92:95]
	v_mfma_f32_16x16x32_bf16 v[92:95], v[204:207], v[172:175], v[92:95]
	v_mfma_f32_16x16x32_bf16 v[88:91], v[212:215], v[172:175], v[88:91]
	v_mfma_f32_16x16x32_bf16 v[88:91], v[208:211], v[168:171], v[88:91]
	v_mfma_f32_16x16x32_bf16 v[68:71], v[208:211], v[176:179], v[68:71]
	v_mfma_f32_16x16x32_bf16 v[68:71], v[212:215], v[180:183], v[68:71]
	v_mfma_f32_16x16x32_bf16 v[80:83], v[204:207], v[180:183], v[80:83]
	v_mfma_f32_16x16x32_bf16 v[80:83], v[200:203], v[176:179], v[80:83]
	v_mfma_f32_16x16x32_bf16 v[60:63], v[200:203], v[184:187], v[60:63]
	v_mfma_f32_16x16x32_bf16 v[60:63], v[204:207], v[188:191], v[60:63]
	v_mfma_f32_16x16x32_bf16 v[56:59], v[212:215], v[188:191], v[56:59]
	v_mfma_f32_16x16x32_bf16 v[56:59], v[208:211], v[184:187], v[56:59]
	v_mfma_f32_16x16x32_bf16 v[48:51], v[208:211], v[192:195], v[48:51]
	v_mfma_f32_16x16x32_bf16 v[48:51], v[212:215], v[196:199], v[48:51]
	v_mfma_f32_16x16x32_bf16 v[52:55], v[204:207], v[196:199], v[52:55]
	v_mfma_f32_16x16x32_bf16 v[52:55], v[200:203], v[192:195], v[52:55]
	s_barrier
	s_addk_i32 s7, 0x180
	s_mov_b32 m0, s93
	ds_read_b128 v[168:171], v129 offset:49152
	ds_read_b128 v[172:175], v129 offset:50176
	ds_read_b128 v[176:179], v132 offset:49152
	ds_read_b128 v[180:183], v132 offset:50176
	ds_read_b128 v[184:187], v131 offset:49152
	ds_read_b128 v[188:191], v131 offset:50176
	ds_read_b128 v[192:195], v130 offset:49152
	ds_read_b128 v[196:199], v130 offset:50176
	buffer_load_dwordx4 v141, s[8:11], s7 offen lds
	s_mov_b32 m0, s56
	s_nop 0
	buffer_load_dwordx4 v142, s[8:11], s7 offen lds
	s_barrier
	s_waitcnt lgkmcnt(0)
	v_mfma_f32_16x16x32_bf16 v[44:47], v[152:155], v[168:171], v[44:47]
	v_mfma_f32_16x16x32_bf16 v[44:47], v[156:159], v[172:175], v[44:47]
	v_mfma_f32_16x16x32_bf16 v[40:43], v[164:167], v[172:175], v[40:43]
	v_mfma_f32_16x16x32_bf16 v[40:43], v[160:163], v[168:171], v[40:43]
	v_mfma_f32_16x16x32_bf16 v[32:35], v[160:163], v[176:179], v[32:35]
	v_mfma_f32_16x16x32_bf16 v[32:35], v[164:167], v[180:183], v[32:35]
	v_mfma_f32_16x16x32_bf16 v[36:39], v[156:159], v[180:183], v[36:39]
	v_mfma_f32_16x16x32_bf16 v[36:39], v[152:155], v[176:179], v[36:39]
	v_mfma_f32_16x16x32_bf16 v[28:31], v[152:155], v[184:187], v[28:31]
	v_mfma_f32_16x16x32_bf16 v[28:31], v[156:159], v[188:191], v[28:31]
	v_mfma_f32_16x16x32_bf16 v[24:27], v[164:167], v[188:191], v[24:27]
	v_mfma_f32_16x16x32_bf16 v[24:27], v[160:163], v[184:187], v[24:27]
	v_mfma_f32_16x16x32_bf16 v[16:19], v[160:163], v[192:195], v[16:19]
	v_mfma_f32_16x16x32_bf16 v[16:19], v[164:167], v[196:199], v[16:19]
	v_mfma_f32_16x16x32_bf16 v[20:23], v[156:159], v[196:199], v[20:23]
	v_mfma_f32_16x16x32_bf16 v[20:23], v[152:155], v[192:195], v[20:23]
	s_barrier
	s_addk_i32 s22, 0x180
	s_mov_b32 m0, s94
	s_nop 0
	buffer_load_dwordx4 v141, s[12:15], s22 offen lds
	s_mov_b32 m0, s57
	s_nop 0
	buffer_load_dwordx4 v142, s[12:15], s22 offen lds
	s_add_i32 s1, s1, 2
	s_addk_i32 s3, 0x100
	s_cmp_gt_u32 s1, 27
	s_cbranch_scc0 .LBB0_657
	s_branch .Lmy_post_657

; #define STAGE(P, RS, SOFF, OFF, kt) do { const int _so = (SOFF) + (kt) * (BK * 2); \
;     _Pragma("unroll") for (int _i = 0; _i < 2; ++_i) { \
;       __builtin_amdgcn_raw_ptr_buffer_load_lds(RS, (__attribute__((address_space(3))) void*)((P) + wave * 1024 + _i * 8192), 16, OFF[_i], _so, 0, 0); } } while (0)
; #define LDA(dst, b, h) _Pragma("unroll") for (int m = 0; m < 4; ++m) _Pragma("unroll") for (int k = 0; k < 2; ++k) \
;     dst[m][k] = *reinterpret_cast<const bf16x8*>(SA(b, h) + lds_byte(wr * 64 + m * 16 + fr, k * 32 + fq * 8))
; #define LDB(dst, b, h) _Pragma("unroll") for (int n = 0; n < 2; ++n) _Pragma("unroll") for (int k = 0; k < 2; ++k) \
;     dst[n][k] = *reinterpret_cast<const bf16x8*>(SB(b, h) + lds_byte(wc * 32 + n * 16 + fr, k * 32 + fq * 8))
; #define WAIT_V(n) asm volatile("s_waitcnt vmcnt(" #n ")" ::: "memory")
; #define WAIT_L(n) asm volatile("s_waitcnt lgkmcnt(" #n ")" ::: "memory")
; #define BAR __builtin_amdgcn_s_barrier()
;     ...
;       WAIT_V(6); BAR; MMA(1, 1, At, B1); BAR;
;     }
;     { LDB(B0, 0, 0); LDA(At, 0, 0); STAGE(SA(1, 1), rsA, sA1, offA, nt - 1);
;       BAR; WAIT_L(0); MMA(0, 0, At, B0); BAR;
;       LDB(B1, 0, 1); BAR; WAIT_L(0); MMA(0, 1, At, B1); BAR;
;       LDA(At, 0, 1); WAIT_V(4); BAR; WAIT_L(0); MMA(1, 0, At, B0); MMA(1, 1, At, B1); BAR; }
.Lmy_post_657:
	s_waitcnt vmcnt(6)
	s_barrier
	v_mfma_f32_16x16x32_bf16 v[12:15], v[200:203], v[168:171], v[12:15]
	v_mfma_f32_16x16x32_bf16 v[12:15], v[204:207], v[172:175], v[12:15]
	v_mfma_f32_16x16x32_bf16 v[8:11], v[212:215], v[172:175], v[8:11]
	v_mfma_f32_16x16x32_bf16 v[8:11], v[208:211], v[168:171], v[8:11]
	v_mfma_f32_16x16x32_bf16 v[0:3], v[208:211], v[176:179], v[0:3]
	v_mfma_f32_16x16x32_bf16 v[0:3], v[212:215], v[180:183], v[0:3]
	v_mfma_f32_16x16x32_bf16 v[4:7], v[204:207], v[180:183], v[4:7]
	v_mfma_f32_16x16x32_bf16 v[4:7], v[200:203], v[176:179], v[4:7]
	v_mfma_f32_16x16x32_bf16 v[64:67], v[200:203], v[184:187], v[64:67]
	v_mfma_f32_16x16x32_bf16 v[64:67], v[204:207], v[188:191], v[64:67]
	v_mfma_f32_16x16x32_bf16 v[72:75], v[212:215], v[188:191], v[72:75]
	v_mfma_f32_16x16x32_bf16 v[72:75], v[208:211], v[184:187], v[72:75]
	v_mfma_f32_16x16x32_bf16 v[84:87], v[208:211], v[192:195], v[84:87]
	v_mfma_f32_16x16x32_bf16 v[84:87], v[212:215], v[196:199], v[84:87]
	v_mfma_f32_16x16x32_bf16 v[76:79], v[204:207], v[196:199], v[76:79]
	v_mfma_f32_16x16x32_bf16 v[76:79], v[200:203], v[192:195], v[76:79]
	s_barrier
	s_add_i32 s1, s81, 0xf80
	s_mov_b32 m0, s39
	ds_read_b128 v[152:155], v147
	ds_read_b128 v[156:159], v148
	ds_read_b128 v[160:163], v149
	ds_read_b128 v[148:151], v150
	ds_read_b128 v[164:167], v129
	ds_read_b128 v[168:171], v129 offset:1024
	ds_read_b128 v[172:175], v132
	ds_read_b128 v[176:179], v132 offset:1024
	ds_read_b128 v[180:183], v131
	ds_read_b128 v[184:187], v131 offset:1024
	ds_read_b128 v[188:191], v130
	ds_read_b128 v[192:195], v130 offset:1024
	buffer_load_dwordx4 v141, s[8:11], s1 offen lds
	s_mov_b32 m0, s58
	s_nop 0
	buffer_load_dwordx4 v142, s[8:11], s1 offen lds
	s_barrier
	s_waitcnt lgkmcnt(0)
	v_mfma_f32_16x16x32_bf16 v[124:127], v[152:155], v[164:167], v[124:127]
	v_mfma_f32_16x16x32_bf16 v[124:127], v[156:159], v[168:171], v[124:127]
	v_mfma_f32_16x16x32_bf16 v[120:123], v[148:151], v[168:171], v[120:123]
	v_mfma_f32_16x16x32_bf16 v[120:123], v[160:163], v[164:167], v[120:123]
	v_mfma_f32_16x16x32_bf16 v[112:115], v[160:163], v[172:175], v[112:115]
	v_mfma_f32_16x16x32_bf16 v[112:115], v[148:151], v[176:179], v[112:115]
	v_mfma_f32_16x16x32_bf16 v[116:119], v[156:159], v[176:179], v[116:119]
	v_mfma_f32_16x16x32_bf16 v[116:119], v[152:155], v[172:175], v[116:119]
	v_mfma_f32_16x16x32_bf16 v[108:111], v[152:155], v[180:183], v[108:111]
	v_mfma_f32_16x16x32_bf16 v[108:111], v[156:159], v[184:187], v[108:111]
	v_mfma_f32_16x16x32_bf16 v[104:107], v[148:151], v[184:187], v[104:107]
	v_mfma_f32_16x16x32_bf16 v[104:107], v[160:163], v[180:183], v[104:107]
	v_mfma_f32_16x16x32_bf16 v[96:99], v[160:163], v[188:191], v[96:99]
	v_mfma_f32_16x16x32_bf16 v[96:99], v[148:151], v[192:195], v[96:99]
	v_mfma_f32_16x16x32_bf16 v[100:103], v[156:159], v[192:195], v[100:103]
	v_mfma_f32_16x16x32_bf16 v[100:103], v[152:155], v[188:191], v[100:103]
	s_barrier
	ds_read_b128 v[196:199], v143
	ds_read_b128 v[200:203], v144
	ds_read_b128 v[142:145], v145
	ds_read_b128 v[204:207], v146
	s_barrier
	s_waitcnt lgkmcnt(0)
	v_mfma_f32_16x16x32_bf16 v[88:91], v[142:145], v[164:167], v[88:91]
	v_mfma_f32_16x16x32_bf16 v[80:83], v[196:199], v[172:175], v[80:83]
	v_mfma_f32_16x16x32_bf16 v[60:63], v[196:199], v[180:183], v[60:63]
	v_mfma_f32_16x16x32_bf16 v[56:59], v[142:145], v[180:183], v[56:59]
	v_mfma_f32_16x16x32_bf16 v[52:55], v[196:199], v[188:191], v[52:55]
	v_mfma_f32_16x16x32_bf16 v[48:51], v[142:145], v[188:191], v[48:51]
	v_mfma_f32_16x16x32_bf16 v[92:95], v[196:199], v[164:167], v[92:95]
	v_mfma_f32_16x16x32_bf16 v[68:71], v[142:145], v[172:175], v[68:71]
	v_mfma_f32_16x16x32_bf16 v[88:91], v[204:207], v[168:171], v[88:91]
	v_mfma_f32_16x16x32_bf16 v[80:83], v[200:203], v[176:179], v[80:83]
	v_mfma_f32_16x16x32_bf16 v[60:63], v[200:203], v[184:187], v[60:63]
	v_mfma_f32_16x16x32_bf16 v[56:59], v[204:207], v[184:187], v[56:59]
	v_mfma_f32_16x16x32_bf16 v[52:55], v[200:203], v[192:195], v[52:55]
	v_mfma_f32_16x16x32_bf16 v[48:51], v[204:207], v[192:195], v[48:51]
	v_mfma_f32_16x16x32_bf16 v[164:167], v[200:203], v[168:171], v[92:95]
	v_mfma_f32_16x16x32_bf16 v[168:171], v[204:207], v[176:179], v[68:71]
	s_barrier
	s_nop 0
	ds_read_b128 v[68:71], v129 offset:16384
	ds_read_b128 v[92:95], v129 offset:17408
	ds_read_b128 v[172:175], v132 offset:16384
	ds_read_b128 v[176:179], v132 offset:17408
	ds_read_b128 v[180:183], v131 offset:16384
	ds_read_b128 v[184:187], v131 offset:17408
	ds_read_b128 v[188:191], v130 offset:16384
	ds_read_b128 v[192:195], v130 offset:17408
	s_waitcnt vmcnt(4)
	s_barrier
; #define LDA(dst, b, h) _Pragma("unroll") for (int m = 0; m < 4; ++m) _Pragma("unroll") for (int k = 0; k < 2; ++k) \
;     dst[m][k] = *reinterpret_cast<const bf16x8*>(SA(b, h) + lds_byte(wr * 64 + m * 16 + fr, k * 32 + fq * 8))
; #define LDB(dst, b, h) _Pragma("unroll") for (int n = 0; n < 2; ++n) _Pragma("unroll") for (int k = 0; k < 2; ++k) \
;     dst[n][k] = *reinterpret_cast<const bf16x8*>(SB(b, h) + lds_byte(wc * 32 + n * 16 + fr, k * 32 + fq * 8))
; #define WAIT_V(n) asm volatile("s_waitcnt vmcnt(" #n ")" ::: "memory")
; #define WAIT_L(n) asm volatile("s_waitcnt lgkmcnt(" #n ")" ::: "memory")
; #define BAR __builtin_amdgcn_s_barrier()
;     ...
;       LDA(At, 0, 1); WAIT_V(4); BAR; WAIT_L(0); MMA(1, 0, At, B0); MMA(1, 1, At, B1); BAR; }
;     { LDB(B0, 1, 0); LDA(At, 1, 0); WAIT_V(2); BAR; WAIT_L(0); MMA(0, 0, At, B0); BAR;
	s_waitcnt lgkmcnt(0)
	v_mfma_f32_16x16x32_bf16 v[44:47], v[152:155], v[68:71], v[44:47]
	v_mfma_f32_16x16x32_bf16 v[40:43], v[160:163], v[68:71], v[40:43]
	v_mfma_f32_16x16x32_bf16 v[36:39], v[152:155], v[172:175], v[36:39]
	v_mfma_f32_16x16x32_bf16 v[32:35], v[160:163], v[172:175], v[32:35]
	v_mfma_f32_16x16x32_bf16 v[28:31], v[152:155], v[180:183], v[28:31]
	v_mfma_f32_16x16x32_bf16 v[24:27], v[160:163], v[180:183], v[24:27]
	v_mfma_f32_16x16x32_bf16 v[20:23], v[152:155], v[188:191], v[20:23]
	v_mfma_f32_16x16x32_bf16 v[16:19], v[160:163], v[188:191], v[16:19]
	v_mfma_f32_16x16x32_bf16 v[44:47], v[156:159], v[92:95], v[44:47]
	v_mfma_f32_16x16x32_bf16 v[40:43], v[148:151], v[92:95], v[40:43]
	v_mfma_f32_16x16x32_bf16 v[36:39], v[156:159], v[176:179], v[36:39]
	v_mfma_f32_16x16x32_bf16 v[32:35], v[148:151], v[176:179], v[32:35]
	v_mfma_f32_16x16x32_bf16 v[28:31], v[156:159], v[184:187], v[28:31]
	v_mfma_f32_16x16x32_bf16 v[24:27], v[148:151], v[184:187], v[24:27]
	v_mfma_f32_16x16x32_bf16 v[20:23], v[156:159], v[192:195], v[20:23]
	v_mfma_f32_16x16x32_bf16 v[16:19], v[148:151], v[192:195], v[16:19]
	v_mfma_f32_16x16x32_bf16 v[4:7], v[196:199], v[172:175], v[4:7]
	v_mfma_f32_16x16x32_bf16 v[0:3], v[142:145], v[172:175], v[0:3]
	v_mfma_f32_16x16x32_bf16 v[12:15], v[196:199], v[68:71], v[12:15]
	v_mfma_f32_16x16x32_bf16 v[8:11], v[142:145], v[68:71], v[8:11]
	v_mfma_f32_16x16x32_bf16 v[64:67], v[196:199], v[180:183], v[64:67]
	v_mfma_f32_16x16x32_bf16 v[68:71], v[142:145], v[180:183], v[72:75]
	v_mfma_f32_16x16x32_bf16 v[72:75], v[196:199], v[188:191], v[76:79]
	v_mfma_f32_16x16x32_bf16 v[76:79], v[142:145], v[188:191], v[84:87]
	v_mfma_f32_16x16x32_bf16 v[4:7], v[200:203], v[176:179], v[4:7]
	v_mfma_f32_16x16x32_bf16 v[0:3], v[204:207], v[176:179], v[0:3]
	v_mfma_f32_16x16x32_bf16 v[142:145], v[200:203], v[92:95], v[12:15]
	v_mfma_f32_16x16x32_bf16 v[146:149], v[204:207], v[92:95], v[8:11]
	v_mfma_f32_16x16x32_bf16 v[150:153], v[200:203], v[184:187], v[64:67]
	v_mfma_f32_16x16x32_bf16 v[154:157], v[204:207], v[184:187], v[68:71]
	v_mfma_f32_16x16x32_bf16 v[158:161], v[200:203], v[192:195], v[72:75]
	v_mfma_f32_16x16x32_bf16 v[172:175], v[204:207], v[192:195], v[76:79]
	s_barrier
	ds_read_b128 v[8:11], v137
	ds_read_b128 v[12:15], v138
	ds_read_b128 v[176:179], v139
	ds_read_b128 v[138:141], v140
	ds_read_b128 v[64:67], v129 offset:32768
	ds_read_b128 v[72:75], v129 offset:33792
	ds_read_b128 v[180:183], v132 offset:32768
	ds_read_b128 v[184:187], v132 offset:33792
	ds_read_b128 v[188:191], v131 offset:32768
	ds_read_b128 v[192:195], v131 offset:33792
	ds_read_b128 v[196:199], v130 offset:32768
	ds_read_b128 v[200:203], v130 offset:33792
	s_waitcnt vmcnt(2)
	s_barrier
	s_waitcnt lgkmcnt(0)
	v_mfma_f32_16x16x32_bf16 v[68:71], v[8:11], v[64:67], v[124:127]
	v_mfma_f32_16x16x32_bf16 v[76:79], v[176:179], v[64:67], v[120:123]
	v_mfma_f32_16x16x32_bf16 v[84:87], v[8:11], v[180:183], v[116:119]
	v_mfma_f32_16x16x32_bf16 v[92:95], v[176:179], v[180:183], v[112:115]
	v_mfma_f32_16x16x32_bf16 v[112:115], v[8:11], v[188:191], v[108:111]
	v_mfma_f32_16x16x32_bf16 v[104:107], v[176:179], v[188:191], v[104:107]
	v_mfma_f32_16x16x32_bf16 v[120:123], v[8:11], v[196:199], v[100:103]
	v_mfma_f32_16x16x32_bf16 v[96:99], v[176:179], v[196:199], v[96:99]
	v_mfma_f32_16x16x32_bf16 v[124:127], v[12:15], v[72:75], v[68:71]
	v_mfma_f32_16x16x32_bf16 v[116:119], v[138:141], v[72:75], v[76:79]
	v_mfma_f32_16x16x32_bf16 v[108:111], v[12:15], v[184:187], v[84:87]
	v_mfma_f32_16x16x32_bf16 v[100:103], v[138:141], v[184:187], v[92:95]
	v_mfma_f32_16x16x32_bf16 v[92:95], v[12:15], v[192:195], v[112:115]
	v_mfma_f32_16x16x32_bf16 v[84:87], v[138:141], v[192:195], v[104:107]
	v_mfma_f32_16x16x32_bf16 v[76:79], v[12:15], v[200:203], v[120:123]
	v_mfma_f32_16x16x32_bf16 v[68:71], v[138:141], v[200:203], v[96:99]
	s_barrier
; #define LDA(dst, b, h) _Pragma("unroll") for (int m = 0; m < 4; ++m) _Pragma("unroll") for (int k = 0; k < 2; ++k) \
;     dst[m][k] = *reinterpret_cast<const bf16x8*>(SA(b, h) + lds_byte(wr * 64 + m * 16 + fr, k * 32 + fq * 8))
; #define LDB(dst, b, h) _Pragma("unroll") for (int n = 0; n < 2; ++n) _Pragma("unroll") for (int k = 0; k < 2; ++k) \
;     dst[n][k] = *reinterpret_cast<const bf16x8*>(SB(b, h) + lds_byte(wc * 32 + n * 16 + fr, k * 32 + fq * 8))
; #define WAIT_V(n) asm volatile("s_waitcnt vmcnt(" #n ")" ::: "memory")
; #define WAIT_L(n) asm volatile("s_waitcnt lgkmcnt(" #n ")" ::: "memory")
; #define BAR __builtin_amdgcn_s_barrier()
;     ...
;     { LDB(B0, 1, 0); LDA(At, 1, 0); WAIT_V(2); BAR; WAIT_L(0); MMA(0, 0, At, B0); BAR;
;       LDB(B1, 1, 1); WAIT_V(0); BAR; WAIT_L(0); MMA(0, 1, At, B1); BAR;
;       LDA(At, 1, 1); BAR; WAIT_L(0); MMA(1, 0, At, B0); MMA(1, 1, At, B1); BAR; }
;     if (wr == 0) BAR;
	ds_read_b128 v[204:207], v133
	ds_read_b128 v[208:211], v134
	ds_read_b128 v[212:215], v135
	ds_read_b128 v[134:137], v136
	s_waitcnt vmcnt(0)
	s_barrier
	s_waitcnt lgkmcnt(0)
	v_mfma_f32_16x16x32_bf16 v[96:99], v[204:207], v[64:67], v[164:167]
	v_mfma_f32_16x16x32_bf16 v[64:67], v[212:215], v[64:67], v[88:91]
	v_mfma_f32_16x16x32_bf16 v[80:83], v[204:207], v[180:183], v[80:83]
	v_mfma_f32_16x16x32_bf16 v[88:91], v[212:215], v[180:183], v[168:171]
	v_mfma_f32_16x16x32_bf16 v[60:63], v[204:207], v[188:191], v[60:63]
	v_mfma_f32_16x16x32_bf16 v[56:59], v[212:215], v[188:191], v[56:59]
	v_mfma_f32_16x16x32_bf16 v[52:55], v[204:207], v[196:199], v[52:55]
	v_mfma_f32_16x16x32_bf16 v[48:51], v[212:215], v[196:199], v[48:51]
	v_mfma_f32_16x16x32_bf16 v[120:123], v[208:211], v[72:75], v[96:99]
	v_mfma_f32_16x16x32_bf16 v[112:115], v[134:137], v[72:75], v[64:67]
	v_mfma_f32_16x16x32_bf16 v[104:107], v[208:211], v[184:187], v[80:83]
	v_mfma_f32_16x16x32_bf16 v[96:99], v[134:137], v[184:187], v[88:91]
	v_mfma_f32_16x16x32_bf16 v[88:91], v[208:211], v[192:195], v[60:63]
	v_mfma_f32_16x16x32_bf16 v[80:83], v[134:137], v[192:195], v[56:59]
	v_mfma_f32_16x16x32_bf16 v[72:75], v[208:211], v[200:203], v[52:55]
	v_mfma_f32_16x16x32_bf16 v[64:67], v[134:137], v[200:203], v[48:51]
	s_barrier
	s_nop 0
	ds_read_b128 v[48:51], v129 offset:49152
	ds_read_b128 v[162:165], v129 offset:50176
	ds_read_b128 v[52:55], v132 offset:49152
	ds_read_b128 v[166:169], v132 offset:50176
	ds_read_b128 v[180:183], v131 offset:49152
	ds_read_b128 v[184:187], v131 offset:50176
	ds_read_b128 v[188:191], v130 offset:49152
	ds_read_b128 v[130:133], v130 offset:50176
	s_barrier
	s_waitcnt lgkmcnt(0)
	v_mfma_f32_16x16x32_bf16 v[44:47], v[8:11], v[48:51], v[44:47]
	v_mfma_f32_16x16x32_bf16 v[40:43], v[176:179], v[48:51], v[40:43]
	v_mfma_f32_16x16x32_bf16 v[36:39], v[8:11], v[52:55], v[36:39]
	v_mfma_f32_16x16x32_bf16 v[32:35], v[176:179], v[52:55], v[32:35]
	v_mfma_f32_16x16x32_bf16 v[28:31], v[8:11], v[180:183], v[28:31]
	v_mfma_f32_16x16x32_bf16 v[24:27], v[176:179], v[180:183], v[24:27]
	v_mfma_f32_16x16x32_bf16 v[8:11], v[8:11], v[188:191], v[20:23]
	v_mfma_f32_16x16x32_bf16 v[16:19], v[176:179], v[188:191], v[16:19]
	v_mfma_f32_16x16x32_bf16 v[60:63], v[12:15], v[162:165], v[44:47]
	v_mfma_f32_16x16x32_bf16 v[56:59], v[138:141], v[162:165], v[40:43]
	v_mfma_f32_16x16x32_bf16 v[44:47], v[12:15], v[166:169], v[36:39]
	v_mfma_f32_16x16x32_bf16 v[40:43], v[138:141], v[166:169], v[32:35]
	v_mfma_f32_16x16x32_bf16 v[28:31], v[12:15], v[184:187], v[28:31]
	v_mfma_f32_16x16x32_bf16 v[24:27], v[138:141], v[184:187], v[24:27]
	v_mfma_f32_16x16x32_bf16 v[12:15], v[12:15], v[130:133], v[8:11]
	v_mfma_f32_16x16x32_bf16 v[8:11], v[138:141], v[130:133], v[16:19]
	v_mfma_f32_16x16x32_bf16 v[16:19], v[204:207], v[48:51], v[142:145]
	v_mfma_f32_16x16x32_bf16 v[20:23], v[212:215], v[48:51], v[146:149]
	v_mfma_f32_16x16x32_bf16 v[4:7], v[204:207], v[52:55], v[4:7]
	v_mfma_f32_16x16x32_bf16 v[0:3], v[212:215], v[52:55], v[0:3]
	v_mfma_f32_16x16x32_bf16 v[138:141], v[204:207], v[180:183], v[150:153]
	v_mfma_f32_16x16x32_bf16 v[142:145], v[212:215], v[180:183], v[154:157]
	v_mfma_f32_16x16x32_bf16 v[146:149], v[204:207], v[188:191], v[158:161]
	v_mfma_f32_16x16x32_bf16 v[150:153], v[212:215], v[188:191], v[172:175]
	v_mfma_f32_16x16x32_bf16 v[52:55], v[208:211], v[162:165], v[16:19]
	v_mfma_f32_16x16x32_bf16 v[48:51], v[134:137], v[162:165], v[20:23]
	v_mfma_f32_16x16x32_bf16 v[36:39], v[208:211], v[166:169], v[4:7]
	v_mfma_f32_16x16x32_bf16 v[32:35], v[134:137], v[166:169], v[0:3]
	v_mfma_f32_16x16x32_bf16 v[20:23], v[208:211], v[184:187], v[138:141]
	v_mfma_f32_16x16x32_bf16 v[16:19], v[134:137], v[184:187], v[142:145]
	v_mfma_f32_16x16x32_bf16 v[4:7], v[208:211], v[130:133], v[146:149]
	v_mfma_f32_16x16x32_bf16 v[0:3], v[134:137], v[130:133], v[150:153]
	v_cmp_gt_u32_e32 vcc, s73, v128
	s_barrier
	s_and_saveexec_b64 s[6:7], vcc
	s_cbranch_execz .LBB0_660
	s_barrier

; #define STAGE(P, RS, SOFF, OFF, kt) do { const int _so = (SOFF) + (kt) * (BK * 2); \
;     _Pragma("unroll") for (int _i = 0; _i < 2; ++_i) { \
;       __builtin_amdgcn_raw_ptr_buffer_load_lds(RS, (__attribute__((address_space(3))) void*)((P) + wave * 1024 + _i * 8192), 16, OFF[_i], _so, 0, 0); } } while (0)
; #define LDA(dst, b, h) _Pragma("unroll") for (int m = 0; m < 4; ++m) _Pragma("unroll") for (int k = 0; k < 2; ++k) \
;     dst[m][k] = *reinterpret_cast<const bf16x8*>(SA(b, h) + lds_byte(wr * 64 + m * 16 + fr, k * 32 + fq * 8))
; #define LDB(dst, b, h) _Pragma("unroll") for (int n = 0; n < 2; ++n) _Pragma("unroll") for (int k = 0; k < 2; ++k) \
;     dst[n][k] = *reinterpret_cast<const bf16x8*>(SB(b, h) + lds_byte(wc * 32 + n * 16 + fr, k * 32 + fq * 8))
; #define WAIT_V(n) asm volatile("s_waitcnt vmcnt(" #n ")" ::: "memory")
; #define WAIT_L(n) asm volatile("s_waitcnt lgkmcnt(" #n ")" ::: "memory")
; #define BAR __builtin_amdgcn_s_barrier()
; #define SCHED __builtin_amdgcn_sched_barrier(0)
;     ...
;     const int tid = opaque_tid(wave);
;     const int wid = tid >> 6, lane = tid & 63, wr = wid >> 2, wc = wid & 3, fr = lane & 15, fq = lane >> 4;
;     int offA[2], offB[2];
;     _Pragma("unroll") for (int i = 0; i < 2; ++i) {
;       int r, c; stage_rc(tid * 16 + i * 8192, r, c);
;       offA[i] = (r * lda + c) * 2; offB[i] = (r * ldb + c) * 2;
;     }
;     const int brow = pm * BM;
;     f32x4 acc[2][2][4][2];
;     _Pragma("unroll") for (int a = 0; a < 2; ++a) _Pragma("unroll") for (int b = 0; b < 2; ++b) _Pragma("unroll") for (int m = 0; m < 4; ++m) _Pragma("unroll") for (int n = 0; n < 2; ++n)
;       acc[a][b][m][n] = f32x4{0.f, 0.f, 0.f, 0.f};
;     bf16x8 At[4][2], B0[2][2], B1[2][2];
;     if (wr == 1) BAR;
;     if (first_tile) { WAIT_V(0); }
;     else if constexpr (mode == MODE_RESID_LN) { WAIT_V(0); }
;     else if constexpr (mode == MODE_SWIGLU) { WAIT_V(6); }
;     else if constexpr (mode == MODE_V) { WAIT_V(24); }
;     else { WAIT_V(12); }
;     first_tile = false;
;     BAR;
;     BAR;
;     for (int t = 0; t < nt - 2; t += 2) {
;       LDB(B0, 0, 0); SCHED; LDA(At, 0, 0); STAGE(SA(1, 1), rsA, sA1, offA, t + 1);
;       WAIT_L(8); BAR; WAIT_L(0); MMA(0, 0, At, B0); BAR; SCHED;
;       LDB(B1, 0, 1); STAGE(SB(0, 0), rsB, sB0, offB, t + 2);
.LBB0_756:
	v_bfe_i32 v4, v128, 27, 1
	v_lshlrev_b32_e32 v2, 4, v128
	v_lshrrev_b32_e32 v4, 22, v4
	v_add_u32_e32 v4, v2, v4
	v_and_b32_e32 v4, 0xfffffc00, v4
	v_sub_u32_e32 v4, v2, v4
	v_lshrrev_b32_e32 v5, 4, v4
	v_bitop3_b32 v4, v5, v4, 32 bitop3:0x6c
	v_ashrrev_i32_e32 v3, 31, v128
	v_ashrrev_i32_e32 v6, 31, v4
	v_lshrrev_b32_e32 v3, 26, v3
	v_lshrrev_b32_e32 v6, 26, v6
	v_add_u32_e32 v3, v128, v3
	v_add_u32_e32 v6, v4, v6
	v_ashrrev_i32_e32 v3, 6, v3
	v_lshrrev_b32_e32 v7, 6, v6
	v_and_b32_e32 v6, 0xc0, v6
	v_lshlrev_b32_e32 v5, 3, v3
	v_lshlrev_b32_e32 v3, 5, v3
	v_sub_u32_e32 v4, v4, v6
	v_and_b32_e32 v5, 0x7fff0, v5
	v_and_b32_e32 v3, 32, v3
	v_ashrrev_i16_sdwa v4, v216, sext(v4) dst_sel:DWORD dst_unused:UNUSED_PAD src0_sel:DWORD src1_sel:BYTE_0
	v_add_u32_sdwa v3, v3, sext(v4) dst_sel:DWORD dst_unused:UNUSED_PAD src0_sel:DWORD src1_sel:WORD_0
	v_add_lshl_u32 v4, v7, v5, 13
	v_add_u32_e32 v2, 0x2000, v2
	v_lshl_add_u32 v141, v3, 1, v4
	v_ashrrev_i32_e32 v3, 31, v2
	v_lshrrev_b32_e32 v3, 22, v3
	v_add_u32_e32 v3, v2, v3
	v_ashrrev_i32_e32 v3, 10, v3
	v_mul_i32_i24_e32 v4, 0x400, v3
	v_sub_u32_e32 v2, v2, v4
	v_lshrrev_b32_e32 v4, 4, v2
	v_bitop3_b32 v2, v4, v2, 32 bitop3:0x6c
	v_ashrrev_i32_e32 v5, 31, v2
	v_lshrrev_b32_e32 v5, 26, v5
	v_add_u32_e32 v5, v2, v5
	v_lshrrev_b32_e32 v6, 6, v5
	v_and_b32_e32 v5, 0xc0, v5
	v_lshlrev_b32_e32 v4, 3, v3
	v_lshlrev_b32_e32 v3, 5, v3
	v_sub_u32_e32 v2, v2, v5
	v_and_b32_e32 v4, 0x7fff0, v4
	v_and_b32_e32 v3, 32, v3
	v_ashrrev_i16_sdwa v2, v216, sext(v2) dst_sel:DWORD dst_unused:UNUSED_PAD src0_sel:DWORD src1_sel:BYTE_0
	v_add_u32_sdwa v2, v3, sext(v2) dst_sel:DWORD dst_unused:UNUSED_PAD src0_sel:DWORD src1_sel:WORD_0
	v_add_lshl_u32 v3, v6, v4, 13
	v_lshl_add_u32 v142, v2, 1, v3
	v_and_b32_e32 v3, 15, v0
	v_lshlrev_b32_e32 v5, 2, v0
	v_and_b32_e32 v2, 48, v0
	v_lshlrev_b32_e32 v3, 6, v3
	v_and_b32_e32 v5, 32, v5
	v_lshlrev_b32_e32 v0, 6, v0
	v_or_b32_e32 v4, v3, v2
	v_bitop3_b32 v3, v3, v5, v2 bitop3:0x36
	v_lshlrev_b32_e32 v6, 6, v128
	v_lshlrev_b32_e32 v1, 13, v1
	v_and_or_b32 v0, v0, s72, v2
	v_and_or_b32 v3, v6, s71, v3
	v_bitop3_b32 v0, v1, v0, v5 bitop3:0xf6
	v_or_b32_e32 v6, 0x400, v3
	v_or_b32_e32 v7, 0x800, v3
	v_or_b32_e32 v8, 0xc00, v3
	v_or_b32_e32 v132, 0x800, v0
	v_or_b32_e32 v131, 0x1000, v0
	v_or_b32_e32 v130, 0x1800, v0
	v_mov_b32_e32 v0, 0
	v_bitop3_b32 v129, v4, v1, v5 bitop3:0xde
	s_mov_b32 s4, -2
	s_mov_b32 s5, 0
	v_or_b32_e32 v147, 0x10000, v3
	v_or_b32_e32 v148, 0x10000, v6
	v_or_b32_e32 v149, 0x10000, v7
	v_or_b32_e32 v150, 0x10000, v8
	v_or_b32_e32 v143, 0x14000, v3
	v_or_b32_e32 v144, 0x14000, v6
	v_or_b32_e32 v145, 0x14000, v7
	v_or_b32_e32 v146, 0x14000, v8
	v_or_b32_e32 v137, 0x18000, v3
	v_or_b32_e32 v138, 0x18000, v6
	v_or_b32_e32 v139, 0x18000, v7
	v_or_b32_e32 v140, 0x18000, v8
	v_or_b32_e32 v133, 0x1c000, v3
	v_or_b32_e32 v134, 0x1c000, v6
	v_or_b32_e32 v135, 0x1c000, v7
	v_or_b32_e32 v136, 0x1c000, v8
	s_barrier
	s_barrier
	ds_read_b128 v[152:155], v147
	ds_read_b128 v[156:159], v148
	ds_read_b128 v[160:163], v149
	ds_read_b128 v[164:167], v150
	s_add_i32 s6, s85, s5
	s_add_i32 s7, s6, 0x80
	s_mov_b32 m0, s39
	ds_read_b128 v[168:171], v129
	ds_read_b128 v[172:175], v129 offset:1024
	ds_read_b128 v[176:179], v132
	ds_read_b128 v[180:183], v132 offset:1024
	ds_read_b128 v[184:187], v131
	ds_read_b128 v[188:191], v131 offset:1024
	ds_read_b128 v[192:195], v130
	ds_read_b128 v[196:199], v130 offset:1024
	buffer_load_dwordx4 v141, s[8:11], s7 offen lds
	s_mov_b32 m0, s56
	s_nop 0
	buffer_load_dwordx4 v142, s[8:11], s7 offen lds
	s_waitcnt lgkmcnt(8)
	s_barrier
	s_waitcnt lgkmcnt(0)
	v_mfma_f32_16x16x32_bf16 v[124:127], v[152:155], v[168:171], 0
	v_mfma_f32_16x16x32_bf16 v[124:127], v[156:159], v[172:175], v[124:127]
	v_mfma_f32_16x16x32_bf16 v[120:123], v[164:167], v[172:175], 0
	v_mfma_f32_16x16x32_bf16 v[120:123], v[160:163], v[168:171], v[120:123]
	v_mfma_f32_16x16x32_bf16 v[112:115], v[160:163], v[176:179], 0
	v_mfma_f32_16x16x32_bf16 v[112:115], v[164:167], v[180:183], v[112:115]
	v_mfma_f32_16x16x32_bf16 v[116:119], v[156:159], v[180:183], 0
	v_mfma_f32_16x16x32_bf16 v[116:119], v[152:155], v[176:179], v[116:119]
	v_mfma_f32_16x16x32_bf16 v[108:111], v[152:155], v[184:187], 0
	v_mfma_f32_16x16x32_bf16 v[108:111], v[156:159], v[188:191], v[108:111]
	v_mfma_f32_16x16x32_bf16 v[104:107], v[164:167], v[188:191], 0
	v_mfma_f32_16x16x32_bf16 v[104:107], v[160:163], v[184:187], v[104:107]
	v_mfma_f32_16x16x32_bf16 v[96:99], v[160:163], v[192:195], 0
	v_mfma_f32_16x16x32_bf16 v[96:99], v[164:167], v[196:199], v[96:99]
	v_mfma_f32_16x16x32_bf16 v[100:103], v[156:159], v[196:199], 0
	v_mfma_f32_16x16x32_bf16 v[100:103], v[152:155], v[192:195], v[100:103]
	s_barrier
	s_add_i32 s7, s87, s5
	s_add_i32 s23, s7, 0x100
	s_mov_b32 s14, s10
	s_mov_b32 s15, s11
	s_mov_b32 m0, s42
	ds_read_b128 v[200:203], v143
	ds_read_b128 v[204:207], v144
	ds_read_b128 v[208:211], v145
	ds_read_b128 v[212:215], v146
	buffer_load_dwordx4 v141, s[12:15], s23 offen lds
	s_mov_b32 m0, s49
	s_nop 0
	buffer_load_dwordx4 v142, s[12:15], s23 offen lds
	s_barrier
	s_waitcnt lgkmcnt(0)
	v_mfma_f32_16x16x32_bf16 v[92:95], v[200:203], v[168:171], 0
	v_mfma_f32_16x16x32_bf16 v[92:95], v[204:207], v[172:175], v[92:95]
	v_mfma_f32_16x16x32_bf16 v[88:91], v[212:215], v[172:175], 0
	v_mfma_f32_16x16x32_bf16 v[88:91], v[208:211], v[168:171], v[88:91]
	v_mfma_f32_16x16x32_bf16 v[68:71], v[208:211], v[176:179], 0
	v_mfma_f32_16x16x32_bf16 v[68:71], v[212:215], v[180:183], v[68:71]
	v_mfma_f32_16x16x32_bf16 v[80:83], v[204:207], v[180:183], 0
	v_mfma_f32_16x16x32_bf16 v[80:83], v[200:203], v[176:179], v[80:83]
	v_mfma_f32_16x16x32_bf16 v[60:63], v[200:203], v[184:187], 0
	v_mfma_f32_16x16x32_bf16 v[60:63], v[204:207], v[188:191], v[60:63]
	v_mfma_f32_16x16x32_bf16 v[56:59], v[212:215], v[188:191], 0
	v_mfma_f32_16x16x32_bf16 v[56:59], v[208:211], v[184:187], v[56:59]
	v_mfma_f32_16x16x32_bf16 v[48:51], v[208:211], v[192:195], 0
	v_mfma_f32_16x16x32_bf16 v[48:51], v[212:215], v[196:199], v[48:51]
	v_mfma_f32_16x16x32_bf16 v[52:55], v[204:207], v[196:199], 0
	v_mfma_f32_16x16x32_bf16 v[52:55], v[200:203], v[192:195], v[52:55]
	s_barrier
; #define STAGE(P, RS, SOFF, OFF, kt) do { const int _so = (SOFF) + (kt) * (BK * 2); \
;     _Pragma("unroll") for (int _i = 0; _i < 2; ++_i) { \
;       __builtin_amdgcn_raw_ptr_buffer_load_lds(RS, (__attribute__((address_space(3))) void*)((P) + wave * 1024 + _i * 8192), 16, OFF[_i], _so, 0, 0); } } while (0)
; #define LDA(dst, b, h) _Pragma("unroll") for (int m = 0; m < 4; ++m) _Pragma("unroll") for (int k = 0; k < 2; ++k) \
;     dst[m][k] = *reinterpret_cast<const bf16x8*>(SA(b, h) + lds_byte(wr * 64 + m * 16 + fr, k * 32 + fq * 8))
; #define LDB(dst, b, h) _Pragma("unroll") for (int n = 0; n < 2; ++n) _Pragma("unroll") for (int k = 0; k < 2; ++k) \
;     dst[n][k] = *reinterpret_cast<const bf16x8*>(SB(b, h) + lds_byte(wc * 32 + n * 16 + fr, k * 32 + fq * 8))
; #define WAIT_V(n) asm volatile("s_waitcnt vmcnt(" #n ")" ::: "memory")
; #define WAIT_L(n) asm volatile("s_waitcnt lgkmcnt(" #n ")" ::: "memory")
; #define BAR __builtin_amdgcn_s_barrier()
; #define SCHED __builtin_amdgcn_sched_barrier(0)
;     ...
;       LDA(At, 0, 1); STAGE(SA(0, 0), rsA, sA0, offA, t + 2);
;       BAR; WAIT_L(0); MMA(1, 0, At, B0); BAR; SCHED;
;       STAGE(SB(0, 1), rsB, sB1, offB, t + 2);
;       WAIT_V(6); BAR; MMA(1, 1, At, B1); BAR;
;       LDB(B0, 1, 0); SCHED; LDA(At, 1, 0); STAGE(SA(0, 1), rsA, sA1, offA, t + 2);
;       WAIT_L(8); BAR; WAIT_L(0); MMA(0, 0, At, B0); BAR; SCHED;
	s_add_i32 s23, s86, s5
	s_add_i32 s26, s23, 0x100
	s_mov_b32 m0, s33
	ds_read_b128 v[168:171], v129 offset:16384
	ds_read_b128 v[172:175], v129 offset:17408
	ds_read_b128 v[176:179], v132 offset:16384
	ds_read_b128 v[180:183], v132 offset:17408
	ds_read_b128 v[184:187], v131 offset:16384
	ds_read_b128 v[188:191], v131 offset:17408
	ds_read_b128 v[192:195], v130 offset:16384
	ds_read_b128 v[196:199], v130 offset:17408
	buffer_load_dwordx4 v141, s[8:11], s26 offen lds
	s_mov_b32 m0, s50
	s_nop 0
	buffer_load_dwordx4 v142, s[8:11], s26 offen lds
	s_barrier
	s_waitcnt lgkmcnt(0)
	v_mfma_f32_16x16x32_bf16 v[44:47], v[152:155], v[168:171], 0
	v_mfma_f32_16x16x32_bf16 v[44:47], v[156:159], v[172:175], v[44:47]
	v_mfma_f32_16x16x32_bf16 v[40:43], v[164:167], v[172:175], 0
	v_mfma_f32_16x16x32_bf16 v[40:43], v[160:163], v[168:171], v[40:43]
	v_mfma_f32_16x16x32_bf16 v[32:35], v[160:163], v[176:179], 0
	v_mfma_f32_16x16x32_bf16 v[32:35], v[164:167], v[180:183], v[32:35]
	v_mfma_f32_16x16x32_bf16 v[36:39], v[156:159], v[180:183], 0
	v_mfma_f32_16x16x32_bf16 v[36:39], v[152:155], v[176:179], v[36:39]
	v_mfma_f32_16x16x32_bf16 v[28:31], v[152:155], v[184:187], 0
	v_mfma_f32_16x16x32_bf16 v[28:31], v[156:159], v[188:191], v[28:31]
	v_mfma_f32_16x16x32_bf16 v[24:27], v[164:167], v[188:191], 0
	v_mfma_f32_16x16x32_bf16 v[24:27], v[160:163], v[184:187], v[24:27]
	v_mfma_f32_16x16x32_bf16 v[16:19], v[160:163], v[192:195], 0
	v_mfma_f32_16x16x32_bf16 v[16:19], v[164:167], v[196:199], v[16:19]
	v_mfma_f32_16x16x32_bf16 v[20:23], v[156:159], v[196:199], 0
	v_mfma_f32_16x16x32_bf16 v[20:23], v[152:155], v[192:195], v[20:23]
	s_barrier
	s_add_i32 s26, s90, s5
	s_add_i32 s27, s26, 0x100
	s_mov_b32 m0, s43
	s_nop 0
	buffer_load_dwordx4 v141, s[12:15], s27 offen lds
	s_mov_b32 m0, s51
	s_nop 0
	buffer_load_dwordx4 v142, s[12:15], s27 offen lds
	s_waitcnt vmcnt(6)
	s_barrier
	v_mfma_f32_16x16x32_bf16 v[12:15], v[200:203], v[168:171], 0
	v_mfma_f32_16x16x32_bf16 v[12:15], v[204:207], v[172:175], v[12:15]
	v_mfma_f32_16x16x32_bf16 v[8:11], v[212:215], v[172:175], 0
	v_mfma_f32_16x16x32_bf16 v[8:11], v[208:211], v[168:171], v[8:11]
	v_mfma_f32_16x16x32_bf16 v[0:3], v[208:211], v[176:179], 0
	v_mfma_f32_16x16x32_bf16 v[0:3], v[212:215], v[180:183], v[0:3]
	v_mfma_f32_16x16x32_bf16 v[4:7], v[204:207], v[180:183], 0
	v_mfma_f32_16x16x32_bf16 v[4:7], v[200:203], v[176:179], v[4:7]
	v_mfma_f32_16x16x32_bf16 v[64:67], v[200:203], v[184:187], 0
	v_mfma_f32_16x16x32_bf16 v[64:67], v[204:207], v[188:191], v[64:67]
	v_mfma_f32_16x16x32_bf16 v[72:75], v[212:215], v[188:191], 0
	v_mfma_f32_16x16x32_bf16 v[72:75], v[208:211], v[184:187], v[72:75]
	v_mfma_f32_16x16x32_bf16 v[84:87], v[208:211], v[192:195], 0
	v_mfma_f32_16x16x32_bf16 v[84:87], v[212:215], v[196:199], v[84:87]
	v_mfma_f32_16x16x32_bf16 v[76:79], v[204:207], v[196:199], 0
	v_mfma_f32_16x16x32_bf16 v[76:79], v[200:203], v[192:195], v[76:79]
	s_barrier
	ds_read_b128 v[152:155], v137
	ds_read_b128 v[156:159], v138
	ds_read_b128 v[160:163], v139
	ds_read_b128 v[164:167], v140
	s_addk_i32 s6, 0x100
	s_mov_b32 m0, s44
	ds_read_b128 v[168:171], v129 offset:32768
	ds_read_b128 v[172:175], v129 offset:33792
	ds_read_b128 v[176:179], v132 offset:32768
	ds_read_b128 v[180:183], v132 offset:33792
	ds_read_b128 v[184:187], v131 offset:32768
	ds_read_b128 v[188:191], v131 offset:33792
	ds_read_b128 v[192:195], v130 offset:32768
	ds_read_b128 v[196:199], v130 offset:33792
	buffer_load_dwordx4 v141, s[8:11], s6 offen lds
	s_mov_b32 m0, s52
	s_nop 0
	buffer_load_dwordx4 v142, s[8:11], s6 offen lds
	s_waitcnt lgkmcnt(8)
	s_barrier
; #define STAGE(P, RS, SOFF, OFF, kt) do { const int _so = (SOFF) + (kt) * (BK * 2); \
;     _Pragma("unroll") for (int _i = 0; _i < 2; ++_i) { \
;       __builtin_amdgcn_raw_ptr_buffer_load_lds(RS, (__attribute__((address_space(3))) void*)((P) + wave * 1024 + _i * 8192), 16, OFF[_i], _so, 0, 0); } } while (0)
; #define LDA(dst, b, h) _Pragma("unroll") for (int m = 0; m < 4; ++m) _Pragma("unroll") for (int k = 0; k < 2; ++k) \
;     dst[m][k] = *reinterpret_cast<const bf16x8*>(SA(b, h) + lds_byte(wr * 64 + m * 16 + fr, k * 32 + fq * 8))
; #define LDB(dst, b, h) _Pragma("unroll") for (int n = 0; n < 2; ++n) _Pragma("unroll") for (int k = 0; k < 2; ++k) \
;     dst[n][k] = *reinterpret_cast<const bf16x8*>(SB(b, h) + lds_byte(wc * 32 + n * 16 + fr, k * 32 + fq * 8))
; #define WAIT_V(n) asm volatile("s_waitcnt vmcnt(" #n ")" ::: "memory")
; #define WAIT_L(n) asm volatile("s_waitcnt lgkmcnt(" #n ")" ::: "memory")
; #define BAR __builtin_amdgcn_s_barrier()
; #define SCHED __builtin_amdgcn_sched_barrier(0)
;     ...
;       WAIT_L(8); BAR; WAIT_L(0); MMA(0, 0, At, B0); BAR; SCHED;
;       LDB(B1, 1, 1); STAGE(SB(1, 0), rsB, sB0, offB, t + 3);
;       BAR; WAIT_L(0); MMA(0, 1, At, B1); BAR;
;       LDA(At, 1, 1); STAGE(SA(1, 0), rsA, sA0, offA, t + 3);
;       BAR; WAIT_L(0); MMA(1, 0, At, B0); BAR; SCHED;
;       STAGE(SB(1, 1), rsB, sB1, offB, t + 3);
;       WAIT_V(6); BAR; MMA(1, 1, At, B1); BAR;
;     }
	s_waitcnt lgkmcnt(0)
	v_mfma_f32_16x16x32_bf16 v[124:127], v[152:155], v[168:171], v[124:127]
	v_mfma_f32_16x16x32_bf16 v[124:127], v[156:159], v[172:175], v[124:127]
	v_mfma_f32_16x16x32_bf16 v[120:123], v[164:167], v[172:175], v[120:123]
	v_mfma_f32_16x16x32_bf16 v[120:123], v[160:163], v[168:171], v[120:123]
	v_mfma_f32_16x16x32_bf16 v[112:115], v[160:163], v[176:179], v[112:115]
	v_mfma_f32_16x16x32_bf16 v[112:115], v[164:167], v[180:183], v[112:115]
	v_mfma_f32_16x16x32_bf16 v[116:119], v[156:159], v[180:183], v[116:119]
	v_mfma_f32_16x16x32_bf16 v[116:119], v[152:155], v[176:179], v[116:119]
	v_mfma_f32_16x16x32_bf16 v[108:111], v[152:155], v[184:187], v[108:111]
	v_mfma_f32_16x16x32_bf16 v[108:111], v[156:159], v[188:191], v[108:111]
	v_mfma_f32_16x16x32_bf16 v[104:107], v[164:167], v[188:191], v[104:107]
	v_mfma_f32_16x16x32_bf16 v[104:107], v[160:163], v[184:187], v[104:107]
	v_mfma_f32_16x16x32_bf16 v[96:99], v[160:163], v[192:195], v[96:99]
	v_mfma_f32_16x16x32_bf16 v[96:99], v[164:167], v[196:199], v[96:99]
	v_mfma_f32_16x16x32_bf16 v[100:103], v[156:159], v[196:199], v[100:103]
	v_mfma_f32_16x16x32_bf16 v[100:103], v[152:155], v[192:195], v[100:103]
	s_barrier
	s_addk_i32 s7, 0x180
	s_mov_b32 m0, s45
	ds_read_b128 v[200:203], v133
	ds_read_b128 v[204:207], v134
	ds_read_b128 v[208:211], v135
	ds_read_b128 v[212:215], v136
	buffer_load_dwordx4 v141, s[12:15], s7 offen lds
	s_mov_b32 m0, s53
	s_nop 0
	buffer_load_dwordx4 v142, s[12:15], s7 offen lds
	s_barrier
	s_waitcnt lgkmcnt(0)
	v_mfma_f32_16x16x32_bf16 v[92:95], v[200:203], v[168:171], v[92:95]
	v_mfma_f32_16x16x32_bf16 v[92:95], v[204:207], v[172:175], v[92:95]
	v_mfma_f32_16x16x32_bf16 v[88:91], v[212:215], v[172:175], v[88:91]
	v_mfma_f32_16x16x32_bf16 v[88:91], v[208:211], v[168:171], v[88:91]
	v_mfma_f32_16x16x32_bf16 v[68:71], v[208:211], v[176:179], v[68:71]
	v_mfma_f32_16x16x32_bf16 v[68:71], v[212:215], v[180:183], v[68:71]
	v_mfma_f32_16x16x32_bf16 v[80:83], v[204:207], v[180:183], v[80:83]
	v_mfma_f32_16x16x32_bf16 v[80:83], v[200:203], v[176:179], v[80:83]
	v_mfma_f32_16x16x32_bf16 v[60:63], v[200:203], v[184:187], v[60:63]
	v_mfma_f32_16x16x32_bf16 v[60:63], v[204:207], v[188:191], v[60:63]
	v_mfma_f32_16x16x32_bf16 v[56:59], v[212:215], v[188:191], v[56:59]
	v_mfma_f32_16x16x32_bf16 v[56:59], v[208:211], v[184:187], v[56:59]
	v_mfma_f32_16x16x32_bf16 v[48:51], v[208:211], v[192:195], v[48:51]
	v_mfma_f32_16x16x32_bf16 v[48:51], v[212:215], v[196:199], v[48:51]
	v_mfma_f32_16x16x32_bf16 v[52:55], v[204:207], v[196:199], v[52:55]
	v_mfma_f32_16x16x32_bf16 v[52:55], v[200:203], v[192:195], v[52:55]
	s_barrier
	s_addk_i32 s23, 0x180
	s_mov_b32 m0, s46
	ds_read_b128 v[168:171], v129 offset:49152
	ds_read_b128 v[172:175], v129 offset:50176
	ds_read_b128 v[176:179], v132 offset:49152
	ds_read_b128 v[180:183], v132 offset:50176
	ds_read_b128 v[184:187], v131 offset:49152
	ds_read_b128 v[188:191], v131 offset:50176
	ds_read_b128 v[192:195], v130 offset:49152
	ds_read_b128 v[196:199], v130 offset:50176
	buffer_load_dwordx4 v141, s[8:11], s23 offen lds
	s_mov_b32 m0, s54
	s_nop 0
	buffer_load_dwordx4 v142, s[8:11], s23 offen lds
	s_barrier
	s_waitcnt lgkmcnt(0)
	v_mfma_f32_16x16x32_bf16 v[44:47], v[152:155], v[168:171], v[44:47]
	v_mfma_f32_16x16x32_bf16 v[44:47], v[156:159], v[172:175], v[44:47]
	v_mfma_f32_16x16x32_bf16 v[40:43], v[164:167], v[172:175], v[40:43]
	v_mfma_f32_16x16x32_bf16 v[40:43], v[160:163], v[168:171], v[40:43]
	v_mfma_f32_16x16x32_bf16 v[32:35], v[160:163], v[176:179], v[32:35]
	v_mfma_f32_16x16x32_bf16 v[32:35], v[164:167], v[180:183], v[32:35]
	v_mfma_f32_16x16x32_bf16 v[36:39], v[156:159], v[180:183], v[36:39]
	v_mfma_f32_16x16x32_bf16 v[36:39], v[152:155], v[176:179], v[36:39]
	v_mfma_f32_16x16x32_bf16 v[28:31], v[152:155], v[184:187], v[28:31]
	v_mfma_f32_16x16x32_bf16 v[28:31], v[156:159], v[188:191], v[28:31]
	v_mfma_f32_16x16x32_bf16 v[24:27], v[164:167], v[188:191], v[24:27]
	v_mfma_f32_16x16x32_bf16 v[24:27], v[160:163], v[184:187], v[24:27]
	v_mfma_f32_16x16x32_bf16 v[16:19], v[160:163], v[192:195], v[16:19]
	v_mfma_f32_16x16x32_bf16 v[16:19], v[164:167], v[196:199], v[16:19]
	v_mfma_f32_16x16x32_bf16 v[20:23], v[156:159], v[196:199], v[20:23]
	v_mfma_f32_16x16x32_bf16 v[20:23], v[152:155], v[192:195], v[20:23]
	s_barrier
	s_addk_i32 s26, 0x180
	s_mov_b32 m0, s47
	s_nop 0
	buffer_load_dwordx4 v141, s[12:15], s26 offen lds
	s_mov_b32 m0, s55
	s_nop 0
	buffer_load_dwordx4 v142, s[12:15], s26 offen lds
	s_add_i32 s4, s4, 2
	s_addk_i32 s5, 0x100
	s_cmp_gt_u32 s4, 59
	s_cbranch_scc0 .LBB0_757
	s_branch .Lmy_post_757

; #define STAGE(P, RS, SOFF, OFF, kt) do { const int _so = (SOFF) + (kt) * (BK * 2); \
;     _Pragma("unroll") for (int _i = 0; _i < 2; ++_i) { \
;       __builtin_amdgcn_raw_ptr_buffer_load_lds(RS, (__attribute__((address_space(3))) void*)((P) + wave * 1024 + _i * 8192), 16, OFF[_i], _so, 0, 0); } } while (0)
; #define LDA(dst, b, h) _Pragma("unroll") for (int m = 0; m < 4; ++m) _Pragma("unroll") for (int k = 0; k < 2; ++k) \
;     dst[m][k] = *reinterpret_cast<const bf16x8*>(SA(b, h) + lds_byte(wr * 64 + m * 16 + fr, k * 32 + fq * 8))
; #define LDB(dst, b, h) _Pragma("unroll") for (int n = 0; n < 2; ++n) _Pragma("unroll") for (int k = 0; k < 2; ++k) \
;     dst[n][k] = *reinterpret_cast<const bf16x8*>(SB(b, h) + lds_byte(wc * 32 + n * 16 + fr, k * 32 + fq * 8))
; #define WAIT_V(n) asm volatile("s_waitcnt vmcnt(" #n ")" ::: "memory")
; #define WAIT_L(n) asm volatile("s_waitcnt lgkmcnt(" #n ")" ::: "memory")
; #define BAR __builtin_amdgcn_s_barrier()
;     ...
;       WAIT_V(6); BAR; MMA(1, 1, At, B1); BAR;
;     }
;     { LDB(B0, 0, 0); LDA(At, 0, 0); STAGE(SA(1, 1), rsA, sA1, offA, nt - 1);
;       BAR; WAIT_L(0); MMA(0, 0, At, B0); BAR;
;       LDB(B1, 0, 1); BAR; WAIT_L(0); MMA(0, 1, At, B1); BAR;
;       LDA(At, 0, 1); WAIT_V(4); BAR; WAIT_L(0); MMA(1, 0, At, B0); MMA(1, 1, At, B1); BAR; }
.Lmy_post_757:
	s_waitcnt vmcnt(6)
	s_barrier
	v_mfma_f32_16x16x32_bf16 v[12:15], v[200:203], v[168:171], v[12:15]
	v_mfma_f32_16x16x32_bf16 v[12:15], v[204:207], v[172:175], v[12:15]
	v_mfma_f32_16x16x32_bf16 v[8:11], v[212:215], v[172:175], v[8:11]
	v_mfma_f32_16x16x32_bf16 v[8:11], v[208:211], v[168:171], v[8:11]
	v_mfma_f32_16x16x32_bf16 v[0:3], v[208:211], v[176:179], v[0:3]
	v_mfma_f32_16x16x32_bf16 v[0:3], v[212:215], v[180:183], v[0:3]
	v_mfma_f32_16x16x32_bf16 v[4:7], v[204:207], v[180:183], v[4:7]
	v_mfma_f32_16x16x32_bf16 v[4:7], v[200:203], v[176:179], v[4:7]
	v_mfma_f32_16x16x32_bf16 v[64:67], v[200:203], v[184:187], v[64:67]
	v_mfma_f32_16x16x32_bf16 v[64:67], v[204:207], v[188:191], v[64:67]
	v_mfma_f32_16x16x32_bf16 v[72:75], v[212:215], v[188:191], v[72:75]
	v_mfma_f32_16x16x32_bf16 v[72:75], v[208:211], v[184:187], v[72:75]
	v_mfma_f32_16x16x32_bf16 v[84:87], v[208:211], v[192:195], v[84:87]
	v_mfma_f32_16x16x32_bf16 v[84:87], v[212:215], v[196:199], v[84:87]
	v_mfma_f32_16x16x32_bf16 v[76:79], v[204:207], v[196:199], v[76:79]
	v_mfma_f32_16x16x32_bf16 v[76:79], v[200:203], v[192:195], v[76:79]
	s_barrier
	s_add_i32 s4, s85, 0x1f80
	s_mov_b32 m0, s39
	ds_read_b128 v[152:155], v147
	ds_read_b128 v[156:159], v148
	ds_read_b128 v[160:163], v149
	ds_read_b128 v[148:151], v150
	ds_read_b128 v[164:167], v129
	ds_read_b128 v[168:171], v129 offset:1024
	ds_read_b128 v[172:175], v132
	ds_read_b128 v[176:179], v132 offset:1024
	ds_read_b128 v[180:183], v131
	ds_read_b128 v[184:187], v131 offset:1024
	ds_read_b128 v[188:191], v130
	ds_read_b128 v[192:195], v130 offset:1024
	buffer_load_dwordx4 v141, s[8:11], s4 offen lds
	s_mov_b32 m0, s56
	s_nop 0
	buffer_load_dwordx4 v142, s[8:11], s4 offen lds
	s_barrier
	s_waitcnt lgkmcnt(0)
	v_mfma_f32_16x16x32_bf16 v[124:127], v[152:155], v[164:167], v[124:127]
	v_mfma_f32_16x16x32_bf16 v[124:127], v[156:159], v[168:171], v[124:127]
	v_mfma_f32_16x16x32_bf16 v[120:123], v[148:151], v[168:171], v[120:123]
	v_mfma_f32_16x16x32_bf16 v[120:123], v[160:163], v[164:167], v[120:123]
	v_mfma_f32_16x16x32_bf16 v[112:115], v[160:163], v[172:175], v[112:115]
	v_mfma_f32_16x16x32_bf16 v[112:115], v[148:151], v[176:179], v[112:115]
	v_mfma_f32_16x16x32_bf16 v[116:119], v[156:159], v[176:179], v[116:119]
	v_mfma_f32_16x16x32_bf16 v[116:119], v[152:155], v[172:175], v[116:119]
	v_mfma_f32_16x16x32_bf16 v[108:111], v[152:155], v[180:183], v[108:111]
	v_mfma_f32_16x16x32_bf16 v[108:111], v[156:159], v[184:187], v[108:111]
	v_mfma_f32_16x16x32_bf16 v[104:107], v[148:151], v[184:187], v[104:107]
	v_mfma_f32_16x16x32_bf16 v[104:107], v[160:163], v[180:183], v[104:107]
	v_mfma_f32_16x16x32_bf16 v[96:99], v[160:163], v[188:191], v[96:99]
	v_mfma_f32_16x16x32_bf16 v[96:99], v[148:151], v[192:195], v[96:99]
	v_mfma_f32_16x16x32_bf16 v[100:103], v[156:159], v[192:195], v[100:103]
	v_mfma_f32_16x16x32_bf16 v[100:103], v[152:155], v[188:191], v[100:103]
	s_barrier
	ds_read_b128 v[196:199], v143
	ds_read_b128 v[200:203], v144
	ds_read_b128 v[142:145], v145
	ds_read_b128 v[204:207], v146
	s_barrier
	s_waitcnt lgkmcnt(0)
	v_mfma_f32_16x16x32_bf16 v[88:91], v[142:145], v[164:167], v[88:91]
	v_mfma_f32_16x16x32_bf16 v[80:83], v[196:199], v[172:175], v[80:83]
	v_mfma_f32_16x16x32_bf16 v[60:63], v[196:199], v[180:183], v[60:63]
	v_mfma_f32_16x16x32_bf16 v[56:59], v[142:145], v[180:183], v[56:59]
	v_mfma_f32_16x16x32_bf16 v[52:55], v[196:199], v[188:191], v[52:55]
	v_mfma_f32_16x16x32_bf16 v[48:51], v[142:145], v[188:191], v[48:51]
	v_mfma_f32_16x16x32_bf16 v[92:95], v[196:199], v[164:167], v[92:95]
	v_mfma_f32_16x16x32_bf16 v[68:71], v[142:145], v[172:175], v[68:71]
	v_mfma_f32_16x16x32_bf16 v[88:91], v[204:207], v[168:171], v[88:91]
	v_mfma_f32_16x16x32_bf16 v[80:83], v[200:203], v[176:179], v[80:83]
	v_mfma_f32_16x16x32_bf16 v[60:63], v[200:203], v[184:187], v[60:63]
	v_mfma_f32_16x16x32_bf16 v[56:59], v[204:207], v[184:187], v[56:59]
	v_mfma_f32_16x16x32_bf16 v[52:55], v[200:203], v[192:195], v[52:55]
	v_mfma_f32_16x16x32_bf16 v[48:51], v[204:207], v[192:195], v[48:51]
	v_mfma_f32_16x16x32_bf16 v[164:167], v[200:203], v[168:171], v[92:95]
	v_mfma_f32_16x16x32_bf16 v[168:171], v[204:207], v[176:179], v[68:71]
	s_barrier
	s_nop 0
	ds_read_b128 v[68:71], v129 offset:16384
	ds_read_b128 v[92:95], v129 offset:17408
	ds_read_b128 v[172:175], v132 offset:16384
	ds_read_b128 v[176:179], v132 offset:17408
	ds_read_b128 v[180:183], v131 offset:16384
	ds_read_b128 v[184:187], v131 offset:17408
	ds_read_b128 v[188:191], v130 offset:16384
	ds_read_b128 v[192:195], v130 offset:17408
	s_waitcnt vmcnt(4)
	s_barrier
; #define LDA(dst, b, h) _Pragma("unroll") for (int m = 0; m < 4; ++m) _Pragma("unroll") for (int k = 0; k < 2; ++k) \
;     dst[m][k] = *reinterpret_cast<const bf16x8*>(SA(b, h) + lds_byte(wr * 64 + m * 16 + fr, k * 32 + fq * 8))
; #define LDB(dst, b, h) _Pragma("unroll") for (int n = 0; n < 2; ++n) _Pragma("unroll") for (int k = 0; k < 2; ++k) \
;     dst[n][k] = *reinterpret_cast<const bf16x8*>(SB(b, h) + lds_byte(wc * 32 + n * 16 + fr, k * 32 + fq * 8))
; #define WAIT_V(n) asm volatile("s_waitcnt vmcnt(" #n ")" ::: "memory")
; #define WAIT_L(n) asm volatile("s_waitcnt lgkmcnt(" #n ")" ::: "memory")
; #define BAR __builtin_amdgcn_s_barrier()
;     ...
;       LDA(At, 0, 1); WAIT_V(4); BAR; WAIT_L(0); MMA(1, 0, At, B0); MMA(1, 1, At, B1); BAR; }
;     { LDB(B0, 1, 0); LDA(At, 1, 0); WAIT_V(2); BAR; WAIT_L(0); MMA(0, 0, At, B0); BAR;
	s_waitcnt lgkmcnt(0)
	v_mfma_f32_16x16x32_bf16 v[44:47], v[152:155], v[68:71], v[44:47]
	v_mfma_f32_16x16x32_bf16 v[40:43], v[160:163], v[68:71], v[40:43]
	v_mfma_f32_16x16x32_bf16 v[36:39], v[152:155], v[172:175], v[36:39]
	v_mfma_f32_16x16x32_bf16 v[32:35], v[160:163], v[172:175], v[32:35]
	v_mfma_f32_16x16x32_bf16 v[28:31], v[152:155], v[180:183], v[28:31]
	v_mfma_f32_16x16x32_bf16 v[24:27], v[160:163], v[180:183], v[24:27]
	v_mfma_f32_16x16x32_bf16 v[20:23], v[152:155], v[188:191], v[20:23]
	v_mfma_f32_16x16x32_bf16 v[16:19], v[160:163], v[188:191], v[16:19]
	v_mfma_f32_16x16x32_bf16 v[44:47], v[156:159], v[92:95], v[44:47]
	v_mfma_f32_16x16x32_bf16 v[40:43], v[148:151], v[92:95], v[40:43]
	v_mfma_f32_16x16x32_bf16 v[36:39], v[156:159], v[176:179], v[36:39]
	v_mfma_f32_16x16x32_bf16 v[32:35], v[148:151], v[176:179], v[32:35]
	v_mfma_f32_16x16x32_bf16 v[28:31], v[156:159], v[184:187], v[28:31]
	v_mfma_f32_16x16x32_bf16 v[24:27], v[148:151], v[184:187], v[24:27]
	v_mfma_f32_16x16x32_bf16 v[20:23], v[156:159], v[192:195], v[20:23]
	v_mfma_f32_16x16x32_bf16 v[16:19], v[148:151], v[192:195], v[16:19]
	v_mfma_f32_16x16x32_bf16 v[4:7], v[196:199], v[172:175], v[4:7]
	v_mfma_f32_16x16x32_bf16 v[0:3], v[142:145], v[172:175], v[0:3]
	v_mfma_f32_16x16x32_bf16 v[12:15], v[196:199], v[68:71], v[12:15]
	v_mfma_f32_16x16x32_bf16 v[8:11], v[142:145], v[68:71], v[8:11]
	v_mfma_f32_16x16x32_bf16 v[64:67], v[196:199], v[180:183], v[64:67]
	v_mfma_f32_16x16x32_bf16 v[68:71], v[142:145], v[180:183], v[72:75]
	v_mfma_f32_16x16x32_bf16 v[72:75], v[196:199], v[188:191], v[76:79]
	v_mfma_f32_16x16x32_bf16 v[76:79], v[142:145], v[188:191], v[84:87]
	v_mfma_f32_16x16x32_bf16 v[4:7], v[200:203], v[176:179], v[4:7]
	v_mfma_f32_16x16x32_bf16 v[0:3], v[204:207], v[176:179], v[0:3]
	v_mfma_f32_16x16x32_bf16 v[142:145], v[200:203], v[92:95], v[12:15]
	v_mfma_f32_16x16x32_bf16 v[146:149], v[204:207], v[92:95], v[8:11]
	v_mfma_f32_16x16x32_bf16 v[150:153], v[200:203], v[184:187], v[64:67]
	v_mfma_f32_16x16x32_bf16 v[154:157], v[204:207], v[184:187], v[68:71]
	v_mfma_f32_16x16x32_bf16 v[158:161], v[200:203], v[192:195], v[72:75]
	v_mfma_f32_16x16x32_bf16 v[172:175], v[204:207], v[192:195], v[76:79]
	s_barrier
	ds_read_b128 v[8:11], v137
	ds_read_b128 v[12:15], v138
	ds_read_b128 v[176:179], v139
	ds_read_b128 v[138:141], v140
	ds_read_b128 v[64:67], v129 offset:32768
	ds_read_b128 v[72:75], v129 offset:33792
	ds_read_b128 v[180:183], v132 offset:32768
	ds_read_b128 v[184:187], v132 offset:33792
	ds_read_b128 v[188:191], v131 offset:32768
	ds_read_b128 v[192:195], v131 offset:33792
	ds_read_b128 v[196:199], v130 offset:32768
	ds_read_b128 v[200:203], v130 offset:33792
	s_waitcnt vmcnt(2)
	s_barrier
	s_waitcnt lgkmcnt(0)
	v_mfma_f32_16x16x32_bf16 v[68:71], v[8:11], v[64:67], v[124:127]
	v_mfma_f32_16x16x32_bf16 v[76:79], v[176:179], v[64:67], v[120:123]
	v_mfma_f32_16x16x32_bf16 v[84:87], v[8:11], v[180:183], v[116:119]
	v_mfma_f32_16x16x32_bf16 v[92:95], v[176:179], v[180:183], v[112:115]
	v_mfma_f32_16x16x32_bf16 v[112:115], v[8:11], v[188:191], v[108:111]
	v_mfma_f32_16x16x32_bf16 v[104:107], v[176:179], v[188:191], v[104:107]
	v_mfma_f32_16x16x32_bf16 v[120:123], v[8:11], v[196:199], v[100:103]
	v_mfma_f32_16x16x32_bf16 v[96:99], v[176:179], v[196:199], v[96:99]
	v_mfma_f32_16x16x32_bf16 v[124:127], v[12:15], v[72:75], v[68:71]
	v_mfma_f32_16x16x32_bf16 v[116:119], v[138:141], v[72:75], v[76:79]
	v_mfma_f32_16x16x32_bf16 v[108:111], v[12:15], v[184:187], v[84:87]
	v_mfma_f32_16x16x32_bf16 v[100:103], v[138:141], v[184:187], v[92:95]
	v_mfma_f32_16x16x32_bf16 v[92:95], v[12:15], v[192:195], v[112:115]
	v_mfma_f32_16x16x32_bf16 v[84:87], v[138:141], v[192:195], v[104:107]
	v_mfma_f32_16x16x32_bf16 v[76:79], v[12:15], v[200:203], v[120:123]
	v_mfma_f32_16x16x32_bf16 v[68:71], v[138:141], v[200:203], v[96:99]
	s_barrier
; #define LDA(dst, b, h) _Pragma("unroll") for (int m = 0; m < 4; ++m) _Pragma("unroll") for (int k = 0; k < 2; ++k) \
;     dst[m][k] = *reinterpret_cast<const bf16x8*>(SA(b, h) + lds_byte(wr * 64 + m * 16 + fr, k * 32 + fq * 8))
; #define LDB(dst, b, h) _Pragma("unroll") for (int n = 0; n < 2; ++n) _Pragma("unroll") for (int k = 0; k < 2; ++k) \
;     dst[n][k] = *reinterpret_cast<const bf16x8*>(SB(b, h) + lds_byte(wc * 32 + n * 16 + fr, k * 32 + fq * 8))
; #define WAIT_V(n) asm volatile("s_waitcnt vmcnt(" #n ")" ::: "memory")
; #define WAIT_L(n) asm volatile("s_waitcnt lgkmcnt(" #n ")" ::: "memory")
; #define BAR __builtin_amdgcn_s_barrier()
;     ...
;     { LDB(B0, 1, 0); LDA(At, 1, 0); WAIT_V(2); BAR; WAIT_L(0); MMA(0, 0, At, B0); BAR;
;       LDB(B1, 1, 1); WAIT_V(0); BAR; WAIT_L(0); MMA(0, 1, At, B1); BAR;
;       LDA(At, 1, 1); BAR; WAIT_L(0); MMA(1, 0, At, B0); MMA(1, 1, At, B1); BAR; }
;     if (wr == 0) BAR;
	ds_read_b128 v[204:207], v133
	ds_read_b128 v[208:211], v134
	ds_read_b128 v[212:215], v135
	ds_read_b128 v[134:137], v136
	s_waitcnt vmcnt(0)
	s_barrier
	s_waitcnt lgkmcnt(0)
	v_mfma_f32_16x16x32_bf16 v[96:99], v[204:207], v[64:67], v[164:167]
	v_mfma_f32_16x16x32_bf16 v[64:67], v[212:215], v[64:67], v[88:91]
	v_mfma_f32_16x16x32_bf16 v[80:83], v[204:207], v[180:183], v[80:83]
	v_mfma_f32_16x16x32_bf16 v[88:91], v[212:215], v[180:183], v[168:171]
	v_mfma_f32_16x16x32_bf16 v[60:63], v[204:207], v[188:191], v[60:63]
	v_mfma_f32_16x16x32_bf16 v[56:59], v[212:215], v[188:191], v[56:59]
	v_mfma_f32_16x16x32_bf16 v[52:55], v[204:207], v[196:199], v[52:55]
	v_mfma_f32_16x16x32_bf16 v[48:51], v[212:215], v[196:199], v[48:51]
	v_mfma_f32_16x16x32_bf16 v[120:123], v[208:211], v[72:75], v[96:99]
	v_mfma_f32_16x16x32_bf16 v[112:115], v[134:137], v[72:75], v[64:67]
	v_mfma_f32_16x16x32_bf16 v[104:107], v[208:211], v[184:187], v[80:83]
	v_mfma_f32_16x16x32_bf16 v[96:99], v[134:137], v[184:187], v[88:91]
	v_mfma_f32_16x16x32_bf16 v[88:91], v[208:211], v[192:195], v[60:63]
	v_mfma_f32_16x16x32_bf16 v[80:83], v[134:137], v[192:195], v[56:59]
	v_mfma_f32_16x16x32_bf16 v[72:75], v[208:211], v[200:203], v[52:55]
	v_mfma_f32_16x16x32_bf16 v[64:67], v[134:137], v[200:203], v[48:51]
	s_barrier
	s_nop 0
	ds_read_b128 v[48:51], v129 offset:49152
	ds_read_b128 v[162:165], v129 offset:50176
	ds_read_b128 v[52:55], v132 offset:49152
	ds_read_b128 v[166:169], v132 offset:50176
	ds_read_b128 v[180:183], v131 offset:49152
	ds_read_b128 v[184:187], v131 offset:50176
	ds_read_b128 v[188:191], v130 offset:49152
	ds_read_b128 v[130:133], v130 offset:50176
	s_barrier
	s_waitcnt lgkmcnt(0)
	v_mfma_f32_16x16x32_bf16 v[44:47], v[8:11], v[48:51], v[44:47]
	v_mfma_f32_16x16x32_bf16 v[40:43], v[176:179], v[48:51], v[40:43]
	v_mfma_f32_16x16x32_bf16 v[36:39], v[8:11], v[52:55], v[36:39]
	v_mfma_f32_16x16x32_bf16 v[32:35], v[176:179], v[52:55], v[32:35]
	v_mfma_f32_16x16x32_bf16 v[28:31], v[8:11], v[180:183], v[28:31]
	v_mfma_f32_16x16x32_bf16 v[24:27], v[176:179], v[180:183], v[24:27]
	v_mfma_f32_16x16x32_bf16 v[8:11], v[8:11], v[188:191], v[20:23]
	v_mfma_f32_16x16x32_bf16 v[16:19], v[176:179], v[188:191], v[16:19]
	v_mfma_f32_16x16x32_bf16 v[60:63], v[12:15], v[162:165], v[44:47]
	v_mfma_f32_16x16x32_bf16 v[56:59], v[138:141], v[162:165], v[40:43]
	v_mfma_f32_16x16x32_bf16 v[44:47], v[12:15], v[166:169], v[36:39]
	v_mfma_f32_16x16x32_bf16 v[40:43], v[138:141], v[166:169], v[32:35]
	v_mfma_f32_16x16x32_bf16 v[28:31], v[12:15], v[184:187], v[28:31]
	v_mfma_f32_16x16x32_bf16 v[24:27], v[138:141], v[184:187], v[24:27]
	v_mfma_f32_16x16x32_bf16 v[12:15], v[12:15], v[130:133], v[8:11]
	v_mfma_f32_16x16x32_bf16 v[8:11], v[138:141], v[130:133], v[16:19]
	v_mfma_f32_16x16x32_bf16 v[16:19], v[204:207], v[48:51], v[142:145]
	v_mfma_f32_16x16x32_bf16 v[20:23], v[212:215], v[48:51], v[146:149]
	v_mfma_f32_16x16x32_bf16 v[4:7], v[204:207], v[52:55], v[4:7]
	v_mfma_f32_16x16x32_bf16 v[0:3], v[212:215], v[52:55], v[0:3]
	v_mfma_f32_16x16x32_bf16 v[138:141], v[204:207], v[180:183], v[150:153]
	v_mfma_f32_16x16x32_bf16 v[142:145], v[212:215], v[180:183], v[154:157]
	v_mfma_f32_16x16x32_bf16 v[146:149], v[204:207], v[188:191], v[158:161]
	v_mfma_f32_16x16x32_bf16 v[150:153], v[212:215], v[188:191], v[172:175]
	v_mfma_f32_16x16x32_bf16 v[52:55], v[208:211], v[162:165], v[16:19]
	v_mfma_f32_16x16x32_bf16 v[48:51], v[134:137], v[162:165], v[20:23]
	v_mfma_f32_16x16x32_bf16 v[36:39], v[208:211], v[166:169], v[4:7]
	v_mfma_f32_16x16x32_bf16 v[32:35], v[134:137], v[166:169], v[0:3]
	v_mfma_f32_16x16x32_bf16 v[20:23], v[208:211], v[184:187], v[138:141]
	v_mfma_f32_16x16x32_bf16 v[16:19], v[134:137], v[184:187], v[142:145]
	v_mfma_f32_16x16x32_bf16 v[4:7], v[208:211], v[130:133], v[146:149]
	v_mfma_f32_16x16x32_bf16 v[0:3], v[134:137], v[130:133], v[150:153]
	v_cmp_gt_u32_e32 vcc, s74, v128
	s_barrier
	s_and_saveexec_b64 s[4:5], vcc
	s_cbranch_execz .LBB0_760
	s_barrier
